# v29 + GEMM phases: per-block s_setprio flips removed, one static s_setprio 1 for waves 4-7 per GEMM phase, reset at seams
# baseline (speedup 1.0000x reference)
.LBB0_133:
	s_setprio 0
	v_readlane_b32 s2, v243, 51
	s_cmp_lt_i32 s2, 2
	s_cselect_b64 s[4:5], -1, 0
	s_and_b64 s[0:1], s[4:5], s[0:1]
	s_andn2_b64 vcc, exec, s[0:1]
	v_readlane_b32 s3, v243, 52
	s_cbranch_vccnz .LBB0_137
	v_readlane_b32 s0, v243, 0
	s_lshl_b32 s0, s0, 3
	v_readlane_b32 s1, v243, 59
	s_add_i32 s6, s1, s0
	s_cmp_gt_i32 s6, 0x81ff
	s_cbranch_scc1 .LBB0_137
	v_mbcnt_lo_u32_b32 v1, -1, 0
	v_mbcnt_hi_u32_b32 v2, -1, v1
	v_and_b32_e32 v1, 64, v2
	v_add_u32_e32 v3, 64, v1
	v_xor_b32_e32 v1, 1, v2
	v_cmp_lt_i32_e32 vcc, v1, v3
	v_xor_b32_e32 v4, 2, v2
	v_readlane_b32 s0, v243, 53
	v_cndmask_b32_e32 v1, v2, v1, vcc
	v_cmp_lt_i32_e32 vcc, v4, v3
	v_readlane_b32 s52, v243, 1
	s_lshl_b32 s8, s0, 3
	v_cndmask_b32_e32 v4, v2, v4, vcc
	v_lshlrev_b32_e32 v48, 2, v4
	v_xor_b32_e32 v4, 4, v2
	v_cmp_lt_i32_e32 vcc, v4, v3
	v_mov_b32_e32 v35, 0
	v_lshlrev_b32_e32 v34, 4, v166
	v_cndmask_b32_e32 v4, v2, v4, vcc
	v_lshlrev_b32_e32 v49, 2, v4
	v_xor_b32_e32 v4, 8, v2
	v_cmp_lt_i32_e32 vcc, v4, v3
	v_readlane_b32 s64, v243, 13
	v_readlane_b32 s65, v243, 14
	v_cndmask_b32_e32 v4, v2, v4, vcc
	v_lshlrev_b32_e32 v50, 2, v4
	v_xor_b32_e32 v4, 16, v2
	v_cmp_lt_i32_e32 vcc, v4, v3
	s_add_u32 s10, s50, 0x100000
	v_lshl_add_u64 v[36:37], s[64:65], 0, v[34:35]
	v_cndmask_b32_e32 v4, v2, v4, vcc
	v_lshlrev_b32_e32 v51, 2, v4
	v_xor_b32_e32 v4, 32, v2
	v_cmp_lt_i32_e32 vcc, v4, v3
	s_addc_u32 s11, s51, 0
	s_ashr_i32 s7, s6, 31
	v_cndmask_b32_e32 v2, v2, v4, vcc
	v_lshlrev_b32_e32 v52, 2, v2
	v_lshlrev_b32_e32 v2, 2, v166
	v_or_b32_e32 v10, 0x400, v2
	v_lshlrev_b32_e32 v34, 2, v10
	v_or_b32_e32 v12, 0x500, v2
	v_lshl_add_u64 v[38:39], s[64:65], 0, v[34:35]
	v_lshlrev_b32_e32 v34, 2, v12
	v_or_b32_e32 v14, 0x600, v2
	v_lshl_add_u64 v[40:41], s[64:65], 0, v[34:35]
	v_lshlrev_b32_e32 v34, 2, v14
	v_or_b32_e32 v16, 0x700, v2
	s_lshl_b64 s[0:1], s[6:7], 12
	v_lshl_add_u64 v[42:43], s[64:65], 0, v[34:35]
	v_lshlrev_b32_e32 v34, 2, v16
	s_add_u32 s0, s50, s0
	v_lshl_add_u64 v[44:45], s[64:65], 0, v[34:35]
	v_lshlrev_b32_e32 v34, 3, v166
	s_addc_u32 s1, s51, s1
	v_or_b32_e32 v4, 0x100, v2
	v_or_b32_e32 v6, 0x200, v2
	v_or_b32_e32 v8, 0x300, v2
	v_lshl_add_u64 v[18:19], s[0:1], 0, v[34:35]
	s_mov_b64 s[0:1], 0xd900000
	s_ashr_i32 s9, s8, 31
	v_lshlrev_b32_e32 v1, 2, v1
	v_readlane_b32 s53, v243, 2
	v_readlane_b32 s56, v243, 5
	v_readlane_b32 s57, v243, 6
	v_lshl_add_u64 v[46:47], v[18:19], 0, s[0:1]
	s_lshl_b64 s[0:1], s[8:9], 12
	s_movk_i32 s12, 0x4800
	v_lshlrev_b32_e32 v34, 4, v166
	s_movk_i32 s13, 0x1000
	v_lshlrev_b32_e32 v53, 2, v2
	v_lshlrev_b32_e32 v54, 2, v4
	v_lshlrev_b32_e32 v55, 2, v6
	v_lshlrev_b32_e32 v56, 2, v8
	v_lshlrev_b32_e32 v57, 2, v10
	v_lshlrev_b32_e32 v58, 2, v12
	v_lshlrev_b32_e32 v59, 2, v14
	v_lshlrev_b32_e32 v60, 2, v16
	v_mov_b32_e32 v61, 0x358637bd
	s_mov_b32 s14, 0xf800000
	v_mov_b32_e32 v62, 0x260
	s_movk_i32 s15, 0x7fff
	s_mov_b32 s16, 0xffff0000
	v_readlane_b32 s54, v243, 3
	v_readlane_b32 s55, v243, 4
	v_readlane_b32 s58, v243, 7
	v_readlane_b32 s59, v243, 8
	v_readlane_b32 s60, v243, 9
	v_readlane_b32 s61, v243, 10
	v_readlane_b32 s62, v243, 11
	v_readlane_b32 s63, v243, 12
	v_readlane_b32 s66, v243, 15
	v_readlane_b32 s67, v243, 16

.LBB0_191:
	s_setprio 0
	v_readlane_b32 s2, v243, 51
	s_cmp_lt_i32 s2, 3
	v_readlane_b32 s3, v243, 52
	s_cselect_b64 s[4:5], -1, 0
	s_add_u32 s2, s50, 0xd900000
	s_addc_u32 s3, s51, 0
	v_writelane_b32 v242, s2, 15
	s_nop 1
	v_writelane_b32 v242, s3, 16
	s_add_u32 s2, s50, 0x15b00000
	s_addc_u32 s3, s51, 0
	s_and_b64 s[0:1], s[4:5], s[0:1]
	v_writelane_b32 v242, s2, 17
	s_andn2_b64 vcc, exec, s[0:1]
	s_nop 0
	v_writelane_b32 v242, s3, 18
	s_cbranch_vccnz .LBB0_208
	v_readlane_b32 s0, v243, 0
	s_cmpk_gt_i32 s0, 0x1657
	v_readfirstlane_b32 s3, v0
	s_cbranch_scc1 .LBB0_208
	v_lshrrev_b32_e32 v1, 5, v0
	v_lshrrev_b32_e32 v3, 1, v0
	v_and_b32_e32 v1, 4, v1
	v_bfe_u32 v2, v0, 2, 2
	v_and_b32_e32 v13, 24, v3
	v_or3_b32 v1, v1, v2, v13
	v_lshlrev_b32_e32 v2, 4, v0
	v_or_b32_e32 v10, 0x2000, v2
	v_lshrrev_b32_e32 v3, 7, v10
	s_movk_i32 s0, 0x60
	v_readlane_b32 s2, v243, 0
	v_and_or_b32 v4, v3, s0, v1
	v_bfe_u32 v14, v0, 2, 4
	s_movk_i32 s0, 0x70
	s_ashr_i32 s24, s2, 31
	v_and_or_b32 v3, v3, s0, v14
	s_lshr_b32 s0, s24, 29
	s_add_i32 s0, s2, s0
	s_lshr_b32 s8, s3, 6
	s_ashr_i32 s1, s0, 3
	s_and_b32 s0, s0, -8
	s_lshr_b32 s10, s3, 8
	s_lshl_b32 s20, s8, 10
	s_sub_i32 s0, s2, s0
	s_cmp_lt_i32 s0, 0
	s_movk_i32 s25, 0x2cc
	s_cselect_b32 s2, s25, 0x2cb
	s_mul_i32 s0, s2, s0
	s_add_i32 s0, s0, s1
	s_mul_hi_i32 s1, s0, 0x2e8ba2e9
	s_lshr_b32 s2, s1, 31
	s_ashr_i32 s1, s1, 6
	v_and_b32_e32 v5, 32, v0
	s_add_i32 s1, s1, s2
	v_bitop3_b32 v11, v2, v5, 48 bitop3:0x6c
	v_and_b32_e32 v12, 64, v0
	s_lshl_b32 s6, s1, 3
	v_or_b32_e32 v2, v11, v12
	s_sub_i32 s2, 0x82, s6
	s_mulk_i32 s1, 0x160
	v_lshl_or_b32 v132, v3, 12, v2
	v_lshrrev_b32_e32 v3, 3, v0
	s_min_u32 s7, s2, 8
	s_sub_i32 s9, s0, s1
	v_lshl_or_b32 v130, v4, 12, v2
	v_and_or_b32 v1, v3, 32, v1
	s_sext_i32_i16 s0, s9
	v_cvt_f32_ubyte0_e32 v4, s7
	v_lshl_or_b32 v134, v1, 12, v2
	v_and_or_b32 v1, v3, 48, v14
	v_cvt_f32_i32_e32 v3, s0
	v_rcp_iflag_f32_e32 v5, v4
	v_lshl_or_b32 v136, v1, 12, v2
	s_ashr_i32 s0, s0, 30
	s_or_b32 s2, s0, 1
	v_mul_f32_e32 v1, v3, v5
	v_trunc_f32_e32 v1, v1
	v_fma_f32 v2, -v1, v4, v3
	v_cvt_i32_f32_e32 v1, v1
	v_cmp_ge_f32_e64 s[0:1], |v2|, v4
	s_and_b64 s[0:1], s[0:1], exec
	s_cselect_b32 s0, s2, 0
	v_readfirstlane_b32 s1, v1
	s_add_i32 s2, s1, s0
	s_mul_i32 s0, s2, s7
	s_sub_i32 s0, s9, s0
	s_sext_i32_i16 s0, s0
	s_add_i32 s30, s6, s0
	s_ashr_i32 s31, s30, 31
	s_bfe_i64 s[0:1], s[2:3], 0x100000
	s_lshl_b64 s[6:7], s[30:31], 20
	s_lshl_b64 s[0:1], s[0:1], 20
	v_readlane_b32 s9, v243, 60
	s_add_u32 s0, s9, s0
	v_readlane_b32 s9, v243, 61
	s_addc_u32 s1, s9, s1
	s_add_i32 s26, s20, 0
	s_add_i32 m0, s26, 0x10000
	v_mov_b32_e32 v135, 0
	global_load_lds_dwordx4 v134, s[0:1]
	s_add_i32 m0, s26, 0x12000
	s_add_u32 s12, s0, 0x80000
	global_load_lds_dwordx4 v130, s[0:1]
	s_addc_u32 s13, s1, 0
	s_add_i32 m0, s26, 0x14000
	v_mov_b32_e32 v131, v135
	global_load_lds_dwordx4 v134, s[12:13]
	s_add_i32 m0, s26, 0x16000
	v_mov_b32_e32 v137, v135
	global_load_lds_dwordx4 v130, s[12:13]
	v_readlane_b32 s12, v242, 15
	v_readlane_b32 s13, v242, 16
	s_add_u32 s22, s12, s6
	s_addc_u32 s23, s13, s7
	s_add_i32 s27, s26, 0x2000
	s_mov_b32 m0, s26
	s_add_u32 s6, s22, 0x80000
	global_load_lds_dwordx4 v136, s[22:23]
	s_mov_b32 m0, s27
	s_addc_u32 s7, s23, 0
	s_add_i32 s31, s26, 0x4000
	global_load_lds_dwordx4 v132, s[22:23]
	s_mov_b32 m0, s31
	s_add_i32 s33, s26, 0x6000
	global_load_lds_dwordx4 v136, s[6:7]
	s_mov_b32 m0, s33
	v_mov_b32_e32 v133, v135
	global_load_lds_dwordx4 v132, s[6:7]
	s_cmp_eq_u32 s10, 1
	s_mov_b32 s86, 0
	v_lshl_add_u64 v[8:9], s[0:1], 0, v[134:135]
	v_lshl_add_u64 v[6:7], s[0:1], 0, v[130:131]
	v_lshl_add_u64 v[2:3], s[22:23], 0, v[136:137]
	s_cselect_b64 s[6:7], -1, 0
	s_cmp_lg_u32 s10, 1
	v_lshl_add_u64 v[4:5], s[22:23], 0, v[132:133]
	s_cbranch_scc1 .LBB0_195
	s_barrier
	s_setprio 1

.LBB0_201:
	ds_read_b128 v[146:149], v152
	ds_read_b128 v[156:159], v152 offset:1024
	ds_read_b128 v[160:163], v152 offset:2048
	ds_read_b128 v[170:173], v152 offset:3072
	ds_read_b128 v[174:177], v153
	ds_read_b128 v[178:181], v153 offset:1024
	ds_read_b128 v[182:185], v153 offset:2048
	ds_read_b128 v[186:189], v153 offset:3072
	s_add_u32 s0, s34, 0xfff80080
	s_addc_u32 s1, s35, -1
	s_cmp_eq_u32 s73, 28
	s_cselect_b32 s23, s15, s1
	s_cselect_b32 s22, s69, s0
	s_cselect_b32 s1, s13, s72
	s_cselect_b32 s0, s70, s71
	v_lshl_add_u64 v[222:223], s[34:35], 0, v[138:139]
	s_add_i32 m0, s26, 0xc000
	ds_read_b128 v[190:193], v154
	ds_read_b128 v[194:197], v154 offset:1024
	ds_read_b128 v[198:201], v154 offset:2048
	ds_read_b128 v[202:205], v154 offset:3072
	ds_read_b128 v[206:209], v154 offset:4096
	ds_read_b128 v[210:213], v154 offset:5120
	ds_read_b128 v[214:217], v154 offset:6144
	ds_read_b128 v[218:221], v154 offset:7168
	global_load_lds_dwordx4 v[222:223], off
	v_lshl_add_u64 v[222:223], s[34:35], 0, v[140:141]
	s_add_i32 m0, s26, 0xe000
	s_nop 0
	global_load_lds_dwordx4 v[222:223], off
	s_waitcnt vmcnt(8)
	s_waitcnt lgkmcnt(0)
	s_barrier
	s_waitcnt lgkmcnt(0)
	v_mfma_f32_16x16x32_bf16 v[126:129], v[146:149], v[190:193], v[126:129]
	v_mfma_f32_16x16x32_bf16 v[118:121], v[160:163], v[190:193], v[118:121]
	v_mfma_f32_16x16x32_bf16 v[110:113], v[146:149], v[198:201], v[110:113]
	v_mfma_f32_16x16x32_bf16 v[102:105], v[160:163], v[198:201], v[102:105]
	v_mfma_f32_16x16x32_bf16 v[94:97], v[146:149], v[206:209], v[94:97]
	v_mfma_f32_16x16x32_bf16 v[86:89], v[160:163], v[206:209], v[86:89]
	v_mfma_f32_16x16x32_bf16 v[78:81], v[146:149], v[214:217], v[78:81]
	v_mfma_f32_16x16x32_bf16 v[70:73], v[160:163], v[214:217], v[70:73]
	v_mfma_f32_16x16x32_bf16 v[126:129], v[156:159], v[194:197], v[126:129]
	v_mfma_f32_16x16x32_bf16 v[118:121], v[170:173], v[194:197], v[118:121]
	v_mfma_f32_16x16x32_bf16 v[110:113], v[156:159], v[202:205], v[110:113]
	v_mfma_f32_16x16x32_bf16 v[102:105], v[170:173], v[202:205], v[102:105]
	v_mfma_f32_16x16x32_bf16 v[94:97], v[156:159], v[210:213], v[94:97]
	v_mfma_f32_16x16x32_bf16 v[86:89], v[170:173], v[210:213], v[86:89]
	v_mfma_f32_16x16x32_bf16 v[78:81], v[156:159], v[218:221], v[78:81]
	v_mfma_f32_16x16x32_bf16 v[70:73], v[170:173], v[218:221], v[70:73]
	v_mfma_f32_16x16x32_bf16 v[122:125], v[174:177], v[190:193], v[122:125]
	v_mfma_f32_16x16x32_bf16 v[114:117], v[182:185], v[190:193], v[114:117]
	v_mfma_f32_16x16x32_bf16 v[106:109], v[174:177], v[198:201], v[106:109]
	v_mfma_f32_16x16x32_bf16 v[98:101], v[182:185], v[198:201], v[98:101]
	v_mfma_f32_16x16x32_bf16 v[90:93], v[174:177], v[206:209], v[90:93]
	v_mfma_f32_16x16x32_bf16 v[82:85], v[182:185], v[206:209], v[82:85]
	v_mfma_f32_16x16x32_bf16 v[74:77], v[174:177], v[214:217], v[74:77]
	v_mfma_f32_16x16x32_bf16 v[66:69], v[182:185], v[214:217], v[66:69]
	v_mfma_f32_16x16x32_bf16 v[122:125], v[178:181], v[194:197], v[122:125]
	v_mfma_f32_16x16x32_bf16 v[114:117], v[186:189], v[194:197], v[114:117]
	v_mfma_f32_16x16x32_bf16 v[106:109], v[178:181], v[202:205], v[106:109]
	v_mfma_f32_16x16x32_bf16 v[98:101], v[186:189], v[202:205], v[98:101]
	v_mfma_f32_16x16x32_bf16 v[90:93], v[178:181], v[210:213], v[90:93]
	v_mfma_f32_16x16x32_bf16 v[82:85], v[186:189], v[210:213], v[82:85]
	v_mfma_f32_16x16x32_bf16 v[74:77], v[178:181], v[218:221], v[74:77]
	v_mfma_f32_16x16x32_bf16 v[66:69], v[186:189], v[218:221], v[66:69]
	s_barrier
	s_add_i32 s21, s90, s20
	v_lshl_add_u64 v[222:223], s[0:1], 0, v[134:135]
	s_mov_b32 m0, s21
	ds_read_b128 v[190:193], v154 offset:16384
	ds_read_b128 v[194:197], v154 offset:17408
	ds_read_b128 v[198:201], v154 offset:18432
	ds_read_b128 v[202:205], v154 offset:19456
	ds_read_b128 v[206:209], v154 offset:20480
	ds_read_b128 v[210:213], v154 offset:21504
	ds_read_b128 v[214:217], v154 offset:22528
	ds_read_b128 v[218:221], v154 offset:23552
	global_load_lds_dwordx4 v[222:223], off
	s_add_i32 m0, s21, 0x2000
	s_add_u32 s28, s0, 0x80000
	v_lshl_add_u64 v[224:225], s[0:1], 0, v[130:131]
	s_addc_u32 s29, s1, 0
	s_add_i32 s21, s91, s20
	global_load_lds_dwordx4 v[224:225], off
	v_lshl_add_u64 v[226:227], s[28:29], 0, v[134:135]
	s_mov_b32 m0, s21
	v_lshl_add_u64 v[228:229], s[22:23], 0, v[132:133]
	global_load_lds_dwordx4 v[226:227], off
	v_lshl_add_u64 v[226:227], s[28:29], 0, v[130:131]
	s_add_i32 m0, s21, 0x2000
	s_nop 0
	global_load_lds_dwordx4 v[226:227], off
	v_lshl_add_u64 v[226:227], s[22:23], 0, v[136:137]
	s_mov_b32 m0, s26
	s_nop 0
	global_load_lds_dwordx4 v[226:227], off
	s_mov_b32 m0, s27
	s_nop 0
	global_load_lds_dwordx4 v[228:229], off
	s_waitcnt vmcnt(8)
	s_waitcnt lgkmcnt(0)
	s_barrier
	s_waitcnt lgkmcnt(0)
	v_mfma_f32_16x16x32_bf16 v[62:65], v[146:149], v[190:193], v[62:65]
	v_mfma_f32_16x16x32_bf16 v[54:57], v[160:163], v[190:193], v[54:57]
	v_mfma_f32_16x16x32_bf16 v[46:49], v[146:149], v[198:201], v[46:49]
	v_mfma_f32_16x16x32_bf16 v[38:41], v[160:163], v[198:201], v[38:41]
	v_mfma_f32_16x16x32_bf16 v[30:33], v[146:149], v[206:209], v[30:33]
	v_mfma_f32_16x16x32_bf16 v[22:25], v[160:163], v[206:209], v[22:25]
	v_mfma_f32_16x16x32_bf16 v[14:17], v[146:149], v[214:217], v[14:17]
	v_mfma_f32_16x16x32_bf16 v[6:9], v[160:163], v[214:217], v[6:9]
	v_mfma_f32_16x16x32_bf16 v[62:65], v[156:159], v[194:197], v[62:65]
	v_mfma_f32_16x16x32_bf16 v[54:57], v[170:173], v[194:197], v[54:57]
	v_mfma_f32_16x16x32_bf16 v[46:49], v[156:159], v[202:205], v[46:49]
	v_mfma_f32_16x16x32_bf16 v[38:41], v[170:173], v[202:205], v[38:41]
	v_mfma_f32_16x16x32_bf16 v[30:33], v[156:159], v[210:213], v[30:33]
	v_mfma_f32_16x16x32_bf16 v[22:25], v[170:173], v[210:213], v[22:25]
	v_mfma_f32_16x16x32_bf16 v[14:17], v[156:159], v[218:221], v[14:17]
	v_mfma_f32_16x16x32_bf16 v[6:9], v[170:173], v[218:221], v[6:9]
	v_mfma_f32_16x16x32_bf16 v[58:61], v[174:177], v[190:193], v[58:61]
	v_mfma_f32_16x16x32_bf16 v[50:53], v[182:185], v[190:193], v[50:53]
	v_mfma_f32_16x16x32_bf16 v[42:45], v[174:177], v[198:201], v[42:45]
	v_mfma_f32_16x16x32_bf16 v[34:37], v[182:185], v[198:201], v[34:37]
	v_mfma_f32_16x16x32_bf16 v[26:29], v[174:177], v[206:209], v[26:29]
	v_mfma_f32_16x16x32_bf16 v[18:21], v[182:185], v[206:209], v[18:21]
	v_mfma_f32_16x16x32_bf16 v[10:13], v[174:177], v[214:217], v[10:13]
	v_mfma_f32_16x16x32_bf16 v[2:5], v[182:185], v[214:217], v[2:5]
	v_mfma_f32_16x16x32_bf16 v[58:61], v[178:181], v[194:197], v[58:61]
	v_mfma_f32_16x16x32_bf16 v[50:53], v[186:189], v[194:197], v[50:53]
	v_mfma_f32_16x16x32_bf16 v[42:45], v[178:181], v[202:205], v[42:45]
	v_mfma_f32_16x16x32_bf16 v[34:37], v[186:189], v[202:205], v[34:37]
	v_mfma_f32_16x16x32_bf16 v[26:29], v[178:181], v[210:213], v[26:29]
	v_mfma_f32_16x16x32_bf16 v[18:21], v[186:189], v[210:213], v[18:21]
	v_mfma_f32_16x16x32_bf16 v[10:13], v[178:181], v[218:221], v[10:13]
	v_mfma_f32_16x16x32_bf16 v[2:5], v[186:189], v[218:221], v[2:5]
	s_barrier
	s_add_i32 s21, 0, 0x18000
	v_add_u32_e32 v155, s21, v150
	s_add_i32 s28, 0, 0x1c000
	ds_read_b128 v[146:149], v155
	ds_read_b128 v[156:159], v155 offset:1024
	ds_read_b128 v[160:163], v155 offset:2048
	ds_read_b128 v[170:173], v155 offset:3072
	v_add_u32_e32 v155, s28, v150
	ds_read_b128 v[174:177], v155
	ds_read_b128 v[178:181], v155 offset:1024
	ds_read_b128 v[182:185], v155 offset:2048
	ds_read_b128 v[186:189], v155 offset:3072
	s_add_u32 s22, s22, 0x80000
	s_addc_u32 s23, s23, 0
	s_mov_b32 m0, s31
	v_lshl_add_u64 v[230:231], s[22:23], 0, v[136:137]
	ds_read_b128 v[190:193], v154 offset:32768
	ds_read_b128 v[194:197], v154 offset:33792
	ds_read_b128 v[198:201], v154 offset:34816
	ds_read_b128 v[202:205], v154 offset:35840
	ds_read_b128 v[206:209], v154 offset:36864
	ds_read_b128 v[210:213], v154 offset:37888
	ds_read_b128 v[214:217], v154 offset:38912
	ds_read_b128 v[218:221], v154 offset:39936
	global_load_lds_dwordx4 v[230:231], off
	v_lshl_add_u64 v[230:231], s[22:23], 0, v[132:133]
	s_mov_b32 m0, s33
	s_nop 0
	global_load_lds_dwordx4 v[230:231], off
	s_waitcnt vmcnt(8)
	s_waitcnt lgkmcnt(0)
	s_barrier
	s_waitcnt lgkmcnt(0)
	v_mfma_f32_16x16x32_bf16 v[126:129], v[146:149], v[190:193], v[126:129]
	v_mfma_f32_16x16x32_bf16 v[118:121], v[160:163], v[190:193], v[118:121]
	v_mfma_f32_16x16x32_bf16 v[110:113], v[146:149], v[198:201], v[110:113]
	v_mfma_f32_16x16x32_bf16 v[102:105], v[160:163], v[198:201], v[102:105]
	v_mfma_f32_16x16x32_bf16 v[94:97], v[146:149], v[206:209], v[94:97]
	v_mfma_f32_16x16x32_bf16 v[86:89], v[160:163], v[206:209], v[86:89]
	v_mfma_f32_16x16x32_bf16 v[78:81], v[146:149], v[214:217], v[78:81]
	v_mfma_f32_16x16x32_bf16 v[70:73], v[160:163], v[214:217], v[70:73]
	v_mfma_f32_16x16x32_bf16 v[126:129], v[156:159], v[194:197], v[126:129]
	v_mfma_f32_16x16x32_bf16 v[118:121], v[170:173], v[194:197], v[118:121]
	v_mfma_f32_16x16x32_bf16 v[110:113], v[156:159], v[202:205], v[110:113]
	v_mfma_f32_16x16x32_bf16 v[102:105], v[170:173], v[202:205], v[102:105]
	v_mfma_f32_16x16x32_bf16 v[94:97], v[156:159], v[210:213], v[94:97]
	v_mfma_f32_16x16x32_bf16 v[86:89], v[170:173], v[210:213], v[86:89]
	v_mfma_f32_16x16x32_bf16 v[78:81], v[156:159], v[218:221], v[78:81]
	v_mfma_f32_16x16x32_bf16 v[70:73], v[170:173], v[218:221], v[70:73]
	v_mfma_f32_16x16x32_bf16 v[122:125], v[174:177], v[190:193], v[122:125]
	v_mfma_f32_16x16x32_bf16 v[114:117], v[182:185], v[190:193], v[114:117]
	v_mfma_f32_16x16x32_bf16 v[106:109], v[174:177], v[198:201], v[106:109]
	v_mfma_f32_16x16x32_bf16 v[98:101], v[182:185], v[198:201], v[98:101]
	v_mfma_f32_16x16x32_bf16 v[90:93], v[174:177], v[206:209], v[90:93]
	v_mfma_f32_16x16x32_bf16 v[82:85], v[182:185], v[206:209], v[82:85]
	v_mfma_f32_16x16x32_bf16 v[74:77], v[174:177], v[214:217], v[74:77]
	v_mfma_f32_16x16x32_bf16 v[66:69], v[182:185], v[214:217], v[66:69]
	v_mfma_f32_16x16x32_bf16 v[122:125], v[178:181], v[194:197], v[122:125]
	v_mfma_f32_16x16x32_bf16 v[114:117], v[186:189], v[194:197], v[114:117]
	v_mfma_f32_16x16x32_bf16 v[106:109], v[178:181], v[202:205], v[106:109]
	v_mfma_f32_16x16x32_bf16 v[98:101], v[186:189], v[202:205], v[98:101]
	v_mfma_f32_16x16x32_bf16 v[90:93], v[178:181], v[210:213], v[90:93]
	v_mfma_f32_16x16x32_bf16 v[82:85], v[186:189], v[210:213], v[82:85]
	v_mfma_f32_16x16x32_bf16 v[74:77], v[178:181], v[218:221], v[74:77]
	v_mfma_f32_16x16x32_bf16 v[66:69], v[186:189], v[218:221], v[66:69]
	s_barrier
	s_add_i32 s21, s21, s20
	v_lshl_add_u64 v[222:223], v[222:223], 0, s[8:9]
	s_mov_b32 m0, s21
	ds_read_b128 v[190:193], v154 offset:49152
	ds_read_b128 v[194:197], v154 offset:50176
	ds_read_b128 v[198:201], v154 offset:51200
	ds_read_b128 v[202:205], v154 offset:52224
	ds_read_b128 v[206:209], v154 offset:53248
	ds_read_b128 v[210:213], v154 offset:54272
	ds_read_b128 v[214:217], v154 offset:55296
	ds_read_b128 v[218:221], v154 offset:56320
	global_load_lds_dwordx4 v[222:223], off
	s_add_i32 m0, s21, 0x2000
	s_add_u32 s0, s0, 0x80080
	v_lshl_add_u64 v[222:223], v[224:225], 0, s[8:9]
	s_addc_u32 s1, s1, 0
	s_add_i32 s21, s28, s20
	global_load_lds_dwordx4 v[222:223], off
	v_lshl_add_u64 v[222:223], s[0:1], 0, v[134:135]
	s_mov_b32 m0, s21
	s_nop 0
	global_load_lds_dwordx4 v[222:223], off
	v_lshl_add_u64 v[222:223], s[0:1], 0, v[130:131]
	s_add_i32 m0, s21, 0x2000
	s_nop 0
	global_load_lds_dwordx4 v[222:223], off
	v_lshl_add_u64 v[222:223], v[226:227], 0, s[8:9]
	s_mov_b32 m0, s87
	s_nop 0
	global_load_lds_dwordx4 v[222:223], off
	v_lshl_add_u64 v[222:223], v[228:229], 0, s[8:9]
	s_mov_b32 m0, s88
	s_nop 0
	global_load_lds_dwordx4 v[222:223], off
	s_waitcnt vmcnt(8)
	s_waitcnt lgkmcnt(0)
	s_barrier
	s_waitcnt lgkmcnt(0)
	v_mfma_f32_16x16x32_bf16 v[62:65], v[146:149], v[190:193], v[62:65]
	v_mfma_f32_16x16x32_bf16 v[54:57], v[160:163], v[190:193], v[54:57]
	v_mfma_f32_16x16x32_bf16 v[46:49], v[146:149], v[198:201], v[46:49]
	v_mfma_f32_16x16x32_bf16 v[38:41], v[160:163], v[198:201], v[38:41]
	v_mfma_f32_16x16x32_bf16 v[30:33], v[146:149], v[206:209], v[30:33]
	v_mfma_f32_16x16x32_bf16 v[22:25], v[160:163], v[206:209], v[22:25]
	v_mfma_f32_16x16x32_bf16 v[14:17], v[146:149], v[214:217], v[14:17]
	v_mfma_f32_16x16x32_bf16 v[6:9], v[160:163], v[214:217], v[6:9]
	v_mfma_f32_16x16x32_bf16 v[62:65], v[156:159], v[194:197], v[62:65]
	v_mfma_f32_16x16x32_bf16 v[54:57], v[170:173], v[194:197], v[54:57]
	v_mfma_f32_16x16x32_bf16 v[46:49], v[156:159], v[202:205], v[46:49]
	v_mfma_f32_16x16x32_bf16 v[38:41], v[170:173], v[202:205], v[38:41]
	v_mfma_f32_16x16x32_bf16 v[30:33], v[156:159], v[210:213], v[30:33]
	v_mfma_f32_16x16x32_bf16 v[22:25], v[170:173], v[210:213], v[22:25]
	v_mfma_f32_16x16x32_bf16 v[14:17], v[156:159], v[218:221], v[14:17]
	v_mfma_f32_16x16x32_bf16 v[6:9], v[170:173], v[218:221], v[6:9]
	v_mfma_f32_16x16x32_bf16 v[58:61], v[174:177], v[190:193], v[58:61]
	v_mfma_f32_16x16x32_bf16 v[50:53], v[182:185], v[190:193], v[50:53]
	v_mfma_f32_16x16x32_bf16 v[42:45], v[174:177], v[198:201], v[42:45]
	v_mfma_f32_16x16x32_bf16 v[34:37], v[182:185], v[198:201], v[34:37]
	v_mfma_f32_16x16x32_bf16 v[26:29], v[174:177], v[206:209], v[26:29]
	v_mfma_f32_16x16x32_bf16 v[18:21], v[182:185], v[206:209], v[18:21]
	v_mfma_f32_16x16x32_bf16 v[10:13], v[174:177], v[214:217], v[10:13]
	v_mfma_f32_16x16x32_bf16 v[2:5], v[182:185], v[214:217], v[2:5]
	v_mfma_f32_16x16x32_bf16 v[58:61], v[178:181], v[194:197], v[58:61]
	v_mfma_f32_16x16x32_bf16 v[50:53], v[186:189], v[194:197], v[50:53]
	v_mfma_f32_16x16x32_bf16 v[42:45], v[178:181], v[202:205], v[42:45]
	v_mfma_f32_16x16x32_bf16 v[34:37], v[186:189], v[202:205], v[34:37]
	v_mfma_f32_16x16x32_bf16 v[26:29], v[178:181], v[210:213], v[26:29]
	v_mfma_f32_16x16x32_bf16 v[18:21], v[186:189], v[210:213], v[18:21]
	v_mfma_f32_16x16x32_bf16 v[10:13], v[178:181], v[218:221], v[10:13]
	v_mfma_f32_16x16x32_bf16 v[2:5], v[186:189], v[218:221], v[2:5]
	s_barrier
	s_add_i32 s73, s73, 2
	s_add_u32 s34, s34, 0x100
	s_addc_u32 s35, s35, 0
	s_add_u32 s71, s71, 0x100
	s_addc_u32 s72, s72, 0
	s_cmp_gt_u32 s73, 29
	s_cbranch_scc0 .LBB0_201
	s_and_b64 vcc, exec, s[10:11]
	s_cbranch_vccz .LBB0_204
	s_barrier

.LBB0_262:
	s_setprio 0
	v_readlane_b32 s2, v243, 51
	s_cmp_lt_i32 s2, 4
	v_readlane_b32 s3, v243, 52
	s_cselect_b64 s[52:53], -1, 0
	s_add_u32 s2, s50, 0x200000
	s_addc_u32 s3, s51, 0
	v_writelane_b32 v242, s2, 19
	s_nop 1
	v_writelane_b32 v242, s3, 20
	s_add_u32 s2, s50, 0x2e100000
	s_addc_u32 s3, s51, 0
	s_and_b64 s[0:1], s[52:53], s[0:1]
	v_writelane_b32 v242, s2, 21
	s_andn2_b64 vcc, exec, s[0:1]
	s_nop 0
	v_writelane_b32 v242, s3, 22
	s_cbranch_vccnz .LBB0_308
	v_readlane_b32 s4, v243, 53
	s_abs_i32 s0, s4
	v_cvt_f32_u32_e32 v1, s0
	v_readlane_b32 s6, v243, 0
	s_sub_i32 s1, s4, s6
	s_add_i32 s2, s1, 0x3ff
	v_rcp_iflag_f32_e32 v1, v1
	s_sub_i32 s1, 0xfffffc01, s1
	s_xor_b32 s4, s2, s4
	s_sub_i32 s3, 0, s0
	v_mul_f32_e32 v1, 0x4f7ffffe, v1
	v_cvt_u32_f32_e32 v1, v1
	s_max_i32 s1, s2, s1
	s_ashr_i32 s2, s4, 31
	v_readfirstlane_b32 s4, v1
	s_mul_i32 s3, s3, s4
	s_mul_hi_u32 s3, s4, s3
	s_add_i32 s4, s4, s3
	s_mul_hi_u32 s3, s1, s4
	s_mul_i32 s4, s3, s0
	s_sub_i32 s1, s1, s4
	s_add_i32 s5, s3, 1
	s_sub_i32 s4, s1, s0
	s_cmp_ge_u32 s1, s0
	s_cselect_b32 s3, s5, s3
	s_cselect_b32 s1, s4, s1
	s_add_i32 s4, s3, 1
	s_cmp_ge_u32 s1, s0
	s_cselect_b32 s0, s4, s3
	s_xor_b32 s0, s0, s2
	s_sub_i32 s20, s0, s2
	s_cmp_lt_i32 s20, 1
	v_readfirstlane_b32 s4, v0
	s_cbranch_scc1 .LBB0_267
	s_mov_b64 s[0:1], 0
	s_cmpk_gt_i32 s6, 0x3ff
	s_mov_b64 s[2:3], 0
	s_cbranch_scc1 .LBB0_268
	v_readlane_b32 s3, v243, 0
	s_ashr_i32 s2, s3, 31
	s_lshr_b32 s2, s2, 29
	s_add_i32 s5, s3, s2
	s_and_b32 s2, s5, -8
	s_sub_i32 s6, s3, s2
	s_cmp_gt_i32 s6, -1
	s_cbranch_scc0 .LBB0_272
	s_lshl_b32 s7, s6, 7
	s_cbranch_execz .LBB0_273
	s_branch .LBB0_274

.LBB0_275:
	s_andn2_b64 vcc, exec, s[2:3]
	s_cbranch_vccnz .LBB0_308
	v_lshlrev_b32_e32 v1, 4, v0
	v_and_b32_e32 v2, 32, v0
	v_bfe_u32 v3, v0, 2, 4
	v_bitop3_b32 v10, v1, v2, 48 bitop3:0x6c
	v_lshrrev_b32_e32 v2, 3, v0
	s_add_u32 s54, s50, 0x6500000
	v_and_or_b32 v4, v2, 48, v3
	v_or_b32_e32 v2, 64, v2
	s_movk_i32 s0, 0x70
	s_addc_u32 s30, s51, 0
	v_and_or_b32 v2, v2, s0, v3
	s_lshr_b32 s3, s4, 6
	s_lshl_b32 s0, s18, 10
	s_lshr_b32 s2, s4, 8
	s_lshl_b32 s31, s3, 10
	s_addk_i32 s0, 0xfc00
	s_cmp_lg_u32 s18, 0
	s_cselect_b32 s8, s0, 0
	s_ashr_i32 s9, s8, 31
	s_mul_i32 s1, s17, 0x2c0000
	s_mul_hi_i32 s0, s17, 0x2c0000
	s_add_u32 s1, s54, s1
	s_addc_u32 s7, s30, s0
	v_and_b32_e32 v11, 64, v0
	s_add_u32 s0, s1, s8
	v_or_b32_e32 v1, v10, v11
	v_mul_u32_u24_e32 v12, 0x2c00, v4
	s_addc_u32 s1, s7, s9
	s_add_i32 s33, s31, 0
	v_or_b32_e32 v134, v12, v1
	s_add_i32 m0, s33, 0x10000
	s_mul_i32 s6, s16, 0x2c0000
	global_load_lds_dwordx4 v134, s[0:1]
	s_add_i32 m0, s33, 0x12000
	v_readlane_b32 s10, v242, 17
	s_mul_hi_i32 s5, s16, 0x2c0000
	v_readlane_b32 s11, v242, 18
	s_add_u32 s10, s10, s6
	v_mul_u32_u24_e32 v13, 0x2c00, v2
	s_addc_u32 s5, s11, s5
	v_or_b32_e32 v136, v13, v1
	s_add_u32 s6, s0, 0x160000
	global_load_lds_dwordx4 v136, s[0:1]
	s_addc_u32 s7, s1, 0
	s_add_i32 m0, s33, 0x14000
	v_mov_b32_e32 v135, 0
	global_load_lds_dwordx4 v134, s[6:7]
	s_add_i32 m0, s33, 0x16000
	s_add_u32 s24, s10, s8
	s_addc_u32 s25, s5, s9
	s_add_i32 s34, s33, 0x2000
	global_load_lds_dwordx4 v136, s[6:7]
	s_mov_b32 m0, s33
	s_add_u32 s6, s24, 0x160000
	global_load_lds_dwordx4 v134, s[24:25]
	s_mov_b32 m0, s34
	s_addc_u32 s7, s25, 0
	s_add_i32 s35, s33, 0x4000
	global_load_lds_dwordx4 v136, s[24:25]
	s_mov_b32 m0, s35
	s_add_i32 s90, s33, 0x6000
	global_load_lds_dwordx4 v134, s[6:7]
	s_mov_b32 m0, s90
	v_mov_b32_e32 v137, v135
	global_load_lds_dwordx4 v136, s[6:7]
	s_cmp_eq_u32 s2, 1
	s_mov_b32 s91, 0
	v_lshl_add_u64 v[8:9], s[0:1], 0, v[134:135]
	v_lshl_add_u64 v[6:7], s[0:1], 0, v[136:137]
	v_lshl_add_u64 v[2:3], s[24:25], 0, v[134:135]
	s_cselect_b64 s[56:57], -1, 0
	s_cmp_lg_u32 s2, 1
	v_lshl_add_u64 v[4:5], s[24:25], 0, v[136:137]
	s_cbranch_scc1 .LBB0_278
	s_barrier
	s_setprio 1

.LBB0_297:
	ds_read_b128 v[130:133], v169
	ds_read_b128 v[160:163], v169 offset:1024
	ds_read_b128 v[170:173], v169 offset:2048
	ds_read_b128 v[174:177], v169 offset:3072
	ds_read_b128 v[178:181], v196
	ds_read_b128 v[182:185], v196 offset:1024
	ds_read_b128 v[186:189], v196 offset:2048
	ds_read_b128 v[190:193], v196 offset:3072
	s_add_i32 s69, s22, 2
	s_add_u32 s0, s88, 0xffea0080
	s_addc_u32 s1, s89, -1
	s_cmp_eq_u32 s68, s22
	s_cselect_b32 s22, s12, s0
	s_cselect_b32 s23, s13, s1
	s_cselect_b32 s1, s15, s25
	s_cselect_b32 s0, s14, s24
	v_lshl_add_u64 v[194:195], s[88:89], 0, v[154:155]
	s_add_i32 m0, s33, 0xc000
	ds_read_b128 v[198:201], v197
	ds_read_b128 v[202:205], v197 offset:1024
	ds_read_b128 v[206:209], v197 offset:2048
	ds_read_b128 v[210:213], v197 offset:3072
	ds_read_b128 v[214:217], v197 offset:4096
	ds_read_b128 v[218:221], v197 offset:5120
	ds_read_b128 v[222:225], v197 offset:6144
	ds_read_b128 v[226:229], v197 offset:7168
	global_load_lds_dwordx4 v[194:195], off
	v_lshl_add_u64 v[194:195], s[88:89], 0, v[156:157]
	s_add_i32 m0, s33, 0xe000
	s_nop 0
	global_load_lds_dwordx4 v[194:195], off
	s_waitcnt vmcnt(8)
	s_waitcnt lgkmcnt(0)
	s_barrier
	s_waitcnt lgkmcnt(0)
	v_mfma_f32_16x16x32_bf16 v[126:129], v[130:133], v[198:201], v[126:129]
	v_mfma_f32_16x16x32_bf16 v[94:97], v[170:173], v[198:201], v[94:97]
	v_mfma_f32_16x16x32_bf16 v[122:125], v[130:133], v[206:209], v[122:125]
	v_mfma_f32_16x16x32_bf16 v[90:93], v[170:173], v[206:209], v[90:93]
	v_mfma_f32_16x16x32_bf16 v[118:121], v[130:133], v[214:217], v[118:121]
	v_mfma_f32_16x16x32_bf16 v[86:89], v[170:173], v[214:217], v[86:89]
	v_mfma_f32_16x16x32_bf16 v[114:117], v[130:133], v[222:225], v[114:117]
	v_mfma_f32_16x16x32_bf16 v[82:85], v[170:173], v[222:225], v[82:85]
	v_mfma_f32_16x16x32_bf16 v[126:129], v[160:163], v[202:205], v[126:129]
	v_mfma_f32_16x16x32_bf16 v[94:97], v[174:177], v[202:205], v[94:97]
	v_mfma_f32_16x16x32_bf16 v[122:125], v[160:163], v[210:213], v[122:125]
	v_mfma_f32_16x16x32_bf16 v[90:93], v[174:177], v[210:213], v[90:93]
	v_mfma_f32_16x16x32_bf16 v[118:121], v[160:163], v[218:221], v[118:121]
	v_mfma_f32_16x16x32_bf16 v[86:89], v[174:177], v[218:221], v[86:89]
	v_mfma_f32_16x16x32_bf16 v[114:117], v[160:163], v[226:229], v[114:117]
	v_mfma_f32_16x16x32_bf16 v[82:85], v[174:177], v[226:229], v[82:85]
	v_mfma_f32_16x16x32_bf16 v[66:69], v[178:181], v[198:201], v[66:69]
	v_mfma_f32_16x16x32_bf16 v[38:41], v[186:189], v[198:201], v[38:41]
	v_mfma_f32_16x16x32_bf16 v[58:61], v[178:181], v[206:209], v[58:61]
	v_mfma_f32_16x16x32_bf16 v[30:33], v[186:189], v[206:209], v[30:33]
	v_mfma_f32_16x16x32_bf16 v[54:57], v[178:181], v[214:217], v[54:57]
	v_mfma_f32_16x16x32_bf16 v[22:25], v[186:189], v[214:217], v[22:25]
	v_mfma_f32_16x16x32_bf16 v[50:53], v[178:181], v[222:225], v[50:53]
	v_mfma_f32_16x16x32_bf16 v[18:21], v[186:189], v[222:225], v[18:21]
	v_mfma_f32_16x16x32_bf16 v[66:69], v[182:185], v[202:205], v[66:69]
	v_mfma_f32_16x16x32_bf16 v[38:41], v[190:193], v[202:205], v[38:41]
	v_mfma_f32_16x16x32_bf16 v[58:61], v[182:185], v[210:213], v[58:61]
	v_mfma_f32_16x16x32_bf16 v[30:33], v[190:193], v[210:213], v[30:33]
	v_mfma_f32_16x16x32_bf16 v[54:57], v[182:185], v[218:221], v[54:57]
	v_mfma_f32_16x16x32_bf16 v[22:25], v[190:193], v[218:221], v[22:25]
	v_mfma_f32_16x16x32_bf16 v[50:53], v[182:185], v[226:229], v[50:53]
	v_mfma_f32_16x16x32_bf16 v[18:21], v[190:193], v[226:229], v[18:21]
	s_barrier
	s_add_i32 s21, s4, s31
	v_lshl_add_u64 v[194:195], s[0:1], 0, v[134:135]
	s_mov_b32 m0, s21
	ds_read_b128 v[198:201], v197 offset:16384
	ds_read_b128 v[202:205], v197 offset:17408
	ds_read_b128 v[206:209], v197 offset:18432
	ds_read_b128 v[210:213], v197 offset:19456
	ds_read_b128 v[214:217], v197 offset:20480
	ds_read_b128 v[218:221], v197 offset:21504
	ds_read_b128 v[222:225], v197 offset:22528
	ds_read_b128 v[226:229], v197 offset:23552
	global_load_lds_dwordx4 v[194:195], off
	s_add_i32 m0, s21, 0x2000
	s_add_u32 s28, s0, 0x160000
	v_lshl_add_u64 v[230:231], s[0:1], 0, v[136:137]
	s_addc_u32 s29, s1, 0
	s_add_i32 s21, s5, s31
	global_load_lds_dwordx4 v[230:231], off
	v_lshl_add_u64 v[232:233], s[28:29], 0, v[134:135]
	s_mov_b32 m0, s21
	v_lshl_add_u64 v[234:235], s[22:23], 0, v[136:137]
	global_load_lds_dwordx4 v[232:233], off
	v_lshl_add_u64 v[232:233], s[28:29], 0, v[136:137]
	s_add_i32 m0, s21, 0x2000
	s_nop 0
	global_load_lds_dwordx4 v[232:233], off
	v_lshl_add_u64 v[232:233], s[22:23], 0, v[134:135]
	s_mov_b32 m0, s33
	s_nop 0
	global_load_lds_dwordx4 v[232:233], off
	s_mov_b32 m0, s34
	s_nop 0
	global_load_lds_dwordx4 v[234:235], off
	s_waitcnt vmcnt(8)
	s_waitcnt lgkmcnt(0)
	s_barrier
	s_waitcnt lgkmcnt(0)
	v_mfma_f32_16x16x32_bf16 v[110:113], v[130:133], v[198:201], v[110:113]
	v_mfma_f32_16x16x32_bf16 v[78:81], v[170:173], v[198:201], v[78:81]
	v_mfma_f32_16x16x32_bf16 v[106:109], v[130:133], v[206:209], v[106:109]
	v_mfma_f32_16x16x32_bf16 v[74:77], v[170:173], v[206:209], v[74:77]
	v_mfma_f32_16x16x32_bf16 v[102:105], v[130:133], v[214:217], v[102:105]
	v_mfma_f32_16x16x32_bf16 v[70:73], v[170:173], v[214:217], v[70:73]
	v_mfma_f32_16x16x32_bf16 v[98:101], v[130:133], v[222:225], v[98:101]
	v_mfma_f32_16x16x32_bf16 v[62:65], v[170:173], v[222:225], v[62:65]
	v_mfma_f32_16x16x32_bf16 v[110:113], v[160:163], v[202:205], v[110:113]
	v_mfma_f32_16x16x32_bf16 v[78:81], v[174:177], v[202:205], v[78:81]
	v_mfma_f32_16x16x32_bf16 v[106:109], v[160:163], v[210:213], v[106:109]
	v_mfma_f32_16x16x32_bf16 v[74:77], v[174:177], v[210:213], v[74:77]
	v_mfma_f32_16x16x32_bf16 v[102:105], v[160:163], v[218:221], v[102:105]
	v_mfma_f32_16x16x32_bf16 v[70:73], v[174:177], v[218:221], v[70:73]
	v_mfma_f32_16x16x32_bf16 v[98:101], v[160:163], v[226:229], v[98:101]
	v_mfma_f32_16x16x32_bf16 v[62:65], v[174:177], v[226:229], v[62:65]
	v_mfma_f32_16x16x32_bf16 v[46:49], v[178:181], v[198:201], v[46:49]
	v_mfma_f32_16x16x32_bf16 v[14:17], v[186:189], v[198:201], v[14:17]
	v_mfma_f32_16x16x32_bf16 v[42:45], v[178:181], v[206:209], v[42:45]
	v_mfma_f32_16x16x32_bf16 v[10:13], v[186:189], v[206:209], v[10:13]
	v_mfma_f32_16x16x32_bf16 v[34:37], v[178:181], v[214:217], v[34:37]
	v_mfma_f32_16x16x32_bf16 v[6:9], v[186:189], v[214:217], v[6:9]
	v_mfma_f32_16x16x32_bf16 v[26:29], v[178:181], v[222:225], v[26:29]
	v_mfma_f32_16x16x32_bf16 v[2:5], v[186:189], v[222:225], v[2:5]
	v_mfma_f32_16x16x32_bf16 v[46:49], v[182:185], v[202:205], v[46:49]
	v_mfma_f32_16x16x32_bf16 v[14:17], v[190:193], v[202:205], v[14:17]
	v_mfma_f32_16x16x32_bf16 v[42:45], v[182:185], v[210:213], v[42:45]
	v_mfma_f32_16x16x32_bf16 v[10:13], v[190:193], v[210:213], v[10:13]
	v_mfma_f32_16x16x32_bf16 v[34:37], v[182:185], v[218:221], v[34:37]
	v_mfma_f32_16x16x32_bf16 v[6:9], v[190:193], v[218:221], v[6:9]
	v_mfma_f32_16x16x32_bf16 v[26:29], v[182:185], v[226:229], v[26:29]
	v_mfma_f32_16x16x32_bf16 v[2:5], v[190:193], v[226:229], v[2:5]
	s_barrier
	s_add_i32 s21, 0, 0x18000
	s_add_i32 s28, 0, 0x1c000
	v_add_u32_e32 v174, s21, v1
	v_add_u32_e32 v190, s28, v1
	ds_read_b128 v[130:133], v174
	ds_read_b128 v[160:163], v174 offset:1024
	ds_read_b128 v[170:173], v174 offset:2048
	ds_read_b128 v[174:177], v174 offset:3072
	ds_read_b128 v[178:181], v190
	ds_read_b128 v[182:185], v190 offset:1024
	ds_read_b128 v[186:189], v190 offset:2048
	ds_read_b128 v[190:193], v190 offset:3072
	s_add_u32 s22, s22, 0x160000
	s_addc_u32 s23, s23, 0
	s_mov_b32 m0, s35
	v_lshl_add_u64 v[236:237], s[22:23], 0, v[134:135]
	ds_read_b128 v[198:201], v197 offset:32768
	ds_read_b128 v[202:205], v197 offset:33792
	ds_read_b128 v[206:209], v197 offset:34816
	ds_read_b128 v[210:213], v197 offset:35840
	ds_read_b128 v[214:217], v197 offset:36864
	ds_read_b128 v[218:221], v197 offset:37888
	ds_read_b128 v[222:225], v197 offset:38912
	ds_read_b128 v[226:229], v197 offset:39936
	global_load_lds_dwordx4 v[236:237], off
	v_lshl_add_u64 v[236:237], s[22:23], 0, v[136:137]
	s_mov_b32 m0, s90
	s_nop 0
	global_load_lds_dwordx4 v[236:237], off
	s_waitcnt vmcnt(8)
	s_waitcnt lgkmcnt(0)
	s_barrier
	s_waitcnt lgkmcnt(0)
	v_mfma_f32_16x16x32_bf16 v[126:129], v[130:133], v[198:201], v[126:129]
	v_mfma_f32_16x16x32_bf16 v[94:97], v[170:173], v[198:201], v[94:97]
	v_mfma_f32_16x16x32_bf16 v[122:125], v[130:133], v[206:209], v[122:125]
	v_mfma_f32_16x16x32_bf16 v[90:93], v[170:173], v[206:209], v[90:93]
	v_mfma_f32_16x16x32_bf16 v[118:121], v[130:133], v[214:217], v[118:121]
	v_mfma_f32_16x16x32_bf16 v[86:89], v[170:173], v[214:217], v[86:89]
	v_mfma_f32_16x16x32_bf16 v[114:117], v[130:133], v[222:225], v[114:117]
	v_mfma_f32_16x16x32_bf16 v[82:85], v[170:173], v[222:225], v[82:85]
	v_mfma_f32_16x16x32_bf16 v[126:129], v[160:163], v[202:205], v[126:129]
	v_mfma_f32_16x16x32_bf16 v[94:97], v[174:177], v[202:205], v[94:97]
	v_mfma_f32_16x16x32_bf16 v[122:125], v[160:163], v[210:213], v[122:125]
	v_mfma_f32_16x16x32_bf16 v[90:93], v[174:177], v[210:213], v[90:93]
	v_mfma_f32_16x16x32_bf16 v[118:121], v[160:163], v[218:221], v[118:121]
	v_mfma_f32_16x16x32_bf16 v[86:89], v[174:177], v[218:221], v[86:89]
	v_mfma_f32_16x16x32_bf16 v[114:117], v[160:163], v[226:229], v[114:117]
	v_mfma_f32_16x16x32_bf16 v[82:85], v[174:177], v[226:229], v[82:85]
	v_mfma_f32_16x16x32_bf16 v[66:69], v[178:181], v[198:201], v[66:69]
	v_mfma_f32_16x16x32_bf16 v[38:41], v[186:189], v[198:201], v[38:41]
	v_mfma_f32_16x16x32_bf16 v[58:61], v[178:181], v[206:209], v[58:61]
	v_mfma_f32_16x16x32_bf16 v[30:33], v[186:189], v[206:209], v[30:33]
	v_mfma_f32_16x16x32_bf16 v[54:57], v[178:181], v[214:217], v[54:57]
	v_mfma_f32_16x16x32_bf16 v[22:25], v[186:189], v[214:217], v[22:25]
	v_mfma_f32_16x16x32_bf16 v[50:53], v[178:181], v[222:225], v[50:53]
	v_mfma_f32_16x16x32_bf16 v[18:21], v[186:189], v[222:225], v[18:21]
	v_mfma_f32_16x16x32_bf16 v[66:69], v[182:185], v[202:205], v[66:69]
	v_mfma_f32_16x16x32_bf16 v[38:41], v[190:193], v[202:205], v[38:41]
	v_mfma_f32_16x16x32_bf16 v[58:61], v[182:185], v[210:213], v[58:61]
	v_mfma_f32_16x16x32_bf16 v[30:33], v[190:193], v[210:213], v[30:33]
	v_mfma_f32_16x16x32_bf16 v[54:57], v[182:185], v[218:221], v[54:57]
	v_mfma_f32_16x16x32_bf16 v[22:25], v[190:193], v[218:221], v[22:25]
	v_mfma_f32_16x16x32_bf16 v[50:53], v[182:185], v[226:229], v[50:53]
	v_mfma_f32_16x16x32_bf16 v[18:21], v[190:193], v[226:229], v[18:21]
	s_barrier
	s_add_i32 s21, s21, s31
	v_lshl_add_u64 v[194:195], v[194:195], 0, s[8:9]
	s_mov_b32 m0, s21
	ds_read_b128 v[198:201], v197 offset:49152
	ds_read_b128 v[202:205], v197 offset:50176
	ds_read_b128 v[206:209], v197 offset:51200
	ds_read_b128 v[210:213], v197 offset:52224
	ds_read_b128 v[214:217], v197 offset:53248
	ds_read_b128 v[218:221], v197 offset:54272
	ds_read_b128 v[222:225], v197 offset:55296
	ds_read_b128 v[226:229], v197 offset:56320
	global_load_lds_dwordx4 v[194:195], off
	s_add_i32 m0, s21, 0x2000
	s_add_u32 s0, s0, 0x160080
	v_lshl_add_u64 v[194:195], v[230:231], 0, s[8:9]
	s_addc_u32 s1, s1, 0
	s_add_i32 s21, s28, s31
	global_load_lds_dwordx4 v[194:195], off
	v_lshl_add_u64 v[194:195], s[0:1], 0, v[134:135]
	s_mov_b32 m0, s21
	s_nop 0
	global_load_lds_dwordx4 v[194:195], off
	v_lshl_add_u64 v[194:195], s[0:1], 0, v[136:137]
	s_add_i32 m0, s21, 0x2000
	s_nop 0
	global_load_lds_dwordx4 v[194:195], off
	v_lshl_add_u64 v[194:195], v[232:233], 0, s[8:9]
	s_mov_b32 m0, s94
	s_nop 0
	global_load_lds_dwordx4 v[194:195], off
	v_lshl_add_u64 v[194:195], v[234:235], 0, s[8:9]
	s_mov_b32 m0, s95
	s_nop 0
	global_load_lds_dwordx4 v[194:195], off
	s_waitcnt vmcnt(8)
	s_waitcnt lgkmcnt(0)
	s_barrier
	s_waitcnt lgkmcnt(0)
	v_mfma_f32_16x16x32_bf16 v[110:113], v[130:133], v[198:201], v[110:113]
	v_mfma_f32_16x16x32_bf16 v[78:81], v[170:173], v[198:201], v[78:81]
	v_mfma_f32_16x16x32_bf16 v[106:109], v[130:133], v[206:209], v[106:109]
	v_mfma_f32_16x16x32_bf16 v[74:77], v[170:173], v[206:209], v[74:77]
	v_mfma_f32_16x16x32_bf16 v[102:105], v[130:133], v[214:217], v[102:105]
	v_mfma_f32_16x16x32_bf16 v[70:73], v[170:173], v[214:217], v[70:73]
	v_mfma_f32_16x16x32_bf16 v[98:101], v[130:133], v[222:225], v[98:101]
	v_mfma_f32_16x16x32_bf16 v[62:65], v[170:173], v[222:225], v[62:65]
	v_mfma_f32_16x16x32_bf16 v[110:113], v[160:163], v[202:205], v[110:113]
	v_mfma_f32_16x16x32_bf16 v[78:81], v[174:177], v[202:205], v[78:81]
	v_mfma_f32_16x16x32_bf16 v[106:109], v[160:163], v[210:213], v[106:109]
	v_mfma_f32_16x16x32_bf16 v[74:77], v[174:177], v[210:213], v[74:77]
	v_mfma_f32_16x16x32_bf16 v[102:105], v[160:163], v[218:221], v[102:105]
	v_mfma_f32_16x16x32_bf16 v[70:73], v[174:177], v[218:221], v[70:73]
	v_mfma_f32_16x16x32_bf16 v[98:101], v[160:163], v[226:229], v[98:101]
	v_mfma_f32_16x16x32_bf16 v[62:65], v[174:177], v[226:229], v[62:65]
	v_mfma_f32_16x16x32_bf16 v[46:49], v[178:181], v[198:201], v[46:49]
	v_mfma_f32_16x16x32_bf16 v[14:17], v[186:189], v[198:201], v[14:17]
	v_mfma_f32_16x16x32_bf16 v[42:45], v[178:181], v[206:209], v[42:45]
	v_mfma_f32_16x16x32_bf16 v[10:13], v[186:189], v[206:209], v[10:13]
	v_mfma_f32_16x16x32_bf16 v[34:37], v[178:181], v[214:217], v[34:37]
	v_mfma_f32_16x16x32_bf16 v[6:9], v[186:189], v[214:217], v[6:9]
	v_mfma_f32_16x16x32_bf16 v[26:29], v[178:181], v[222:225], v[26:29]
	v_mfma_f32_16x16x32_bf16 v[2:5], v[186:189], v[222:225], v[2:5]
	v_mfma_f32_16x16x32_bf16 v[46:49], v[182:185], v[202:205], v[46:49]
	v_mfma_f32_16x16x32_bf16 v[14:17], v[190:193], v[202:205], v[14:17]
	v_mfma_f32_16x16x32_bf16 v[42:45], v[182:185], v[210:213], v[42:45]
	v_mfma_f32_16x16x32_bf16 v[10:13], v[190:193], v[210:213], v[10:13]
	v_mfma_f32_16x16x32_bf16 v[34:37], v[182:185], v[218:221], v[34:37]
	v_mfma_f32_16x16x32_bf16 v[6:9], v[190:193], v[218:221], v[6:9]
	v_mfma_f32_16x16x32_bf16 v[26:29], v[182:185], v[226:229], v[26:29]
	v_mfma_f32_16x16x32_bf16 v[2:5], v[190:193], v[226:229], v[2:5]
	s_barrier
	s_add_u32 s88, s88, 0x100
	s_addc_u32 s89, s89, 0
	s_add_u32 s24, s24, 0x100
	s_addc_u32 s25, s25, 0
	s_cmp_ge_u32 s69, s19
	s_mov_b32 s22, s69
	s_cbranch_scc0 .LBB0_297
	s_and_b64 vcc, exec, s[10:11]
	s_cbranch_vccz .LBB0_300
	s_barrier

.LBB0_362:
	s_setprio 0
	v_readlane_b32 s2, v243, 51
	s_cmp_lt_i32 s2, 5
	s_cselect_b64 s[4:5], -1, 0
	s_and_b64 s[0:1], s[4:5], s[0:1]
	s_andn2_b64 vcc, exec, s[0:1]
	v_readlane_b32 s3, v243, 52
	s_cbranch_vccnz .LBB0_372
	v_readlane_b32 s0, v243, 0
	s_lshl_b32 s0, s0, 3
	v_readlane_b32 s1, v243, 59
	s_add_i32 s6, s1, s0
	s_cmp_gt_i32 s6, 0x81ff
	s_cbranch_scc1 .LBB0_372
	v_mbcnt_lo_u32_b32 v1, -1, 0
	v_mbcnt_hi_u32_b32 v2, -1, v1
	v_and_b32_e32 v1, 64, v2
	v_add_u32_e32 v3, 64, v1
	v_xor_b32_e32 v1, 1, v2
	v_cmp_lt_i32_e32 vcc, v1, v3
	v_xor_b32_e32 v4, 2, v2
	v_readlane_b32 s16, v243, 1
	v_cndmask_b32_e32 v1, v2, v1, vcc
	v_cmp_lt_i32_e32 vcc, v4, v3
	v_readlane_b32 s0, v243, 53
	v_readlane_b32 s17, v243, 2
	v_cndmask_b32_e32 v4, v2, v4, vcc
	v_lshlrev_b32_e32 v165, 2, v4
	v_xor_b32_e32 v4, 4, v2
	v_cmp_lt_i32_e32 vcc, v4, v3
	v_readlane_b32 s18, v243, 3
	v_readlane_b32 s19, v243, 4
	v_cndmask_b32_e32 v4, v2, v4, vcc
	v_lshlrev_b32_e32 v169, 2, v4
	v_xor_b32_e32 v4, 8, v2
	v_cmp_lt_i32_e32 vcc, v4, v3
	v_readlane_b32 s28, v243, 13
	v_readlane_b32 s29, v243, 14
	v_cndmask_b32_e32 v4, v2, v4, vcc
	v_lshlrev_b32_e32 v180, 2, v4
	v_xor_b32_e32 v4, 16, v2
	v_cmp_lt_i32_e32 vcc, v4, v3
	s_lshl_b32 s12, s0, 3
	v_readlane_b32 s30, v243, 15
	v_cndmask_b32_e32 v4, v2, v4, vcc
	v_lshlrev_b32_e32 v181, 2, v4
	v_xor_b32_e32 v4, 32, v2
	v_cmp_lt_i32_e32 vcc, v4, v3
	v_readlane_b32 s31, v243, 16
	s_mov_b64 s[16:17], s[28:29]
	v_cndmask_b32_e32 v2, v2, v4, vcc
	v_lshlrev_b32_e32 v182, 2, v2
	v_lshlrev_b32_e32 v2, 2, v166
	s_add_u32 s0, s16, 0x2000
	v_mov_b32_e32 v131, 0
	v_or_b32_e32 v4, 0x100, v2
	s_addc_u32 s1, s17, 0
	v_lshlrev_b32_e32 v6, 2, v4
	v_mov_b32_e32 v7, v131
	v_lshl_add_u64 v[134:135], s[0:1], 0, v[6:7]
	v_or_b32_e32 v6, 0x200, v2
	v_lshlrev_b32_e32 v8, 2, v6
	v_mov_b32_e32 v9, v131
	v_lshl_add_u64 v[136:137], s[0:1], 0, v[8:9]
	v_or_b32_e32 v8, 0x300, v2
	v_lshlrev_b32_e32 v10, 2, v8
	v_mov_b32_e32 v11, v131
	v_lshl_add_u64 v[138:139], s[0:1], 0, v[10:11]
	v_or_b32_e32 v10, 0x400, v2
	v_lshlrev_b32_e32 v12, 2, v10
	v_mov_b32_e32 v13, v131
	v_lshl_add_u64 v[140:141], s[0:1], 0, v[12:13]
	v_or_b32_e32 v12, 0x500, v2
	v_lshlrev_b32_e32 v14, 2, v12
	v_mov_b32_e32 v15, v131
	v_lshl_add_u64 v[142:143], s[0:1], 0, v[14:15]
	v_or_b32_e32 v14, 0x600, v2
	v_lshlrev_b32_e32 v16, 2, v14
	v_mov_b32_e32 v17, v131
	v_lshl_add_u64 v[144:145], s[0:1], 0, v[16:17]
	v_or_b32_e32 v16, 0x700, v2
	v_lshlrev_b32_e32 v130, 4, v166
	v_lshlrev_b32_e32 v18, 2, v16
	v_mov_b32_e32 v19, v131
	v_lshl_add_u64 v[132:133], s[0:1], 0, v[130:131]
	v_lshl_add_u64 v[146:147], s[0:1], 0, v[18:19]
	v_readlane_b32 s0, v242, 19
	v_readlane_b32 s1, v242, 20
	v_readlane_b32 s20, v243, 5
	v_readlane_b32 s22, v243, 7
	v_lshl_add_u64 v[148:149], s[0:1], 0, v[130:131]
	v_readlane_b32 s0, v242, 15
	s_mov_b64 s[18:19], s[30:31]
	s_add_u32 s13, s50, 0x106000
	v_lshlrev_b32_e32 v18, 3, v166
	v_readlane_b32 s1, v242, 16
	s_addc_u32 s14, s51, 0
	s_mov_b32 s9, 0
	v_lshlrev_b32_e32 v1, 2, v1
	v_lshl_add_u64 v[150:151], s[0:1], 0, v[18:19]
	v_lshl_add_u64 v[152:153], s[50:51], 0, v[130:131]
	s_add_i32 s10, s6, 0xffff8000
	s_movk_i32 s15, 0x4800
	v_lshlrev_b32_e32 v130, 4, v166
	s_movk_i32 s16, 0x1000
	v_lshlrev_b32_e32 v183, 2, v2
	v_lshlrev_b32_e32 v184, 2, v4
	v_lshlrev_b32_e32 v185, 2, v6
	v_lshlrev_b32_e32 v186, 2, v8
	v_lshlrev_b32_e32 v187, 2, v10
	v_lshlrev_b32_e32 v188, 2, v12
	v_lshlrev_b32_e32 v189, 2, v14
	v_lshlrev_b32_e32 v190, 2, v16
	s_movk_i32 s17, 0x7fff
	s_mov_b32 s18, 0x2e100000
	s_mov_b32 s19, 0x2e101000
	v_mov_b32_e32 v191, 0x358637bd
	s_mov_b32 s20, 0xf800000
	v_mov_b32_e32 v192, 0x260
	s_mov_b32 s22, 0xffff0000
	v_readlane_b32 s21, v243, 6
	v_readlane_b32 s23, v243, 8
	v_readlane_b32 s24, v243, 9
	v_readlane_b32 s25, v243, 10
	v_readlane_b32 s26, v243, 11
	v_readlane_b32 s27, v243, 12
	s_branch .LBB0_366

.LBB0_426:
	s_setprio 0
	v_readlane_b32 s2, v243, 51
	s_cmp_lt_i32 s2, 6
	s_cselect_b64 s[6:7], -1, 0
	s_and_b64 s[0:1], s[6:7], s[0:1]
	s_andn2_b64 vcc, exec, s[0:1]
	v_readlane_b32 s3, v243, 52
	s_cbranch_vccnz .LBB0_477
	v_readlane_b32 s2, v243, 0
	s_cmpk_lt_i32 s2, 0xc30
	s_cselect_b64 s[0:1], -1, 0
	s_cmpk_gt_i32 s2, 0xc2f
	v_readfirstlane_b32 s2, v0
	s_cbranch_scc1 .LBB0_429
	v_readlane_b32 s5, v243, 0
	s_ashr_i32 s3, s5, 31
	s_lshr_b32 s3, s3, 29
	s_add_i32 s3, s5, s3
	s_ashr_i32 s4, s3, 3
	s_and_b32 s3, s3, -8
	s_sub_i32 s3, s5, s3
	s_cmp_lt_i32 s3, 0
	s_movk_i32 s5, 0x187
	s_cselect_b32 s5, s5, 0x186
	s_mul_i32 s3, s5, s3
	s_add_i32 s3, s3, s4
	s_mul_hi_i32 s4, s3, 0x2aaaaaab
	s_lshr_b32 s5, s4, 31
	s_ashr_i32 s4, s4, 5
	s_add_i32 s4, s4, s5
	s_lshl_b32 s8, s4, 3
	s_sub_i32 s5, 0x82, s8
	s_mulk_i32 s4, 0xc0
	s_min_u32 s9, s5, 8
	s_sub_i32 s3, s3, s4
	s_sext_i32_i16 s4, s3
	v_cvt_f32_ubyte0_e32 v2, s9
	v_cvt_f32_i32_e32 v1, s4
	v_rcp_iflag_f32_e32 v3, v2
	s_ashr_i32 s4, s4, 30
	s_or_b32 s10, s4, 1
	v_mul_f32_e32 v3, v1, v3
	v_trunc_f32_e32 v3, v3
	v_fma_f32 v1, -v3, v2, v1
	v_cvt_i32_f32_e32 v3, v3
	v_cmp_ge_f32_e64 s[4:5], |v1|, v2
	s_and_b64 s[4:5], s[4:5], exec
	s_cselect_b32 s4, s10, 0
	v_readfirstlane_b32 s5, v3
	s_add_i32 s5, s5, s4
	s_sext_i32_i16 s4, s5
	s_mul_i32 s5, s5, s9
	s_sub_i32 s3, s3, s5
	s_sext_i32_i16 s3, s3
	s_add_i32 s88, s8, s3
.LBB0_429:
	s_andn2_b64 vcc, exec, s[0:1]
	s_cbranch_vccnz .LBB0_477
	v_lshrrev_b32_e32 v3, 1, v0
	v_and_b32_e32 v13, 24, v3
	v_lshrrev_b32_e32 v3, 5, v0
	v_readlane_b32 s8, v243, 63
	v_lshlrev_b32_e32 v1, 4, v0
	v_and_b32_e32 v2, 32, v0
	v_and_b32_e32 v3, 4, v3
	v_bfe_u32 v4, v0, 2, 2
	v_readlane_b32 s20, v242, 11
	v_readlane_b32 s22, v242, 13
	v_bfe_u32 v12, v0, 2, 4
	v_bitop3_b32 v10, v1, v2, 48 bitop3:0x6c
	v_and_b32_e32 v11, 64, v0
	v_or3_b32 v3, v3, v4, v13
	v_lshrrev_b32_e32 v4, 3, v0
	v_or_b32_e32 v14, 0x2000, v1
	v_readlane_b32 s10, v242, 1
	v_readlane_b32 s23, v242, 14
	s_add_u32 s20, s22, 0x9100000
	v_or_b32_e32 v2, v10, v11
	v_and_or_b32 v5, v4, 48, v12
	v_and_or_b32 v4, v4, 32, v3
	v_lshrrev_b32_e32 v1, 7, v14
	s_movk_i32 s0, 0x70
	v_readlane_b32 s9, v242, 0
	s_addc_u32 s26, s23, 0
	v_lshl_or_b32 v132, v4, 12, v2
	v_and_or_b32 v4, v1, s0, v12
	s_movk_i32 s0, 0x60
	s_lshr_b32 s10, s2, 6
	s_ashr_i32 s89, s88, 31
	s_ashr_i32 s5, s4, 31
	s_lshr_b32 s3, s2, 8
	v_and_or_b32 v1, v1, s0, v3
	s_lshl_b32 s27, s10, 10
	s_lshl_b64 s[8:9], s[88:89], 20
	s_lshl_b64 s[0:1], s[4:5], 20
	s_add_u32 s0, s20, s0
	s_addc_u32 s1, s26, s1
	s_add_i32 s30, s27, 0
	s_add_i32 m0, s30, 0x10000
	v_readlane_b32 s12, v242, 3
	global_load_lds_dwordx4 v132, s[0:1]
	s_add_i32 m0, s30, 0x12000
	v_readlane_b32 s13, v242, 4
	v_lshl_or_b32 v136, v1, 12, v2
	s_add_u32 s12, s0, 0x80000
	global_load_lds_dwordx4 v136, s[0:1]
	s_addc_u32 s13, s1, 0
	s_add_i32 m0, s30, 0x14000
	v_lshl_or_b32 v130, v5, 12, v2
	global_load_lds_dwordx4 v132, s[12:13]
	s_add_i32 m0, s30, 0x16000
	v_lshl_or_b32 v134, v4, 12, v2
	global_load_lds_dwordx4 v136, s[12:13]
	v_readlane_b32 s12, v242, 15
	v_readlane_b32 s13, v242, 16
	s_add_u32 s24, s12, s8
	s_addc_u32 s25, s13, s9
	s_add_i32 s31, s30, 0x2000
	s_mov_b32 m0, s30
	s_add_u32 s8, s24, 0x80000
	global_load_lds_dwordx4 v130, s[24:25]
	s_mov_b32 m0, s31
	s_addc_u32 s9, s25, 0
	s_add_i32 s33, s30, 0x4000
	global_load_lds_dwordx4 v134, s[24:25]
	s_mov_b32 m0, s33
	s_add_i32 s34, s30, 0x6000
	global_load_lds_dwordx4 v130, s[8:9]
	s_mov_b32 m0, s34
	v_mov_b32_e32 v133, 0
	global_load_lds_dwordx4 v134, s[8:9]
	v_mov_b32_e32 v137, v133
	v_mov_b32_e32 v131, v133
	v_mov_b32_e32 v135, v133
	s_cmp_eq_u32 s3, 1
	s_mov_b32 s35, 0
	v_lshl_add_u64 v[8:9], s[0:1], 0, v[132:133]
	v_lshl_add_u64 v[6:7], s[0:1], 0, v[136:137]
	v_lshl_add_u64 v[2:3], s[24:25], 0, v[130:131]
	s_cselect_b64 s[8:9], -1, 0
	s_cmp_lg_u32 s3, 1
	v_lshl_add_u64 v[4:5], s[24:25], 0, v[134:135]
	v_readlane_b32 s11, v242, 2
	v_readlane_b32 s14, v242, 5
	v_readlane_b32 s15, v242, 6
	v_readlane_b32 s16, v242, 7
	v_readlane_b32 s17, v242, 8
	v_readlane_b32 s18, v242, 9
	v_readlane_b32 s19, v242, 10
	v_readlane_b32 s21, v242, 12
	s_cbranch_scc1 .LBB0_432
	s_barrier
	s_setprio 1

.LBB0_438:
	ds_read_b128 v[146:149], v152
	ds_read_b128 v[156:159], v152 offset:1024
	ds_read_b128 v[160:163], v152 offset:2048
	ds_read_b128 v[170:173], v152 offset:3072
	ds_read_b128 v[174:177], v153
	ds_read_b128 v[178:181], v153 offset:1024
	ds_read_b128 v[182:185], v153 offset:2048
	ds_read_b128 v[186:189], v153 offset:3072
	s_add_u32 s0, s90, 0xfff80080
	s_addc_u32 s1, s91, -1
	s_cmp_eq_u32 s69, 28
	s_cselect_b32 s23, s5, s1
	s_cselect_b32 s22, s17, s0
	s_cselect_b32 s1, s15, s25
	s_cselect_b32 s0, s68, s24
	v_lshl_add_u64 v[222:223], s[90:91], 0, v[138:139]
	s_add_i32 m0, s30, 0xc000
	ds_read_b128 v[190:193], v154
	ds_read_b128 v[194:197], v154 offset:1024
	ds_read_b128 v[198:201], v154 offset:2048
	ds_read_b128 v[202:205], v154 offset:3072
	ds_read_b128 v[206:209], v154 offset:4096
	ds_read_b128 v[210:213], v154 offset:5120
	ds_read_b128 v[214:217], v154 offset:6144
	ds_read_b128 v[218:221], v154 offset:7168
	global_load_lds_dwordx4 v[222:223], off
	v_lshl_add_u64 v[222:223], s[90:91], 0, v[140:141]
	s_add_i32 m0, s30, 0xe000
	s_nop 0
	global_load_lds_dwordx4 v[222:223], off
	s_waitcnt vmcnt(8)
	s_waitcnt lgkmcnt(0)
	s_barrier
	s_waitcnt lgkmcnt(0)
	v_mfma_f32_16x16x32_bf16 v[126:129], v[146:149], v[190:193], v[126:129]
	v_mfma_f32_16x16x32_bf16 v[122:125], v[160:163], v[190:193], v[122:125]
	v_mfma_f32_16x16x32_bf16 v[110:113], v[146:149], v[198:201], v[110:113]
	v_mfma_f32_16x16x32_bf16 v[106:109], v[160:163], v[198:201], v[106:109]
	v_mfma_f32_16x16x32_bf16 v[94:97], v[146:149], v[206:209], v[94:97]
	v_mfma_f32_16x16x32_bf16 v[90:93], v[160:163], v[206:209], v[90:93]
	v_mfma_f32_16x16x32_bf16 v[78:81], v[146:149], v[214:217], v[78:81]
	v_mfma_f32_16x16x32_bf16 v[74:77], v[160:163], v[214:217], v[74:77]
	v_mfma_f32_16x16x32_bf16 v[126:129], v[156:159], v[194:197], v[126:129]
	v_mfma_f32_16x16x32_bf16 v[122:125], v[170:173], v[194:197], v[122:125]
	v_mfma_f32_16x16x32_bf16 v[110:113], v[156:159], v[202:205], v[110:113]
	v_mfma_f32_16x16x32_bf16 v[106:109], v[170:173], v[202:205], v[106:109]
	v_mfma_f32_16x16x32_bf16 v[94:97], v[156:159], v[210:213], v[94:97]
	v_mfma_f32_16x16x32_bf16 v[90:93], v[170:173], v[210:213], v[90:93]
	v_mfma_f32_16x16x32_bf16 v[78:81], v[156:159], v[218:221], v[78:81]
	v_mfma_f32_16x16x32_bf16 v[74:77], v[170:173], v[218:221], v[74:77]
	v_mfma_f32_16x16x32_bf16 v[118:121], v[174:177], v[190:193], v[118:121]
	v_mfma_f32_16x16x32_bf16 v[114:117], v[182:185], v[190:193], v[114:117]
	v_mfma_f32_16x16x32_bf16 v[102:105], v[174:177], v[198:201], v[102:105]
	v_mfma_f32_16x16x32_bf16 v[98:101], v[182:185], v[198:201], v[98:101]
	v_mfma_f32_16x16x32_bf16 v[86:89], v[174:177], v[206:209], v[86:89]
	v_mfma_f32_16x16x32_bf16 v[82:85], v[182:185], v[206:209], v[82:85]
	v_mfma_f32_16x16x32_bf16 v[70:73], v[174:177], v[214:217], v[70:73]
	v_mfma_f32_16x16x32_bf16 v[66:69], v[182:185], v[214:217], v[66:69]
	v_mfma_f32_16x16x32_bf16 v[118:121], v[178:181], v[194:197], v[118:121]
	v_mfma_f32_16x16x32_bf16 v[114:117], v[186:189], v[194:197], v[114:117]
	v_mfma_f32_16x16x32_bf16 v[102:105], v[178:181], v[202:205], v[102:105]
	v_mfma_f32_16x16x32_bf16 v[98:101], v[186:189], v[202:205], v[98:101]
	v_mfma_f32_16x16x32_bf16 v[86:89], v[178:181], v[210:213], v[86:89]
	v_mfma_f32_16x16x32_bf16 v[82:85], v[186:189], v[210:213], v[82:85]
	v_mfma_f32_16x16x32_bf16 v[70:73], v[178:181], v[218:221], v[70:73]
	v_mfma_f32_16x16x32_bf16 v[66:69], v[186:189], v[218:221], v[66:69]
	s_barrier
	s_add_i32 s21, s95, s27
	v_lshl_add_u64 v[222:223], s[0:1], 0, v[132:133]
	s_mov_b32 m0, s21
	ds_read_b128 v[190:193], v154 offset:16384
	ds_read_b128 v[194:197], v154 offset:17408
	ds_read_b128 v[198:201], v154 offset:18432
	ds_read_b128 v[202:205], v154 offset:19456
	ds_read_b128 v[206:209], v154 offset:20480
	ds_read_b128 v[210:213], v154 offset:21504
	ds_read_b128 v[214:217], v154 offset:22528
	ds_read_b128 v[218:221], v154 offset:23552
	global_load_lds_dwordx4 v[222:223], off
	s_add_i32 m0, s21, 0x2000
	s_add_u32 s28, s0, 0x80000
	v_lshl_add_u64 v[224:225], s[0:1], 0, v[136:137]
	s_addc_u32 s29, s1, 0
	s_add_i32 s21, s96, s27
	global_load_lds_dwordx4 v[224:225], off
	v_lshl_add_u64 v[226:227], s[28:29], 0, v[132:133]
	s_mov_b32 m0, s21
	v_lshl_add_u64 v[228:229], s[22:23], 0, v[134:135]
	global_load_lds_dwordx4 v[226:227], off
	v_lshl_add_u64 v[226:227], s[28:29], 0, v[136:137]
	s_add_i32 m0, s21, 0x2000
	s_nop 0
	global_load_lds_dwordx4 v[226:227], off
	v_lshl_add_u64 v[226:227], s[22:23], 0, v[130:131]
	s_mov_b32 m0, s30
	s_nop 0
	global_load_lds_dwordx4 v[226:227], off
	s_mov_b32 m0, s31
	s_nop 0
	global_load_lds_dwordx4 v[228:229], off
	s_waitcnt vmcnt(8)
	s_waitcnt lgkmcnt(0)
	s_barrier
	s_waitcnt lgkmcnt(0)
	v_mfma_f32_16x16x32_bf16 v[62:65], v[146:149], v[190:193], v[62:65]
	v_mfma_f32_16x16x32_bf16 v[58:61], v[160:163], v[190:193], v[58:61]
	v_mfma_f32_16x16x32_bf16 v[46:49], v[146:149], v[198:201], v[46:49]
	v_mfma_f32_16x16x32_bf16 v[42:45], v[160:163], v[198:201], v[42:45]
	v_mfma_f32_16x16x32_bf16 v[30:33], v[146:149], v[206:209], v[30:33]
	v_mfma_f32_16x16x32_bf16 v[26:29], v[160:163], v[206:209], v[26:29]
	v_mfma_f32_16x16x32_bf16 v[14:17], v[146:149], v[214:217], v[14:17]
	v_mfma_f32_16x16x32_bf16 v[10:13], v[160:163], v[214:217], v[10:13]
	v_mfma_f32_16x16x32_bf16 v[62:65], v[156:159], v[194:197], v[62:65]
	v_mfma_f32_16x16x32_bf16 v[58:61], v[170:173], v[194:197], v[58:61]
	v_mfma_f32_16x16x32_bf16 v[46:49], v[156:159], v[202:205], v[46:49]
	v_mfma_f32_16x16x32_bf16 v[42:45], v[170:173], v[202:205], v[42:45]
	v_mfma_f32_16x16x32_bf16 v[30:33], v[156:159], v[210:213], v[30:33]
	v_mfma_f32_16x16x32_bf16 v[26:29], v[170:173], v[210:213], v[26:29]
	v_mfma_f32_16x16x32_bf16 v[14:17], v[156:159], v[218:221], v[14:17]
	v_mfma_f32_16x16x32_bf16 v[10:13], v[170:173], v[218:221], v[10:13]
	v_mfma_f32_16x16x32_bf16 v[54:57], v[174:177], v[190:193], v[54:57]
	v_mfma_f32_16x16x32_bf16 v[50:53], v[182:185], v[190:193], v[50:53]
	v_mfma_f32_16x16x32_bf16 v[38:41], v[174:177], v[198:201], v[38:41]
	v_mfma_f32_16x16x32_bf16 v[34:37], v[182:185], v[198:201], v[34:37]
	v_mfma_f32_16x16x32_bf16 v[22:25], v[174:177], v[206:209], v[22:25]
	v_mfma_f32_16x16x32_bf16 v[18:21], v[182:185], v[206:209], v[18:21]
	v_mfma_f32_16x16x32_bf16 v[6:9], v[174:177], v[214:217], v[6:9]
	v_mfma_f32_16x16x32_bf16 v[2:5], v[182:185], v[214:217], v[2:5]
	v_mfma_f32_16x16x32_bf16 v[54:57], v[178:181], v[194:197], v[54:57]
	v_mfma_f32_16x16x32_bf16 v[50:53], v[186:189], v[194:197], v[50:53]
	v_mfma_f32_16x16x32_bf16 v[38:41], v[178:181], v[202:205], v[38:41]
	v_mfma_f32_16x16x32_bf16 v[34:37], v[186:189], v[202:205], v[34:37]
	v_mfma_f32_16x16x32_bf16 v[22:25], v[178:181], v[210:213], v[22:25]
	v_mfma_f32_16x16x32_bf16 v[18:21], v[186:189], v[210:213], v[18:21]
	v_mfma_f32_16x16x32_bf16 v[6:9], v[178:181], v[218:221], v[6:9]
	v_mfma_f32_16x16x32_bf16 v[2:5], v[186:189], v[218:221], v[2:5]
	s_barrier
	s_add_i32 s21, 0, 0x18000
	v_add_u32_e32 v155, s21, v150
	s_add_i32 s28, 0, 0x1c000
	ds_read_b128 v[146:149], v155
	ds_read_b128 v[156:159], v155 offset:1024
	ds_read_b128 v[160:163], v155 offset:2048
	ds_read_b128 v[170:173], v155 offset:3072
	v_add_u32_e32 v155, s28, v150
	ds_read_b128 v[174:177], v155
	ds_read_b128 v[178:181], v155 offset:1024
	ds_read_b128 v[182:185], v155 offset:2048
	ds_read_b128 v[186:189], v155 offset:3072
	s_add_u32 s22, s22, 0x80000
	s_addc_u32 s23, s23, 0
	s_mov_b32 m0, s33
	v_lshl_add_u64 v[230:231], s[22:23], 0, v[130:131]
	ds_read_b128 v[190:193], v154 offset:32768
	ds_read_b128 v[194:197], v154 offset:33792
	ds_read_b128 v[198:201], v154 offset:34816
	ds_read_b128 v[202:205], v154 offset:35840
	ds_read_b128 v[206:209], v154 offset:36864
	ds_read_b128 v[210:213], v154 offset:37888
	ds_read_b128 v[214:217], v154 offset:38912
	ds_read_b128 v[218:221], v154 offset:39936
	global_load_lds_dwordx4 v[230:231], off
	v_lshl_add_u64 v[230:231], s[22:23], 0, v[134:135]
	s_mov_b32 m0, s34
	s_nop 0
	global_load_lds_dwordx4 v[230:231], off
	s_waitcnt vmcnt(8)
	s_waitcnt lgkmcnt(0)
	s_barrier
	s_waitcnt lgkmcnt(0)
	v_mfma_f32_16x16x32_bf16 v[126:129], v[146:149], v[190:193], v[126:129]
	v_mfma_f32_16x16x32_bf16 v[122:125], v[160:163], v[190:193], v[122:125]
	v_mfma_f32_16x16x32_bf16 v[110:113], v[146:149], v[198:201], v[110:113]
	v_mfma_f32_16x16x32_bf16 v[106:109], v[160:163], v[198:201], v[106:109]
	v_mfma_f32_16x16x32_bf16 v[94:97], v[146:149], v[206:209], v[94:97]
	v_mfma_f32_16x16x32_bf16 v[90:93], v[160:163], v[206:209], v[90:93]
	v_mfma_f32_16x16x32_bf16 v[78:81], v[146:149], v[214:217], v[78:81]
	v_mfma_f32_16x16x32_bf16 v[74:77], v[160:163], v[214:217], v[74:77]
	v_mfma_f32_16x16x32_bf16 v[126:129], v[156:159], v[194:197], v[126:129]
	v_mfma_f32_16x16x32_bf16 v[122:125], v[170:173], v[194:197], v[122:125]
	v_mfma_f32_16x16x32_bf16 v[110:113], v[156:159], v[202:205], v[110:113]
	v_mfma_f32_16x16x32_bf16 v[106:109], v[170:173], v[202:205], v[106:109]
	v_mfma_f32_16x16x32_bf16 v[94:97], v[156:159], v[210:213], v[94:97]
	v_mfma_f32_16x16x32_bf16 v[90:93], v[170:173], v[210:213], v[90:93]
	v_mfma_f32_16x16x32_bf16 v[78:81], v[156:159], v[218:221], v[78:81]
	v_mfma_f32_16x16x32_bf16 v[74:77], v[170:173], v[218:221], v[74:77]
	v_mfma_f32_16x16x32_bf16 v[118:121], v[174:177], v[190:193], v[118:121]
	v_mfma_f32_16x16x32_bf16 v[114:117], v[182:185], v[190:193], v[114:117]
	v_mfma_f32_16x16x32_bf16 v[102:105], v[174:177], v[198:201], v[102:105]
	v_mfma_f32_16x16x32_bf16 v[98:101], v[182:185], v[198:201], v[98:101]
	v_mfma_f32_16x16x32_bf16 v[86:89], v[174:177], v[206:209], v[86:89]
	v_mfma_f32_16x16x32_bf16 v[82:85], v[182:185], v[206:209], v[82:85]
	v_mfma_f32_16x16x32_bf16 v[70:73], v[174:177], v[214:217], v[70:73]
	v_mfma_f32_16x16x32_bf16 v[66:69], v[182:185], v[214:217], v[66:69]
	v_mfma_f32_16x16x32_bf16 v[118:121], v[178:181], v[194:197], v[118:121]
	v_mfma_f32_16x16x32_bf16 v[114:117], v[186:189], v[194:197], v[114:117]
	v_mfma_f32_16x16x32_bf16 v[102:105], v[178:181], v[202:205], v[102:105]
	v_mfma_f32_16x16x32_bf16 v[98:101], v[186:189], v[202:205], v[98:101]
	v_mfma_f32_16x16x32_bf16 v[86:89], v[178:181], v[210:213], v[86:89]
	v_mfma_f32_16x16x32_bf16 v[82:85], v[186:189], v[210:213], v[82:85]
	v_mfma_f32_16x16x32_bf16 v[70:73], v[178:181], v[218:221], v[70:73]
	v_mfma_f32_16x16x32_bf16 v[66:69], v[186:189], v[218:221], v[66:69]
	s_barrier
	s_add_i32 s21, s21, s27
	v_lshl_add_u64 v[222:223], v[222:223], 0, s[10:11]
	s_mov_b32 m0, s21
	ds_read_b128 v[190:193], v154 offset:49152
	ds_read_b128 v[194:197], v154 offset:50176
	ds_read_b128 v[198:201], v154 offset:51200
	ds_read_b128 v[202:205], v154 offset:52224
	ds_read_b128 v[206:209], v154 offset:53248
	ds_read_b128 v[210:213], v154 offset:54272
	ds_read_b128 v[214:217], v154 offset:55296
	ds_read_b128 v[218:221], v154 offset:56320
	global_load_lds_dwordx4 v[222:223], off
	s_add_i32 m0, s21, 0x2000
	s_add_u32 s0, s0, 0x80080
	v_lshl_add_u64 v[222:223], v[224:225], 0, s[10:11]
	s_addc_u32 s1, s1, 0
	s_add_i32 s21, s28, s27
	global_load_lds_dwordx4 v[222:223], off
	v_lshl_add_u64 v[222:223], s[0:1], 0, v[132:133]
	s_mov_b32 m0, s21
	s_nop 0
	global_load_lds_dwordx4 v[222:223], off
	v_lshl_add_u64 v[222:223], s[0:1], 0, v[136:137]
	s_add_i32 m0, s21, 0x2000
	s_nop 0
	global_load_lds_dwordx4 v[222:223], off
	v_lshl_add_u64 v[222:223], v[226:227], 0, s[10:11]
	s_mov_b32 m0, s89
	s_nop 0
	global_load_lds_dwordx4 v[222:223], off
	v_lshl_add_u64 v[222:223], v[228:229], 0, s[10:11]
	s_mov_b32 m0, s92
	s_nop 0
	global_load_lds_dwordx4 v[222:223], off
	s_waitcnt vmcnt(8)
	s_waitcnt lgkmcnt(0)
	s_barrier
	s_waitcnt lgkmcnt(0)
	v_mfma_f32_16x16x32_bf16 v[62:65], v[146:149], v[190:193], v[62:65]
	v_mfma_f32_16x16x32_bf16 v[58:61], v[160:163], v[190:193], v[58:61]
	v_mfma_f32_16x16x32_bf16 v[46:49], v[146:149], v[198:201], v[46:49]
	v_mfma_f32_16x16x32_bf16 v[42:45], v[160:163], v[198:201], v[42:45]
	v_mfma_f32_16x16x32_bf16 v[30:33], v[146:149], v[206:209], v[30:33]
	v_mfma_f32_16x16x32_bf16 v[26:29], v[160:163], v[206:209], v[26:29]
	v_mfma_f32_16x16x32_bf16 v[14:17], v[146:149], v[214:217], v[14:17]
	v_mfma_f32_16x16x32_bf16 v[10:13], v[160:163], v[214:217], v[10:13]
	v_mfma_f32_16x16x32_bf16 v[62:65], v[156:159], v[194:197], v[62:65]
	v_mfma_f32_16x16x32_bf16 v[58:61], v[170:173], v[194:197], v[58:61]
	v_mfma_f32_16x16x32_bf16 v[46:49], v[156:159], v[202:205], v[46:49]
	v_mfma_f32_16x16x32_bf16 v[42:45], v[170:173], v[202:205], v[42:45]
	v_mfma_f32_16x16x32_bf16 v[30:33], v[156:159], v[210:213], v[30:33]
	v_mfma_f32_16x16x32_bf16 v[26:29], v[170:173], v[210:213], v[26:29]
	v_mfma_f32_16x16x32_bf16 v[14:17], v[156:159], v[218:221], v[14:17]
	v_mfma_f32_16x16x32_bf16 v[10:13], v[170:173], v[218:221], v[10:13]
	v_mfma_f32_16x16x32_bf16 v[54:57], v[174:177], v[190:193], v[54:57]
	v_mfma_f32_16x16x32_bf16 v[50:53], v[182:185], v[190:193], v[50:53]
	v_mfma_f32_16x16x32_bf16 v[38:41], v[174:177], v[198:201], v[38:41]
	v_mfma_f32_16x16x32_bf16 v[34:37], v[182:185], v[198:201], v[34:37]
	v_mfma_f32_16x16x32_bf16 v[22:25], v[174:177], v[206:209], v[22:25]
	v_mfma_f32_16x16x32_bf16 v[18:21], v[182:185], v[206:209], v[18:21]
	v_mfma_f32_16x16x32_bf16 v[6:9], v[174:177], v[214:217], v[6:9]
	v_mfma_f32_16x16x32_bf16 v[2:5], v[182:185], v[214:217], v[2:5]
	v_mfma_f32_16x16x32_bf16 v[54:57], v[178:181], v[194:197], v[54:57]
	v_mfma_f32_16x16x32_bf16 v[50:53], v[186:189], v[194:197], v[50:53]
	v_mfma_f32_16x16x32_bf16 v[38:41], v[178:181], v[202:205], v[38:41]
	v_mfma_f32_16x16x32_bf16 v[34:37], v[186:189], v[202:205], v[34:37]
	v_mfma_f32_16x16x32_bf16 v[22:25], v[178:181], v[210:213], v[22:25]
	v_mfma_f32_16x16x32_bf16 v[18:21], v[186:189], v[210:213], v[18:21]
	v_mfma_f32_16x16x32_bf16 v[6:9], v[178:181], v[218:221], v[6:9]
	v_mfma_f32_16x16x32_bf16 v[2:5], v[186:189], v[218:221], v[2:5]
	s_barrier
	s_add_i32 s69, s69, 2
	s_add_u32 s90, s90, 0x100
	s_addc_u32 s91, s91, 0
	s_add_u32 s24, s24, 0x100
	s_addc_u32 s25, s25, 0
	s_cmp_gt_u32 s69, 29
	s_cbranch_scc0 .LBB0_438
	s_and_b64 vcc, exec, s[12:13]
	s_cbranch_vccz .LBB0_441
	s_barrier

.LBB0_531:
	s_setprio 0
	v_readlane_b32 s2, v243, 51
	s_cmp_lt_i32 s2, 7
	s_cselect_b64 s[34:35], -1, 0
	s_and_b64 s[0:1], s[34:35], s[0:1]
	s_andn2_b64 vcc, exec, s[0:1]
	v_readlane_b32 s3, v243, 52
	s_cbranch_vccnz .LBB0_573
	v_readlane_b32 s0, v243, 0
	s_lshl_b32 s0, s0, 3
	v_readlane_b32 s1, v243, 59
	s_add_i32 s4, s1, s0
	s_cmp_gt_i32 s4, 0x81ff
	s_cbranch_scc1 .LBB0_541
	s_add_u32 s6, s58, 0x900000
	s_addc_u32 s7, s59, 0
	s_add_u32 s8, s58, 0xb00000
	v_readlane_b32 s12, v243, 53
	s_addc_u32 s9, s59, 0
	s_lshl_b32 s0, s12, 3
	s_mul_i32 s14, s4, 0x3000
	v_readlane_b32 s2, v242, 17
	v_mov_b32_e32 v47, 0
	v_mov_b32_e32 v1, s47
	v_mov_b32_e32 v2, s45
	v_cmp_gt_u32_e32 vcc, 32, v166
	s_mul_hi_i32 s5, s4, 0x3000
	v_readlane_b32 s3, v242, 18
	s_add_u32 s10, s2, s14
	v_cndmask_b32_e32 v11, v1, v2, vcc
	v_mov_b32_e32 v1, s46
	v_mov_b32_e32 v2, s44
	v_lshlrev_b32_e32 v12, 7, v166
	v_lshlrev_b32_e32 v48, 4, v166
	s_addc_u32 s11, s3, s5
	v_mov_b32_e32 v49, v47
	v_cndmask_b32_e32 v10, v1, v2, vcc
	v_readlane_b32 s16, v243, 33
	v_and_b32_e32 v12, 0x80, v12
	v_mov_b32_e32 v13, v47
	v_lshl_add_u64 v[34:35], s[10:11], 0, v[48:49]
	s_movk_i32 s1, 0x2000
	v_lshlrev_b32_e32 v46, 3, v166
	v_lshlrev_b32_e32 v1, 5, v166
	v_readlane_b32 s20, v243, 37
	v_readlane_b32 s21, v243, 38
	v_lshl_add_u64 v[38:39], v[10:11], 0, v[12:13]
	v_add_co_u32_e64 v34, s[2:3], s1, v34
	s_nop 2
	global_load_dwordx4 v[2:5], v1, s[20:21] offset:16
	global_load_dwordx4 v[6:9], v1, s[20:21]
	global_load_dwordx4 v[10:13], v[38:39], off offset:112
	global_load_dwordx4 v[14:17], v[38:39], off offset:96
	global_load_dwordx4 v[18:21], v[38:39], off offset:80
	global_load_dwordx4 v[22:25], v[38:39], off offset:64
	global_load_dwordx4 v[26:29], v[38:39], off offset:48
	global_load_dwordx4 v[30:33], v[38:39], off offset:32
	v_addc_co_u32_e64 v35, s[2:3], 0, v35, s[2:3]
	v_lshl_add_u64 v[36:37], s[10:11], 0, v[46:47]
	v_add_co_u32_e64 v36, s[2:3], s1, v36
	v_lshlrev_b32_e32 v50, 6, v166
	s_nop 0
	v_addc_co_u32_e64 v37, s[2:3], 0, v37, s[2:3]
	v_mov_b32_e32 v51, v47
	v_lshl_add_u64 v[40:41], s[10:11], 0, v[50:51]
	s_mov_b64 s[2:3], 0x1000
	s_movk_i32 s1, 0x1000
	v_lshl_add_u64 v[42:43], v[40:41], 0, s[2:3]
	v_add_co_u32_e64 v40, s[2:3], s1, v40
	v_readlane_b32 s22, v243, 39
	s_nop 0
	v_addc_co_u32_e64 v41, s[2:3], 0, v41, s[2:3]
	v_readlane_b32 s23, v243, 40
	global_load_dwordx4 v[134:137], v[42:43], off offset:32
	global_load_dwordx4 v[138:141], v[42:43], off offset:16
	global_load_dwordx4 v[142:145], v[40:41], off
	global_load_dwordx4 v[130:133], v[42:43], off offset:48
	global_load_dwordx4 v[146:149], v[34:35], off offset:2048
	global_load_dwordx2 v[172:173], v[36:37], off offset:3072
	s_nop 0
	global_load_dwordx4 v[34:37], v[38:39], off offset:16
	s_nop 0
	global_load_dwordx4 v[38:41], v[38:39], off
	s_nop 0
	global_load_dwordx4 v[42:45], v48, s[22:23]
	v_mbcnt_lo_u32_b32 v1, -1, 0
	v_mbcnt_hi_u32_b32 v47, -1, v1
	v_and_b32_e32 v1, 64, v47
	v_add_u32_e32 v49, 64, v1
	v_xor_b32_e32 v1, 1, v47
	v_cmp_lt_i32_e64 s[2:3], v1, v49
	v_xor_b32_e32 v51, 2, v47
	v_readlane_b32 s1, v243, 0
	v_cndmask_b32_e64 v1, v47, v1, s[2:3]
	v_cmp_lt_i32_e64 s[2:3], v51, v49
	v_readlane_b32 s10, v243, 59
	s_lshl_b32 s1, s1, 8
	v_cndmask_b32_e64 v51, v47, v51, s[2:3]
	v_lshlrev_b32_e32 v165, 2, v51
	v_xor_b32_e32 v51, 4, v47
	v_cmp_lt_i32_e64 s[2:3], v51, v49
	s_lshl_b32 s10, s10, 5
	s_add_i32 s1, s1, s10
	v_cndmask_b32_e64 v51, v47, v51, s[2:3]
	v_lshlrev_b32_e32 v169, 2, v51
	v_xor_b32_e32 v51, 8, v47
	v_cmp_lt_i32_e64 s[2:3], v51, v49
	s_add_i32 s10, s4, s0
	s_mul_hi_i32 s11, s10, 0x3000
	v_cndmask_b32_e64 v51, v47, v51, s[2:3]
	v_lshlrev_b32_e32 v186, 2, v51
	v_xor_b32_e32 v51, 16, v47
	v_cmp_lt_i32_e64 s[2:3], v51, v49
	s_mul_i32 s15, s10, 0x3000
	v_readlane_b32 s18, v243, 35
	v_cndmask_b32_e64 v51, v47, v51, s[2:3]
	v_lshlrev_b32_e32 v187, 2, v51
	v_xor_b32_e32 v51, 32, v47
	v_cmp_lt_i32_e64 s[2:3], v51, v49
	v_or_b32_e32 v158, s14, v48
	v_mov_b32_e32 v159, s5
	v_cndmask_b32_e64 v47, v47, v51, s[2:3]
	v_lshlrev_b32_e32 v188, 2, v47
	v_mov_b32_e32 v47, 0x3e38aa3b
	v_readlane_b32 s19, v243, 36
	v_cndmask_b32_e32 v150, 1.0, v47, vcc
	v_and_b32_e32 v47, 1, v0
	s_lshl_b32 s18, s12, 8
	s_mov_b64 s[12:13], 0x15b02c00
	v_lshlrev_b32_e32 v1, 2, v1
	v_cmp_eq_u32_e64 s[2:3], 0, v47
	v_mov_b32_e32 v151, v150
	s_mov_b32 s19, 0x15b01000
	s_movk_i32 s20, 0x7fff
	s_mov_b32 s22, 0xffff0000
	v_mov_b32_e32 v189, 0x358637bd
	s_mov_b32 s23, 0xf800000
	v_mov_b32_e32 v190, 0x260
	v_mov_b32_e32 v191, 1
	v_readlane_b32 s17, v243, 34
	v_readlane_b32 s24, v243, 41
	v_readlane_b32 s25, v243, 42
	v_readlane_b32 s26, v243, 43
	s_waitcnt vmcnt(0)
	v_mov_b32_e32 v152, v7
	v_mov_b32_e32 v153, v9
	v_mov_b32_e32 v7, v8
	v_mov_b32_e32 v8, v3
	v_mov_b32_e32 v9, v5
	v_mov_b32_e32 v3, v4
	v_or_b32_e32 v4, s15, v48
	v_mov_b32_e32 v5, s11
	s_mov_b64 s[10:11], 0x15b02800
	v_lshl_add_u64 v[154:155], v[4:5], 0, s[10:11]
	v_or_b32_e32 v4, s15, v46
	v_lshl_add_u64 v[160:161], v[158:159], 0, s[10:11]
	v_or_b32_e32 v158, s14, v46
	v_mov_b64_e32 v[74:75], v[134:135]
	v_mov_b64_e32 v[70:71], v[138:139]
	v_mov_b64_e32 v[66:67], v[142:143]
	v_mov_b64_e32 v[78:79], v[130:131]
	v_mov_b64_e32 v[62:63], v[146:147]
	v_lshl_add_u64 v[156:157], v[4:5], 0, s[12:13]
	v_or_b32_e32 v4, s15, v50
	v_lshl_add_u64 v[162:163], v[158:159], 0, s[12:13]
	v_or_b32_e32 v158, s14, v50
	s_mov_b64 s[10:11], 0x15b01000
	s_mov_b64 s[12:13], s[58:59]
	v_mov_b64_e32 v[68:69], v[144:145]
	v_mov_b64_e32 v[72:73], v[140:141]
	v_mov_b64_e32 v[76:77], v[136:137]
	v_mov_b64_e32 v[80:81], v[132:133]
	v_mov_b64_e32 v[170:171], v[172:173]
	v_mov_b64_e32 v[64:65], v[148:149]
	v_readlane_b32 s27, v243, 44
	v_readlane_b32 s28, v243, 45
	v_readlane_b32 s29, v243, 46
	v_readlane_b32 s30, v243, 47
	v_readlane_b32 s31, v243, 48
	s_branch .LBB0_535

.LBB0_627:
	s_setprio 0
	v_readlane_b32 s2, v243, 51
	s_cmp_lt_i32 s2, 8
	s_cselect_b64 s[60:61], -1, 0
	s_and_b64 s[0:1], s[60:61], s[0:1]
	s_andn2_b64 vcc, exec, s[0:1]
	v_readlane_b32 s3, v243, 52
	s_cbranch_vccnz .LBB0_710
	v_lshlrev_b32_e32 v1, 4, v0
	v_and_b32_e32 v176, 32, v0
	v_bitop3_b32 v10, v1, v176, 48 bitop3:0x6c
	v_lshrrev_b32_e32 v1, 5, v0
	v_and_b32_e32 v4, 4, v1
	v_lshrrev_b32_e32 v1, 1, v0
	v_bfe_u32 v5, v0, 2, 2
	v_and_b32_e32 v1, 24, v1
	v_bfe_u32 v2, v0, 2, 4
	v_and_b32_e32 v11, 64, v0
	v_or3_b32 v4, v4, v5, v1
	v_lshrrev_b32_e32 v5, 3, v0
	v_or_b32_e32 v149, v10, v11
	v_and_or_b32 v6, v5, 48, v2
	v_lshrrev_b32_e32 v3, 1, v149
	v_mul_u32_u24_e32 v12, 0x1800, v6
	v_and_or_b32 v150, v5, 32, v4
	v_or_b32_e32 v5, v3, v12
	v_lshlrev_b32_e32 v130, 1, v5
	v_bfe_u32 v5, v0, 3, 25
	v_or_b32_e32 v5, 64, v5
	s_movk_i32 s0, 0x70
	v_and_or_b32 v2, v5, s0, v2
	v_mul_u32_u24_e32 v13, 0x1800, v2
	v_or_b32_e32 v2, v13, v3
	v_lshlrev_b32_e32 v132, 1, v2
	v_lshlrev_b32_e32 v2, 6, v0
	s_movk_i32 s0, 0x60
	v_lshlrev_b32_e32 v148, 1, v1
	v_and_b32_e32 v2, 0x3c0, v2
	v_and_b32_e32 v3, 32, v164
	v_readlane_b32 s1, v243, 0
	v_readfirstlane_b32 s3, v0
	v_and_b32_e32 v146, 15, v0
	v_and_or_b32 v151, v5, s0, v4
	s_cmpk_gt_i32 s1, 0x30b
	v_bitop3_b32 v147, v148, v3, v2 bitop3:0x36
	s_cbranch_scc1 .LBB0_654
	s_ashr_i32 s20, s1, 31
	s_lshr_b32 s0, s20, 29
	s_add_i32 s4, s1, s0
	s_and_b32 s0, s4, -8
	s_sub_i32 s5, s1, s0
	s_cmp_gt_i32 s5, 3
	s_cbranch_scc0 .LBB0_631
	s_mul_i32 s0, s5, 0x61
	s_add_i32 s2, s0, 4
	s_cbranch_execz .LBB0_632
	s_branch .LBB0_633

.LBB0_633:
	s_ashr_i32 s0, s4, 3
	s_add_u32 s24, s58, 0x15b02800
	s_addc_u32 s25, s59, 0
	s_add_u32 s26, s58, 0xd500000
	s_addc_u32 s27, s59, 0
	s_add_i32 s0, s2, s0
	s_mul_hi_i32 s1, s0, 0x2aaaaaab
	s_lshr_b32 s2, s1, 31
	s_ashr_i32 s1, s1, 3
	s_add_i32 s1, s1, s2
	s_lshl_b32 s6, s1, 3
	s_sub_i32 s2, 0x82, s6
	s_mul_i32 s1, s1, 48
	s_min_u32 s7, s2, 8
	s_sub_i32 s8, s0, s1
	s_sext_i32_i8 s0, s8
	v_cvt_f32_ubyte0_e32 v3, s7
	v_cvt_f32_i32_e32 v2, s0
	v_rcp_iflag_f32_e32 v4, v3
	s_lshr_b32 s4, s3, 6
	s_ashr_i32 s0, s0, 30
	s_lshr_b32 s5, s3, 8
	v_mul_f32_e32 v4, v2, v4
	v_trunc_f32_e32 v4, v4
	v_fma_f32 v2, -v4, v3, v2
	v_cvt_i32_f32_e32 v4, v4
	s_lshl_b32 s30, s4, 10
	s_or_b32 s2, s0, 1
	v_cmp_ge_f32_e64 s[0:1], |v2|, v3
	s_and_b64 s[0:1], s[0:1], exec
	s_cselect_b32 s0, s2, 0
	v_readfirstlane_b32 s1, v4
	s_add_i32 s2, s1, s0
	s_mul_i32 s0, s2, s7
	s_sub_i32 s0, s8, s0
	s_sext_i32_i8 s0, s0
	s_add_i32 s72, s6, s0
	s_bfe_i64 s[0:1], s[2:3], 0x80000
	s_lshl_b64 s[0:1], s[0:1], 18
	s_add_u32 s0, s26, s0
	s_addc_u32 s1, s27, s1
	s_add_i32 s16, s30, 0
	v_lshl_or_b32 v134, v150, 10, v149
	s_add_i32 m0, s16, 0x10000
	v_lshl_or_b32 v136, v151, 10, v149
	global_load_lds_dwordx4 v134, s[0:1]
	s_add_i32 m0, s16, 0x12000
	s_add_u32 s6, s0, 0x20000
	global_load_lds_dwordx4 v136, s[0:1]
	s_addc_u32 s7, s1, 0
	s_add_i32 m0, s16, 0x14000
	s_mul_i32 s9, s72, 0x300000
	global_load_lds_dwordx4 v134, s[6:7]
	s_add_i32 m0, s16, 0x16000
	s_mul_hi_i32 s8, s72, 0x300000
	s_add_u32 s22, s24, s9
	s_addc_u32 s23, s25, s8
	s_add_i32 s17, s16, 0x2000
	global_load_lds_dwordx4 v136, s[6:7]
	s_mov_b32 m0, s16
	s_add_u32 s6, s22, 0x180000
	global_load_lds_dwordx4 v130, s[22:23]
	s_mov_b32 m0, s17
	s_addc_u32 s7, s23, 0
	s_add_i32 s31, s16, 0x4000
	global_load_lds_dwordx4 v132, s[22:23]
	s_mov_b32 m0, s31
	s_add_i32 s33, s16, 0x6000
	global_load_lds_dwordx4 v130, s[6:7]
	s_mov_b32 m0, s33
	v_mov_b32_e32 v135, 0
	global_load_lds_dwordx4 v132, s[6:7]
	v_mov_b32_e32 v137, v135
	v_mov_b32_e32 v131, v135
	v_mov_b32_e32 v133, v135
	s_cmp_eq_u32 s5, 1
	s_mov_b32 s34, 0
	v_lshl_add_u64 v[8:9], s[0:1], 0, v[134:135]
	v_lshl_add_u64 v[6:7], s[0:1], 0, v[136:137]
	v_lshl_add_u64 v[2:3], s[22:23], 0, v[130:131]
	s_cselect_b64 s[6:7], -1, 0
	s_cmp_lg_u32 s5, 1
	v_lshl_add_u64 v[4:5], s[22:23], 0, v[132:133]
	s_cbranch_scc1 .LBB0_635
	s_barrier
	s_setprio 1

.LBB0_647:
	ds_read_b128 v[158:161], v155
	ds_read_b128 v[170:173], v155 offset:1024
	ds_read_b128 v[178:181], v155 offset:2048
	ds_read_b128 v[182:185], v155 offset:3072
	ds_read_b128 v[186:189], v156
	ds_read_b128 v[190:193], v156 offset:1024
	ds_read_b128 v[194:197], v156 offset:2048
	ds_read_b128 v[198:201], v156 offset:3072
	s_add_u32 s0, s4, 0xffe80080
	s_addc_u32 s1, s5, -1
	s_cmp_eq_u32 s78, 4
	s_cselect_b32 s23, s15, s1
	s_cselect_b32 s22, s14, s0
	s_cselect_b32 s1, s13, s77
	s_cselect_b32 s0, s75, s76
	v_lshl_add_u64 v[162:163], s[4:5], 0, v[138:139]
	s_add_i32 m0, s16, 0xc000
	ds_read_b128 v[202:205], v157
	ds_read_b128 v[206:209], v157 offset:1024
	ds_read_b128 v[210:213], v157 offset:2048
	ds_read_b128 v[214:217], v157 offset:3072
	ds_read_b128 v[218:221], v157 offset:4096
	ds_read_b128 v[222:225], v157 offset:5120
	ds_read_b128 v[226:229], v157 offset:6144
	ds_read_b128 v[230:233], v157 offset:7168
	global_load_lds_dwordx4 v[162:163], off
	v_lshl_add_u64 v[162:163], s[4:5], 0, v[140:141]
	s_add_i32 m0, s16, 0xe000
	s_nop 0
	global_load_lds_dwordx4 v[162:163], off
	s_waitcnt vmcnt(8)
	s_waitcnt lgkmcnt(0)
	s_barrier
	s_waitcnt lgkmcnt(0)
	v_mfma_f32_16x16x32_bf16 v[126:129], v[158:161], v[202:205], v[126:129]
	v_mfma_f32_16x16x32_bf16 v[122:125], v[178:181], v[202:205], v[122:125]
	v_mfma_f32_16x16x32_bf16 v[118:121], v[158:161], v[210:213], v[118:121]
	v_mfma_f32_16x16x32_bf16 v[114:117], v[178:181], v[210:213], v[114:117]
	v_mfma_f32_16x16x32_bf16 v[102:105], v[158:161], v[218:221], v[102:105]
	v_mfma_f32_16x16x32_bf16 v[98:101], v[178:181], v[218:221], v[98:101]
	v_mfma_f32_16x16x32_bf16 v[86:89], v[158:161], v[226:229], v[86:89]
	v_mfma_f32_16x16x32_bf16 v[82:85], v[178:181], v[226:229], v[82:85]
	v_mfma_f32_16x16x32_bf16 v[126:129], v[170:173], v[206:209], v[126:129]
	v_mfma_f32_16x16x32_bf16 v[122:125], v[182:185], v[206:209], v[122:125]
	v_mfma_f32_16x16x32_bf16 v[118:121], v[170:173], v[214:217], v[118:121]
	v_mfma_f32_16x16x32_bf16 v[114:117], v[182:185], v[214:217], v[114:117]
	v_mfma_f32_16x16x32_bf16 v[102:105], v[170:173], v[222:225], v[102:105]
	v_mfma_f32_16x16x32_bf16 v[98:101], v[182:185], v[222:225], v[98:101]
	v_mfma_f32_16x16x32_bf16 v[86:89], v[170:173], v[230:233], v[86:89]
	v_mfma_f32_16x16x32_bf16 v[82:85], v[182:185], v[230:233], v[82:85]
	v_mfma_f32_16x16x32_bf16 v[110:113], v[186:189], v[202:205], v[110:113]
	v_mfma_f32_16x16x32_bf16 v[106:109], v[194:197], v[202:205], v[106:109]
	v_mfma_f32_16x16x32_bf16 v[94:97], v[186:189], v[210:213], v[94:97]
	v_mfma_f32_16x16x32_bf16 v[90:93], v[194:197], v[210:213], v[90:93]
	v_mfma_f32_16x16x32_bf16 v[78:81], v[186:189], v[218:221], v[78:81]
	v_mfma_f32_16x16x32_bf16 v[74:77], v[194:197], v[218:221], v[74:77]
	v_mfma_f32_16x16x32_bf16 v[70:73], v[186:189], v[226:229], v[70:73]
	v_mfma_f32_16x16x32_bf16 v[66:69], v[194:197], v[226:229], v[66:69]
	v_mfma_f32_16x16x32_bf16 v[110:113], v[190:193], v[206:209], v[110:113]
	v_mfma_f32_16x16x32_bf16 v[106:109], v[198:201], v[206:209], v[106:109]
	v_mfma_f32_16x16x32_bf16 v[94:97], v[190:193], v[214:217], v[94:97]
	v_mfma_f32_16x16x32_bf16 v[90:93], v[198:201], v[214:217], v[90:93]
	v_mfma_f32_16x16x32_bf16 v[78:81], v[190:193], v[222:225], v[78:81]
	v_mfma_f32_16x16x32_bf16 v[74:77], v[198:201], v[222:225], v[74:77]
	v_mfma_f32_16x16x32_bf16 v[70:73], v[190:193], v[230:233], v[70:73]
	v_mfma_f32_16x16x32_bf16 v[66:69], v[198:201], v[230:233], v[66:69]
	s_barrier
	s_add_i32 s21, s69, s30
	v_lshl_add_u64 v[162:163], s[0:1], 0, v[134:135]
	s_mov_b32 m0, s21
	ds_read_b128 v[202:205], v157 offset:16384
	ds_read_b128 v[206:209], v157 offset:17408
	ds_read_b128 v[210:213], v157 offset:18432
	ds_read_b128 v[214:217], v157 offset:19456
	ds_read_b128 v[218:221], v157 offset:20480
	ds_read_b128 v[222:225], v157 offset:21504
	ds_read_b128 v[226:229], v157 offset:22528
	ds_read_b128 v[230:233], v157 offset:23552
	global_load_lds_dwordx4 v[162:163], off
	s_add_i32 m0, s21, 0x2000
	s_add_u32 s28, s0, 0x20000
	v_lshl_add_u64 v[174:175], s[0:1], 0, v[136:137]
	s_addc_u32 s29, s1, 0
	s_add_i32 s21, s70, s30
	global_load_lds_dwordx4 v[174:175], off
	v_lshl_add_u64 v[234:235], s[28:29], 0, v[134:135]
	s_mov_b32 m0, s21
	v_lshl_add_u64 v[236:237], s[22:23], 0, v[132:133]
	global_load_lds_dwordx4 v[234:235], off
	v_lshl_add_u64 v[234:235], s[28:29], 0, v[136:137]
	s_add_i32 m0, s21, 0x2000
	s_nop 0
	global_load_lds_dwordx4 v[234:235], off
	v_lshl_add_u64 v[234:235], s[22:23], 0, v[130:131]
	s_mov_b32 m0, s16
	s_nop 0
	global_load_lds_dwordx4 v[234:235], off
	s_mov_b32 m0, s17
	s_nop 0
	global_load_lds_dwordx4 v[236:237], off
	s_waitcnt vmcnt(8)
	s_waitcnt lgkmcnt(0)
	s_barrier
	s_waitcnt lgkmcnt(0)
	v_mfma_f32_16x16x32_bf16 v[62:65], v[158:161], v[202:205], v[62:65]
	v_mfma_f32_16x16x32_bf16 v[58:61], v[178:181], v[202:205], v[58:61]
	v_mfma_f32_16x16x32_bf16 v[54:57], v[158:161], v[210:213], v[54:57]
	v_mfma_f32_16x16x32_bf16 v[50:53], v[178:181], v[210:213], v[50:53]
	v_mfma_f32_16x16x32_bf16 v[38:41], v[158:161], v[218:221], v[38:41]
	v_mfma_f32_16x16x32_bf16 v[34:37], v[178:181], v[218:221], v[34:37]
	v_mfma_f32_16x16x32_bf16 v[22:25], v[158:161], v[226:229], v[22:25]
	v_mfma_f32_16x16x32_bf16 v[18:21], v[178:181], v[226:229], v[18:21]
	v_mfma_f32_16x16x32_bf16 v[62:65], v[170:173], v[206:209], v[62:65]
	v_mfma_f32_16x16x32_bf16 v[58:61], v[182:185], v[206:209], v[58:61]
	v_mfma_f32_16x16x32_bf16 v[54:57], v[170:173], v[214:217], v[54:57]
	v_mfma_f32_16x16x32_bf16 v[50:53], v[182:185], v[214:217], v[50:53]
	v_mfma_f32_16x16x32_bf16 v[38:41], v[170:173], v[222:225], v[38:41]
	v_mfma_f32_16x16x32_bf16 v[34:37], v[182:185], v[222:225], v[34:37]
	v_mfma_f32_16x16x32_bf16 v[22:25], v[170:173], v[230:233], v[22:25]
	v_mfma_f32_16x16x32_bf16 v[18:21], v[182:185], v[230:233], v[18:21]
	v_mfma_f32_16x16x32_bf16 v[46:49], v[186:189], v[202:205], v[46:49]
	v_mfma_f32_16x16x32_bf16 v[42:45], v[194:197], v[202:205], v[42:45]
	v_mfma_f32_16x16x32_bf16 v[30:33], v[186:189], v[210:213], v[30:33]
	v_mfma_f32_16x16x32_bf16 v[26:29], v[194:197], v[210:213], v[26:29]
	v_mfma_f32_16x16x32_bf16 v[14:17], v[186:189], v[218:221], v[14:17]
	v_mfma_f32_16x16x32_bf16 v[10:13], v[194:197], v[218:221], v[10:13]
	v_mfma_f32_16x16x32_bf16 v[6:9], v[186:189], v[226:229], v[6:9]
	v_mfma_f32_16x16x32_bf16 v[2:5], v[194:197], v[226:229], v[2:5]
	v_mfma_f32_16x16x32_bf16 v[46:49], v[190:193], v[206:209], v[46:49]
	v_mfma_f32_16x16x32_bf16 v[42:45], v[198:201], v[206:209], v[42:45]
	v_mfma_f32_16x16x32_bf16 v[30:33], v[190:193], v[214:217], v[30:33]
	v_mfma_f32_16x16x32_bf16 v[26:29], v[198:201], v[214:217], v[26:29]
	v_mfma_f32_16x16x32_bf16 v[14:17], v[190:193], v[222:225], v[14:17]
	v_mfma_f32_16x16x32_bf16 v[10:13], v[198:201], v[222:225], v[10:13]
	v_mfma_f32_16x16x32_bf16 v[6:9], v[190:193], v[230:233], v[6:9]
	v_mfma_f32_16x16x32_bf16 v[2:5], v[198:201], v[230:233], v[2:5]
	s_barrier
	s_add_i32 s21, 0, 0x18000
	v_add_u32_e32 v165, s21, v153
	s_add_i32 s28, 0, 0x1c000
	ds_read_b128 v[158:161], v165
	ds_read_b128 v[170:173], v165 offset:1024
	ds_read_b128 v[178:181], v165 offset:2048
	ds_read_b128 v[182:185], v165 offset:3072
	v_add_u32_e32 v165, s28, v153
	ds_read_b128 v[186:189], v165
	ds_read_b128 v[190:193], v165 offset:1024
	ds_read_b128 v[194:197], v165 offset:2048
	ds_read_b128 v[198:201], v165 offset:3072
	s_add_u32 s22, s22, 0x180000
	s_addc_u32 s23, s23, 0
	s_mov_b32 m0, s31
	v_lshl_add_u64 v[238:239], s[22:23], 0, v[130:131]
	ds_read_b128 v[202:205], v157 offset:32768
	ds_read_b128 v[206:209], v157 offset:33792
	ds_read_b128 v[210:213], v157 offset:34816
	ds_read_b128 v[214:217], v157 offset:35840
	ds_read_b128 v[218:221], v157 offset:36864
	ds_read_b128 v[222:225], v157 offset:37888
	ds_read_b128 v[226:229], v157 offset:38912
	ds_read_b128 v[230:233], v157 offset:39936
	global_load_lds_dwordx4 v[238:239], off
	v_lshl_add_u64 v[238:239], s[22:23], 0, v[132:133]
	s_mov_b32 m0, s33
	s_nop 0
	global_load_lds_dwordx4 v[238:239], off
	s_waitcnt vmcnt(8)
	s_waitcnt lgkmcnt(0)
	s_barrier
	s_waitcnt lgkmcnt(0)
	v_mfma_f32_16x16x32_bf16 v[126:129], v[158:161], v[202:205], v[126:129]
	v_mfma_f32_16x16x32_bf16 v[122:125], v[178:181], v[202:205], v[122:125]
	v_mfma_f32_16x16x32_bf16 v[118:121], v[158:161], v[210:213], v[118:121]
	v_mfma_f32_16x16x32_bf16 v[114:117], v[178:181], v[210:213], v[114:117]
	v_mfma_f32_16x16x32_bf16 v[102:105], v[158:161], v[218:221], v[102:105]
	v_mfma_f32_16x16x32_bf16 v[98:101], v[178:181], v[218:221], v[98:101]
	v_mfma_f32_16x16x32_bf16 v[86:89], v[158:161], v[226:229], v[86:89]
	v_mfma_f32_16x16x32_bf16 v[82:85], v[178:181], v[226:229], v[82:85]
	v_mfma_f32_16x16x32_bf16 v[126:129], v[170:173], v[206:209], v[126:129]
	v_mfma_f32_16x16x32_bf16 v[122:125], v[182:185], v[206:209], v[122:125]
	v_mfma_f32_16x16x32_bf16 v[118:121], v[170:173], v[214:217], v[118:121]
	v_mfma_f32_16x16x32_bf16 v[114:117], v[182:185], v[214:217], v[114:117]
	v_mfma_f32_16x16x32_bf16 v[102:105], v[170:173], v[222:225], v[102:105]
	v_mfma_f32_16x16x32_bf16 v[98:101], v[182:185], v[222:225], v[98:101]
	v_mfma_f32_16x16x32_bf16 v[86:89], v[170:173], v[230:233], v[86:89]
	v_mfma_f32_16x16x32_bf16 v[82:85], v[182:185], v[230:233], v[82:85]
	v_mfma_f32_16x16x32_bf16 v[110:113], v[186:189], v[202:205], v[110:113]
	v_mfma_f32_16x16x32_bf16 v[106:109], v[194:197], v[202:205], v[106:109]
	v_mfma_f32_16x16x32_bf16 v[94:97], v[186:189], v[210:213], v[94:97]
	v_mfma_f32_16x16x32_bf16 v[90:93], v[194:197], v[210:213], v[90:93]
	v_mfma_f32_16x16x32_bf16 v[78:81], v[186:189], v[218:221], v[78:81]
	v_mfma_f32_16x16x32_bf16 v[74:77], v[194:197], v[218:221], v[74:77]
	v_mfma_f32_16x16x32_bf16 v[70:73], v[186:189], v[226:229], v[70:73]
	v_mfma_f32_16x16x32_bf16 v[66:69], v[194:197], v[226:229], v[66:69]
	v_mfma_f32_16x16x32_bf16 v[110:113], v[190:193], v[206:209], v[110:113]
	v_mfma_f32_16x16x32_bf16 v[106:109], v[198:201], v[206:209], v[106:109]
	v_mfma_f32_16x16x32_bf16 v[94:97], v[190:193], v[214:217], v[94:97]
	v_mfma_f32_16x16x32_bf16 v[90:93], v[198:201], v[214:217], v[90:93]
	v_mfma_f32_16x16x32_bf16 v[78:81], v[190:193], v[222:225], v[78:81]
	v_mfma_f32_16x16x32_bf16 v[74:77], v[198:201], v[222:225], v[74:77]
	v_mfma_f32_16x16x32_bf16 v[70:73], v[190:193], v[230:233], v[70:73]
	v_mfma_f32_16x16x32_bf16 v[66:69], v[198:201], v[230:233], v[66:69]
	s_barrier
	s_add_i32 s21, s21, s30
	v_lshl_add_u64 v[162:163], v[162:163], 0, s[8:9]
	s_mov_b32 m0, s21
	ds_read_b128 v[202:205], v157 offset:49152
	ds_read_b128 v[206:209], v157 offset:50176
	ds_read_b128 v[210:213], v157 offset:51200
	ds_read_b128 v[214:217], v157 offset:52224
	ds_read_b128 v[218:221], v157 offset:53248
	ds_read_b128 v[222:225], v157 offset:54272
	ds_read_b128 v[226:229], v157 offset:55296
	ds_read_b128 v[230:233], v157 offset:56320
	global_load_lds_dwordx4 v[162:163], off
	s_add_i32 m0, s21, 0x2000
	s_add_u32 s0, s0, 0x20080
	v_lshl_add_u64 v[162:163], v[174:175], 0, s[8:9]
	s_addc_u32 s1, s1, 0
	s_add_i32 s21, s28, s30
	global_load_lds_dwordx4 v[162:163], off
	v_lshl_add_u64 v[162:163], s[0:1], 0, v[134:135]
	s_mov_b32 m0, s21
	s_nop 0
	global_load_lds_dwordx4 v[162:163], off
	v_lshl_add_u64 v[162:163], s[0:1], 0, v[136:137]
	s_add_i32 m0, s21, 0x2000
	s_nop 0
	global_load_lds_dwordx4 v[162:163], off
	v_lshl_add_u64 v[162:163], v[234:235], 0, s[8:9]
	s_mov_b32 m0, s35
	s_nop 0
	global_load_lds_dwordx4 v[162:163], off
	v_lshl_add_u64 v[162:163], v[236:237], 0, s[8:9]
	s_mov_b32 m0, s84
	s_nop 0
	global_load_lds_dwordx4 v[162:163], off
	s_waitcnt vmcnt(8)
	s_waitcnt lgkmcnt(0)
	s_barrier
	s_waitcnt lgkmcnt(0)
	v_mfma_f32_16x16x32_bf16 v[62:65], v[158:161], v[202:205], v[62:65]
	v_mfma_f32_16x16x32_bf16 v[58:61], v[178:181], v[202:205], v[58:61]
	v_mfma_f32_16x16x32_bf16 v[54:57], v[158:161], v[210:213], v[54:57]
	v_mfma_f32_16x16x32_bf16 v[50:53], v[178:181], v[210:213], v[50:53]
	v_mfma_f32_16x16x32_bf16 v[38:41], v[158:161], v[218:221], v[38:41]
	v_mfma_f32_16x16x32_bf16 v[34:37], v[178:181], v[218:221], v[34:37]
	v_mfma_f32_16x16x32_bf16 v[22:25], v[158:161], v[226:229], v[22:25]
	v_mfma_f32_16x16x32_bf16 v[18:21], v[178:181], v[226:229], v[18:21]
	v_mfma_f32_16x16x32_bf16 v[62:65], v[170:173], v[206:209], v[62:65]
	v_mfma_f32_16x16x32_bf16 v[58:61], v[182:185], v[206:209], v[58:61]
	v_mfma_f32_16x16x32_bf16 v[54:57], v[170:173], v[214:217], v[54:57]
	v_mfma_f32_16x16x32_bf16 v[50:53], v[182:185], v[214:217], v[50:53]
	v_mfma_f32_16x16x32_bf16 v[38:41], v[170:173], v[222:225], v[38:41]
	v_mfma_f32_16x16x32_bf16 v[34:37], v[182:185], v[222:225], v[34:37]
	v_mfma_f32_16x16x32_bf16 v[22:25], v[170:173], v[230:233], v[22:25]
	v_mfma_f32_16x16x32_bf16 v[18:21], v[182:185], v[230:233], v[18:21]
	v_mfma_f32_16x16x32_bf16 v[46:49], v[186:189], v[202:205], v[46:49]
	v_mfma_f32_16x16x32_bf16 v[42:45], v[194:197], v[202:205], v[42:45]
	v_mfma_f32_16x16x32_bf16 v[30:33], v[186:189], v[210:213], v[30:33]
	v_mfma_f32_16x16x32_bf16 v[26:29], v[194:197], v[210:213], v[26:29]
	v_mfma_f32_16x16x32_bf16 v[14:17], v[186:189], v[218:221], v[14:17]
	v_mfma_f32_16x16x32_bf16 v[10:13], v[194:197], v[218:221], v[10:13]
	v_mfma_f32_16x16x32_bf16 v[6:9], v[186:189], v[226:229], v[6:9]
	v_mfma_f32_16x16x32_bf16 v[2:5], v[194:197], v[226:229], v[2:5]
	v_mfma_f32_16x16x32_bf16 v[46:49], v[190:193], v[206:209], v[46:49]
	v_mfma_f32_16x16x32_bf16 v[42:45], v[198:201], v[206:209], v[42:45]
	v_mfma_f32_16x16x32_bf16 v[30:33], v[190:193], v[214:217], v[30:33]
	v_mfma_f32_16x16x32_bf16 v[26:29], v[198:201], v[214:217], v[26:29]
	v_mfma_f32_16x16x32_bf16 v[14:17], v[190:193], v[222:225], v[14:17]
	v_mfma_f32_16x16x32_bf16 v[10:13], v[198:201], v[222:225], v[10:13]
	v_mfma_f32_16x16x32_bf16 v[6:9], v[190:193], v[230:233], v[6:9]
	v_mfma_f32_16x16x32_bf16 v[2:5], v[198:201], v[230:233], v[2:5]
	s_barrier
	s_add_i32 s78, s78, 2
	s_add_u32 s4, s4, 0x100
	s_addc_u32 s5, s5, 0
	s_add_u32 s76, s76, 0x100
	s_addc_u32 s77, s77, 0
	s_cmp_gt_u32 s78, 5
	s_cbranch_scc0 .LBB0_647
	s_and_b64 vcc, exec, s[10:11]
	s_cbranch_vccz .LBB0_650
	s_barrier

.LBB0_654:
	s_cmpk_lt_i32 s1, 0x410
	s_cselect_b64 s[62:63], -1, 0
	s_cmpk_gt_i32 s1, 0x40f
	v_readfirstlane_b32 s1, v0
	s_cbranch_scc1 .LBB0_672
	s_add_u32 s20, s58, 0x15b02c00
	s_addc_u32 s26, s59, 0
	s_add_u32 s27, s58, 0xd680000
	v_readlane_b32 s5, v243, 0
	s_addc_u32 s30, s59, 0
	s_ashr_i32 s33, s5, 31
	s_lshr_b32 s0, s33, 29
	s_add_i32 s0, s5, s0
	s_lshr_b32 s2, s1, 6
	s_ashr_i32 s4, s0, 3
	s_and_b32 s0, s0, -8
	s_lshr_b32 s3, s1, 8
	s_lshl_b32 s31, s2, 10
	s_sub_i32 s0, s5, s0
	s_cmp_lt_i32 s0, 0
	s_movk_i32 s52, 0x83
	s_cselect_b32 s5, s52, 0x82
	s_mul_i32 s0, s5, s0
	s_add_i32 s0, s0, s4
	s_ashr_i32 s4, s0, 31
	s_lshr_b32 s4, s4, 26
	s_add_i32 s4, s0, s4
	s_ashr_i32 s4, s4, 6
	s_lshl_b32 s6, s4, 3
	s_sub_i32 s5, 0x82, s6
	s_lshl_b32 s4, s4, 6
	s_min_u32 s7, s5, 8
	s_sub_i32 s8, s0, s4
	s_sext_i32_i8 s0, s8
	v_cvt_f32_ubyte0_e32 v3, s7
	v_cvt_f32_i32_e32 v2, s0
	v_rcp_iflag_f32_e32 v4, v3
	s_ashr_i32 s0, s0, 30
	s_or_b32 s0, s0, 1
	v_lshl_or_b32 v136, v150, 9, v149
	v_mul_f32_e32 v4, v2, v4
	v_trunc_f32_e32 v4, v4
	v_fma_f32 v2, -v4, v3, v2
	v_cvt_i32_f32_e32 v4, v4
	v_cmp_ge_f32_e64 s[4:5], |v2|, v3
	s_and_b64 s[4:5], s[4:5], exec
	s_cselect_b32 s0, s0, 0
	v_readfirstlane_b32 s4, v4
	s_add_i32 s0, s4, s0
	s_mul_i32 s4, s0, s7
	s_sub_i32 s4, s8, s4
	s_sext_i32_i8 s4, s4
	s_add_i32 s70, s6, s4
	s_bfe_i64 s[4:5], s[0:1], 0x80000
	s_lshl_b64 s[4:5], s[4:5], 17
	s_add_u32 s18, s27, s4
	s_addc_u32 s19, s30, s5
	s_add_i32 s28, s31, 0
	s_add_i32 m0, s28, 0x10000
	v_lshl_or_b32 v134, v151, 9, v149
	global_load_lds_dwordx4 v136, s[18:19]
	s_add_i32 m0, s28, 0x12000
	s_add_u32 s4, s18, 0x10000
	global_load_lds_dwordx4 v134, s[18:19]
	s_addc_u32 s5, s19, 0
	s_add_i32 m0, s28, 0x14000
	s_mul_i32 s7, s70, 0x300000
	global_load_lds_dwordx4 v136, s[4:5]
	s_add_i32 m0, s28, 0x16000
	s_mul_hi_i32 s6, s70, 0x300000
	s_add_u32 s88, s20, s7
	s_addc_u32 s89, s26, s6
	s_add_i32 s16, s28, 0x2000
	global_load_lds_dwordx4 v134, s[4:5]
	s_mov_b32 m0, s28
	s_add_u32 s4, s88, 0x180000
	global_load_lds_dwordx4 v130, s[88:89]
	s_mov_b32 m0, s16
	s_addc_u32 s5, s89, 0
	s_add_i32 s17, s28, 0x4000
	global_load_lds_dwordx4 v132, s[88:89]
	s_mov_b32 m0, s17
	s_add_i32 s6, s28, 0x6000
	global_load_lds_dwordx4 v130, s[4:5]
	s_mov_b32 m0, s6
	v_mov_b32_e32 v137, 0
	global_load_lds_dwordx4 v132, s[4:5]
	v_mov_b32_e32 v135, v137
	v_mov_b32_e32 v131, v137
	v_mov_b32_e32 v133, v137
	s_cmp_eq_u32 s3, 1
	s_mov_b32 s7, 0
	v_lshl_add_u64 v[8:9], s[18:19], 0, v[136:137]
	v_lshl_add_u64 v[6:7], s[18:19], 0, v[134:135]
	v_lshl_add_u64 v[2:3], s[88:89], 0, v[130:131]
	s_cselect_b64 s[8:9], -1, 0
	s_cmp_lg_u32 s3, 1
	v_lshl_add_u64 v[4:5], s[88:89], 0, v[132:133]
	s_cbranch_scc1 .LBB0_657
	s_barrier
	s_setprio 1

.LBB0_665:
	s_add_u32 s21, s88, s24
	s_addc_u32 s25, s89, 0
	s_add_u32 s29, s21, 0x100
	s_addc_u32 s35, s25, 0
	s_and_b64 s[22:23], s[0:1], exec
	s_cselect_b32 s23, s91, s35
	s_cselect_b32 s22, s90, s29
	s_add_u32 s24, s18, s24
	s_addc_u32 s29, s19, 0
	s_add_u32 s24, s24, 0x100
	s_addc_u32 s29, s29, 0
	s_and_b64 s[0:1], s[0:1], exec
	s_cselect_b32 s95, s73, s29
	s_cselect_b32 s94, s74, s24
	s_add_u32 vcc_lo, s21, 0x180080
	ds_read_b128 v[148:151], v144
	ds_read_b128 v[152:155], v144 offset:1024
	ds_read_b128 v[156:159], v144 offset:2048
	ds_read_b128 v[160:163], v144 offset:3072
	ds_read_b128 v[170:173], v145
	ds_read_b128 v[178:181], v145 offset:1024
	ds_read_b128 v[182:185], v145 offset:2048
	ds_read_b128 v[186:189], v145 offset:3072
	s_addc_u32 vcc_hi, s25, 0
	s_add_i32 s87, s68, s31
	s_add_i32 m0, s28, 0xc000
	s_add_i32 s35, s28, 0xe000
	s_add_i32 s81, s87, 0x2000
	s_add_u32 s96, s94, 0x10000
	s_addc_u32 s97, s95, 0
	s_add_i32 s83, s69, s31
	s_add_i32 s82, s83, 0x2000
	s_add_i32 s80, 0, 0x18000
	s_add_i32 s79, 0, 0x1c000
	s_add_u32 s24, s22, 0x180000
	s_addc_u32 s25, s23, 0
	s_add_i32 s78, s80, s31
	s_add_i32 s76, s78, 0x2000
	s_add_u32 s0, s94, 0x10080
	s_addc_u32 s1, s95, 0
	s_add_i32 s77, s79, s31
	s_add_i32 s75, s77, 0x2000
	v_lshl_add_u64 v[174:175], vcc, 0, v[130:131]
	ds_read_b128 v[190:193], v147
	ds_read_b128 v[194:197], v147 offset:1024
	ds_read_b128 v[198:201], v147 offset:2048
	ds_read_b128 v[202:205], v147 offset:3072
	ds_read_b128 v[206:209], v147 offset:4096
	ds_read_b128 v[210:213], v147 offset:5120
	ds_read_b128 v[214:217], v147 offset:6144
	ds_read_b128 v[218:221], v147 offset:7168
	global_load_lds_dwordx4 v[174:175], off
	v_lshl_add_u64 v[174:175], vcc, 0, v[132:133]
	s_mov_b32 m0, s35
	s_nop 0
	global_load_lds_dwordx4 v[174:175], off
	s_waitcnt vmcnt(8)
	s_waitcnt lgkmcnt(0)
	s_barrier
	s_waitcnt lgkmcnt(0)
	v_mfma_f32_16x16x32_bf16 v[126:129], v[148:151], v[190:193], v[126:129]
	v_mfma_f32_16x16x32_bf16 v[122:125], v[156:159], v[190:193], v[122:125]
	v_mfma_f32_16x16x32_bf16 v[118:121], v[148:151], v[198:201], v[118:121]
	v_mfma_f32_16x16x32_bf16 v[114:117], v[156:159], v[198:201], v[114:117]
	v_mfma_f32_16x16x32_bf16 v[102:105], v[148:151], v[206:209], v[102:105]
	v_mfma_f32_16x16x32_bf16 v[98:101], v[156:159], v[206:209], v[98:101]
	v_mfma_f32_16x16x32_bf16 v[86:89], v[148:151], v[214:217], v[86:89]
	v_mfma_f32_16x16x32_bf16 v[82:85], v[156:159], v[214:217], v[82:85]
	v_mfma_f32_16x16x32_bf16 v[126:129], v[152:155], v[194:197], v[126:129]
	v_mfma_f32_16x16x32_bf16 v[122:125], v[160:163], v[194:197], v[122:125]
	v_mfma_f32_16x16x32_bf16 v[118:121], v[152:155], v[202:205], v[118:121]
	v_mfma_f32_16x16x32_bf16 v[114:117], v[160:163], v[202:205], v[114:117]
	v_mfma_f32_16x16x32_bf16 v[102:105], v[152:155], v[210:213], v[102:105]
	v_mfma_f32_16x16x32_bf16 v[98:101], v[160:163], v[210:213], v[98:101]
	v_mfma_f32_16x16x32_bf16 v[86:89], v[152:155], v[218:221], v[86:89]
	v_mfma_f32_16x16x32_bf16 v[82:85], v[160:163], v[218:221], v[82:85]
	v_mfma_f32_16x16x32_bf16 v[110:113], v[170:173], v[190:193], v[110:113]
	v_mfma_f32_16x16x32_bf16 v[106:109], v[182:185], v[190:193], v[106:109]
	v_mfma_f32_16x16x32_bf16 v[94:97], v[170:173], v[198:201], v[94:97]
	v_mfma_f32_16x16x32_bf16 v[90:93], v[182:185], v[198:201], v[90:93]
	v_mfma_f32_16x16x32_bf16 v[78:81], v[170:173], v[206:209], v[78:81]
	v_mfma_f32_16x16x32_bf16 v[74:77], v[182:185], v[206:209], v[74:77]
	v_mfma_f32_16x16x32_bf16 v[70:73], v[170:173], v[214:217], v[70:73]
	v_mfma_f32_16x16x32_bf16 v[66:69], v[182:185], v[214:217], v[66:69]
	v_mfma_f32_16x16x32_bf16 v[110:113], v[178:181], v[194:197], v[110:113]
	v_mfma_f32_16x16x32_bf16 v[106:109], v[186:189], v[194:197], v[106:109]
	v_mfma_f32_16x16x32_bf16 v[94:97], v[178:181], v[202:205], v[94:97]
	v_mfma_f32_16x16x32_bf16 v[90:93], v[186:189], v[202:205], v[90:93]
	v_mfma_f32_16x16x32_bf16 v[78:81], v[178:181], v[210:213], v[78:81]
	v_mfma_f32_16x16x32_bf16 v[74:77], v[186:189], v[210:213], v[74:77]
	v_mfma_f32_16x16x32_bf16 v[70:73], v[178:181], v[218:221], v[70:73]
	v_mfma_f32_16x16x32_bf16 v[66:69], v[186:189], v[218:221], v[66:69]
	s_barrier
	s_mov_b32 m0, s87
	v_lshl_add_u64 v[174:175], s[94:95], 0, v[136:137]
	ds_read_b128 v[190:193], v147 offset:16384
	ds_read_b128 v[194:197], v147 offset:17408
	ds_read_b128 v[198:201], v147 offset:18432
	ds_read_b128 v[202:205], v147 offset:19456
	ds_read_b128 v[206:209], v147 offset:20480
	ds_read_b128 v[210:213], v147 offset:21504
	ds_read_b128 v[214:217], v147 offset:22528
	ds_read_b128 v[218:221], v147 offset:23552
	global_load_lds_dwordx4 v[174:175], off
	v_lshl_add_u64 v[222:223], s[94:95], 0, v[134:135]
	s_mov_b32 m0, s81
	v_lshl_add_u64 v[224:225], s[96:97], 0, v[136:137]
	global_load_lds_dwordx4 v[222:223], off
	s_mov_b32 m0, s83
	v_lshl_add_u64 v[226:227], s[22:23], 0, v[132:133]
	global_load_lds_dwordx4 v[224:225], off
	v_lshl_add_u64 v[224:225], s[96:97], 0, v[134:135]
	s_mov_b32 m0, s82
	s_nop 0
	global_load_lds_dwordx4 v[224:225], off
	v_lshl_add_u64 v[224:225], s[22:23], 0, v[130:131]
	s_mov_b32 m0, s28
	s_nop 0
	global_load_lds_dwordx4 v[224:225], off
	s_mov_b32 m0, s16
	s_nop 0
	global_load_lds_dwordx4 v[226:227], off
	s_waitcnt vmcnt(8)
	s_waitcnt lgkmcnt(0)
	s_barrier
	s_waitcnt lgkmcnt(0)
	v_mfma_f32_16x16x32_bf16 v[62:65], v[148:151], v[190:193], v[62:65]
	v_mfma_f32_16x16x32_bf16 v[58:61], v[156:159], v[190:193], v[58:61]
	v_mfma_f32_16x16x32_bf16 v[54:57], v[148:151], v[198:201], v[54:57]
	v_mfma_f32_16x16x32_bf16 v[50:53], v[156:159], v[198:201], v[50:53]
	v_mfma_f32_16x16x32_bf16 v[38:41], v[148:151], v[206:209], v[38:41]
	v_mfma_f32_16x16x32_bf16 v[34:37], v[156:159], v[206:209], v[34:37]
	v_mfma_f32_16x16x32_bf16 v[22:25], v[148:151], v[214:217], v[22:25]
	v_mfma_f32_16x16x32_bf16 v[18:21], v[156:159], v[214:217], v[18:21]
	v_mfma_f32_16x16x32_bf16 v[62:65], v[152:155], v[194:197], v[62:65]
	v_mfma_f32_16x16x32_bf16 v[58:61], v[160:163], v[194:197], v[58:61]
	v_mfma_f32_16x16x32_bf16 v[54:57], v[152:155], v[202:205], v[54:57]
	v_mfma_f32_16x16x32_bf16 v[50:53], v[160:163], v[202:205], v[50:53]
	v_mfma_f32_16x16x32_bf16 v[38:41], v[152:155], v[210:213], v[38:41]
	v_mfma_f32_16x16x32_bf16 v[34:37], v[160:163], v[210:213], v[34:37]
	v_mfma_f32_16x16x32_bf16 v[22:25], v[152:155], v[218:221], v[22:25]
	v_mfma_f32_16x16x32_bf16 v[18:21], v[160:163], v[218:221], v[18:21]
	v_mfma_f32_16x16x32_bf16 v[46:49], v[170:173], v[190:193], v[46:49]
	v_mfma_f32_16x16x32_bf16 v[42:45], v[182:185], v[190:193], v[42:45]
	v_mfma_f32_16x16x32_bf16 v[30:33], v[170:173], v[198:201], v[30:33]
	v_mfma_f32_16x16x32_bf16 v[26:29], v[182:185], v[198:201], v[26:29]
	v_mfma_f32_16x16x32_bf16 v[14:17], v[170:173], v[206:209], v[14:17]
	v_mfma_f32_16x16x32_bf16 v[10:13], v[182:185], v[206:209], v[10:13]
	v_mfma_f32_16x16x32_bf16 v[6:9], v[170:173], v[214:217], v[6:9]
	v_mfma_f32_16x16x32_bf16 v[2:5], v[182:185], v[214:217], v[2:5]
	v_mfma_f32_16x16x32_bf16 v[46:49], v[178:181], v[194:197], v[46:49]
	v_mfma_f32_16x16x32_bf16 v[42:45], v[186:189], v[194:197], v[42:45]
	v_mfma_f32_16x16x32_bf16 v[30:33], v[178:181], v[202:205], v[30:33]
	v_mfma_f32_16x16x32_bf16 v[26:29], v[186:189], v[202:205], v[26:29]
	v_mfma_f32_16x16x32_bf16 v[14:17], v[178:181], v[210:213], v[14:17]
	v_mfma_f32_16x16x32_bf16 v[10:13], v[186:189], v[210:213], v[10:13]
	v_mfma_f32_16x16x32_bf16 v[6:9], v[178:181], v[218:221], v[6:9]
	v_mfma_f32_16x16x32_bf16 v[2:5], v[186:189], v[218:221], v[2:5]
	s_barrier
	v_add_u32_e32 v160, s80, v143
	v_add_u32_e32 v165, s79, v143
	ds_read_b128 v[148:151], v160
	ds_read_b128 v[152:155], v160 offset:1024
	ds_read_b128 v[156:159], v160 offset:2048
	ds_read_b128 v[160:163], v160 offset:3072
	ds_read_b128 v[170:173], v165
	ds_read_b128 v[178:181], v165 offset:1024
	ds_read_b128 v[182:185], v165 offset:2048
	ds_read_b128 v[186:189], v165 offset:3072
	s_mov_b32 m0, s17
	v_lshl_add_u64 v[228:229], s[24:25], 0, v[130:131]
	ds_read_b128 v[190:193], v147 offset:32768
	ds_read_b128 v[194:197], v147 offset:33792
	ds_read_b128 v[198:201], v147 offset:34816
	ds_read_b128 v[202:205], v147 offset:35840
	ds_read_b128 v[206:209], v147 offset:36864
	ds_read_b128 v[210:213], v147 offset:37888
	ds_read_b128 v[214:217], v147 offset:38912
	ds_read_b128 v[218:221], v147 offset:39936
	global_load_lds_dwordx4 v[228:229], off
	v_lshl_add_u64 v[228:229], s[24:25], 0, v[132:133]
	s_mov_b32 m0, s6
	s_nop 0
	global_load_lds_dwordx4 v[228:229], off
	s_waitcnt vmcnt(8)
	s_waitcnt lgkmcnt(0)
	s_barrier
	s_waitcnt lgkmcnt(0)
	v_mfma_f32_16x16x32_bf16 v[126:129], v[148:151], v[190:193], v[126:129]
	v_mfma_f32_16x16x32_bf16 v[122:125], v[156:159], v[190:193], v[122:125]
	v_mfma_f32_16x16x32_bf16 v[118:121], v[148:151], v[198:201], v[118:121]
	v_mfma_f32_16x16x32_bf16 v[114:117], v[156:159], v[198:201], v[114:117]
	v_mfma_f32_16x16x32_bf16 v[102:105], v[148:151], v[206:209], v[102:105]
	v_mfma_f32_16x16x32_bf16 v[98:101], v[156:159], v[206:209], v[98:101]
	v_mfma_f32_16x16x32_bf16 v[86:89], v[148:151], v[214:217], v[86:89]
	v_mfma_f32_16x16x32_bf16 v[82:85], v[156:159], v[214:217], v[82:85]
	v_mfma_f32_16x16x32_bf16 v[126:129], v[152:155], v[194:197], v[126:129]
	v_mfma_f32_16x16x32_bf16 v[122:125], v[160:163], v[194:197], v[122:125]
	v_mfma_f32_16x16x32_bf16 v[118:121], v[152:155], v[202:205], v[118:121]
	v_mfma_f32_16x16x32_bf16 v[114:117], v[160:163], v[202:205], v[114:117]
	v_mfma_f32_16x16x32_bf16 v[102:105], v[152:155], v[210:213], v[102:105]
	v_mfma_f32_16x16x32_bf16 v[98:101], v[160:163], v[210:213], v[98:101]
	v_mfma_f32_16x16x32_bf16 v[86:89], v[152:155], v[218:221], v[86:89]
	v_mfma_f32_16x16x32_bf16 v[82:85], v[160:163], v[218:221], v[82:85]
	v_mfma_f32_16x16x32_bf16 v[110:113], v[170:173], v[190:193], v[110:113]
	v_mfma_f32_16x16x32_bf16 v[106:109], v[182:185], v[190:193], v[106:109]
	v_mfma_f32_16x16x32_bf16 v[94:97], v[170:173], v[198:201], v[94:97]
	v_mfma_f32_16x16x32_bf16 v[90:93], v[182:185], v[198:201], v[90:93]
	v_mfma_f32_16x16x32_bf16 v[78:81], v[170:173], v[206:209], v[78:81]
	v_mfma_f32_16x16x32_bf16 v[74:77], v[182:185], v[206:209], v[74:77]
	v_mfma_f32_16x16x32_bf16 v[70:73], v[170:173], v[214:217], v[70:73]
	v_mfma_f32_16x16x32_bf16 v[66:69], v[182:185], v[214:217], v[66:69]
	v_mfma_f32_16x16x32_bf16 v[110:113], v[178:181], v[194:197], v[110:113]
	v_mfma_f32_16x16x32_bf16 v[106:109], v[186:189], v[194:197], v[106:109]
	v_mfma_f32_16x16x32_bf16 v[94:97], v[178:181], v[202:205], v[94:97]
	v_mfma_f32_16x16x32_bf16 v[90:93], v[186:189], v[202:205], v[90:93]
	v_mfma_f32_16x16x32_bf16 v[78:81], v[178:181], v[210:213], v[78:81]
	v_mfma_f32_16x16x32_bf16 v[74:77], v[186:189], v[210:213], v[74:77]
	v_mfma_f32_16x16x32_bf16 v[70:73], v[178:181], v[218:221], v[70:73]
	v_mfma_f32_16x16x32_bf16 v[66:69], v[186:189], v[218:221], v[66:69]
	s_barrier
	s_mov_b32 m0, s78
	v_lshl_add_u64 v[174:175], v[174:175], 0, s[12:13]
	ds_read_b128 v[190:193], v147 offset:49152
	ds_read_b128 v[194:197], v147 offset:50176
	ds_read_b128 v[198:201], v147 offset:51200
	ds_read_b128 v[202:205], v147 offset:52224
	ds_read_b128 v[206:209], v147 offset:53248
	ds_read_b128 v[210:213], v147 offset:54272
	ds_read_b128 v[214:217], v147 offset:55296
	ds_read_b128 v[218:221], v147 offset:56320
	global_load_lds_dwordx4 v[174:175], off
	v_lshl_add_u64 v[174:175], v[222:223], 0, s[12:13]
	s_mov_b32 m0, s76
	s_nop 0
	global_load_lds_dwordx4 v[174:175], off
	v_lshl_add_u64 v[174:175], s[0:1], 0, v[136:137]
	s_mov_b32 m0, s77
	s_nop 0
	global_load_lds_dwordx4 v[174:175], off
	v_lshl_add_u64 v[174:175], s[0:1], 0, v[134:135]
	s_mov_b32 m0, s75
	s_nop 0
	global_load_lds_dwordx4 v[174:175], off
	v_lshl_add_u64 v[174:175], v[224:225], 0, s[12:13]
	s_mov_b32 m0, s34
	s_nop 0
	global_load_lds_dwordx4 v[174:175], off
	v_lshl_add_u64 v[174:175], v[226:227], 0, s[12:13]
	s_mov_b32 m0, s84
	s_nop 0
	global_load_lds_dwordx4 v[174:175], off
	s_waitcnt vmcnt(8)
	s_waitcnt lgkmcnt(0)
	s_barrier
	s_waitcnt lgkmcnt(0)
	v_mfma_f32_16x16x32_bf16 v[62:65], v[148:151], v[190:193], v[62:65]
	v_mfma_f32_16x16x32_bf16 v[58:61], v[156:159], v[190:193], v[58:61]
	v_mfma_f32_16x16x32_bf16 v[54:57], v[148:151], v[198:201], v[54:57]
	v_mfma_f32_16x16x32_bf16 v[50:53], v[156:159], v[198:201], v[50:53]
	v_mfma_f32_16x16x32_bf16 v[38:41], v[148:151], v[206:209], v[38:41]
	v_mfma_f32_16x16x32_bf16 v[34:37], v[156:159], v[206:209], v[34:37]
	v_mfma_f32_16x16x32_bf16 v[22:25], v[148:151], v[214:217], v[22:25]
	v_mfma_f32_16x16x32_bf16 v[18:21], v[156:159], v[214:217], v[18:21]
	v_mfma_f32_16x16x32_bf16 v[62:65], v[152:155], v[194:197], v[62:65]
	v_mfma_f32_16x16x32_bf16 v[58:61], v[160:163], v[194:197], v[58:61]
	v_mfma_f32_16x16x32_bf16 v[54:57], v[152:155], v[202:205], v[54:57]
	v_mfma_f32_16x16x32_bf16 v[50:53], v[160:163], v[202:205], v[50:53]
	v_mfma_f32_16x16x32_bf16 v[38:41], v[152:155], v[210:213], v[38:41]
	v_mfma_f32_16x16x32_bf16 v[34:37], v[160:163], v[210:213], v[34:37]
	v_mfma_f32_16x16x32_bf16 v[22:25], v[152:155], v[218:221], v[22:25]
	v_mfma_f32_16x16x32_bf16 v[18:21], v[160:163], v[218:221], v[18:21]
	v_mfma_f32_16x16x32_bf16 v[46:49], v[170:173], v[190:193], v[46:49]
	v_mfma_f32_16x16x32_bf16 v[42:45], v[182:185], v[190:193], v[42:45]
	v_mfma_f32_16x16x32_bf16 v[30:33], v[170:173], v[198:201], v[30:33]
	v_mfma_f32_16x16x32_bf16 v[26:29], v[182:185], v[198:201], v[26:29]
	v_mfma_f32_16x16x32_bf16 v[14:17], v[170:173], v[206:209], v[14:17]
	v_mfma_f32_16x16x32_bf16 v[10:13], v[182:185], v[206:209], v[10:13]
	v_mfma_f32_16x16x32_bf16 v[6:9], v[170:173], v[214:217], v[6:9]
	v_mfma_f32_16x16x32_bf16 v[2:5], v[182:185], v[214:217], v[2:5]
	v_mfma_f32_16x16x32_bf16 v[46:49], v[178:181], v[194:197], v[46:49]
	v_mfma_f32_16x16x32_bf16 v[42:45], v[186:189], v[194:197], v[42:45]
	v_mfma_f32_16x16x32_bf16 v[30:33], v[178:181], v[202:205], v[30:33]
	v_mfma_f32_16x16x32_bf16 v[26:29], v[186:189], v[202:205], v[26:29]
	v_mfma_f32_16x16x32_bf16 v[14:17], v[178:181], v[210:213], v[14:17]
	v_mfma_f32_16x16x32_bf16 v[10:13], v[186:189], v[210:213], v[10:13]
	v_mfma_f32_16x16x32_bf16 v[6:9], v[178:181], v[218:221], v[6:9]
	v_mfma_f32_16x16x32_bf16 v[2:5], v[186:189], v[218:221], v[2:5]
	s_barrier
	s_movk_i32 s24, 0x100
	s_andn2_b64 vcc, exec, s[4:5]
	s_mov_b64 s[0:1], -1
	s_mov_b64 s[4:5], 0
	s_cbranch_vccz .LBB0_665
	s_and_b64 vcc, exec, s[14:15]
	s_cbranch_vccz .LBB0_668
	s_barrier

.LBB0_764:
	s_setprio 0
	v_readlane_b32 s2, v243, 51
	s_cmp_lt_i32 s2, 9
	s_cselect_b64 s[8:9], -1, 0
	s_and_b64 s[0:1], s[8:9], s[0:1]
	s_andn2_b64 vcc, exec, s[0:1]
	v_readlane_b32 s3, v243, 52
	s_cbranch_vccnz .LBB0_777
	v_readlane_b32 s0, v243, 0
	s_lshl_b32 s0, s0, 3
	v_readlane_b32 s1, v243, 59
	s_add_i32 s0, s1, s0
	s_cmp_gt_i32 s0, 0x81ff
	s_cbranch_scc1 .LBB0_777
	v_and_b32_e32 v1, 7, v0
	v_readlane_b32 s14, v243, 53
	v_readlane_b32 s16, v243, 33
	v_lshlrev_b32_e32 v2, 4, v1
	s_lshl_b32 s10, s14, 3
	v_lshrrev_b32_e32 v5, 3, v166
	v_lshlrev_b32_e32 v4, 5, v1
	v_readlane_b32 s30, v243, 47
	v_readlane_b32 s31, v243, 48
	v_lshlrev_b32_e32 v1, 6, v1
	s_ashr_i32 s1, s0, 31
	s_mul_i32 s5, s0, 0xc00
	v_readlane_b32 s2, v242, 21
	v_mov_b32_e32 v3, 0
	v_readlane_b32 s28, v243, 45
	v_readlane_b32 s29, v243, 46
	global_load_dwordx4 v[6:9], v4, s[30:31] offset:528
	s_nop 3
	global_load_dwordx4 v[10:13], v4, s[28:29] offset:528
	global_load_dwordx4 v[14:17], v4, s[30:31] offset:512
	global_load_dwordx4 v[18:21], v4, s[28:29] offset:512
	global_load_dwordx4 v[22:25], v1, s[30:31]
	global_load_dwordx4 v[26:29], v1, s[30:31] offset:16
	global_load_dwordx4 v[30:33], v1, s[30:31] offset:48
	global_load_dwordx4 v[34:37], v1, s[28:29] offset:48
	global_load_dwordx4 v[38:41], v1, s[30:31] offset:32
	global_load_dwordx4 v[42:45], v1, s[28:29] offset:32
	global_load_dwordx4 v[46:49], v1, s[28:29] offset:16
	global_load_dwordx4 v[50:53], v1, s[28:29]
	s_mul_hi_i32 s4, s0, 0xc00
	v_readlane_b32 s3, v242, 22
	s_add_u32 s2, s2, s5
	v_mul_u32_u24_e32 v1, 0xc0, v5
	s_addc_u32 s3, s3, s4
	v_lshlrev_b32_e32 v54, 1, v1
	v_mov_b32_e32 v55, v3
	v_lshl_add_u64 v[56:57], s[2:3], 0, v[54:55]
	s_lshl_b64 s[2:3], s[0:1], 12
	s_add_u32 s2, s58, s2
	s_addc_u32 s3, s59, s3
	v_lshlrev_b32_e32 v58, 9, v5
	v_mov_b32_e32 v59, v3
	v_lshl_add_u64 v[58:59], s[2:3], 0, v[58:59]
	v_mov_b32_e32 v5, v3
	v_lshl_add_u64 v[58:59], v[58:59], 0, v[4:5]
	v_lshl_add_u64 v[62:63], v[56:57], 0, v[4:5]
	v_lshl_add_u64 v[56:57], v[56:57], 0, v[2:3]
	s_mov_b32 s1, 0x34300000
	s_mul_i32 s2, s0, 0x3000
	v_readlane_b32 s6, v242, 17
	global_load_dwordx4 v[104:107], v[62:63], off offset:16
	global_load_dwordx4 v[100:103], v[56:57], off offset:256
	v_add_co_u32_e32 v56, vcc, s1, v58
	s_mul_hi_i32 s1, s0, 0x3000
	v_readlane_b32 s7, v242, 18
	s_add_u32 s2, s6, s2
	s_mov_b64 s[12:13], 0x34300000
	s_addc_u32 s3, s7, s1
	v_lshl_add_u64 v[60:61], v[58:59], 0, s[12:13]
	v_addc_co_u32_e32 v57, vcc, 0, v59, vcc
	v_lshl_add_u64 v[58:59], s[2:3], 0, v[2:3]
	s_movk_i32 s1, 0x2000
	v_add_co_u32_e32 v58, vcc, s1, v58
	global_load_dwordx4 v[108:111], v[62:63], off
	global_load_dwordx4 v[88:91], v[60:61], off offset:16
	v_addc_co_u32_e32 v59, vcc, 0, v59, vcc
	global_load_dwordx4 v[96:99], v[56:57], off
	global_load_dwordx4 v[92:95], v[58:59], off offset:3584
	v_lshlrev_b32_e32 v1, 5, v0
	v_and_b32_e32 v56, 0x60, v1
	v_mov_b32_e32 v57, v3
	v_lshl_add_u64 v[56:57], s[58:59], 0, v[56:57]
	s_mov_b64 s[2:3], 0x900000
	v_mbcnt_lo_u32_b32 v1, -1, 0
	v_lshl_add_u64 v[112:113], v[56:57], 0, s[2:3]
	s_mov_b64 s[2:3], 0xb00000
	v_mbcnt_hi_u32_b32 v5, -1, v1
	v_lshl_add_u64 v[114:115], v[56:57], 0, s[2:3]
	v_and_b32_e32 v56, 64, v5
	v_xor_b32_e32 v1, 1, v5
	v_add_u32_e32 v56, 64, v56
	v_cmp_lt_i32_e32 vcc, v1, v56
	v_xor_b32_e32 v57, 2, v5
	v_readlane_b32 s1, v243, 0
	v_cndmask_b32_e32 v1, v5, v1, vcc
	v_cmp_lt_i32_e32 vcc, v57, v56
	v_readlane_b32 s6, v243, 59
	s_lshl_b32 s1, s1, 8
	v_cndmask_b32_e32 v57, v5, v57, vcc
	v_lshlrev_b32_e32 v148, 2, v57
	v_xor_b32_e32 v57, 4, v5
	v_cmp_lt_i32_e32 vcc, v57, v56
	s_lshl_b32 s6, s6, 5
	s_add_i32 s1, s1, s6
	v_cndmask_b32_e32 v5, v5, v57, vcc
	v_lshlrev_b32_e32 v149, 2, v5
	v_and_b32_e32 v5, 4, v0
	v_cmp_eq_u32_e64 s[2:3], 0, v5
	v_and_b32_e32 v5, 56, v0
	v_lshlrev_b32_e32 v5, 6, v5
	s_waitcnt vmcnt(0)
	v_mov_b32_e32 v116, v23
	v_mov_b32_e32 v117, v25
	v_mov_b32_e32 v23, v24
	v_mov_b32_e32 v24, v27
	v_mov_b32_e32 v25, v29
	v_mov_b32_e32 v27, v28
	v_mov_b32_e32 v28, v39
	v_mov_b32_e32 v29, v41
	v_mov_b32_e32 v39, v40
	v_mov_b32_e32 v40, v31
	v_mov_b32_e32 v41, v33
	v_mov_b32_e32 v31, v32
	v_mov_b32_e32 v32, v51
	v_mov_b32_e32 v33, v53
	v_mov_b32_e32 v51, v52
	v_or_b32_e32 v52, s5, v2
	v_mov_b32_e32 v53, s4
	s_add_i32 s4, s0, s10
	v_mov_b32_e32 v118, v47
	v_mov_b32_e32 v119, v49
	v_mov_b32_e32 v47, v48
	v_mov_b32_e32 v48, v43
	v_mov_b32_e32 v49, v45
	v_mov_b32_e32 v43, v44
	v_mov_b32_e32 v44, v35
	v_mov_b32_e32 v45, v37
	v_mov_b32_e32 v35, v36
	v_lshl_add_u64 v[36:37], v[52:53], 0, v[54:55]
	v_or_b32_e32 v52, s5, v4
	s_mul_hi_i32 s6, s4, 0x3000
	s_mul_i32 s7, s4, 0x3000
	v_lshl_add_u64 v[120:121], v[52:53], 0, v[54:55]
	s_ashr_i32 s5, s4, 31
	v_or_b32_e32 v52, s7, v2
	v_mov_b32_e32 v53, s6
	s_mov_b64 s[6:7], 0x15b02e00
	v_lshl_add_u64 v[122:123], v[52:53], 0, s[6:7]
	s_lshl_b64 s[6:7], s[4:5], 12
	v_or3_b32 v124, s6, v5, v4
	s_mul_hi_i32 s5, s4, 0xc00
	s_mul_i32 s6, s4, 0xc00
	v_or_b32_e32 v52, s6, v2
	v_mov_b32_e32 v53, s5
	v_readlane_b32 s17, v243, 34
	v_readlane_b32 s18, v243, 35
	v_readlane_b32 s19, v243, 36
	v_readlane_b32 s20, v243, 37
	v_readlane_b32 s22, v243, 39
	v_readlane_b32 s23, v243, 40
	v_readlane_b32 s24, v243, 41
	s_ashr_i32 s11, s10, 31
	v_lshl_add_u64 v[56:57], v[52:53], 0, v[54:55]
	s_mov_b64 s[4:5], 0x2e100100
	v_or_b32_e32 v52, s6, v4
	v_mov_b64_e32 v[64:65], v[108:109]
	v_mov_b64_e32 v[72:73], v[104:105]
	v_mov_b64_e32 v[68:69], v[100:101]
	v_mov_b64_e32 v[80:81], v[96:97]
	v_mov_b64_e32 v[76:77], v[88:89]
	v_mov_b64_e32 v[84:85], v[92:93]
	s_mov_b32 s15, 0
	v_lshlrev_b32_e32 v1, 2, v1
	s_lshl_b32 s20, s14, 8
	s_mul_i32 s16, s14, 0x6000
	s_mul_hi_i32 s17, s10, 0xc00
	s_mul_i32 s18, s14, 0x18000
	s_mul_hi_i32 s19, s10, 0x3000
	v_mov_b32_e32 v125, s7
	s_lshl_b64 s[86:87], s[10:11], 12
	v_lshl_add_u64 v[126:127], v[56:57], 0, s[4:5]
	v_lshl_add_u64 v[128:129], v[52:53], 0, v[54:55]
	s_mov_b32 s11, 0x2e100000
	s_movk_i32 s22, 0x7fff
	s_mov_b32 s23, 0xffff0000
	v_mov_b32_e32 v150, 0x358637bd
	s_mov_b32 s24, 0xf800000
	v_mov_b32_e32 v151, 0x260
	s_mov_b32 s88, 0x3dd53b94
	v_mov_b32_e32 v2, v3
	v_mov_b32_e32 v4, v3
	v_mov_b32_e32 v5, v3
	v_mov_b32_e32 v52, v3
	v_mov_b32_e32 v53, v3
	v_mov_b32_e32 v54, v3
	v_mov_b64_e32 v[66:67], v[110:111]
	v_mov_b64_e32 v[74:75], v[106:107]
	v_mov_b64_e32 v[70:71], v[102:103]
	v_mov_b64_e32 v[82:83], v[98:99]
	v_mov_b64_e32 v[78:79], v[90:91]
	v_mov_b64_e32 v[86:87], v[94:95]
	v_readlane_b32 s21, v243, 38
	v_readlane_b32 s25, v243, 42
	v_readlane_b32 s26, v243, 43
	v_readlane_b32 s27, v243, 44
	s_branch .LBB0_768

.LBB0_831:
	s_setprio 0
	v_readlane_b32 s2, v243, 51
	s_cmp_lt_i32 s2, 10
	s_cselect_b64 s[60:61], -1, 0
	s_and_b64 s[0:1], s[60:61], s[0:1]
	s_andn2_b64 vcc, exec, s[0:1]
	v_readlane_b32 s3, v243, 52
	s_cbranch_vccnz .LBB0_913
	v_readlane_b32 s0, v243, 33
	v_lshlrev_b32_e32 v2, 2, v166
	v_mov_b32_e32 v3, 0
	v_readlane_b32 s1, v243, 34
	v_readlane_b32 s2, v243, 35
	v_readlane_b32 s3, v243, 36
	v_readlane_b32 s4, v243, 37
	v_readlane_b32 s12, v243, 45
	v_readlane_b32 s13, v243, 46
	v_readlane_b32 s14, v243, 47
	v_readlane_b32 s15, v243, 48
	v_lshl_add_u64 v[4:5], s[12:13], 0, v[2:3]
	v_or_b32_e32 v8, 0xffffffc0, v166
	v_lshl_add_u64 v[6:7], s[14:15], 0, v[2:3]
	s_mov_b64 s[0:1], 0
	s_mov_b64 s[2:3], 0x100
	s_movk_i32 s4, 0x7f
	v_mov_b32_e32 v1, v3
	v_readlane_b32 s5, v243, 38
	v_readlane_b32 s6, v243, 39
	v_readlane_b32 s7, v243, 40
	v_readlane_b32 s8, v243, 41
	v_readlane_b32 s9, v243, 42
	v_readlane_b32 s10, v243, 43
	v_readlane_b32 s11, v243, 44

.LBB0_967:
	s_setprio 0
	v_readlane_b32 s2, v243, 51
	s_cmp_gt_i32 s2, 10
	s_cselect_b64 s[4:5], -1, 0
	s_xor_b64 s[0:1], s[0:1], -1
	v_readlane_b32 s3, v243, 52
	s_or_b64 s[0:1], s[4:5], s[0:1]
	s_mov_b64 s[2:3], -1
	s_and_b64 vcc, exec, s[0:1]
	v_and_b32_e32 v1, 7, v0
	s_cbranch_vccnz .LBB0_977
	v_lshlrev_b32_e32 v2, 2, v166
	global_load_dword v3, v2, s[48:49]
	global_load_dword v4, v2, s[48:49] offset:256
	global_load_dword v5, v2, s[48:49] offset:512
	s_nop 0
	global_load_dword v2, v2, s[48:49] offset:768
	v_mbcnt_lo_u32_b32 v6, -1, 0
	v_mbcnt_hi_u32_b32 v6, -1, v6
	v_and_b32_e32 v7, 64, v6
	v_xor_b32_e32 v8, 1, v6
	v_add_u32_e32 v7, 64, v7
	v_cmp_lt_i32_e32 vcc, v8, v7
	v_xor_b32_e32 v9, 2, v6
	v_xor_b32_e32 v10, 4, v6
	v_cndmask_b32_e32 v8, v6, v8, vcc
	v_lshlrev_b32_e32 v60, 2, v8
	v_cmp_lt_i32_e32 vcc, v9, v7
	v_xor_b32_e32 v11, 8, v6
	v_xor_b32_e32 v12, 16, v6
	v_cndmask_b32_e32 v9, v6, v9, vcc
	v_lshlrev_b32_e32 v61, 2, v9
	v_cmp_lt_i32_e32 vcc, v10, v7
	v_xor_b32_e32 v13, 32, v6
	v_readlane_b32 s0, v243, 0
	s_lshl_b32 s0, s0, 3
	v_readlane_b32 s1, v243, 59
	s_add_i32 s0, s1, s0
	s_cmp_lt_i32 s0, 0x8200
	s_cselect_b64 s[4:5], -1, 0
	v_lshlrev_b32_e32 v34, 4, v1
	s_waitcnt vmcnt(0)
	v_mul_f32_e32 v8, v3, v4
	ds_bpermute_b32 v8, v60, v8
	v_mul_f32_e32 v14, v5, v2
	ds_bpermute_b32 v14, v60, v14
	s_waitcnt lgkmcnt(1)
	v_fmac_f32_e32 v8, v3, v4
	v_cndmask_b32_e32 v4, v6, v10, vcc
	s_waitcnt lgkmcnt(0)
	v_fmac_f32_e32 v14, v5, v2
	ds_bpermute_b32 v2, v61, v8
	ds_bpermute_b32 v3, v61, v14
	v_lshlrev_b32_e32 v62, 2, v4
	v_cmp_lt_i32_e32 vcc, v11, v7
	s_waitcnt lgkmcnt(1)
	v_add_f32_e32 v2, v8, v2
	s_waitcnt lgkmcnt(0)
	v_add_f32_e32 v3, v14, v3
	ds_bpermute_b32 v4, v62, v2
	ds_bpermute_b32 v5, v62, v3
	v_cndmask_b32_e32 v8, v6, v11, vcc
	v_lshlrev_b32_e32 v8, 2, v8
	v_cmp_lt_i32_e32 vcc, v12, v7
	s_waitcnt lgkmcnt(1)
	v_add_f32_e32 v2, v2, v4
	s_waitcnt lgkmcnt(0)
	v_add_f32_e32 v3, v3, v5
	ds_bpermute_b32 v4, v8, v2
	ds_bpermute_b32 v5, v8, v3
	v_cndmask_b32_e32 v8, v6, v12, vcc
	v_lshlrev_b32_e32 v8, 2, v8
	v_cmp_lt_i32_e32 vcc, v13, v7
	s_waitcnt lgkmcnt(1)
	v_add_f32_e32 v2, v2, v4
	s_waitcnt lgkmcnt(0)
	v_add_f32_e32 v3, v3, v5
	ds_bpermute_b32 v4, v8, v2
	ds_bpermute_b32 v5, v8, v3
	v_cndmask_b32_e32 v6, v6, v13, vcc
	v_lshlrev_b32_e32 v6, 2, v6
	s_and_b64 vcc, exec, s[4:5]
	s_waitcnt lgkmcnt(1)
	v_add_f32_e32 v36, v2, v4
	s_waitcnt lgkmcnt(0)
	v_add_f32_e32 v37, v3, v5
	ds_bpermute_b32 v38, v6, v36
	ds_bpermute_b32 v39, v6, v37
	s_cbranch_vccnz .LBB0_970
	v_mov_b32_e32 v35, 0
	s_mov_b64 s[2:3], 0

.LBB0_977:
	v_readlane_b32 s2, v243, 51
	s_cmp_lt_i32 s2, 12
	v_readlane_b32 s3, v243, 52
	s_cselect_b64 s[4:5], -1, 0
	s_cmp_gt_i32 s2, 11
	s_cselect_b64 s[0:1], -1, 0
	s_cmp_lt_i32 s3, 12
	s_cselect_b64 s[2:3], -1, 0
	s_or_b64 s[0:1], s[0:1], s[2:3]
	s_and_b64 vcc, exec, s[0:1]
	s_cbranch_vccnz .LBB0_994
	v_readlane_b32 s0, v243, 0
	s_cmpk_gt_i32 s0, 0xc2f
	v_readfirstlane_b32 s3, v0
	s_cbranch_scc1 .LBB0_994
	v_lshrrev_b32_e32 v2, 5, v0
	v_lshrrev_b32_e32 v4, 1, v0
	v_and_b32_e32 v2, 4, v2
	v_bfe_u32 v3, v0, 2, 2
	v_and_b32_e32 v13, 24, v4
	v_or3_b32 v2, v2, v3, v13
	v_lshlrev_b32_e32 v3, 4, v0
	v_or_b32_e32 v10, 0x2000, v3
	s_add_u32 s20, s58, 0xa900000
	v_lshrrev_b32_e32 v4, 7, v10
	s_movk_i32 s0, 0x60
	v_readlane_b32 s2, v243, 0
	s_addc_u32 s24, s59, 0
	v_and_or_b32 v5, v4, s0, v2
	v_bfe_u32 v14, v0, 2, 4
	s_movk_i32 s0, 0x70
	s_ashr_i32 s26, s2, 31
	v_and_or_b32 v4, v4, s0, v14
	s_lshr_b32 s0, s26, 29
	s_add_i32 s0, s2, s0
	s_lshr_b32 s8, s3, 6
	s_ashr_i32 s1, s0, 3
	s_and_b32 s0, s0, -8
	s_lshr_b32 s9, s3, 8
	s_lshl_b32 s25, s8, 10
	s_sub_i32 s0, s2, s0
	s_cmp_lt_i32 s0, 0
	s_movk_i32 s27, 0x187
	s_cselect_b32 s2, s27, 0x186
	s_mul_i32 s0, s2, s0
	s_add_i32 s0, s0, s1
	s_mul_hi_i32 s1, s0, 0x2aaaaaab
	s_lshr_b32 s2, s1, 31
	s_ashr_i32 s1, s1, 5
	v_and_b32_e32 v6, 32, v0
	s_add_i32 s1, s1, s2
	v_bitop3_b32 v11, v3, v6, 48 bitop3:0x6c
	v_and_b32_e32 v12, 64, v0
	s_lshl_b32 s6, s1, 3
	v_or_b32_e32 v3, v11, v12
	s_sub_i32 s2, 0x82, s6
	s_mulk_i32 s1, 0xc0
	v_lshl_or_b32 v132, v4, 12, v3
	v_lshrrev_b32_e32 v4, 3, v0
	s_min_u32 s7, s2, 8
	s_sub_i32 s10, s0, s1
	v_lshl_or_b32 v130, v5, 12, v3
	v_and_or_b32 v2, v4, 32, v2
	s_sext_i32_i16 s0, s10
	v_cvt_f32_ubyte0_e32 v5, s7
	v_lshl_or_b32 v134, v2, 12, v3
	v_and_or_b32 v2, v4, 48, v14
	v_cvt_f32_i32_e32 v4, s0
	v_rcp_iflag_f32_e32 v6, v5
	v_lshl_or_b32 v136, v2, 12, v3
	s_ashr_i32 s0, s0, 30
	s_or_b32 s2, s0, 1
	v_mul_f32_e32 v2, v4, v6
	v_trunc_f32_e32 v2, v2
	v_fma_f32 v3, -v2, v5, v4
	v_cvt_i32_f32_e32 v2, v2
	v_cmp_ge_f32_e64 s[0:1], |v3|, v5
	s_and_b64 s[0:1], s[0:1], exec
	s_cselect_b32 s0, s2, 0
	v_readfirstlane_b32 s1, v2
	s_add_i32 s2, s1, s0
	s_mul_i32 s0, s2, s7
	s_sub_i32 s0, s10, s0
	s_sext_i32_i16 s0, s0
	s_add_i32 s86, s6, s0
	s_ashr_i32 s87, s86, 31
	s_bfe_i64 s[0:1], s[2:3], 0x100000
	s_lshl_b64 s[6:7], s[86:87], 20
	s_lshl_b64 s[0:1], s[0:1], 20
	s_add_u32 s0, s20, s0
	s_addc_u32 s1, s24, s1
	s_add_i32 s30, s25, 0
	s_add_i32 m0, s30, 0x10000
	v_mov_b32_e32 v135, 0
	global_load_lds_dwordx4 v134, s[0:1]
	s_add_i32 m0, s30, 0x12000
	s_add_u32 s10, s0, 0x80000
	global_load_lds_dwordx4 v130, s[0:1]
	s_addc_u32 s11, s1, 0
	s_add_i32 m0, s30, 0x14000
	v_mov_b32_e32 v131, v135
	global_load_lds_dwordx4 v134, s[10:11]
	s_add_i32 m0, s30, 0x16000
	v_mov_b32_e32 v137, v135
	global_load_lds_dwordx4 v130, s[10:11]
	v_readlane_b32 s10, v242, 15
	v_readlane_b32 s11, v242, 16
	s_add_u32 s22, s10, s6
	s_addc_u32 s23, s11, s7
	s_add_i32 s31, s30, 0x2000
	s_mov_b32 m0, s30
	s_add_u32 s6, s22, 0x80000
	global_load_lds_dwordx4 v136, s[22:23]
	s_mov_b32 m0, s31
	s_addc_u32 s7, s23, 0
	s_add_i32 s33, s30, 0x4000
	global_load_lds_dwordx4 v132, s[22:23]
	s_mov_b32 m0, s33
	s_add_i32 s34, s30, 0x6000
	global_load_lds_dwordx4 v136, s[6:7]
	s_mov_b32 m0, s34
	v_mov_b32_e32 v133, v135
	global_load_lds_dwordx4 v132, s[6:7]
	s_cmp_eq_u32 s9, 1
	s_mov_b32 s35, 0
	v_lshl_add_u64 v[8:9], s[0:1], 0, v[134:135]
	v_lshl_add_u64 v[6:7], s[0:1], 0, v[130:131]
	v_lshl_add_u64 v[2:3], s[22:23], 0, v[136:137]
	s_cselect_b64 s[6:7], -1, 0
	s_cmp_lg_u32 s9, 1
	v_lshl_add_u64 v[4:5], s[22:23], 0, v[132:133]
	s_cbranch_scc1 .LBB0_981
	s_barrier
	s_setprio 1

.LBB0_987:
	ds_read_b128 v[146:149], v153
	ds_read_b128 v[156:159], v153 offset:1024
	ds_read_b128 v[160:163], v153 offset:2048
	ds_read_b128 v[170:173], v153 offset:3072
	ds_read_b128 v[174:177], v154
	ds_read_b128 v[178:181], v154 offset:1024
	ds_read_b128 v[182:185], v154 offset:2048
	ds_read_b128 v[186:189], v154 offset:3072
	s_add_u32 s0, s88, 0xfff80080
	s_addc_u32 s1, s89, -1
	s_cmp_eq_u32 s73, 28
	s_cselect_b32 s23, s15, s1
	s_cselect_b32 s22, s69, s0
	s_cselect_b32 s1, s13, s72
	s_cselect_b32 s0, s70, s71
	v_lshl_add_u64 v[222:223], s[88:89], 0, v[138:139]
	s_add_i32 m0, s30, 0xc000
	ds_read_b128 v[190:193], v155
	ds_read_b128 v[194:197], v155 offset:1024
	ds_read_b128 v[198:201], v155 offset:2048
	ds_read_b128 v[202:205], v155 offset:3072
	ds_read_b128 v[206:209], v155 offset:4096
	ds_read_b128 v[210:213], v155 offset:5120
	ds_read_b128 v[214:217], v155 offset:6144
	ds_read_b128 v[218:221], v155 offset:7168
	global_load_lds_dwordx4 v[222:223], off
	v_lshl_add_u64 v[222:223], s[88:89], 0, v[140:141]
	s_add_i32 m0, s30, 0xe000
	s_nop 0
	global_load_lds_dwordx4 v[222:223], off
	s_waitcnt vmcnt(8)
	s_waitcnt lgkmcnt(0)
	s_barrier
	s_waitcnt lgkmcnt(0)
	v_mfma_f32_16x16x32_bf16 v[126:129], v[146:149], v[190:193], v[126:129]
	v_mfma_f32_16x16x32_bf16 v[122:125], v[160:163], v[190:193], v[122:125]
	v_mfma_f32_16x16x32_bf16 v[110:113], v[146:149], v[198:201], v[110:113]
	v_mfma_f32_16x16x32_bf16 v[106:109], v[160:163], v[198:201], v[106:109]
	v_mfma_f32_16x16x32_bf16 v[94:97], v[146:149], v[206:209], v[94:97]
	v_mfma_f32_16x16x32_bf16 v[90:93], v[160:163], v[206:209], v[90:93]
	v_mfma_f32_16x16x32_bf16 v[78:81], v[146:149], v[214:217], v[78:81]
	v_mfma_f32_16x16x32_bf16 v[74:77], v[160:163], v[214:217], v[74:77]
	v_mfma_f32_16x16x32_bf16 v[126:129], v[156:159], v[194:197], v[126:129]
	v_mfma_f32_16x16x32_bf16 v[122:125], v[170:173], v[194:197], v[122:125]
	v_mfma_f32_16x16x32_bf16 v[110:113], v[156:159], v[202:205], v[110:113]
	v_mfma_f32_16x16x32_bf16 v[106:109], v[170:173], v[202:205], v[106:109]
	v_mfma_f32_16x16x32_bf16 v[94:97], v[156:159], v[210:213], v[94:97]
	v_mfma_f32_16x16x32_bf16 v[90:93], v[170:173], v[210:213], v[90:93]
	v_mfma_f32_16x16x32_bf16 v[78:81], v[156:159], v[218:221], v[78:81]
	v_mfma_f32_16x16x32_bf16 v[74:77], v[170:173], v[218:221], v[74:77]
	v_mfma_f32_16x16x32_bf16 v[118:121], v[174:177], v[190:193], v[118:121]
	v_mfma_f32_16x16x32_bf16 v[114:117], v[182:185], v[190:193], v[114:117]
	v_mfma_f32_16x16x32_bf16 v[102:105], v[174:177], v[198:201], v[102:105]
	v_mfma_f32_16x16x32_bf16 v[98:101], v[182:185], v[198:201], v[98:101]
	v_mfma_f32_16x16x32_bf16 v[86:89], v[174:177], v[206:209], v[86:89]
	v_mfma_f32_16x16x32_bf16 v[82:85], v[182:185], v[206:209], v[82:85]
	v_mfma_f32_16x16x32_bf16 v[70:73], v[174:177], v[214:217], v[70:73]
	v_mfma_f32_16x16x32_bf16 v[66:69], v[182:185], v[214:217], v[66:69]
	v_mfma_f32_16x16x32_bf16 v[118:121], v[178:181], v[194:197], v[118:121]
	v_mfma_f32_16x16x32_bf16 v[114:117], v[186:189], v[194:197], v[114:117]
	v_mfma_f32_16x16x32_bf16 v[102:105], v[178:181], v[202:205], v[102:105]
	v_mfma_f32_16x16x32_bf16 v[98:101], v[186:189], v[202:205], v[98:101]
	v_mfma_f32_16x16x32_bf16 v[86:89], v[178:181], v[210:213], v[86:89]
	v_mfma_f32_16x16x32_bf16 v[82:85], v[186:189], v[210:213], v[82:85]
	v_mfma_f32_16x16x32_bf16 v[70:73], v[178:181], v[218:221], v[70:73]
	v_mfma_f32_16x16x32_bf16 v[66:69], v[186:189], v[218:221], v[66:69]
	s_barrier
	s_add_i32 s21, s92, s25
	v_lshl_add_u64 v[222:223], s[0:1], 0, v[134:135]
	s_mov_b32 m0, s21
	ds_read_b128 v[190:193], v155 offset:16384
	ds_read_b128 v[194:197], v155 offset:17408
	ds_read_b128 v[198:201], v155 offset:18432
	ds_read_b128 v[202:205], v155 offset:19456
	ds_read_b128 v[206:209], v155 offset:20480
	ds_read_b128 v[210:213], v155 offset:21504
	ds_read_b128 v[214:217], v155 offset:22528
	ds_read_b128 v[218:221], v155 offset:23552
	global_load_lds_dwordx4 v[222:223], off
	s_add_i32 m0, s21, 0x2000
	s_add_u32 s28, s0, 0x80000
	v_lshl_add_u64 v[224:225], s[0:1], 0, v[130:131]
	s_addc_u32 s29, s1, 0
	s_add_i32 s21, s93, s25
	global_load_lds_dwordx4 v[224:225], off
	v_lshl_add_u64 v[226:227], s[28:29], 0, v[134:135]
	s_mov_b32 m0, s21
	v_lshl_add_u64 v[228:229], s[22:23], 0, v[132:133]
	global_load_lds_dwordx4 v[226:227], off
	v_lshl_add_u64 v[226:227], s[28:29], 0, v[130:131]
	s_add_i32 m0, s21, 0x2000
	s_nop 0
	global_load_lds_dwordx4 v[226:227], off
	v_lshl_add_u64 v[226:227], s[22:23], 0, v[136:137]
	s_mov_b32 m0, s30
	s_nop 0
	global_load_lds_dwordx4 v[226:227], off
	s_mov_b32 m0, s31
	s_nop 0
	global_load_lds_dwordx4 v[228:229], off
	s_waitcnt vmcnt(8)
	s_waitcnt lgkmcnt(0)
	s_barrier
	s_waitcnt lgkmcnt(0)
	v_mfma_f32_16x16x32_bf16 v[62:65], v[146:149], v[190:193], v[62:65]
	v_mfma_f32_16x16x32_bf16 v[58:61], v[160:163], v[190:193], v[58:61]
	v_mfma_f32_16x16x32_bf16 v[46:49], v[146:149], v[198:201], v[46:49]
	v_mfma_f32_16x16x32_bf16 v[42:45], v[160:163], v[198:201], v[42:45]
	v_mfma_f32_16x16x32_bf16 v[30:33], v[146:149], v[206:209], v[30:33]
	v_mfma_f32_16x16x32_bf16 v[26:29], v[160:163], v[206:209], v[26:29]
	v_mfma_f32_16x16x32_bf16 v[14:17], v[146:149], v[214:217], v[14:17]
	v_mfma_f32_16x16x32_bf16 v[10:13], v[160:163], v[214:217], v[10:13]
	v_mfma_f32_16x16x32_bf16 v[62:65], v[156:159], v[194:197], v[62:65]
	v_mfma_f32_16x16x32_bf16 v[58:61], v[170:173], v[194:197], v[58:61]
	v_mfma_f32_16x16x32_bf16 v[46:49], v[156:159], v[202:205], v[46:49]
	v_mfma_f32_16x16x32_bf16 v[42:45], v[170:173], v[202:205], v[42:45]
	v_mfma_f32_16x16x32_bf16 v[30:33], v[156:159], v[210:213], v[30:33]
	v_mfma_f32_16x16x32_bf16 v[26:29], v[170:173], v[210:213], v[26:29]
	v_mfma_f32_16x16x32_bf16 v[14:17], v[156:159], v[218:221], v[14:17]
	v_mfma_f32_16x16x32_bf16 v[10:13], v[170:173], v[218:221], v[10:13]
	v_mfma_f32_16x16x32_bf16 v[54:57], v[174:177], v[190:193], v[54:57]
	v_mfma_f32_16x16x32_bf16 v[50:53], v[182:185], v[190:193], v[50:53]
	v_mfma_f32_16x16x32_bf16 v[38:41], v[174:177], v[198:201], v[38:41]
	v_mfma_f32_16x16x32_bf16 v[34:37], v[182:185], v[198:201], v[34:37]
	v_mfma_f32_16x16x32_bf16 v[22:25], v[174:177], v[206:209], v[22:25]
	v_mfma_f32_16x16x32_bf16 v[18:21], v[182:185], v[206:209], v[18:21]
	v_mfma_f32_16x16x32_bf16 v[6:9], v[174:177], v[214:217], v[6:9]
	v_mfma_f32_16x16x32_bf16 v[2:5], v[182:185], v[214:217], v[2:5]
	v_mfma_f32_16x16x32_bf16 v[54:57], v[178:181], v[194:197], v[54:57]
	v_mfma_f32_16x16x32_bf16 v[50:53], v[186:189], v[194:197], v[50:53]
	v_mfma_f32_16x16x32_bf16 v[38:41], v[178:181], v[202:205], v[38:41]
	v_mfma_f32_16x16x32_bf16 v[34:37], v[186:189], v[202:205], v[34:37]
	v_mfma_f32_16x16x32_bf16 v[22:25], v[178:181], v[210:213], v[22:25]
	v_mfma_f32_16x16x32_bf16 v[18:21], v[186:189], v[210:213], v[18:21]
	v_mfma_f32_16x16x32_bf16 v[6:9], v[178:181], v[218:221], v[6:9]
	v_mfma_f32_16x16x32_bf16 v[2:5], v[186:189], v[218:221], v[2:5]
	s_barrier
	s_add_i32 s21, 0, 0x18000
	v_add_u32_e32 v165, s21, v151
	s_add_i32 s28, 0, 0x1c000
	ds_read_b128 v[146:149], v165
	ds_read_b128 v[156:159], v165 offset:1024
	ds_read_b128 v[160:163], v165 offset:2048
	ds_read_b128 v[170:173], v165 offset:3072
	v_add_u32_e32 v165, s28, v151
	ds_read_b128 v[174:177], v165
	ds_read_b128 v[178:181], v165 offset:1024
	ds_read_b128 v[182:185], v165 offset:2048
	ds_read_b128 v[186:189], v165 offset:3072
	s_add_u32 s22, s22, 0x80000
	s_addc_u32 s23, s23, 0
	s_mov_b32 m0, s33
	v_lshl_add_u64 v[230:231], s[22:23], 0, v[136:137]
	ds_read_b128 v[190:193], v155 offset:32768
	ds_read_b128 v[194:197], v155 offset:33792
	ds_read_b128 v[198:201], v155 offset:34816
	ds_read_b128 v[202:205], v155 offset:35840
	ds_read_b128 v[206:209], v155 offset:36864
	ds_read_b128 v[210:213], v155 offset:37888
	ds_read_b128 v[214:217], v155 offset:38912
	ds_read_b128 v[218:221], v155 offset:39936
	global_load_lds_dwordx4 v[230:231], off
	v_lshl_add_u64 v[230:231], s[22:23], 0, v[132:133]
	s_mov_b32 m0, s34
	s_nop 0
	global_load_lds_dwordx4 v[230:231], off
	s_waitcnt vmcnt(8)
	s_waitcnt lgkmcnt(0)
	s_barrier
	s_waitcnt lgkmcnt(0)
	v_mfma_f32_16x16x32_bf16 v[126:129], v[146:149], v[190:193], v[126:129]
	v_mfma_f32_16x16x32_bf16 v[122:125], v[160:163], v[190:193], v[122:125]
	v_mfma_f32_16x16x32_bf16 v[110:113], v[146:149], v[198:201], v[110:113]
	v_mfma_f32_16x16x32_bf16 v[106:109], v[160:163], v[198:201], v[106:109]
	v_mfma_f32_16x16x32_bf16 v[94:97], v[146:149], v[206:209], v[94:97]
	v_mfma_f32_16x16x32_bf16 v[90:93], v[160:163], v[206:209], v[90:93]
	v_mfma_f32_16x16x32_bf16 v[78:81], v[146:149], v[214:217], v[78:81]
	v_mfma_f32_16x16x32_bf16 v[74:77], v[160:163], v[214:217], v[74:77]
	v_mfma_f32_16x16x32_bf16 v[126:129], v[156:159], v[194:197], v[126:129]
	v_mfma_f32_16x16x32_bf16 v[122:125], v[170:173], v[194:197], v[122:125]
	v_mfma_f32_16x16x32_bf16 v[110:113], v[156:159], v[202:205], v[110:113]
	v_mfma_f32_16x16x32_bf16 v[106:109], v[170:173], v[202:205], v[106:109]
	v_mfma_f32_16x16x32_bf16 v[94:97], v[156:159], v[210:213], v[94:97]
	v_mfma_f32_16x16x32_bf16 v[90:93], v[170:173], v[210:213], v[90:93]
	v_mfma_f32_16x16x32_bf16 v[78:81], v[156:159], v[218:221], v[78:81]
	v_mfma_f32_16x16x32_bf16 v[74:77], v[170:173], v[218:221], v[74:77]
	v_mfma_f32_16x16x32_bf16 v[118:121], v[174:177], v[190:193], v[118:121]
	v_mfma_f32_16x16x32_bf16 v[114:117], v[182:185], v[190:193], v[114:117]
	v_mfma_f32_16x16x32_bf16 v[102:105], v[174:177], v[198:201], v[102:105]
	v_mfma_f32_16x16x32_bf16 v[98:101], v[182:185], v[198:201], v[98:101]
	v_mfma_f32_16x16x32_bf16 v[86:89], v[174:177], v[206:209], v[86:89]
	v_mfma_f32_16x16x32_bf16 v[82:85], v[182:185], v[206:209], v[82:85]
	v_mfma_f32_16x16x32_bf16 v[70:73], v[174:177], v[214:217], v[70:73]
	v_mfma_f32_16x16x32_bf16 v[66:69], v[182:185], v[214:217], v[66:69]
	v_mfma_f32_16x16x32_bf16 v[118:121], v[178:181], v[194:197], v[118:121]
	v_mfma_f32_16x16x32_bf16 v[114:117], v[186:189], v[194:197], v[114:117]
	v_mfma_f32_16x16x32_bf16 v[102:105], v[178:181], v[202:205], v[102:105]
	v_mfma_f32_16x16x32_bf16 v[98:101], v[186:189], v[202:205], v[98:101]
	v_mfma_f32_16x16x32_bf16 v[86:89], v[178:181], v[210:213], v[86:89]
	v_mfma_f32_16x16x32_bf16 v[82:85], v[186:189], v[210:213], v[82:85]
	v_mfma_f32_16x16x32_bf16 v[70:73], v[178:181], v[218:221], v[70:73]
	v_mfma_f32_16x16x32_bf16 v[66:69], v[186:189], v[218:221], v[66:69]
	s_barrier
	s_add_i32 s21, s21, s25
	v_lshl_add_u64 v[222:223], v[222:223], 0, s[8:9]
	s_mov_b32 m0, s21
	ds_read_b128 v[190:193], v155 offset:49152
	ds_read_b128 v[194:197], v155 offset:50176
	ds_read_b128 v[198:201], v155 offset:51200
	ds_read_b128 v[202:205], v155 offset:52224
	ds_read_b128 v[206:209], v155 offset:53248
	ds_read_b128 v[210:213], v155 offset:54272
	ds_read_b128 v[214:217], v155 offset:55296
	ds_read_b128 v[218:221], v155 offset:56320
	global_load_lds_dwordx4 v[222:223], off
	s_add_i32 m0, s21, 0x2000
	s_add_u32 s0, s0, 0x80080
	v_lshl_add_u64 v[222:223], v[224:225], 0, s[8:9]
	s_addc_u32 s1, s1, 0
	s_add_i32 s21, s28, s25
	global_load_lds_dwordx4 v[222:223], off
	v_lshl_add_u64 v[222:223], s[0:1], 0, v[134:135]
	s_mov_b32 m0, s21
	s_nop 0
	global_load_lds_dwordx4 v[222:223], off
	v_lshl_add_u64 v[222:223], s[0:1], 0, v[130:131]
	s_add_i32 m0, s21, 0x2000
	s_nop 0
	global_load_lds_dwordx4 v[222:223], off
	v_lshl_add_u64 v[222:223], v[226:227], 0, s[8:9]
	s_mov_b32 m0, s87
	s_nop 0
	global_load_lds_dwordx4 v[222:223], off
	v_lshl_add_u64 v[222:223], v[228:229], 0, s[8:9]
	s_mov_b32 m0, s90
	s_nop 0
	global_load_lds_dwordx4 v[222:223], off
	s_waitcnt vmcnt(8)
	s_waitcnt lgkmcnt(0)
	s_barrier
	s_waitcnt lgkmcnt(0)
	v_mfma_f32_16x16x32_bf16 v[62:65], v[146:149], v[190:193], v[62:65]
	v_mfma_f32_16x16x32_bf16 v[58:61], v[160:163], v[190:193], v[58:61]
	v_mfma_f32_16x16x32_bf16 v[46:49], v[146:149], v[198:201], v[46:49]
	v_mfma_f32_16x16x32_bf16 v[42:45], v[160:163], v[198:201], v[42:45]
	v_mfma_f32_16x16x32_bf16 v[30:33], v[146:149], v[206:209], v[30:33]
	v_mfma_f32_16x16x32_bf16 v[26:29], v[160:163], v[206:209], v[26:29]
	v_mfma_f32_16x16x32_bf16 v[14:17], v[146:149], v[214:217], v[14:17]
	v_mfma_f32_16x16x32_bf16 v[10:13], v[160:163], v[214:217], v[10:13]
	v_mfma_f32_16x16x32_bf16 v[62:65], v[156:159], v[194:197], v[62:65]
	v_mfma_f32_16x16x32_bf16 v[58:61], v[170:173], v[194:197], v[58:61]
	v_mfma_f32_16x16x32_bf16 v[46:49], v[156:159], v[202:205], v[46:49]
	v_mfma_f32_16x16x32_bf16 v[42:45], v[170:173], v[202:205], v[42:45]
	v_mfma_f32_16x16x32_bf16 v[30:33], v[156:159], v[210:213], v[30:33]
	v_mfma_f32_16x16x32_bf16 v[26:29], v[170:173], v[210:213], v[26:29]
	v_mfma_f32_16x16x32_bf16 v[14:17], v[156:159], v[218:221], v[14:17]
	v_mfma_f32_16x16x32_bf16 v[10:13], v[170:173], v[218:221], v[10:13]
	v_mfma_f32_16x16x32_bf16 v[54:57], v[174:177], v[190:193], v[54:57]
	v_mfma_f32_16x16x32_bf16 v[50:53], v[182:185], v[190:193], v[50:53]
	v_mfma_f32_16x16x32_bf16 v[38:41], v[174:177], v[198:201], v[38:41]
	v_mfma_f32_16x16x32_bf16 v[34:37], v[182:185], v[198:201], v[34:37]
	v_mfma_f32_16x16x32_bf16 v[22:25], v[174:177], v[206:209], v[22:25]
	v_mfma_f32_16x16x32_bf16 v[18:21], v[182:185], v[206:209], v[18:21]
	v_mfma_f32_16x16x32_bf16 v[6:9], v[174:177], v[214:217], v[6:9]
	v_mfma_f32_16x16x32_bf16 v[2:5], v[182:185], v[214:217], v[2:5]
	v_mfma_f32_16x16x32_bf16 v[54:57], v[178:181], v[194:197], v[54:57]
	v_mfma_f32_16x16x32_bf16 v[50:53], v[186:189], v[194:197], v[50:53]
	v_mfma_f32_16x16x32_bf16 v[38:41], v[178:181], v[202:205], v[38:41]
	v_mfma_f32_16x16x32_bf16 v[34:37], v[186:189], v[202:205], v[34:37]
	v_mfma_f32_16x16x32_bf16 v[22:25], v[178:181], v[210:213], v[22:25]
	v_mfma_f32_16x16x32_bf16 v[18:21], v[186:189], v[210:213], v[18:21]
	v_mfma_f32_16x16x32_bf16 v[6:9], v[178:181], v[218:221], v[6:9]
	v_mfma_f32_16x16x32_bf16 v[2:5], v[186:189], v[218:221], v[2:5]
	s_barrier
	s_add_i32 s73, s73, 2
	s_add_u32 s88, s88, 0x100
	s_addc_u32 s89, s89, 0
	s_add_u32 s71, s71, 0x100
	s_addc_u32 s72, s72, 0
	s_cmp_gt_u32 s73, 29
	s_cbranch_scc0 .LBB0_987
	s_and_b64 vcc, exec, s[10:11]
	s_cbranch_vccz .LBB0_990
	s_barrier

.LBB0_1048:
	s_setprio 0
	v_readlane_b32 s2, v243, 51
	s_cmp_lt_i32 s2, 13
	s_cselect_b64 s[6:7], -1, 0
	s_and_b64 s[0:1], s[6:7], s[0:1]
	s_andn2_b64 vcc, exec, s[0:1]
	v_readlane_b32 s3, v243, 52
	s_cbranch_vccnz .LBB0_1103
	v_readlane_b32 s2, v243, 0
	s_cmpk_lt_i32 s2, 0x410
	s_cselect_b64 s[0:1], -1, 0
	s_cmpk_gt_i32 s2, 0x40f
	v_readfirstlane_b32 s4, v0
	s_cbranch_scc1 .LBB0_1051
	v_readlane_b32 s5, v243, 0
	s_ashr_i32 s2, s5, 31
	s_lshr_b32 s2, s2, 29
	s_add_i32 s2, s5, s2
	s_ashr_i32 s3, s2, 3
	s_and_b32 s2, s2, -8
	s_sub_i32 s2, s5, s2
	s_cmp_lt_i32 s2, 0
	s_movk_i32 s5, 0x83
	s_cselect_b32 s5, s5, 0x82
	s_mul_i32 s2, s5, s2
	s_add_i32 s2, s2, s3
	s_ashr_i32 s3, s2, 31
	s_lshr_b32 s3, s3, 26
	s_add_i32 s3, s2, s3
	s_ashr_i32 s3, s3, 6
	s_lshl_b32 s5, s3, 3
	s_sub_i32 s8, 0x82, s5
	s_lshl_b32 s3, s3, 6
	s_min_u32 s8, s8, 8
	s_sub_i32 s9, s2, s3
	s_sext_i32_i8 s2, s9
	v_cvt_f32_ubyte0_e32 v3, s8
	v_cvt_f32_i32_e32 v2, s2
	v_rcp_iflag_f32_e32 v4, v3
	s_ashr_i32 s2, s2, 30
	s_or_b32 s10, s2, 1
	v_mul_f32_e32 v4, v2, v4
	v_trunc_f32_e32 v4, v4
	v_fma_f32 v2, -v4, v3, v2
	v_cvt_i32_f32_e32 v4, v4
	v_cmp_ge_f32_e64 s[2:3], |v2|, v3
	s_and_b64 s[2:3], s[2:3], exec
	s_cselect_b32 s2, s10, 0
	v_readfirstlane_b32 s3, v4
	s_add_i32 s2, s3, s2
	s_sext_i32_i8 s88, s2
	s_mul_i32 s2, s2, s8
	s_sub_i32 s2, s9, s2
	s_sext_i32_i8 s2, s2
	s_add_i32 s84, s5, s2
.LBB0_1051:
	s_andn2_b64 vcc, exec, s[0:1]
	s_cbranch_vccnz .LBB0_1103
	v_lshlrev_b32_e32 v2, 4, v0
	v_and_b32_e32 v3, 32, v0
	v_bitop3_b32 v10, v2, v3, 48 bitop3:0x6c
	v_lshrrev_b32_e32 v3, 1, v0
	v_and_b32_e32 v12, 24, v3
	v_lshrrev_b32_e32 v3, 5, v0
	v_and_b32_e32 v3, 4, v3
	v_bfe_u32 v5, v0, 2, 2
	v_readlane_b32 s8, v243, 63
	v_bfe_u32 v4, v0, 2, 4
	v_and_b32_e32 v11, 64, v0
	v_or3_b32 v3, v3, v5, v12
	v_lshrrev_b32_e32 v5, 3, v0
	v_readlane_b32 s20, v242, 11
	v_readlane_b32 s22, v242, 13
	v_or_b32_e32 v2, v10, v11
	v_and_or_b32 v6, v5, 48, v4
	v_and_or_b32 v5, v5, 32, v3
	v_readlane_b32 s10, v242, 1
	v_readlane_b32 s23, v242, 14
	s_add_u32 s20, s22, 0xc100000
	v_lshl_or_b32 v172, v5, 11, v2
	v_bfe_u32 v5, v0, 3, 25
	s_addc_u32 s24, s23, 0
	v_or_b32_e32 v5, 64, v5
	s_movk_i32 s0, 0x70
	s_lshr_b32 s10, s4, 6
	s_lshr_b32 s5, s4, 8
	v_and_or_b32 v4, v5, s0, v4
	s_movk_i32 s0, 0x60
	s_lshl_b32 s25, s10, 10
	s_mul_i32 s1, s84, 0x300000
	v_readlane_b32 s2, v242, 17
	v_and_or_b32 v3, v5, s0, v3
	s_mul_hi_i32 s0, s84, 0x300000
	v_readlane_b32 s3, v242, 18
	s_add_u32 s2, s2, s1
	s_addc_u32 s3, s3, s0
	s_ashr_i32 s89, s88, 31
	s_lshl_b64 s[0:1], s[88:89], 19
	s_add_u32 s0, s20, s0
	s_addc_u32 s1, s24, s1
	s_add_i32 s26, s25, 0
	s_add_i32 m0, s26, 0x10000
	v_readlane_b32 s9, v242, 0
	global_load_lds_dwordx4 v172, s[0:1]
	s_add_i32 m0, s26, 0x12000
	v_lshl_or_b32 v176, v3, 11, v2
	s_add_u32 s8, s0, 0x40000
	v_mul_u32_u24_e32 v13, 0x3000, v6
	v_mov_b32_e32 v173, 0
	global_load_lds_dwordx4 v176, s[0:1]
	s_addc_u32 s9, s1, 0
	s_add_i32 m0, s26, 0x14000
	v_or_b32_e32 v170, v2, v13
	v_mul_u32_u24_e32 v14, 0x3000, v4
	global_load_lds_dwordx4 v172, s[8:9]
	s_add_i32 m0, s26, 0x16000
	v_mov_b32_e32 v171, v173
	v_or_b32_e32 v174, v14, v2
	global_load_lds_dwordx4 v176, s[8:9]
	v_lshl_add_u64 v[2:3], s[2:3], 0, v[170:171]
	s_mov_b64 s[8:9], 0x800
	v_lshl_add_u64 v[4:5], v[2:3], 0, s[8:9]
	s_mov_b32 m0, s26
	v_mov_b32_e32 v175, v173
	global_load_lds_dwordx4 v[4:5], off
	v_lshl_add_u64 v[4:5], s[2:3], 0, v[174:175]
	s_add_i32 s27, s26, 0x2000
	v_lshl_add_u64 v[6:7], v[4:5], 0, s[8:9]
	s_add_u32 s8, s2, 0x180800
	s_mov_b32 m0, s27
	s_addc_u32 s9, s3, 0
	s_add_i32 s30, s26, 0x4000
	global_load_lds_dwordx4 v[6:7], off
	s_mov_b32 m0, s30
	s_add_i32 s31, s26, 0x6000
	global_load_lds_dwordx4 v170, s[8:9]
	s_mov_b32 m0, s31
	v_mov_b32_e32 v177, v173
	global_load_lds_dwordx4 v174, s[8:9]
	s_cmp_eq_u32 s5, 1
	s_movk_i32 s33, 0x3000
	s_mov_b32 s68, 0
	v_lshl_add_u64 v[6:7], s[0:1], 0, v[172:173]
	s_cselect_b64 s[8:9], -1, 0
	s_cmp_lg_u32 s5, 1
	v_lshl_add_u64 v[8:9], s[0:1], 0, v[176:177]
	v_readlane_b32 s11, v242, 2
	v_readlane_b32 s12, v242, 3
	v_readlane_b32 s13, v242, 4
	v_readlane_b32 s14, v242, 5
	v_readlane_b32 s15, v242, 6
	v_readlane_b32 s16, v242, 7
	v_readlane_b32 s17, v242, 8
	v_readlane_b32 s18, v242, 9
	v_readlane_b32 s19, v242, 10
	v_readlane_b32 s21, v242, 12
	s_cbranch_scc1 .LBB0_1054
	s_barrier
	s_setprio 1

.LBB0_1062:
	ds_read_b128 v[130:133], v201
	ds_read_b128 v[134:137], v201 offset:1024
	ds_read_b128 v[138:141], v201 offset:2048
	ds_read_b128 v[142:145], v201 offset:3072
	ds_read_b128 v[146:149], v202
	ds_read_b128 v[150:153], v202 offset:1024
	ds_read_b128 v[154:157], v202 offset:2048
	ds_read_b128 v[158:161], v202 offset:3072
	s_add_u32 s0, s4, 0xffe80080
	s_addc_u32 s1, s5, -1
	s_cmp_eq_u32 s71, 12
	s_cselect_b32 s23, s19, s1
	s_cselect_b32 s22, s18, s0
	s_cselect_b32 s1, s15, s70
	s_cselect_b32 s0, s17, s69
	v_lshl_add_u64 v[162:163], s[4:5], 0, v[178:179]
	s_add_i32 m0, s26, 0xc000
	ds_read_b128 v[186:189], v203
	ds_read_b128 v[190:193], v203 offset:1024
	ds_read_b128 v[194:197], v203 offset:2048
	ds_read_b128 v[204:207], v203 offset:3072
	ds_read_b128 v[208:211], v203 offset:4096
	ds_read_b128 v[212:215], v203 offset:5120
	ds_read_b128 v[216:219], v203 offset:6144
	ds_read_b128 v[220:223], v203 offset:7168
	global_load_lds_dwordx4 v[162:163], off
	v_lshl_add_u64 v[162:163], s[4:5], 0, v[180:181]
	s_add_i32 m0, s26, 0xe000
	s_nop 0
	global_load_lds_dwordx4 v[162:163], off
	s_waitcnt vmcnt(8)
	s_waitcnt lgkmcnt(0)
	s_barrier
	s_waitcnt lgkmcnt(0)
	v_mfma_f32_16x16x32_bf16 v[126:129], v[130:133], v[186:189], v[126:129]
	v_mfma_f32_16x16x32_bf16 v[122:125], v[138:141], v[186:189], v[122:125]
	v_mfma_f32_16x16x32_bf16 v[118:121], v[130:133], v[194:197], v[118:121]
	v_mfma_f32_16x16x32_bf16 v[114:117], v[138:141], v[194:197], v[114:117]
	v_mfma_f32_16x16x32_bf16 v[94:97], v[130:133], v[208:211], v[94:97]
	v_mfma_f32_16x16x32_bf16 v[90:93], v[138:141], v[208:211], v[90:93]
	v_mfma_f32_16x16x32_bf16 v[86:89], v[130:133], v[216:219], v[86:89]
	v_mfma_f32_16x16x32_bf16 v[82:85], v[138:141], v[216:219], v[82:85]
	v_mfma_f32_16x16x32_bf16 v[126:129], v[134:137], v[190:193], v[126:129]
	v_mfma_f32_16x16x32_bf16 v[122:125], v[142:145], v[190:193], v[122:125]
	v_mfma_f32_16x16x32_bf16 v[118:121], v[134:137], v[204:207], v[118:121]
	v_mfma_f32_16x16x32_bf16 v[114:117], v[142:145], v[204:207], v[114:117]
	v_mfma_f32_16x16x32_bf16 v[94:97], v[134:137], v[212:215], v[94:97]
	v_mfma_f32_16x16x32_bf16 v[90:93], v[142:145], v[212:215], v[90:93]
	v_mfma_f32_16x16x32_bf16 v[86:89], v[134:137], v[220:223], v[86:89]
	v_mfma_f32_16x16x32_bf16 v[82:85], v[142:145], v[220:223], v[82:85]
	v_mfma_f32_16x16x32_bf16 v[110:113], v[146:149], v[186:189], v[110:113]
	v_mfma_f32_16x16x32_bf16 v[106:109], v[154:157], v[186:189], v[106:109]
	v_mfma_f32_16x16x32_bf16 v[102:105], v[146:149], v[194:197], v[102:105]
	v_mfma_f32_16x16x32_bf16 v[98:101], v[154:157], v[194:197], v[98:101]
	v_mfma_f32_16x16x32_bf16 v[78:81], v[146:149], v[208:211], v[78:81]
	v_mfma_f32_16x16x32_bf16 v[74:77], v[154:157], v[208:211], v[74:77]
	v_mfma_f32_16x16x32_bf16 v[70:73], v[146:149], v[216:219], v[70:73]
	v_mfma_f32_16x16x32_bf16 v[66:69], v[154:157], v[216:219], v[66:69]
	v_mfma_f32_16x16x32_bf16 v[110:113], v[150:153], v[190:193], v[110:113]
	v_mfma_f32_16x16x32_bf16 v[106:109], v[158:161], v[190:193], v[106:109]
	v_mfma_f32_16x16x32_bf16 v[102:105], v[150:153], v[204:207], v[102:105]
	v_mfma_f32_16x16x32_bf16 v[98:101], v[158:161], v[204:207], v[98:101]
	v_mfma_f32_16x16x32_bf16 v[78:81], v[150:153], v[212:215], v[78:81]
	v_mfma_f32_16x16x32_bf16 v[74:77], v[158:161], v[212:215], v[74:77]
	v_mfma_f32_16x16x32_bf16 v[70:73], v[150:153], v[220:223], v[70:73]
	v_mfma_f32_16x16x32_bf16 v[66:69], v[158:161], v[220:223], v[66:69]
	s_barrier
	s_add_i32 s21, s90, s25
	v_lshl_add_u64 v[162:163], s[0:1], 0, v[172:173]
	s_mov_b32 m0, s21
	ds_read_b128 v[186:189], v203 offset:16384
	ds_read_b128 v[190:193], v203 offset:17408
	ds_read_b128 v[194:197], v203 offset:18432
	ds_read_b128 v[204:207], v203 offset:19456
	ds_read_b128 v[208:211], v203 offset:20480
	ds_read_b128 v[212:215], v203 offset:21504
	ds_read_b128 v[216:219], v203 offset:22528
	ds_read_b128 v[220:223], v203 offset:23552
	global_load_lds_dwordx4 v[162:163], off
	s_add_i32 m0, s21, 0x2000
	s_add_u32 s28, s0, 0x40000
	v_lshl_add_u64 v[198:199], s[0:1], 0, v[176:177]
	s_addc_u32 s29, s1, 0
	s_add_i32 s21, s91, s25
	global_load_lds_dwordx4 v[198:199], off
	v_lshl_add_u64 v[224:225], s[28:29], 0, v[172:173]
	s_mov_b32 m0, s21
	v_lshl_add_u64 v[226:227], s[22:23], 0, v[174:175]
	global_load_lds_dwordx4 v[224:225], off
	v_lshl_add_u64 v[224:225], s[28:29], 0, v[176:177]
	s_add_i32 m0, s21, 0x2000
	s_nop 0
	global_load_lds_dwordx4 v[224:225], off
	v_lshl_add_u64 v[224:225], s[22:23], 0, v[170:171]
	s_mov_b32 m0, s26
	s_nop 0
	global_load_lds_dwordx4 v[224:225], off
	s_mov_b32 m0, s27
	s_nop 0
	global_load_lds_dwordx4 v[226:227], off
	s_waitcnt vmcnt(8)
	s_waitcnt lgkmcnt(0)
	s_barrier
	s_waitcnt lgkmcnt(0)
	v_mfma_f32_16x16x32_bf16 v[62:65], v[130:133], v[186:189], v[62:65]
	v_mfma_f32_16x16x32_bf16 v[58:61], v[138:141], v[186:189], v[58:61]
	v_mfma_f32_16x16x32_bf16 v[54:57], v[130:133], v[194:197], v[54:57]
	v_mfma_f32_16x16x32_bf16 v[50:53], v[138:141], v[194:197], v[50:53]
	v_mfma_f32_16x16x32_bf16 v[30:33], v[130:133], v[208:211], v[30:33]
	v_mfma_f32_16x16x32_bf16 v[26:29], v[138:141], v[208:211], v[26:29]
	v_mfma_f32_16x16x32_bf16 v[18:21], v[130:133], v[216:219], v[18:21]
	v_mfma_f32_16x16x32_bf16 v[10:13], v[138:141], v[216:219], v[10:13]
	v_mfma_f32_16x16x32_bf16 v[62:65], v[134:137], v[190:193], v[62:65]
	v_mfma_f32_16x16x32_bf16 v[58:61], v[142:145], v[190:193], v[58:61]
	v_mfma_f32_16x16x32_bf16 v[54:57], v[134:137], v[204:207], v[54:57]
	v_mfma_f32_16x16x32_bf16 v[50:53], v[142:145], v[204:207], v[50:53]
	v_mfma_f32_16x16x32_bf16 v[30:33], v[134:137], v[212:215], v[30:33]
	v_mfma_f32_16x16x32_bf16 v[26:29], v[142:145], v[212:215], v[26:29]
	v_mfma_f32_16x16x32_bf16 v[18:21], v[134:137], v[220:223], v[18:21]
	v_mfma_f32_16x16x32_bf16 v[10:13], v[142:145], v[220:223], v[10:13]
	v_mfma_f32_16x16x32_bf16 v[46:49], v[146:149], v[186:189], v[46:49]
	v_mfma_f32_16x16x32_bf16 v[42:45], v[154:157], v[186:189], v[42:45]
	v_mfma_f32_16x16x32_bf16 v[38:41], v[146:149], v[194:197], v[38:41]
	v_mfma_f32_16x16x32_bf16 v[34:37], v[154:157], v[194:197], v[34:37]
	v_mfma_f32_16x16x32_bf16 v[22:25], v[146:149], v[208:211], v[22:25]
	v_mfma_f32_16x16x32_bf16 v[14:17], v[154:157], v[208:211], v[14:17]
	v_mfma_f32_16x16x32_bf16 v[6:9], v[146:149], v[216:219], v[6:9]
	v_mfma_f32_16x16x32_bf16 v[2:5], v[154:157], v[216:219], v[2:5]
	v_mfma_f32_16x16x32_bf16 v[46:49], v[150:153], v[190:193], v[46:49]
	v_mfma_f32_16x16x32_bf16 v[42:45], v[158:161], v[190:193], v[42:45]
	v_mfma_f32_16x16x32_bf16 v[38:41], v[150:153], v[204:207], v[38:41]
	v_mfma_f32_16x16x32_bf16 v[34:37], v[158:161], v[204:207], v[34:37]
	v_mfma_f32_16x16x32_bf16 v[22:25], v[150:153], v[212:215], v[22:25]
	v_mfma_f32_16x16x32_bf16 v[14:17], v[158:161], v[212:215], v[14:17]
	v_mfma_f32_16x16x32_bf16 v[6:9], v[150:153], v[220:223], v[6:9]
	v_mfma_f32_16x16x32_bf16 v[2:5], v[158:161], v[220:223], v[2:5]
	s_barrier
	s_add_i32 s21, 0, 0x18000
	s_add_i32 s28, 0, 0x1c000
	v_add_u32_e32 v142, s21, v169
	v_add_u32_e32 v158, s28, v169
	ds_read_b128 v[130:133], v142
	ds_read_b128 v[134:137], v142 offset:1024
	ds_read_b128 v[138:141], v142 offset:2048
	ds_read_b128 v[142:145], v142 offset:3072
	ds_read_b128 v[146:149], v158
	ds_read_b128 v[150:153], v158 offset:1024
	ds_read_b128 v[154:157], v158 offset:2048
	ds_read_b128 v[158:161], v158 offset:3072
	s_add_u32 s22, s22, 0x180000
	s_addc_u32 s23, s23, 0
	s_mov_b32 m0, s30
	v_lshl_add_u64 v[228:229], s[22:23], 0, v[170:171]
	ds_read_b128 v[186:189], v203 offset:32768
	ds_read_b128 v[190:193], v203 offset:33792
	ds_read_b128 v[194:197], v203 offset:34816
	ds_read_b128 v[204:207], v203 offset:35840
	ds_read_b128 v[208:211], v203 offset:36864
	ds_read_b128 v[212:215], v203 offset:37888
	ds_read_b128 v[216:219], v203 offset:38912
	ds_read_b128 v[220:223], v203 offset:39936
	global_load_lds_dwordx4 v[228:229], off
	v_lshl_add_u64 v[228:229], s[22:23], 0, v[174:175]
	s_mov_b32 m0, s31
	s_nop 0
	global_load_lds_dwordx4 v[228:229], off
	s_waitcnt vmcnt(8)
	s_waitcnt lgkmcnt(0)
	s_barrier
	s_waitcnt lgkmcnt(0)
	v_mfma_f32_16x16x32_bf16 v[126:129], v[130:133], v[186:189], v[126:129]
	v_mfma_f32_16x16x32_bf16 v[122:125], v[138:141], v[186:189], v[122:125]
	v_mfma_f32_16x16x32_bf16 v[118:121], v[130:133], v[194:197], v[118:121]
	v_mfma_f32_16x16x32_bf16 v[114:117], v[138:141], v[194:197], v[114:117]
	v_mfma_f32_16x16x32_bf16 v[94:97], v[130:133], v[208:211], v[94:97]
	v_mfma_f32_16x16x32_bf16 v[90:93], v[138:141], v[208:211], v[90:93]
	v_mfma_f32_16x16x32_bf16 v[86:89], v[130:133], v[216:219], v[86:89]
	v_mfma_f32_16x16x32_bf16 v[82:85], v[138:141], v[216:219], v[82:85]
	v_mfma_f32_16x16x32_bf16 v[126:129], v[134:137], v[190:193], v[126:129]
	v_mfma_f32_16x16x32_bf16 v[122:125], v[142:145], v[190:193], v[122:125]
	v_mfma_f32_16x16x32_bf16 v[118:121], v[134:137], v[204:207], v[118:121]
	v_mfma_f32_16x16x32_bf16 v[114:117], v[142:145], v[204:207], v[114:117]
	v_mfma_f32_16x16x32_bf16 v[94:97], v[134:137], v[212:215], v[94:97]
	v_mfma_f32_16x16x32_bf16 v[90:93], v[142:145], v[212:215], v[90:93]
	v_mfma_f32_16x16x32_bf16 v[86:89], v[134:137], v[220:223], v[86:89]
	v_mfma_f32_16x16x32_bf16 v[82:85], v[142:145], v[220:223], v[82:85]
	v_mfma_f32_16x16x32_bf16 v[110:113], v[146:149], v[186:189], v[110:113]
	v_mfma_f32_16x16x32_bf16 v[106:109], v[154:157], v[186:189], v[106:109]
	v_mfma_f32_16x16x32_bf16 v[102:105], v[146:149], v[194:197], v[102:105]
	v_mfma_f32_16x16x32_bf16 v[98:101], v[154:157], v[194:197], v[98:101]
	v_mfma_f32_16x16x32_bf16 v[78:81], v[146:149], v[208:211], v[78:81]
	v_mfma_f32_16x16x32_bf16 v[74:77], v[154:157], v[208:211], v[74:77]
	v_mfma_f32_16x16x32_bf16 v[70:73], v[146:149], v[216:219], v[70:73]
	v_mfma_f32_16x16x32_bf16 v[66:69], v[154:157], v[216:219], v[66:69]
	v_mfma_f32_16x16x32_bf16 v[110:113], v[150:153], v[190:193], v[110:113]
	v_mfma_f32_16x16x32_bf16 v[106:109], v[158:161], v[190:193], v[106:109]
	v_mfma_f32_16x16x32_bf16 v[102:105], v[150:153], v[204:207], v[102:105]
	v_mfma_f32_16x16x32_bf16 v[98:101], v[158:161], v[204:207], v[98:101]
	v_mfma_f32_16x16x32_bf16 v[78:81], v[150:153], v[212:215], v[78:81]
	v_mfma_f32_16x16x32_bf16 v[74:77], v[158:161], v[212:215], v[74:77]
	v_mfma_f32_16x16x32_bf16 v[70:73], v[150:153], v[220:223], v[70:73]
	v_mfma_f32_16x16x32_bf16 v[66:69], v[158:161], v[220:223], v[66:69]
	s_barrier
	s_add_i32 s21, s21, s25
	v_lshl_add_u64 v[162:163], v[162:163], 0, s[10:11]
	s_mov_b32 m0, s21
	ds_read_b128 v[186:189], v203 offset:49152
	ds_read_b128 v[190:193], v203 offset:50176
	ds_read_b128 v[194:197], v203 offset:51200
	ds_read_b128 v[204:207], v203 offset:52224
	ds_read_b128 v[208:211], v203 offset:53248
	ds_read_b128 v[212:215], v203 offset:54272
	ds_read_b128 v[216:219], v203 offset:55296
	ds_read_b128 v[220:223], v203 offset:56320
	global_load_lds_dwordx4 v[162:163], off
	s_add_i32 m0, s21, 0x2000
	s_add_u32 s0, s0, 0x40080
	v_lshl_add_u64 v[162:163], v[198:199], 0, s[10:11]
	s_addc_u32 s1, s1, 0
	s_add_i32 s21, s28, s25
	global_load_lds_dwordx4 v[162:163], off
	v_lshl_add_u64 v[162:163], s[0:1], 0, v[172:173]
	s_mov_b32 m0, s21
	s_nop 0
	global_load_lds_dwordx4 v[162:163], off
	v_lshl_add_u64 v[162:163], s[0:1], 0, v[176:177]
	s_add_i32 m0, s21, 0x2000
	s_nop 0
	global_load_lds_dwordx4 v[162:163], off
	v_lshl_add_u64 v[162:163], v[224:225], 0, s[10:11]
	s_mov_b32 m0, s34
	s_nop 0
	global_load_lds_dwordx4 v[162:163], off
	v_lshl_add_u64 v[162:163], v[226:227], 0, s[10:11]
	s_mov_b32 m0, s35
	s_nop 0
	global_load_lds_dwordx4 v[162:163], off
	s_waitcnt vmcnt(8)
	s_waitcnt lgkmcnt(0)
	s_barrier
	s_waitcnt lgkmcnt(0)
	v_mfma_f32_16x16x32_bf16 v[62:65], v[130:133], v[186:189], v[62:65]
	v_mfma_f32_16x16x32_bf16 v[58:61], v[138:141], v[186:189], v[58:61]
	v_mfma_f32_16x16x32_bf16 v[54:57], v[130:133], v[194:197], v[54:57]
	v_mfma_f32_16x16x32_bf16 v[50:53], v[138:141], v[194:197], v[50:53]
	v_mfma_f32_16x16x32_bf16 v[30:33], v[130:133], v[208:211], v[30:33]
	v_mfma_f32_16x16x32_bf16 v[26:29], v[138:141], v[208:211], v[26:29]
	v_mfma_f32_16x16x32_bf16 v[18:21], v[130:133], v[216:219], v[18:21]
	v_mfma_f32_16x16x32_bf16 v[10:13], v[138:141], v[216:219], v[10:13]
	v_mfma_f32_16x16x32_bf16 v[62:65], v[134:137], v[190:193], v[62:65]
	v_mfma_f32_16x16x32_bf16 v[58:61], v[142:145], v[190:193], v[58:61]
	v_mfma_f32_16x16x32_bf16 v[54:57], v[134:137], v[204:207], v[54:57]
	v_mfma_f32_16x16x32_bf16 v[50:53], v[142:145], v[204:207], v[50:53]
	v_mfma_f32_16x16x32_bf16 v[30:33], v[134:137], v[212:215], v[30:33]
	v_mfma_f32_16x16x32_bf16 v[26:29], v[142:145], v[212:215], v[26:29]
	v_mfma_f32_16x16x32_bf16 v[18:21], v[134:137], v[220:223], v[18:21]
	v_mfma_f32_16x16x32_bf16 v[10:13], v[142:145], v[220:223], v[10:13]
	v_mfma_f32_16x16x32_bf16 v[46:49], v[146:149], v[186:189], v[46:49]
	v_mfma_f32_16x16x32_bf16 v[42:45], v[154:157], v[186:189], v[42:45]
	v_mfma_f32_16x16x32_bf16 v[38:41], v[146:149], v[194:197], v[38:41]
	v_mfma_f32_16x16x32_bf16 v[34:37], v[154:157], v[194:197], v[34:37]
	v_mfma_f32_16x16x32_bf16 v[22:25], v[146:149], v[208:211], v[22:25]
	v_mfma_f32_16x16x32_bf16 v[14:17], v[154:157], v[208:211], v[14:17]
	v_mfma_f32_16x16x32_bf16 v[6:9], v[146:149], v[216:219], v[6:9]
	v_mfma_f32_16x16x32_bf16 v[2:5], v[154:157], v[216:219], v[2:5]
	v_mfma_f32_16x16x32_bf16 v[46:49], v[150:153], v[190:193], v[46:49]
	v_mfma_f32_16x16x32_bf16 v[42:45], v[158:161], v[190:193], v[42:45]
	v_mfma_f32_16x16x32_bf16 v[38:41], v[150:153], v[204:207], v[38:41]
	v_mfma_f32_16x16x32_bf16 v[34:37], v[158:161], v[204:207], v[34:37]
	v_mfma_f32_16x16x32_bf16 v[22:25], v[150:153], v[212:215], v[22:25]
	v_mfma_f32_16x16x32_bf16 v[14:17], v[158:161], v[212:215], v[14:17]
	v_mfma_f32_16x16x32_bf16 v[6:9], v[150:153], v[220:223], v[6:9]
	v_mfma_f32_16x16x32_bf16 v[2:5], v[158:161], v[220:223], v[2:5]
	s_barrier
	s_add_i32 s71, s71, 2
	s_add_u32 s4, s4, 0x100
	s_addc_u32 s5, s5, 0
	s_add_u32 s69, s69, 0x100
	s_addc_u32 s70, s70, 0
	s_cmp_gt_u32 s71, 13
	s_cbranch_scc0 .LBB0_1062
	s_and_b64 vcc, exec, s[12:13]
	s_cbranch_vccz .LBB0_1065
	s_barrier

.LBB0_1157:
	s_setprio 0
	v_readlane_b32 s2, v243, 51
	s_cmp_lt_i32 s2, 14
	s_cselect_b64 s[4:5], -1, 0
	s_and_b64 s[0:1], s[4:5], s[0:1]
	s_andn2_b64 vcc, exec, s[0:1]
	v_readlane_b32 s3, v243, 52
	s_cbranch_vccnz .LBB0_1174
	v_readlane_b32 s0, v243, 0
	s_cmpk_gt_i32 s0, 0x40f
	v_readfirstlane_b32 s3, v0
	s_cbranch_scc1 .LBB0_1174
	v_lshlrev_b32_e32 v2, 4, v0
	s_add_u32 s20, s90, 0xcd00000
	v_or_b32_e32 v10, 0x2000, v2
	v_readlane_b32 s2, v243, 0
	s_addc_u32 s24, s91, 0
	v_lshrrev_b32_e32 v3, 7, v10
	v_bfe_u32 v13, v0, 2, 4
	s_movk_i32 s0, 0x70
	s_ashr_i32 s26, s2, 31
	v_and_or_b32 v3, v3, s0, v13
	s_lshr_b32 s0, s26, 29
	s_add_i32 s0, s2, s0
	s_lshr_b32 s8, s3, 6
	s_ashr_i32 s1, s0, 3
	s_and_b32 s0, s0, -8
	s_lshr_b32 s10, s3, 8
	s_lshl_b32 s25, s8, 10
	s_sub_i32 s0, s2, s0
	s_cmp_lt_i32 s0, 0
	s_movk_i32 s27, 0x83
	s_cselect_b32 s2, s27, 0x82
	s_mul_i32 s0, s2, s0
	s_add_i32 s0, s0, s1
	s_ashr_i32 s1, s0, 31
	s_lshr_b32 s1, s1, 26
	s_add_i32 s1, s0, s1
	s_ashr_i32 s1, s1, 6
	s_lshl_b32 s6, s1, 3
	s_sub_i32 s2, 0x82, s6
	s_lshl_b32 s1, s1, 6
	s_min_u32 s7, s2, 8
	s_sub_i32 s9, s0, s1
	v_and_b32_e32 v4, 32, v0
	s_sext_i32_i8 s0, s9
	v_cvt_f32_ubyte0_e32 v5, s7
	v_bitop3_b32 v11, v2, v4, 48 bitop3:0x6c
	v_and_b32_e32 v12, 64, v0
	v_cvt_f32_i32_e32 v4, s0
	v_rcp_iflag_f32_e32 v6, v5
	v_or_b32_e32 v2, v11, v12
	v_lshl_or_b32 v142, v3, 12, v2
	v_lshrrev_b32_e32 v3, 3, v0
	v_and_or_b32 v3, v3, 48, v13
	v_lshl_or_b32 v144, v3, 12, v2
	v_mul_f32_e32 v2, v4, v6
	v_trunc_f32_e32 v2, v2
	v_fma_f32 v3, -v2, v5, v4
	v_cvt_i32_f32_e32 v2, v2
	s_ashr_i32 s0, s0, 30
	s_or_b32 s2, s0, 1
	v_cmp_ge_f32_e64 s[0:1], |v3|, v5
	s_and_b64 s[0:1], s[0:1], exec
	s_cselect_b32 s0, s2, 0
	v_readfirstlane_b32 s1, v2
	s_add_i32 s2, s1, s0
	s_mul_i32 s0, s2, s7
	s_sub_i32 s0, s9, s0
	s_sext_i32_i8 s0, s0
	s_add_i32 s86, s6, s0
	s_ashr_i32 s87, s86, 31
	s_bfe_i64 s[0:1], s[2:3], 0x80000
	s_lshl_b64 s[6:7], s[86:87], 20
	s_lshl_b64 s[0:1], s[0:1], 20
	s_add_u32 s0, s20, s0
	s_addc_u32 s1, s24, s1
	s_add_i32 s30, s25, 0
	s_add_i32 m0, s30, 0x10000
	v_mov_b32_e32 v145, 0
	global_load_lds_dwordx4 v144, s[0:1]
	s_add_i32 m0, s30, 0x12000
	s_add_u32 s12, s0, 0x80000
	global_load_lds_dwordx4 v142, s[0:1]
	s_addc_u32 s13, s1, 0
	s_add_i32 m0, s30, 0x14000
	v_mov_b32_e32 v143, v145
	global_load_lds_dwordx4 v144, s[12:13]
	s_add_i32 m0, s30, 0x16000
	s_mov_b32 s35, 0
	global_load_lds_dwordx4 v142, s[12:13]
	v_readlane_b32 s12, v242, 15
	v_readlane_b32 s13, v242, 16
	s_add_u32 s22, s12, s6
	s_addc_u32 s23, s13, s7
	s_add_i32 s31, s30, 0x2000
	s_mov_b32 m0, s30
	s_add_u32 s6, s22, 0x80000
	global_load_lds_dwordx4 v144, s[22:23]
	s_mov_b32 m0, s31
	s_addc_u32 s7, s23, 0
	s_add_i32 s33, s30, 0x4000
	global_load_lds_dwordx4 v142, s[22:23]
	s_mov_b32 m0, s33
	s_add_i32 s34, s30, 0x6000
	global_load_lds_dwordx4 v144, s[6:7]
	s_mov_b32 m0, s34
	s_cmp_eq_u32 s10, 1
	global_load_lds_dwordx4 v142, s[6:7]
	v_lshl_add_u64 v[8:9], s[0:1], 0, v[144:145]
	v_lshl_add_u64 v[6:7], s[0:1], 0, v[142:143]
	v_lshl_add_u64 v[2:3], s[22:23], 0, v[144:145]
	s_cselect_b64 s[6:7], -1, 0
	s_cmp_lg_u32 s10, 1
	v_lshl_add_u64 v[4:5], s[22:23], 0, v[142:143]
	s_cbranch_scc1 .LBB0_1161
	s_barrier
	s_setprio 1

.LBB0_1167:
	ds_read_b128 v[90:93], v192
	ds_read_b128 v[134:137], v192 offset:1024
	ds_read_b128 v[138:141], v192 offset:2048
	ds_read_b128 v[176:179], v192 offset:3072
	ds_read_b128 v[180:183], v193
	ds_read_b128 v[184:187], v193 offset:1024
	ds_read_b128 v[188:191], v193 offset:2048
	ds_read_b128 v[196:199], v193 offset:3072
	s_add_u32 s0, s88, 0xfff80080
	s_addc_u32 s1, s89, -1
	s_cmp_eq_u32 s73, 28
	s_cselect_b32 s23, s15, s1
	s_cselect_b32 s22, s69, s0
	s_cselect_b32 s1, s13, s72
	s_cselect_b32 s0, s70, s71
	v_lshl_add_u64 v[232:233], s[88:89], 0, v[162:163]
	s_add_i32 m0, s30, 0xc000
	ds_read_b128 v[200:203], v194
	ds_read_b128 v[204:207], v194 offset:1024
	ds_read_b128 v[208:211], v194 offset:2048
	ds_read_b128 v[212:215], v194 offset:3072
	ds_read_b128 v[216:219], v194 offset:4096
	ds_read_b128 v[220:223], v194 offset:5120
	ds_read_b128 v[224:227], v194 offset:6144
	ds_read_b128 v[228:231], v194 offset:7168
	global_load_lds_dwordx4 v[232:233], off
	v_lshl_add_u64 v[232:233], s[88:89], 0, v[170:171]
	s_add_i32 m0, s30, 0xe000
	s_nop 0
	global_load_lds_dwordx4 v[232:233], off
	s_waitcnt vmcnt(8)
	s_waitcnt lgkmcnt(0)
	s_barrier
	s_waitcnt lgkmcnt(0)
	v_mfma_f32_16x16x32_bf16 v[130:133], v[90:93], v[200:203], v[130:133]
	v_mfma_f32_16x16x32_bf16 v[98:101], v[138:141], v[200:203], v[98:101]
	v_mfma_f32_16x16x32_bf16 v[126:129], v[90:93], v[208:211], v[126:129]
	v_mfma_f32_16x16x32_bf16 v[94:97], v[138:141], v[208:211], v[94:97]
	v_mfma_f32_16x16x32_bf16 v[122:125], v[90:93], v[216:219], v[122:125]
	v_mfma_f32_16x16x32_bf16 v[86:89], v[138:141], v[216:219], v[86:89]
	v_mfma_f32_16x16x32_bf16 v[118:121], v[90:93], v[224:227], v[118:121]
	v_mfma_f32_16x16x32_bf16 v[82:85], v[138:141], v[224:227], v[82:85]
	v_mfma_f32_16x16x32_bf16 v[130:133], v[134:137], v[204:207], v[130:133]
	v_mfma_f32_16x16x32_bf16 v[98:101], v[176:179], v[204:207], v[98:101]
	v_mfma_f32_16x16x32_bf16 v[126:129], v[134:137], v[212:215], v[126:129]
	v_mfma_f32_16x16x32_bf16 v[94:97], v[176:179], v[212:215], v[94:97]
	v_mfma_f32_16x16x32_bf16 v[122:125], v[134:137], v[220:223], v[122:125]
	v_mfma_f32_16x16x32_bf16 v[86:89], v[176:179], v[220:223], v[86:89]
	v_mfma_f32_16x16x32_bf16 v[118:121], v[134:137], v[228:231], v[118:121]
	v_mfma_f32_16x16x32_bf16 v[82:85], v[176:179], v[228:231], v[82:85]
	v_mfma_f32_16x16x32_bf16 v[62:65], v[180:183], v[200:203], v[62:65]
	v_mfma_f32_16x16x32_bf16 v[30:33], v[188:191], v[200:203], v[30:33]
	v_mfma_f32_16x16x32_bf16 v[58:61], v[180:183], v[208:211], v[58:61]
	v_mfma_f32_16x16x32_bf16 v[26:29], v[188:191], v[208:211], v[26:29]
	v_mfma_f32_16x16x32_bf16 v[54:57], v[180:183], v[216:219], v[54:57]
	v_mfma_f32_16x16x32_bf16 v[22:25], v[188:191], v[216:219], v[22:25]
	v_mfma_f32_16x16x32_bf16 v[50:53], v[180:183], v[224:227], v[50:53]
	v_mfma_f32_16x16x32_bf16 v[18:21], v[188:191], v[224:227], v[18:21]
	v_mfma_f32_16x16x32_bf16 v[62:65], v[184:187], v[204:207], v[62:65]
	v_mfma_f32_16x16x32_bf16 v[30:33], v[196:199], v[204:207], v[30:33]
	v_mfma_f32_16x16x32_bf16 v[58:61], v[184:187], v[212:215], v[58:61]
	v_mfma_f32_16x16x32_bf16 v[26:29], v[196:199], v[212:215], v[26:29]
	v_mfma_f32_16x16x32_bf16 v[54:57], v[184:187], v[220:223], v[54:57]
	v_mfma_f32_16x16x32_bf16 v[22:25], v[196:199], v[220:223], v[22:25]
	v_mfma_f32_16x16x32_bf16 v[50:53], v[184:187], v[228:231], v[50:53]
	v_mfma_f32_16x16x32_bf16 v[18:21], v[196:199], v[228:231], v[18:21]
	s_barrier
	s_add_i32 s21, s94, s25
	v_lshl_add_u64 v[232:233], s[0:1], 0, v[144:145]
	s_mov_b32 m0, s21
	ds_read_b128 v[200:203], v194 offset:16384
	ds_read_b128 v[204:207], v194 offset:17408
	ds_read_b128 v[208:211], v194 offset:18432
	ds_read_b128 v[212:215], v194 offset:19456
	ds_read_b128 v[216:219], v194 offset:20480
	ds_read_b128 v[220:223], v194 offset:21504
	ds_read_b128 v[224:227], v194 offset:22528
	ds_read_b128 v[228:231], v194 offset:23552
	global_load_lds_dwordx4 v[232:233], off
	s_add_i32 m0, s21, 0x2000
	s_add_u32 s28, s0, 0x80000
	v_lshl_add_u64 v[234:235], s[0:1], 0, v[142:143]
	s_addc_u32 s29, s1, 0
	s_add_i32 s21, s95, s25
	global_load_lds_dwordx4 v[234:235], off
	v_lshl_add_u64 v[236:237], s[28:29], 0, v[144:145]
	s_mov_b32 m0, s21
	v_lshl_add_u64 v[238:239], s[22:23], 0, v[142:143]
	global_load_lds_dwordx4 v[236:237], off
	v_lshl_add_u64 v[236:237], s[28:29], 0, v[142:143]
	s_add_i32 m0, s21, 0x2000
	s_nop 0
	global_load_lds_dwordx4 v[236:237], off
	v_lshl_add_u64 v[236:237], s[22:23], 0, v[144:145]
	s_mov_b32 m0, s30
	s_nop 0
	global_load_lds_dwordx4 v[236:237], off
	s_mov_b32 m0, s31
	s_nop 0
	global_load_lds_dwordx4 v[238:239], off
	s_waitcnt vmcnt(8)
	s_waitcnt lgkmcnt(0)
	s_barrier
	s_waitcnt lgkmcnt(0)
	v_mfma_f32_16x16x32_bf16 v[114:117], v[90:93], v[200:203], v[114:117]
	v_mfma_f32_16x16x32_bf16 v[78:81], v[138:141], v[200:203], v[78:81]
	v_mfma_f32_16x16x32_bf16 v[110:113], v[90:93], v[208:211], v[110:113]
	v_mfma_f32_16x16x32_bf16 v[74:77], v[138:141], v[208:211], v[74:77]
	v_mfma_f32_16x16x32_bf16 v[106:109], v[90:93], v[216:219], v[106:109]
	v_mfma_f32_16x16x32_bf16 v[70:73], v[138:141], v[216:219], v[70:73]
	v_mfma_f32_16x16x32_bf16 v[66:69], v[138:141], v[224:227], v[66:69]
	v_mfma_f32_16x16x32_bf16 v[114:117], v[134:137], v[204:207], v[114:117]
	v_mfma_f32_16x16x32_bf16 v[78:81], v[176:179], v[204:207], v[78:81]
	v_mfma_f32_16x16x32_bf16 v[110:113], v[134:137], v[212:215], v[110:113]
	v_mfma_f32_16x16x32_bf16 v[74:77], v[176:179], v[212:215], v[74:77]
	v_mfma_f32_16x16x32_bf16 v[106:109], v[134:137], v[220:223], v[106:109]
	v_mfma_f32_16x16x32_bf16 v[70:73], v[176:179], v[220:223], v[70:73]
	v_mfma_f32_16x16x32_bf16 v[90:93], v[90:93], v[224:227], v[102:105]
	v_mfma_f32_16x16x32_bf16 v[66:69], v[176:179], v[228:231], v[66:69]
	v_mfma_f32_16x16x32_bf16 v[90:93], v[134:137], v[228:231], v[90:93]
	v_mfma_f32_16x16x32_bf16 v[46:49], v[180:183], v[200:203], v[46:49]
	v_mfma_f32_16x16x32_bf16 v[14:17], v[188:191], v[200:203], v[14:17]
	v_mfma_f32_16x16x32_bf16 v[42:45], v[180:183], v[208:211], v[42:45]
	v_mfma_f32_16x16x32_bf16 v[10:13], v[188:191], v[208:211], v[10:13]
	v_mfma_f32_16x16x32_bf16 v[38:41], v[180:183], v[216:219], v[38:41]
	v_mfma_f32_16x16x32_bf16 v[6:9], v[188:191], v[216:219], v[6:9]
	v_mfma_f32_16x16x32_bf16 v[34:37], v[180:183], v[224:227], v[34:37]
	v_mfma_f32_16x16x32_bf16 v[2:5], v[188:191], v[224:227], v[2:5]
	v_mfma_f32_16x16x32_bf16 v[46:49], v[184:187], v[204:207], v[46:49]
	v_mfma_f32_16x16x32_bf16 v[14:17], v[196:199], v[204:207], v[14:17]
	v_mfma_f32_16x16x32_bf16 v[42:45], v[184:187], v[212:215], v[42:45]
	v_mfma_f32_16x16x32_bf16 v[10:13], v[196:199], v[212:215], v[10:13]
	v_mfma_f32_16x16x32_bf16 v[38:41], v[184:187], v[220:223], v[38:41]
	v_mfma_f32_16x16x32_bf16 v[6:9], v[196:199], v[220:223], v[6:9]
	v_mfma_f32_16x16x32_bf16 v[34:37], v[184:187], v[228:231], v[34:37]
	v_mfma_f32_16x16x32_bf16 v[2:5], v[196:199], v[228:231], v[2:5]
	s_barrier
	s_add_i32 s21, 0, 0x18000
	s_add_i32 s28, 0, 0x1c000
	v_add_u32_e32 v176, s21, v165
	v_add_u32_e32 v195, s28, v165
	ds_read_b128 v[102:105], v176
	ds_read_b128 v[134:137], v176 offset:1024
	ds_read_b128 v[138:141], v176 offset:2048
	ds_read_b128 v[176:179], v176 offset:3072
	ds_read_b128 v[180:183], v195
	ds_read_b128 v[184:187], v195 offset:1024
	ds_read_b128 v[188:191], v195 offset:2048
	ds_read_b128 v[196:199], v195 offset:3072
	s_add_u32 s22, s22, 0x80000
	s_addc_u32 s23, s23, 0
	s_mov_b32 m0, s33
	v_lshl_add_u64 v[240:241], s[22:23], 0, v[144:145]
	ds_read_b128 v[200:203], v194 offset:32768
	ds_read_b128 v[204:207], v194 offset:33792
	ds_read_b128 v[208:211], v194 offset:34816
	ds_read_b128 v[212:215], v194 offset:35840
	ds_read_b128 v[216:219], v194 offset:36864
	ds_read_b128 v[220:223], v194 offset:37888
	ds_read_b128 v[224:227], v194 offset:38912
	ds_read_b128 v[228:231], v194 offset:39936
	global_load_lds_dwordx4 v[240:241], off
	v_lshl_add_u64 v[240:241], s[22:23], 0, v[142:143]
	s_mov_b32 m0, s34
	s_nop 0
	global_load_lds_dwordx4 v[240:241], off
	s_waitcnt vmcnt(8)
	s_waitcnt lgkmcnt(0)
	s_barrier
	s_waitcnt lgkmcnt(0)
	v_mfma_f32_16x16x32_bf16 v[130:133], v[102:105], v[200:203], v[130:133]
	v_mfma_f32_16x16x32_bf16 v[98:101], v[138:141], v[200:203], v[98:101]
	v_mfma_f32_16x16x32_bf16 v[126:129], v[102:105], v[208:211], v[126:129]
	v_mfma_f32_16x16x32_bf16 v[94:97], v[138:141], v[208:211], v[94:97]
	v_mfma_f32_16x16x32_bf16 v[122:125], v[102:105], v[216:219], v[122:125]
	v_mfma_f32_16x16x32_bf16 v[86:89], v[138:141], v[216:219], v[86:89]
	v_mfma_f32_16x16x32_bf16 v[118:121], v[102:105], v[224:227], v[118:121]
	v_mfma_f32_16x16x32_bf16 v[82:85], v[138:141], v[224:227], v[82:85]
	v_mfma_f32_16x16x32_bf16 v[130:133], v[134:137], v[204:207], v[130:133]
	v_mfma_f32_16x16x32_bf16 v[98:101], v[176:179], v[204:207], v[98:101]
	v_mfma_f32_16x16x32_bf16 v[126:129], v[134:137], v[212:215], v[126:129]
	v_mfma_f32_16x16x32_bf16 v[94:97], v[176:179], v[212:215], v[94:97]
	v_mfma_f32_16x16x32_bf16 v[122:125], v[134:137], v[220:223], v[122:125]
	v_mfma_f32_16x16x32_bf16 v[86:89], v[176:179], v[220:223], v[86:89]
	v_mfma_f32_16x16x32_bf16 v[118:121], v[134:137], v[228:231], v[118:121]
	v_mfma_f32_16x16x32_bf16 v[82:85], v[176:179], v[228:231], v[82:85]
	v_mfma_f32_16x16x32_bf16 v[62:65], v[180:183], v[200:203], v[62:65]
	v_mfma_f32_16x16x32_bf16 v[30:33], v[188:191], v[200:203], v[30:33]
	v_mfma_f32_16x16x32_bf16 v[58:61], v[180:183], v[208:211], v[58:61]
	v_mfma_f32_16x16x32_bf16 v[26:29], v[188:191], v[208:211], v[26:29]
	v_mfma_f32_16x16x32_bf16 v[54:57], v[180:183], v[216:219], v[54:57]
	v_mfma_f32_16x16x32_bf16 v[22:25], v[188:191], v[216:219], v[22:25]
	v_mfma_f32_16x16x32_bf16 v[50:53], v[180:183], v[224:227], v[50:53]
	v_mfma_f32_16x16x32_bf16 v[18:21], v[188:191], v[224:227], v[18:21]
	v_mfma_f32_16x16x32_bf16 v[62:65], v[184:187], v[204:207], v[62:65]
	v_mfma_f32_16x16x32_bf16 v[30:33], v[196:199], v[204:207], v[30:33]
	v_mfma_f32_16x16x32_bf16 v[58:61], v[184:187], v[212:215], v[58:61]
	v_mfma_f32_16x16x32_bf16 v[26:29], v[196:199], v[212:215], v[26:29]
	v_mfma_f32_16x16x32_bf16 v[54:57], v[184:187], v[220:223], v[54:57]
	v_mfma_f32_16x16x32_bf16 v[22:25], v[196:199], v[220:223], v[22:25]
	v_mfma_f32_16x16x32_bf16 v[50:53], v[184:187], v[228:231], v[50:53]
	v_mfma_f32_16x16x32_bf16 v[18:21], v[196:199], v[228:231], v[18:21]
	s_barrier
	s_add_i32 s21, s21, s25
	v_lshl_add_u64 v[232:233], v[232:233], 0, s[8:9]
	s_mov_b32 m0, s21
	ds_read_b128 v[200:203], v194 offset:49152
	ds_read_b128 v[204:207], v194 offset:50176
	ds_read_b128 v[208:211], v194 offset:51200
	ds_read_b128 v[212:215], v194 offset:52224
	ds_read_b128 v[216:219], v194 offset:53248
	ds_read_b128 v[220:223], v194 offset:54272
	ds_read_b128 v[224:227], v194 offset:55296
	ds_read_b128 v[228:231], v194 offset:56320
	global_load_lds_dwordx4 v[232:233], off
	s_add_i32 m0, s21, 0x2000
	s_add_u32 s0, s0, 0x80080
	v_lshl_add_u64 v[232:233], v[234:235], 0, s[8:9]
	s_addc_u32 s1, s1, 0
	s_add_i32 s21, s28, s25
	global_load_lds_dwordx4 v[232:233], off
	v_lshl_add_u64 v[232:233], s[0:1], 0, v[144:145]
	s_mov_b32 m0, s21
	s_nop 0
	global_load_lds_dwordx4 v[232:233], off
	v_lshl_add_u64 v[232:233], s[0:1], 0, v[142:143]
	s_add_i32 m0, s21, 0x2000
	s_nop 0
	global_load_lds_dwordx4 v[232:233], off
	v_lshl_add_u64 v[232:233], v[236:237], 0, s[8:9]
	s_mov_b32 m0, s91
	s_nop 0
	global_load_lds_dwordx4 v[232:233], off
	v_lshl_add_u64 v[232:233], v[238:239], 0, s[8:9]
	s_mov_b32 m0, s92
	s_nop 0
	global_load_lds_dwordx4 v[232:233], off
	s_waitcnt vmcnt(8)
	s_waitcnt lgkmcnt(0)
	s_barrier
	s_waitcnt lgkmcnt(0)
	v_mfma_f32_16x16x32_bf16 v[114:117], v[102:105], v[200:203], v[114:117]
	v_mfma_f32_16x16x32_bf16 v[78:81], v[138:141], v[200:203], v[78:81]
	v_mfma_f32_16x16x32_bf16 v[110:113], v[102:105], v[208:211], v[110:113]
	v_mfma_f32_16x16x32_bf16 v[74:77], v[138:141], v[208:211], v[74:77]
	v_mfma_f32_16x16x32_bf16 v[106:109], v[102:105], v[216:219], v[106:109]
	v_mfma_f32_16x16x32_bf16 v[70:73], v[138:141], v[216:219], v[70:73]
	v_mfma_f32_16x16x32_bf16 v[90:93], v[102:105], v[224:227], v[90:93]
	v_mfma_f32_16x16x32_bf16 v[66:69], v[138:141], v[224:227], v[66:69]
	v_mfma_f32_16x16x32_bf16 v[114:117], v[134:137], v[204:207], v[114:117]
	v_mfma_f32_16x16x32_bf16 v[78:81], v[176:179], v[204:207], v[78:81]
	v_mfma_f32_16x16x32_bf16 v[110:113], v[134:137], v[212:215], v[110:113]
	v_mfma_f32_16x16x32_bf16 v[74:77], v[176:179], v[212:215], v[74:77]
	v_mfma_f32_16x16x32_bf16 v[106:109], v[134:137], v[220:223], v[106:109]
	v_mfma_f32_16x16x32_bf16 v[70:73], v[176:179], v[220:223], v[70:73]
	v_mfma_f32_16x16x32_bf16 v[102:105], v[134:137], v[228:231], v[90:93]
	v_mfma_f32_16x16x32_bf16 v[66:69], v[176:179], v[228:231], v[66:69]
	v_mfma_f32_16x16x32_bf16 v[46:49], v[180:183], v[200:203], v[46:49]
	v_mfma_f32_16x16x32_bf16 v[14:17], v[188:191], v[200:203], v[14:17]
	v_mfma_f32_16x16x32_bf16 v[42:45], v[180:183], v[208:211], v[42:45]
	v_mfma_f32_16x16x32_bf16 v[10:13], v[188:191], v[208:211], v[10:13]
	v_mfma_f32_16x16x32_bf16 v[38:41], v[180:183], v[216:219], v[38:41]
	v_mfma_f32_16x16x32_bf16 v[6:9], v[188:191], v[216:219], v[6:9]
	v_mfma_f32_16x16x32_bf16 v[34:37], v[180:183], v[224:227], v[34:37]
	v_mfma_f32_16x16x32_bf16 v[2:5], v[188:191], v[224:227], v[2:5]
	v_mfma_f32_16x16x32_bf16 v[46:49], v[184:187], v[204:207], v[46:49]
	v_mfma_f32_16x16x32_bf16 v[14:17], v[196:199], v[204:207], v[14:17]
	v_mfma_f32_16x16x32_bf16 v[42:45], v[184:187], v[212:215], v[42:45]
	v_mfma_f32_16x16x32_bf16 v[10:13], v[196:199], v[212:215], v[10:13]
	v_mfma_f32_16x16x32_bf16 v[38:41], v[184:187], v[220:223], v[38:41]
	v_mfma_f32_16x16x32_bf16 v[6:9], v[196:199], v[220:223], v[6:9]
	v_mfma_f32_16x16x32_bf16 v[34:37], v[184:187], v[228:231], v[34:37]
	v_mfma_f32_16x16x32_bf16 v[2:5], v[196:199], v[228:231], v[2:5]
	s_barrier
	s_add_i32 s73, s73, 2
	s_add_u32 s88, s88, 0x100
	s_addc_u32 s89, s89, 0
	s_add_u32 s71, s71, 0x100
	s_addc_u32 s72, s72, 0
	s_cmp_gt_u32 s73, 29
	s_cbranch_scc0 .LBB0_1167
	s_and_b64 vcc, exec, s[10:11]
	s_cbranch_vccz .LBB0_1170
	s_barrier

.LBB0_1228:
	s_setprio 0
	v_readlane_b32 s0, v243, 51
	v_readlane_b32 s1, v243, 52
	s_cmp_lt_i32 s0, 15
	s_cselect_b64 s[0:1], -1, 0
	s_and_b64 s[2:3], s[0:1], s[2:3]
	s_andn2_b64 vcc, exec, s[2:3]
	s_cbranch_vccnz .LBB0_1232
	v_readlane_b32 s2, v243, 0
	s_lshl_b32 s2, s2, 3
	v_readlane_b32 s3, v243, 59
	s_add_i32 s4, s3, s2
	s_cmp_gt_i32 s4, 0x81ff
	s_cbranch_scc1 .LBB0_1232
	v_mbcnt_lo_u32_b32 v2, -1, 0
	v_mbcnt_hi_u32_b32 v2, -1, v2
	v_and_b32_e32 v3, 64, v2
	v_add_u32_e32 v3, 64, v3
	v_xor_b32_e32 v4, 1, v2
	v_cmp_lt_i32_e32 vcc, v4, v3
	v_readlane_b32 s8, v243, 1
	v_readlane_b32 s2, v243, 53
	v_cndmask_b32_e32 v4, v2, v4, vcc
	v_lshlrev_b32_e32 v150, 2, v4
	v_xor_b32_e32 v4, 2, v2
	v_cmp_lt_i32_e32 vcc, v4, v3
	v_readlane_b32 s12, v243, 5
	v_readlane_b32 s13, v243, 6
	v_cndmask_b32_e32 v4, v2, v4, vcc
	v_lshlrev_b32_e32 v151, 2, v4
	v_xor_b32_e32 v4, 4, v2
	v_cmp_lt_i32_e32 vcc, v4, v3
	v_readlane_b32 s14, v243, 7
	v_readlane_b32 s15, v243, 8
	v_cndmask_b32_e32 v4, v2, v4, vcc
	v_lshlrev_b32_e32 v152, 2, v4
	v_xor_b32_e32 v4, 8, v2
	v_cmp_lt_i32_e32 vcc, v4, v3
	v_readlane_b32 s20, v243, 13
	v_readlane_b32 s21, v243, 14
	v_cndmask_b32_e32 v4, v2, v4, vcc
	v_lshlrev_b32_e32 v153, 2, v4
	v_xor_b32_e32 v4, 16, v2
	v_cmp_lt_i32_e32 vcc, v4, v3
	s_lshl_b32 s6, s2, 3
	v_readlane_b32 s22, v243, 15
	v_cndmask_b32_e32 v4, v2, v4, vcc
	v_lshlrev_b32_e32 v154, 2, v4
	v_xor_b32_e32 v4, 32, v2
	v_cmp_lt_i32_e32 vcc, v4, v3
	v_readlane_b32 s23, v243, 16
	s_mov_b64 s[12:13], s[20:21]
	v_cndmask_b32_e32 v2, v2, v4, vcc
	s_add_u32 s2, s12, 0x4000
	v_lshlrev_b32_e32 v155, 2, v2
	v_lshlrev_b32_e32 v2, 2, v166
	s_addc_u32 s3, s13, 0
	v_mov_b32_e32 v131, 0
	v_lshlrev_b32_e32 v130, 4, v166
	v_or_b32_e32 v4, 0x100, v2
	v_lshl_add_u64 v[132:133], s[2:3], 0, v[130:131]
	v_lshlrev_b32_e32 v130, 2, v4
	v_or_b32_e32 v6, 0x200, v2
	v_lshl_add_u64 v[134:135], s[2:3], 0, v[130:131]
	v_lshlrev_b32_e32 v130, 2, v6
	v_or_b32_e32 v8, 0x300, v2
	v_lshl_add_u64 v[136:137], s[2:3], 0, v[130:131]
	v_lshlrev_b32_e32 v130, 2, v8
	v_or_b32_e32 v10, 0x400, v2
	v_lshl_add_u64 v[138:139], s[2:3], 0, v[130:131]
	v_lshlrev_b32_e32 v130, 2, v10
	v_or_b32_e32 v12, 0x500, v2
	v_readlane_b32 s10, v243, 3
	v_lshl_add_u64 v[140:141], s[2:3], 0, v[130:131]
	v_lshlrev_b32_e32 v130, 2, v12
	v_or_b32_e32 v14, 0x600, v2
	v_readlane_b32 s11, v243, 4
	s_add_u32 s10, s90, 0x10c000
	v_lshl_add_u64 v[142:143], s[2:3], 0, v[130:131]
	v_lshlrev_b32_e32 v130, 2, v14
	v_or_b32_e32 v16, 0x700, v2
	s_addc_u32 s11, s91, 0
	v_lshl_add_u64 v[144:145], s[2:3], 0, v[130:131]
	v_lshlrev_b32_e32 v130, 2, v16
	s_ashr_i32 s5, s4, 31
	v_lshl_add_u64 v[146:147], s[2:3], 0, v[130:131]
	s_lshl_b64 s[2:3], s[4:5], 12
	s_add_u32 s2, s90, s2
	v_lshlrev_b32_e32 v130, 3, v166
	s_addc_u32 s3, s91, s3
	v_readlane_b32 s9, v243, 2
	v_readlane_b32 s16, v243, 9
	s_mov_b64 s[14:15], s[22:23]
	s_waitcnt vmcnt(0)
	v_lshl_add_u64 v[18:19], s[2:3], 0, v[130:131]
	s_mov_b64 s[2:3], 0xd900000
	s_ashr_i32 s7, s6, 31
	v_readlane_b32 s20, v242, 19
	v_lshl_add_u64 v[148:149], v[18:19], 0, s[2:3]
	s_lshl_b64 s[8:9], s[6:7], 12
	s_movk_i32 s12, 0x4800
	v_lshlrev_b32_e32 v130, 4, v166
	s_movk_i32 s13, 0x1000
	v_lshlrev_b32_e32 v156, 2, v2
	v_lshlrev_b32_e32 v157, 2, v4
	v_lshlrev_b32_e32 v158, 2, v6
	v_lshlrev_b32_e32 v159, 2, v8
	v_lshlrev_b32_e32 v160, 2, v10
	v_lshlrev_b32_e32 v161, 2, v12
	v_lshlrev_b32_e32 v162, 2, v14
	v_lshlrev_b32_e32 v163, 2, v16
	v_mov_b32_e32 v165, 0x358637bd
	s_mov_b32 s14, 0xf800000
	v_mov_b32_e32 v169, 0x260
	s_movk_i32 s15, 0x7fff
	s_mov_b32 s16, 0xffff0000
	v_readlane_b32 s21, v242, 20
	v_readlane_b32 s17, v243, 10
	v_readlane_b32 s18, v243, 11
	v_readlane_b32 s19, v243, 12

.LBB0_1286:
	s_setprio 0
	v_readlane_b32 s0, v243, 51
	s_cmp_lt_i32 s0, 16
	v_readlane_b32 s1, v243, 52
	s_cselect_b64 s[4:5], -1, 0
	s_and_b64 s[0:1], s[4:5], s[2:3]
	s_andn2_b64 vcc, exec, s[0:1]
	s_cbranch_vccnz .LBB0_1303
	v_readlane_b32 s0, v243, 0
	s_cmpk_gt_i32 s0, 0x1657
	v_readfirstlane_b32 s3, v0
	s_cbranch_scc1 .LBB0_1303
	v_lshrrev_b32_e32 v2, 5, v0
	v_lshrrev_b32_e32 v4, 1, v0
	v_and_b32_e32 v2, 4, v2
	v_bfe_u32 v3, v0, 2, 2
	v_and_b32_e32 v13, 24, v4
	v_or3_b32 v2, v2, v3, v13
	v_lshlrev_b32_e32 v3, 4, v0
	v_or_b32_e32 v10, 0x2000, v3
	s_add_u32 s20, s90, 0x3900000
	v_lshrrev_b32_e32 v4, 7, v10
	s_movk_i32 s0, 0x60
	v_readlane_b32 s2, v243, 0
	s_addc_u32 s24, s91, 0
	v_and_or_b32 v5, v4, s0, v2
	v_bfe_u32 v14, v0, 2, 4
	s_movk_i32 s0, 0x70
	s_ashr_i32 s26, s2, 31
	v_and_or_b32 v4, v4, s0, v14
	s_lshr_b32 s0, s26, 29
	s_add_i32 s0, s2, s0
	s_lshr_b32 s8, s3, 6
	s_ashr_i32 s1, s0, 3
	s_and_b32 s0, s0, -8
	s_lshr_b32 s9, s3, 8
	s_lshl_b32 s25, s8, 10
	s_sub_i32 s0, s2, s0
	s_cmp_lt_i32 s0, 0
	s_movk_i32 s27, 0x2cc
	s_cselect_b32 s2, s27, 0x2cb
	s_mul_i32 s0, s2, s0
	s_add_i32 s0, s0, s1
	s_mul_hi_i32 s1, s0, 0x2e8ba2e9
	s_lshr_b32 s2, s1, 31
	s_ashr_i32 s1, s1, 6
	v_and_b32_e32 v6, 32, v0
	s_add_i32 s1, s1, s2
	v_bitop3_b32 v11, v3, v6, 48 bitop3:0x6c
	v_and_b32_e32 v12, 64, v0
	s_lshl_b32 s6, s1, 3
	v_or_b32_e32 v3, v11, v12
	s_sub_i32 s2, 0x82, s6
	s_mulk_i32 s1, 0x160
	v_lshl_or_b32 v132, v4, 12, v3
	v_lshrrev_b32_e32 v4, 3, v0
	s_min_u32 s7, s2, 8
	s_sub_i32 s10, s0, s1
	v_lshl_or_b32 v130, v5, 12, v3
	v_and_or_b32 v2, v4, 32, v2
	s_sext_i32_i16 s0, s10
	v_cvt_f32_ubyte0_e32 v5, s7
	v_lshl_or_b32 v134, v2, 12, v3
	v_and_or_b32 v2, v4, 48, v14
	v_cvt_f32_i32_e32 v4, s0
	v_rcp_iflag_f32_e32 v6, v5
	v_lshl_or_b32 v136, v2, 12, v3
	s_ashr_i32 s0, s0, 30
	s_or_b32 s2, s0, 1
	v_mul_f32_e32 v2, v4, v6
	v_trunc_f32_e32 v2, v2
	v_fma_f32 v3, -v2, v5, v4
	v_cvt_i32_f32_e32 v2, v2
	v_cmp_ge_f32_e64 s[0:1], |v3|, v5
	s_and_b64 s[0:1], s[0:1], exec
	s_cselect_b32 s0, s2, 0
	v_readfirstlane_b32 s1, v2
	s_add_i32 s2, s1, s0
	s_mul_i32 s0, s2, s7
	s_sub_i32 s0, s10, s0
	s_sext_i32_i16 s0, s0
	s_add_i32 s86, s6, s0
	s_ashr_i32 s87, s86, 31
	s_bfe_i64 s[0:1], s[2:3], 0x100000
	s_lshl_b64 s[6:7], s[86:87], 20
	s_lshl_b64 s[0:1], s[0:1], 20
	s_add_u32 s0, s20, s0
	s_addc_u32 s1, s24, s1
	s_add_i32 s30, s25, 0
	s_add_i32 m0, s30, 0x10000
	v_mov_b32_e32 v135, 0
	global_load_lds_dwordx4 v134, s[0:1]
	s_add_i32 m0, s30, 0x12000
	s_add_u32 s10, s0, 0x80000
	global_load_lds_dwordx4 v130, s[0:1]
	s_addc_u32 s11, s1, 0
	s_add_i32 m0, s30, 0x14000
	v_mov_b32_e32 v131, v135
	global_load_lds_dwordx4 v134, s[10:11]
	s_add_i32 m0, s30, 0x16000
	v_mov_b32_e32 v137, v135
	global_load_lds_dwordx4 v130, s[10:11]
	v_readlane_b32 s10, v242, 15
	v_readlane_b32 s11, v242, 16
	s_add_u32 s22, s10, s6
	s_addc_u32 s23, s11, s7
	s_add_i32 s31, s30, 0x2000
	s_mov_b32 m0, s30
	s_add_u32 s6, s22, 0x80000
	global_load_lds_dwordx4 v136, s[22:23]
	s_mov_b32 m0, s31
	s_addc_u32 s7, s23, 0
	s_add_i32 s33, s30, 0x4000
	global_load_lds_dwordx4 v132, s[22:23]
	s_mov_b32 m0, s33
	s_add_i32 s34, s30, 0x6000
	global_load_lds_dwordx4 v136, s[6:7]
	s_mov_b32 m0, s34
	v_mov_b32_e32 v133, v135
	global_load_lds_dwordx4 v132, s[6:7]
	s_cmp_eq_u32 s9, 1
	s_mov_b32 s35, 0
	v_lshl_add_u64 v[8:9], s[0:1], 0, v[134:135]
	v_lshl_add_u64 v[6:7], s[0:1], 0, v[130:131]
	v_lshl_add_u64 v[2:3], s[22:23], 0, v[136:137]
	s_cselect_b64 s[6:7], -1, 0
	s_cmp_lg_u32 s9, 1
	v_lshl_add_u64 v[4:5], s[22:23], 0, v[132:133]
	s_cbranch_scc1 .LBB0_1290
	s_barrier
	s_setprio 1

.LBB0_1296:
	ds_read_b128 v[146:149], v153
	ds_read_b128 v[156:159], v153 offset:1024
	ds_read_b128 v[160:163], v153 offset:2048
	ds_read_b128 v[170:173], v153 offset:3072
	ds_read_b128 v[174:177], v154
	ds_read_b128 v[178:181], v154 offset:1024
	ds_read_b128 v[182:185], v154 offset:2048
	ds_read_b128 v[186:189], v154 offset:3072
	s_add_u32 s0, s88, 0xfff80080
	s_addc_u32 s1, s89, -1
	s_cmp_eq_u32 s73, 28
	s_cselect_b32 s23, s15, s1
	s_cselect_b32 s22, s69, s0
	s_cselect_b32 s1, s13, s72
	s_cselect_b32 s0, s70, s71
	v_lshl_add_u64 v[222:223], s[88:89], 0, v[138:139]
	s_add_i32 m0, s30, 0xc000
	ds_read_b128 v[190:193], v155
	ds_read_b128 v[194:197], v155 offset:1024
	ds_read_b128 v[198:201], v155 offset:2048
	ds_read_b128 v[202:205], v155 offset:3072
	ds_read_b128 v[206:209], v155 offset:4096
	ds_read_b128 v[210:213], v155 offset:5120
	ds_read_b128 v[214:217], v155 offset:6144
	ds_read_b128 v[218:221], v155 offset:7168
	global_load_lds_dwordx4 v[222:223], off
	v_lshl_add_u64 v[222:223], s[88:89], 0, v[140:141]
	s_add_i32 m0, s30, 0xe000
	s_nop 0
	global_load_lds_dwordx4 v[222:223], off
	s_waitcnt vmcnt(8)
	s_waitcnt lgkmcnt(0)
	s_barrier
	s_waitcnt lgkmcnt(0)
	v_mfma_f32_16x16x32_bf16 v[126:129], v[146:149], v[190:193], v[126:129]
	v_mfma_f32_16x16x32_bf16 v[118:121], v[160:163], v[190:193], v[118:121]
	v_mfma_f32_16x16x32_bf16 v[110:113], v[146:149], v[198:201], v[110:113]
	v_mfma_f32_16x16x32_bf16 v[102:105], v[160:163], v[198:201], v[102:105]
	v_mfma_f32_16x16x32_bf16 v[94:97], v[146:149], v[206:209], v[94:97]
	v_mfma_f32_16x16x32_bf16 v[86:89], v[160:163], v[206:209], v[86:89]
	v_mfma_f32_16x16x32_bf16 v[78:81], v[146:149], v[214:217], v[78:81]
	v_mfma_f32_16x16x32_bf16 v[70:73], v[160:163], v[214:217], v[70:73]
	v_mfma_f32_16x16x32_bf16 v[126:129], v[156:159], v[194:197], v[126:129]
	v_mfma_f32_16x16x32_bf16 v[118:121], v[170:173], v[194:197], v[118:121]
	v_mfma_f32_16x16x32_bf16 v[110:113], v[156:159], v[202:205], v[110:113]
	v_mfma_f32_16x16x32_bf16 v[102:105], v[170:173], v[202:205], v[102:105]
	v_mfma_f32_16x16x32_bf16 v[94:97], v[156:159], v[210:213], v[94:97]
	v_mfma_f32_16x16x32_bf16 v[86:89], v[170:173], v[210:213], v[86:89]
	v_mfma_f32_16x16x32_bf16 v[78:81], v[156:159], v[218:221], v[78:81]
	v_mfma_f32_16x16x32_bf16 v[70:73], v[170:173], v[218:221], v[70:73]
	v_mfma_f32_16x16x32_bf16 v[122:125], v[174:177], v[190:193], v[122:125]
	v_mfma_f32_16x16x32_bf16 v[114:117], v[182:185], v[190:193], v[114:117]
	v_mfma_f32_16x16x32_bf16 v[106:109], v[174:177], v[198:201], v[106:109]
	v_mfma_f32_16x16x32_bf16 v[98:101], v[182:185], v[198:201], v[98:101]
	v_mfma_f32_16x16x32_bf16 v[90:93], v[174:177], v[206:209], v[90:93]
	v_mfma_f32_16x16x32_bf16 v[82:85], v[182:185], v[206:209], v[82:85]
	v_mfma_f32_16x16x32_bf16 v[74:77], v[174:177], v[214:217], v[74:77]
	v_mfma_f32_16x16x32_bf16 v[66:69], v[182:185], v[214:217], v[66:69]
	v_mfma_f32_16x16x32_bf16 v[122:125], v[178:181], v[194:197], v[122:125]
	v_mfma_f32_16x16x32_bf16 v[114:117], v[186:189], v[194:197], v[114:117]
	v_mfma_f32_16x16x32_bf16 v[106:109], v[178:181], v[202:205], v[106:109]
	v_mfma_f32_16x16x32_bf16 v[98:101], v[186:189], v[202:205], v[98:101]
	v_mfma_f32_16x16x32_bf16 v[90:93], v[178:181], v[210:213], v[90:93]
	v_mfma_f32_16x16x32_bf16 v[82:85], v[186:189], v[210:213], v[82:85]
	v_mfma_f32_16x16x32_bf16 v[74:77], v[178:181], v[218:221], v[74:77]
	v_mfma_f32_16x16x32_bf16 v[66:69], v[186:189], v[218:221], v[66:69]
	s_barrier
	s_add_i32 s21, s92, s25
	v_lshl_add_u64 v[222:223], s[0:1], 0, v[134:135]
	s_mov_b32 m0, s21
	ds_read_b128 v[190:193], v155 offset:16384
	ds_read_b128 v[194:197], v155 offset:17408
	ds_read_b128 v[198:201], v155 offset:18432
	ds_read_b128 v[202:205], v155 offset:19456
	ds_read_b128 v[206:209], v155 offset:20480
	ds_read_b128 v[210:213], v155 offset:21504
	ds_read_b128 v[214:217], v155 offset:22528
	ds_read_b128 v[218:221], v155 offset:23552
	global_load_lds_dwordx4 v[222:223], off
	s_add_i32 m0, s21, 0x2000
	s_add_u32 s28, s0, 0x80000
	v_lshl_add_u64 v[224:225], s[0:1], 0, v[130:131]
	s_addc_u32 s29, s1, 0
	s_add_i32 s21, s93, s25
	global_load_lds_dwordx4 v[224:225], off
	v_lshl_add_u64 v[226:227], s[28:29], 0, v[134:135]
	s_mov_b32 m0, s21
	v_lshl_add_u64 v[228:229], s[22:23], 0, v[132:133]
	global_load_lds_dwordx4 v[226:227], off
	v_lshl_add_u64 v[226:227], s[28:29], 0, v[130:131]
	s_add_i32 m0, s21, 0x2000
	s_nop 0
	global_load_lds_dwordx4 v[226:227], off
	v_lshl_add_u64 v[226:227], s[22:23], 0, v[136:137]
	s_mov_b32 m0, s30
	s_nop 0
	global_load_lds_dwordx4 v[226:227], off
	s_mov_b32 m0, s31
	s_nop 0
	global_load_lds_dwordx4 v[228:229], off
	s_waitcnt vmcnt(8)
	s_waitcnt lgkmcnt(0)
	s_barrier
	s_waitcnt lgkmcnt(0)
	v_mfma_f32_16x16x32_bf16 v[62:65], v[146:149], v[190:193], v[62:65]
	v_mfma_f32_16x16x32_bf16 v[54:57], v[160:163], v[190:193], v[54:57]
	v_mfma_f32_16x16x32_bf16 v[46:49], v[146:149], v[198:201], v[46:49]
	v_mfma_f32_16x16x32_bf16 v[38:41], v[160:163], v[198:201], v[38:41]
	v_mfma_f32_16x16x32_bf16 v[30:33], v[146:149], v[206:209], v[30:33]
	v_mfma_f32_16x16x32_bf16 v[22:25], v[160:163], v[206:209], v[22:25]
	v_mfma_f32_16x16x32_bf16 v[14:17], v[146:149], v[214:217], v[14:17]
	v_mfma_f32_16x16x32_bf16 v[6:9], v[160:163], v[214:217], v[6:9]
	v_mfma_f32_16x16x32_bf16 v[62:65], v[156:159], v[194:197], v[62:65]
	v_mfma_f32_16x16x32_bf16 v[54:57], v[170:173], v[194:197], v[54:57]
	v_mfma_f32_16x16x32_bf16 v[46:49], v[156:159], v[202:205], v[46:49]
	v_mfma_f32_16x16x32_bf16 v[38:41], v[170:173], v[202:205], v[38:41]
	v_mfma_f32_16x16x32_bf16 v[30:33], v[156:159], v[210:213], v[30:33]
	v_mfma_f32_16x16x32_bf16 v[22:25], v[170:173], v[210:213], v[22:25]
	v_mfma_f32_16x16x32_bf16 v[14:17], v[156:159], v[218:221], v[14:17]
	v_mfma_f32_16x16x32_bf16 v[6:9], v[170:173], v[218:221], v[6:9]
	v_mfma_f32_16x16x32_bf16 v[58:61], v[174:177], v[190:193], v[58:61]
	v_mfma_f32_16x16x32_bf16 v[50:53], v[182:185], v[190:193], v[50:53]
	v_mfma_f32_16x16x32_bf16 v[42:45], v[174:177], v[198:201], v[42:45]
	v_mfma_f32_16x16x32_bf16 v[34:37], v[182:185], v[198:201], v[34:37]
	v_mfma_f32_16x16x32_bf16 v[26:29], v[174:177], v[206:209], v[26:29]
	v_mfma_f32_16x16x32_bf16 v[18:21], v[182:185], v[206:209], v[18:21]
	v_mfma_f32_16x16x32_bf16 v[10:13], v[174:177], v[214:217], v[10:13]
	v_mfma_f32_16x16x32_bf16 v[2:5], v[182:185], v[214:217], v[2:5]
	v_mfma_f32_16x16x32_bf16 v[58:61], v[178:181], v[194:197], v[58:61]
	v_mfma_f32_16x16x32_bf16 v[50:53], v[186:189], v[194:197], v[50:53]
	v_mfma_f32_16x16x32_bf16 v[42:45], v[178:181], v[202:205], v[42:45]
	v_mfma_f32_16x16x32_bf16 v[34:37], v[186:189], v[202:205], v[34:37]
	v_mfma_f32_16x16x32_bf16 v[26:29], v[178:181], v[210:213], v[26:29]
	v_mfma_f32_16x16x32_bf16 v[18:21], v[186:189], v[210:213], v[18:21]
	v_mfma_f32_16x16x32_bf16 v[10:13], v[178:181], v[218:221], v[10:13]
	v_mfma_f32_16x16x32_bf16 v[2:5], v[186:189], v[218:221], v[2:5]
	s_barrier
	s_add_i32 s21, 0, 0x18000
	v_add_u32_e32 v165, s21, v151
	s_add_i32 s28, 0, 0x1c000
	ds_read_b128 v[146:149], v165
	ds_read_b128 v[156:159], v165 offset:1024
	ds_read_b128 v[160:163], v165 offset:2048
	ds_read_b128 v[170:173], v165 offset:3072
	v_add_u32_e32 v165, s28, v151
	ds_read_b128 v[174:177], v165
	ds_read_b128 v[178:181], v165 offset:1024
	ds_read_b128 v[182:185], v165 offset:2048
	ds_read_b128 v[186:189], v165 offset:3072
	s_add_u32 s22, s22, 0x80000
	s_addc_u32 s23, s23, 0
	s_mov_b32 m0, s33
	v_lshl_add_u64 v[230:231], s[22:23], 0, v[136:137]
	ds_read_b128 v[190:193], v155 offset:32768
	ds_read_b128 v[194:197], v155 offset:33792
	ds_read_b128 v[198:201], v155 offset:34816
	ds_read_b128 v[202:205], v155 offset:35840
	ds_read_b128 v[206:209], v155 offset:36864
	ds_read_b128 v[210:213], v155 offset:37888
	ds_read_b128 v[214:217], v155 offset:38912
	ds_read_b128 v[218:221], v155 offset:39936
	global_load_lds_dwordx4 v[230:231], off
	v_lshl_add_u64 v[230:231], s[22:23], 0, v[132:133]
	s_mov_b32 m0, s34
	s_nop 0
	global_load_lds_dwordx4 v[230:231], off
	s_waitcnt vmcnt(8)
	s_waitcnt lgkmcnt(0)
	s_barrier
	s_waitcnt lgkmcnt(0)
	v_mfma_f32_16x16x32_bf16 v[126:129], v[146:149], v[190:193], v[126:129]
	v_mfma_f32_16x16x32_bf16 v[118:121], v[160:163], v[190:193], v[118:121]
	v_mfma_f32_16x16x32_bf16 v[110:113], v[146:149], v[198:201], v[110:113]
	v_mfma_f32_16x16x32_bf16 v[102:105], v[160:163], v[198:201], v[102:105]
	v_mfma_f32_16x16x32_bf16 v[94:97], v[146:149], v[206:209], v[94:97]
	v_mfma_f32_16x16x32_bf16 v[86:89], v[160:163], v[206:209], v[86:89]
	v_mfma_f32_16x16x32_bf16 v[78:81], v[146:149], v[214:217], v[78:81]
	v_mfma_f32_16x16x32_bf16 v[70:73], v[160:163], v[214:217], v[70:73]
	v_mfma_f32_16x16x32_bf16 v[126:129], v[156:159], v[194:197], v[126:129]
	v_mfma_f32_16x16x32_bf16 v[118:121], v[170:173], v[194:197], v[118:121]
	v_mfma_f32_16x16x32_bf16 v[110:113], v[156:159], v[202:205], v[110:113]
	v_mfma_f32_16x16x32_bf16 v[102:105], v[170:173], v[202:205], v[102:105]
	v_mfma_f32_16x16x32_bf16 v[94:97], v[156:159], v[210:213], v[94:97]
	v_mfma_f32_16x16x32_bf16 v[86:89], v[170:173], v[210:213], v[86:89]
	v_mfma_f32_16x16x32_bf16 v[78:81], v[156:159], v[218:221], v[78:81]
	v_mfma_f32_16x16x32_bf16 v[70:73], v[170:173], v[218:221], v[70:73]
	v_mfma_f32_16x16x32_bf16 v[122:125], v[174:177], v[190:193], v[122:125]
	v_mfma_f32_16x16x32_bf16 v[114:117], v[182:185], v[190:193], v[114:117]
	v_mfma_f32_16x16x32_bf16 v[106:109], v[174:177], v[198:201], v[106:109]
	v_mfma_f32_16x16x32_bf16 v[98:101], v[182:185], v[198:201], v[98:101]
	v_mfma_f32_16x16x32_bf16 v[90:93], v[174:177], v[206:209], v[90:93]
	v_mfma_f32_16x16x32_bf16 v[82:85], v[182:185], v[206:209], v[82:85]
	v_mfma_f32_16x16x32_bf16 v[74:77], v[174:177], v[214:217], v[74:77]
	v_mfma_f32_16x16x32_bf16 v[66:69], v[182:185], v[214:217], v[66:69]
	v_mfma_f32_16x16x32_bf16 v[122:125], v[178:181], v[194:197], v[122:125]
	v_mfma_f32_16x16x32_bf16 v[114:117], v[186:189], v[194:197], v[114:117]
	v_mfma_f32_16x16x32_bf16 v[106:109], v[178:181], v[202:205], v[106:109]
	v_mfma_f32_16x16x32_bf16 v[98:101], v[186:189], v[202:205], v[98:101]
	v_mfma_f32_16x16x32_bf16 v[90:93], v[178:181], v[210:213], v[90:93]
	v_mfma_f32_16x16x32_bf16 v[82:85], v[186:189], v[210:213], v[82:85]
	v_mfma_f32_16x16x32_bf16 v[74:77], v[178:181], v[218:221], v[74:77]
	v_mfma_f32_16x16x32_bf16 v[66:69], v[186:189], v[218:221], v[66:69]
	s_barrier
	s_add_i32 s21, s21, s25
	v_lshl_add_u64 v[222:223], v[222:223], 0, s[8:9]
	s_mov_b32 m0, s21
	ds_read_b128 v[190:193], v155 offset:49152
	ds_read_b128 v[194:197], v155 offset:50176
	ds_read_b128 v[198:201], v155 offset:51200
	ds_read_b128 v[202:205], v155 offset:52224
	ds_read_b128 v[206:209], v155 offset:53248
	ds_read_b128 v[210:213], v155 offset:54272
	ds_read_b128 v[214:217], v155 offset:55296
	ds_read_b128 v[218:221], v155 offset:56320
	global_load_lds_dwordx4 v[222:223], off
	s_add_i32 m0, s21, 0x2000
	s_add_u32 s0, s0, 0x80080
	v_lshl_add_u64 v[222:223], v[224:225], 0, s[8:9]
	s_addc_u32 s1, s1, 0
	s_add_i32 s21, s28, s25
	global_load_lds_dwordx4 v[222:223], off
	v_lshl_add_u64 v[222:223], s[0:1], 0, v[134:135]
	s_mov_b32 m0, s21
	s_nop 0
	global_load_lds_dwordx4 v[222:223], off
	v_lshl_add_u64 v[222:223], s[0:1], 0, v[130:131]
	s_add_i32 m0, s21, 0x2000
	s_nop 0
	global_load_lds_dwordx4 v[222:223], off
	v_lshl_add_u64 v[222:223], v[226:227], 0, s[8:9]
	s_mov_b32 m0, s87
	s_nop 0
	global_load_lds_dwordx4 v[222:223], off
	v_lshl_add_u64 v[222:223], v[228:229], 0, s[8:9]
	s_mov_b32 m0, s90
	s_nop 0
	global_load_lds_dwordx4 v[222:223], off
	s_waitcnt vmcnt(8)
	s_waitcnt lgkmcnt(0)
	s_barrier
	s_waitcnt lgkmcnt(0)
	v_mfma_f32_16x16x32_bf16 v[62:65], v[146:149], v[190:193], v[62:65]
	v_mfma_f32_16x16x32_bf16 v[54:57], v[160:163], v[190:193], v[54:57]
	v_mfma_f32_16x16x32_bf16 v[46:49], v[146:149], v[198:201], v[46:49]
	v_mfma_f32_16x16x32_bf16 v[38:41], v[160:163], v[198:201], v[38:41]
	v_mfma_f32_16x16x32_bf16 v[30:33], v[146:149], v[206:209], v[30:33]
	v_mfma_f32_16x16x32_bf16 v[22:25], v[160:163], v[206:209], v[22:25]
	v_mfma_f32_16x16x32_bf16 v[14:17], v[146:149], v[214:217], v[14:17]
	v_mfma_f32_16x16x32_bf16 v[6:9], v[160:163], v[214:217], v[6:9]
	v_mfma_f32_16x16x32_bf16 v[62:65], v[156:159], v[194:197], v[62:65]
	v_mfma_f32_16x16x32_bf16 v[54:57], v[170:173], v[194:197], v[54:57]
	v_mfma_f32_16x16x32_bf16 v[46:49], v[156:159], v[202:205], v[46:49]
	v_mfma_f32_16x16x32_bf16 v[38:41], v[170:173], v[202:205], v[38:41]
	v_mfma_f32_16x16x32_bf16 v[30:33], v[156:159], v[210:213], v[30:33]
	v_mfma_f32_16x16x32_bf16 v[22:25], v[170:173], v[210:213], v[22:25]
	v_mfma_f32_16x16x32_bf16 v[14:17], v[156:159], v[218:221], v[14:17]
	v_mfma_f32_16x16x32_bf16 v[6:9], v[170:173], v[218:221], v[6:9]
	v_mfma_f32_16x16x32_bf16 v[58:61], v[174:177], v[190:193], v[58:61]
	v_mfma_f32_16x16x32_bf16 v[50:53], v[182:185], v[190:193], v[50:53]
	v_mfma_f32_16x16x32_bf16 v[42:45], v[174:177], v[198:201], v[42:45]
	v_mfma_f32_16x16x32_bf16 v[34:37], v[182:185], v[198:201], v[34:37]
	v_mfma_f32_16x16x32_bf16 v[26:29], v[174:177], v[206:209], v[26:29]
	v_mfma_f32_16x16x32_bf16 v[18:21], v[182:185], v[206:209], v[18:21]
	v_mfma_f32_16x16x32_bf16 v[10:13], v[174:177], v[214:217], v[10:13]
	v_mfma_f32_16x16x32_bf16 v[2:5], v[182:185], v[214:217], v[2:5]
	v_mfma_f32_16x16x32_bf16 v[58:61], v[178:181], v[194:197], v[58:61]
	v_mfma_f32_16x16x32_bf16 v[50:53], v[186:189], v[194:197], v[50:53]
	v_mfma_f32_16x16x32_bf16 v[42:45], v[178:181], v[202:205], v[42:45]
	v_mfma_f32_16x16x32_bf16 v[34:37], v[186:189], v[202:205], v[34:37]
	v_mfma_f32_16x16x32_bf16 v[26:29], v[178:181], v[210:213], v[26:29]
	v_mfma_f32_16x16x32_bf16 v[18:21], v[186:189], v[210:213], v[18:21]
	v_mfma_f32_16x16x32_bf16 v[10:13], v[178:181], v[218:221], v[10:13]
	v_mfma_f32_16x16x32_bf16 v[2:5], v[186:189], v[218:221], v[2:5]
	s_barrier
	s_add_i32 s73, s73, 2
	s_add_u32 s88, s88, 0x100
	s_addc_u32 s89, s89, 0
	s_add_u32 s71, s71, 0x100
	s_addc_u32 s72, s72, 0
	s_cmp_gt_u32 s73, 29
	s_cbranch_scc0 .LBB0_1296
	s_and_b64 vcc, exec, s[10:11]
	s_cbranch_vccz .LBB0_1299
	s_barrier

.LBB0_1357:
	s_setprio 0
	v_readlane_b32 s2, v243, 51
	s_cmp_lt_i32 s2, 17
	s_cselect_b64 s[52:53], -1, 0
	s_and_b64 s[0:1], s[52:53], s[0:1]
	s_andn2_b64 vcc, exec, s[0:1]
	v_readlane_b32 s3, v243, 52
	s_cbranch_vccnz .LBB0_1403
	v_readlane_b32 s4, v243, 53
	s_abs_i32 s0, s4
	v_cvt_f32_u32_e32 v2, s0
	v_readlane_b32 s6, v243, 0
	s_sub_i32 s1, s4, s6
	s_add_i32 s2, s1, 0x3ff
	v_rcp_iflag_f32_e32 v2, v2
	s_sub_i32 s1, 0xfffffc01, s1
	s_xor_b32 s4, s2, s4
	s_sub_i32 s3, 0, s0
	v_mul_f32_e32 v2, 0x4f7ffffe, v2
	v_cvt_u32_f32_e32 v2, v2
	s_max_i32 s1, s2, s1
	s_ashr_i32 s2, s4, 31
	v_readfirstlane_b32 s4, v2
	s_mul_i32 s3, s3, s4
	s_mul_hi_u32 s3, s4, s3
	s_add_i32 s4, s4, s3
	s_mul_hi_u32 s3, s1, s4
	s_mul_i32 s4, s3, s0
	s_sub_i32 s1, s1, s4
	s_add_i32 s5, s3, 1
	s_sub_i32 s4, s1, s0
	s_cmp_ge_u32 s1, s0
	s_cselect_b32 s3, s5, s3
	s_cselect_b32 s1, s4, s1
	s_add_i32 s4, s3, 1
	s_cmp_ge_u32 s1, s0
	s_cselect_b32 s0, s4, s3
	s_xor_b32 s0, s0, s2
	s_sub_i32 s20, s0, s2
	s_cmp_lt_i32 s20, 1
	v_readfirstlane_b32 s4, v0
	s_cbranch_scc1 .LBB0_1362
	s_mov_b64 s[0:1], 0
	s_cmpk_gt_i32 s6, 0x3ff
	s_mov_b64 s[2:3], 0
	s_cbranch_scc1 .LBB0_1363
	v_readlane_b32 s3, v243, 0
	s_ashr_i32 s2, s3, 31
	s_lshr_b32 s2, s2, 29
	s_add_i32 s5, s3, s2
	s_and_b32 s2, s5, -8
	s_sub_i32 s6, s3, s2
	s_cmp_gt_i32 s6, -1
	s_cbranch_scc0 .LBB0_1367
	s_lshl_b32 s7, s6, 7
	s_cbranch_execz .LBB0_1368
	s_branch .LBB0_1369

.LBB0_1370:
	s_andn2_b64 vcc, exec, s[2:3]
	s_cbranch_vccnz .LBB0_1403
	v_lshlrev_b32_e32 v2, 4, v0
	v_and_b32_e32 v3, 32, v0
	v_bfe_u32 v4, v0, 2, 4
	v_bitop3_b32 v10, v2, v3, 48 bitop3:0x6c
	v_lshrrev_b32_e32 v3, 3, v0
	s_add_u32 s54, s90, 0x7b00000
	v_and_or_b32 v5, v3, 48, v4
	v_or_b32_e32 v3, 64, v3
	s_movk_i32 s0, 0x70
	s_addc_u32 s30, s91, 0
	v_and_or_b32 v3, v3, s0, v4
	s_lshr_b32 s3, s4, 6
	s_lshl_b32 s0, s18, 10
	s_lshr_b32 s2, s4, 8
	s_lshl_b32 s31, s3, 10
	s_addk_i32 s0, 0xfc00
	s_cmp_lg_u32 s18, 0
	s_cselect_b32 s8, s0, 0
	s_ashr_i32 s9, s8, 31
	s_mul_i32 s1, s17, 0x2c0000
	s_mul_hi_i32 s0, s17, 0x2c0000
	s_add_u32 s1, s54, s1
	s_addc_u32 s7, s30, s0
	v_and_b32_e32 v11, 64, v0
	s_add_u32 s0, s1, s8
	v_or_b32_e32 v2, v10, v11
	v_mul_u32_u24_e32 v12, 0x2c00, v5
	s_addc_u32 s1, s7, s9
	s_add_i32 s33, s31, 0
	v_or_b32_e32 v134, v12, v2
	s_add_i32 m0, s33, 0x10000
	s_mul_i32 s6, s16, 0x2c0000
	global_load_lds_dwordx4 v134, s[0:1]
	s_add_i32 m0, s33, 0x12000
	v_readlane_b32 s10, v242, 17
	s_mul_hi_i32 s5, s16, 0x2c0000
	v_readlane_b32 s11, v242, 18
	s_add_u32 s10, s10, s6
	v_mul_u32_u24_e32 v13, 0x2c00, v3
	s_addc_u32 s5, s11, s5
	v_or_b32_e32 v136, v13, v2
	s_add_u32 s6, s0, 0x160000
	global_load_lds_dwordx4 v136, s[0:1]
	s_addc_u32 s7, s1, 0
	s_add_i32 m0, s33, 0x14000
	v_mov_b32_e32 v135, 0
	global_load_lds_dwordx4 v134, s[6:7]
	s_add_i32 m0, s33, 0x16000
	s_add_u32 s24, s10, s8
	s_addc_u32 s25, s5, s9
	s_add_i32 s34, s33, 0x2000
	global_load_lds_dwordx4 v136, s[6:7]
	s_mov_b32 m0, s33
	s_add_u32 s6, s24, 0x160000
	global_load_lds_dwordx4 v134, s[24:25]
	s_mov_b32 m0, s34
	s_addc_u32 s7, s25, 0
	s_add_i32 s35, s33, 0x4000
	global_load_lds_dwordx4 v136, s[24:25]
	s_mov_b32 m0, s35
	s_add_i32 s90, s33, 0x6000
	global_load_lds_dwordx4 v134, s[6:7]
	s_mov_b32 m0, s90
	v_mov_b32_e32 v137, v135
	global_load_lds_dwordx4 v136, s[6:7]
	s_cmp_eq_u32 s2, 1
	s_mov_b32 s91, 0
	v_lshl_add_u64 v[8:9], s[0:1], 0, v[134:135]
	v_lshl_add_u64 v[6:7], s[0:1], 0, v[136:137]
	v_lshl_add_u64 v[2:3], s[24:25], 0, v[134:135]
	s_cselect_b64 s[56:57], -1, 0
	s_cmp_lg_u32 s2, 1
	v_lshl_add_u64 v[4:5], s[24:25], 0, v[136:137]
	s_cbranch_scc1 .LBB0_1373
	s_barrier
	s_setprio 1

.LBB0_1392:
	ds_read_b128 v[130:133], v196
	ds_read_b128 v[160:163], v196 offset:1024
	ds_read_b128 v[170:173], v196 offset:2048
	ds_read_b128 v[174:177], v196 offset:3072
	ds_read_b128 v[178:181], v197
	ds_read_b128 v[182:185], v197 offset:1024
	ds_read_b128 v[186:189], v197 offset:2048
	ds_read_b128 v[190:193], v197 offset:3072
	s_add_i32 s69, s22, 2
	s_add_u32 s0, s88, 0xffea0080
	s_addc_u32 s1, s89, -1
	s_cmp_eq_u32 s68, s22
	s_cselect_b32 s22, s12, s0
	s_cselect_b32 s23, s13, s1
	s_cselect_b32 s1, s15, s25
	s_cselect_b32 s0, s14, s24
	v_lshl_add_u64 v[194:195], s[88:89], 0, v[154:155]
	s_add_i32 m0, s33, 0xc000
	ds_read_b128 v[200:203], v198
	ds_read_b128 v[204:207], v198 offset:1024
	ds_read_b128 v[208:211], v198 offset:2048
	ds_read_b128 v[212:215], v198 offset:3072
	ds_read_b128 v[216:219], v198 offset:4096
	ds_read_b128 v[220:223], v198 offset:5120
	ds_read_b128 v[224:227], v198 offset:6144
	ds_read_b128 v[228:231], v198 offset:7168
	global_load_lds_dwordx4 v[194:195], off
	v_lshl_add_u64 v[194:195], s[88:89], 0, v[156:157]
	s_add_i32 m0, s33, 0xe000
	s_nop 0
	global_load_lds_dwordx4 v[194:195], off
	s_waitcnt vmcnt(8)
	s_waitcnt lgkmcnt(0)
	s_barrier
	s_waitcnt lgkmcnt(0)
	v_mfma_f32_16x16x32_bf16 v[126:129], v[130:133], v[200:203], v[126:129]
	v_mfma_f32_16x16x32_bf16 v[94:97], v[170:173], v[200:203], v[94:97]
	v_mfma_f32_16x16x32_bf16 v[122:125], v[130:133], v[208:211], v[122:125]
	v_mfma_f32_16x16x32_bf16 v[90:93], v[170:173], v[208:211], v[90:93]
	v_mfma_f32_16x16x32_bf16 v[118:121], v[130:133], v[216:219], v[118:121]
	v_mfma_f32_16x16x32_bf16 v[86:89], v[170:173], v[216:219], v[86:89]
	v_mfma_f32_16x16x32_bf16 v[114:117], v[130:133], v[224:227], v[114:117]
	v_mfma_f32_16x16x32_bf16 v[82:85], v[170:173], v[224:227], v[82:85]
	v_mfma_f32_16x16x32_bf16 v[126:129], v[160:163], v[204:207], v[126:129]
	v_mfma_f32_16x16x32_bf16 v[94:97], v[174:177], v[204:207], v[94:97]
	v_mfma_f32_16x16x32_bf16 v[122:125], v[160:163], v[212:215], v[122:125]
	v_mfma_f32_16x16x32_bf16 v[90:93], v[174:177], v[212:215], v[90:93]
	v_mfma_f32_16x16x32_bf16 v[118:121], v[160:163], v[220:223], v[118:121]
	v_mfma_f32_16x16x32_bf16 v[86:89], v[174:177], v[220:223], v[86:89]
	v_mfma_f32_16x16x32_bf16 v[114:117], v[160:163], v[228:231], v[114:117]
	v_mfma_f32_16x16x32_bf16 v[82:85], v[174:177], v[228:231], v[82:85]
	v_mfma_f32_16x16x32_bf16 v[62:65], v[178:181], v[200:203], v[62:65]
	v_mfma_f32_16x16x32_bf16 v[30:33], v[186:189], v[200:203], v[30:33]
	v_mfma_f32_16x16x32_bf16 v[58:61], v[178:181], v[208:211], v[58:61]
	v_mfma_f32_16x16x32_bf16 v[26:29], v[186:189], v[208:211], v[26:29]
	v_mfma_f32_16x16x32_bf16 v[54:57], v[178:181], v[216:219], v[54:57]
	v_mfma_f32_16x16x32_bf16 v[22:25], v[186:189], v[216:219], v[22:25]
	v_mfma_f32_16x16x32_bf16 v[50:53], v[178:181], v[224:227], v[50:53]
	v_mfma_f32_16x16x32_bf16 v[18:21], v[186:189], v[224:227], v[18:21]
	v_mfma_f32_16x16x32_bf16 v[62:65], v[182:185], v[204:207], v[62:65]
	v_mfma_f32_16x16x32_bf16 v[30:33], v[190:193], v[204:207], v[30:33]
	v_mfma_f32_16x16x32_bf16 v[58:61], v[182:185], v[212:215], v[58:61]
	v_mfma_f32_16x16x32_bf16 v[26:29], v[190:193], v[212:215], v[26:29]
	v_mfma_f32_16x16x32_bf16 v[54:57], v[182:185], v[220:223], v[54:57]
	v_mfma_f32_16x16x32_bf16 v[22:25], v[190:193], v[220:223], v[22:25]
	v_mfma_f32_16x16x32_bf16 v[50:53], v[182:185], v[228:231], v[50:53]
	v_mfma_f32_16x16x32_bf16 v[18:21], v[190:193], v[228:231], v[18:21]
	s_barrier
	s_add_i32 s21, s4, s31
	v_lshl_add_u64 v[194:195], s[0:1], 0, v[134:135]
	s_mov_b32 m0, s21
	ds_read_b128 v[200:203], v198 offset:16384
	ds_read_b128 v[204:207], v198 offset:17408
	ds_read_b128 v[208:211], v198 offset:18432
	ds_read_b128 v[212:215], v198 offset:19456
	ds_read_b128 v[216:219], v198 offset:20480
	ds_read_b128 v[220:223], v198 offset:21504
	ds_read_b128 v[224:227], v198 offset:22528
	ds_read_b128 v[228:231], v198 offset:23552
	global_load_lds_dwordx4 v[194:195], off
	s_add_i32 m0, s21, 0x2000
	s_add_u32 s28, s0, 0x160000
	v_lshl_add_u64 v[232:233], s[0:1], 0, v[136:137]
	s_addc_u32 s29, s1, 0
	s_add_i32 s21, s5, s31
	global_load_lds_dwordx4 v[232:233], off
	v_lshl_add_u64 v[234:235], s[28:29], 0, v[134:135]
	s_mov_b32 m0, s21
	v_lshl_add_u64 v[236:237], s[22:23], 0, v[136:137]
	global_load_lds_dwordx4 v[234:235], off
	v_lshl_add_u64 v[234:235], s[28:29], 0, v[136:137]
	s_add_i32 m0, s21, 0x2000
	s_nop 0
	global_load_lds_dwordx4 v[234:235], off
	v_lshl_add_u64 v[234:235], s[22:23], 0, v[134:135]
	s_mov_b32 m0, s33
	s_nop 0
	global_load_lds_dwordx4 v[234:235], off
	s_mov_b32 m0, s34
	s_nop 0
	global_load_lds_dwordx4 v[236:237], off
	s_waitcnt vmcnt(8)
	s_waitcnt lgkmcnt(0)
	s_barrier
	s_waitcnt lgkmcnt(0)
	v_mfma_f32_16x16x32_bf16 v[110:113], v[130:133], v[200:203], v[110:113]
	v_mfma_f32_16x16x32_bf16 v[78:81], v[170:173], v[200:203], v[78:81]
	v_mfma_f32_16x16x32_bf16 v[106:109], v[130:133], v[208:211], v[106:109]
	v_mfma_f32_16x16x32_bf16 v[74:77], v[170:173], v[208:211], v[74:77]
	v_mfma_f32_16x16x32_bf16 v[102:105], v[130:133], v[216:219], v[102:105]
	v_mfma_f32_16x16x32_bf16 v[70:73], v[170:173], v[216:219], v[70:73]
	v_mfma_f32_16x16x32_bf16 v[98:101], v[130:133], v[224:227], v[98:101]
	v_mfma_f32_16x16x32_bf16 v[66:69], v[170:173], v[224:227], v[66:69]
	v_mfma_f32_16x16x32_bf16 v[110:113], v[160:163], v[204:207], v[110:113]
	v_mfma_f32_16x16x32_bf16 v[78:81], v[174:177], v[204:207], v[78:81]
	v_mfma_f32_16x16x32_bf16 v[106:109], v[160:163], v[212:215], v[106:109]
	v_mfma_f32_16x16x32_bf16 v[74:77], v[174:177], v[212:215], v[74:77]
	v_mfma_f32_16x16x32_bf16 v[102:105], v[160:163], v[220:223], v[102:105]
	v_mfma_f32_16x16x32_bf16 v[70:73], v[174:177], v[220:223], v[70:73]
	v_mfma_f32_16x16x32_bf16 v[98:101], v[160:163], v[228:231], v[98:101]
	v_mfma_f32_16x16x32_bf16 v[66:69], v[174:177], v[228:231], v[66:69]
	v_mfma_f32_16x16x32_bf16 v[46:49], v[178:181], v[200:203], v[46:49]
	v_mfma_f32_16x16x32_bf16 v[14:17], v[186:189], v[200:203], v[14:17]
	v_mfma_f32_16x16x32_bf16 v[42:45], v[178:181], v[208:211], v[42:45]
	v_mfma_f32_16x16x32_bf16 v[10:13], v[186:189], v[208:211], v[10:13]
	v_mfma_f32_16x16x32_bf16 v[38:41], v[178:181], v[216:219], v[38:41]
	v_mfma_f32_16x16x32_bf16 v[6:9], v[186:189], v[216:219], v[6:9]
	v_mfma_f32_16x16x32_bf16 v[34:37], v[178:181], v[224:227], v[34:37]
	v_mfma_f32_16x16x32_bf16 v[2:5], v[186:189], v[224:227], v[2:5]
	v_mfma_f32_16x16x32_bf16 v[46:49], v[182:185], v[204:207], v[46:49]
	v_mfma_f32_16x16x32_bf16 v[14:17], v[190:193], v[204:207], v[14:17]
	v_mfma_f32_16x16x32_bf16 v[42:45], v[182:185], v[212:215], v[42:45]
	v_mfma_f32_16x16x32_bf16 v[10:13], v[190:193], v[212:215], v[10:13]
	v_mfma_f32_16x16x32_bf16 v[38:41], v[182:185], v[220:223], v[38:41]
	v_mfma_f32_16x16x32_bf16 v[6:9], v[190:193], v[220:223], v[6:9]
	v_mfma_f32_16x16x32_bf16 v[34:37], v[182:185], v[228:231], v[34:37]
	v_mfma_f32_16x16x32_bf16 v[2:5], v[190:193], v[228:231], v[2:5]
	s_barrier
	s_add_i32 s21, 0, 0x18000
	s_add_i32 s28, 0, 0x1c000
	v_add_u32_e32 v174, s21, v165
	v_add_u32_e32 v190, s28, v165
	ds_read_b128 v[130:133], v174
	ds_read_b128 v[160:163], v174 offset:1024
	ds_read_b128 v[170:173], v174 offset:2048
	ds_read_b128 v[174:177], v174 offset:3072
	ds_read_b128 v[178:181], v190
	ds_read_b128 v[182:185], v190 offset:1024
	ds_read_b128 v[186:189], v190 offset:2048
	ds_read_b128 v[190:193], v190 offset:3072
	s_add_u32 s22, s22, 0x160000
	s_addc_u32 s23, s23, 0
	s_mov_b32 m0, s35
	v_lshl_add_u64 v[238:239], s[22:23], 0, v[134:135]
	ds_read_b128 v[200:203], v198 offset:32768
	ds_read_b128 v[204:207], v198 offset:33792
	ds_read_b128 v[208:211], v198 offset:34816
	ds_read_b128 v[212:215], v198 offset:35840
	ds_read_b128 v[216:219], v198 offset:36864
	ds_read_b128 v[220:223], v198 offset:37888
	ds_read_b128 v[224:227], v198 offset:38912
	ds_read_b128 v[228:231], v198 offset:39936
	global_load_lds_dwordx4 v[238:239], off
	v_lshl_add_u64 v[238:239], s[22:23], 0, v[136:137]
	s_mov_b32 m0, s90
	s_nop 0
	global_load_lds_dwordx4 v[238:239], off
	s_waitcnt vmcnt(8)
	s_waitcnt lgkmcnt(0)
	s_barrier
	s_waitcnt lgkmcnt(0)
	v_mfma_f32_16x16x32_bf16 v[126:129], v[130:133], v[200:203], v[126:129]
	v_mfma_f32_16x16x32_bf16 v[94:97], v[170:173], v[200:203], v[94:97]
	v_mfma_f32_16x16x32_bf16 v[122:125], v[130:133], v[208:211], v[122:125]
	v_mfma_f32_16x16x32_bf16 v[90:93], v[170:173], v[208:211], v[90:93]
	v_mfma_f32_16x16x32_bf16 v[118:121], v[130:133], v[216:219], v[118:121]
	v_mfma_f32_16x16x32_bf16 v[86:89], v[170:173], v[216:219], v[86:89]
	v_mfma_f32_16x16x32_bf16 v[114:117], v[130:133], v[224:227], v[114:117]
	v_mfma_f32_16x16x32_bf16 v[82:85], v[170:173], v[224:227], v[82:85]
	v_mfma_f32_16x16x32_bf16 v[126:129], v[160:163], v[204:207], v[126:129]
	v_mfma_f32_16x16x32_bf16 v[94:97], v[174:177], v[204:207], v[94:97]
	v_mfma_f32_16x16x32_bf16 v[122:125], v[160:163], v[212:215], v[122:125]
	v_mfma_f32_16x16x32_bf16 v[90:93], v[174:177], v[212:215], v[90:93]
	v_mfma_f32_16x16x32_bf16 v[118:121], v[160:163], v[220:223], v[118:121]
	v_mfma_f32_16x16x32_bf16 v[86:89], v[174:177], v[220:223], v[86:89]
	v_mfma_f32_16x16x32_bf16 v[114:117], v[160:163], v[228:231], v[114:117]
	v_mfma_f32_16x16x32_bf16 v[82:85], v[174:177], v[228:231], v[82:85]
	v_mfma_f32_16x16x32_bf16 v[62:65], v[178:181], v[200:203], v[62:65]
	v_mfma_f32_16x16x32_bf16 v[30:33], v[186:189], v[200:203], v[30:33]
	v_mfma_f32_16x16x32_bf16 v[58:61], v[178:181], v[208:211], v[58:61]
	v_mfma_f32_16x16x32_bf16 v[26:29], v[186:189], v[208:211], v[26:29]
	v_mfma_f32_16x16x32_bf16 v[54:57], v[178:181], v[216:219], v[54:57]
	v_mfma_f32_16x16x32_bf16 v[22:25], v[186:189], v[216:219], v[22:25]
	v_mfma_f32_16x16x32_bf16 v[50:53], v[178:181], v[224:227], v[50:53]
	v_mfma_f32_16x16x32_bf16 v[18:21], v[186:189], v[224:227], v[18:21]
	v_mfma_f32_16x16x32_bf16 v[62:65], v[182:185], v[204:207], v[62:65]
	v_mfma_f32_16x16x32_bf16 v[30:33], v[190:193], v[204:207], v[30:33]
	v_mfma_f32_16x16x32_bf16 v[58:61], v[182:185], v[212:215], v[58:61]
	v_mfma_f32_16x16x32_bf16 v[26:29], v[190:193], v[212:215], v[26:29]
	v_mfma_f32_16x16x32_bf16 v[54:57], v[182:185], v[220:223], v[54:57]
	v_mfma_f32_16x16x32_bf16 v[22:25], v[190:193], v[220:223], v[22:25]
	v_mfma_f32_16x16x32_bf16 v[50:53], v[182:185], v[228:231], v[50:53]
	v_mfma_f32_16x16x32_bf16 v[18:21], v[190:193], v[228:231], v[18:21]
	s_barrier
	s_add_i32 s21, s21, s31
	v_lshl_add_u64 v[194:195], v[194:195], 0, s[8:9]
	s_mov_b32 m0, s21
	ds_read_b128 v[200:203], v198 offset:49152
	ds_read_b128 v[204:207], v198 offset:50176
	ds_read_b128 v[208:211], v198 offset:51200
	ds_read_b128 v[212:215], v198 offset:52224
	ds_read_b128 v[216:219], v198 offset:53248
	ds_read_b128 v[220:223], v198 offset:54272
	ds_read_b128 v[224:227], v198 offset:55296
	ds_read_b128 v[228:231], v198 offset:56320
	global_load_lds_dwordx4 v[194:195], off
	s_add_i32 m0, s21, 0x2000
	s_add_u32 s0, s0, 0x160080
	v_lshl_add_u64 v[194:195], v[232:233], 0, s[8:9]
	s_addc_u32 s1, s1, 0
	s_add_i32 s21, s28, s31
	global_load_lds_dwordx4 v[194:195], off
	v_lshl_add_u64 v[194:195], s[0:1], 0, v[134:135]
	s_mov_b32 m0, s21
	s_nop 0
	global_load_lds_dwordx4 v[194:195], off
	v_lshl_add_u64 v[194:195], s[0:1], 0, v[136:137]
	s_add_i32 m0, s21, 0x2000
	s_nop 0
	global_load_lds_dwordx4 v[194:195], off
	v_lshl_add_u64 v[194:195], v[234:235], 0, s[8:9]
	s_mov_b32 m0, s94
	s_nop 0
	global_load_lds_dwordx4 v[194:195], off
	v_lshl_add_u64 v[194:195], v[236:237], 0, s[8:9]
	s_mov_b32 m0, s95
	s_nop 0
	global_load_lds_dwordx4 v[194:195], off
	s_waitcnt vmcnt(8)
	s_waitcnt lgkmcnt(0)
	s_barrier
	s_waitcnt lgkmcnt(0)
	v_mfma_f32_16x16x32_bf16 v[110:113], v[130:133], v[200:203], v[110:113]
	v_mfma_f32_16x16x32_bf16 v[78:81], v[170:173], v[200:203], v[78:81]
	v_mfma_f32_16x16x32_bf16 v[106:109], v[130:133], v[208:211], v[106:109]
	v_mfma_f32_16x16x32_bf16 v[74:77], v[170:173], v[208:211], v[74:77]
	v_mfma_f32_16x16x32_bf16 v[102:105], v[130:133], v[216:219], v[102:105]
	v_mfma_f32_16x16x32_bf16 v[70:73], v[170:173], v[216:219], v[70:73]
	v_mfma_f32_16x16x32_bf16 v[98:101], v[130:133], v[224:227], v[98:101]
	v_mfma_f32_16x16x32_bf16 v[66:69], v[170:173], v[224:227], v[66:69]
	v_mfma_f32_16x16x32_bf16 v[110:113], v[160:163], v[204:207], v[110:113]
	v_mfma_f32_16x16x32_bf16 v[78:81], v[174:177], v[204:207], v[78:81]
	v_mfma_f32_16x16x32_bf16 v[106:109], v[160:163], v[212:215], v[106:109]
	v_mfma_f32_16x16x32_bf16 v[74:77], v[174:177], v[212:215], v[74:77]
	v_mfma_f32_16x16x32_bf16 v[102:105], v[160:163], v[220:223], v[102:105]
	v_mfma_f32_16x16x32_bf16 v[70:73], v[174:177], v[220:223], v[70:73]
	v_mfma_f32_16x16x32_bf16 v[98:101], v[160:163], v[228:231], v[98:101]
	v_mfma_f32_16x16x32_bf16 v[66:69], v[174:177], v[228:231], v[66:69]
	v_mfma_f32_16x16x32_bf16 v[46:49], v[178:181], v[200:203], v[46:49]
	v_mfma_f32_16x16x32_bf16 v[14:17], v[186:189], v[200:203], v[14:17]
	v_mfma_f32_16x16x32_bf16 v[42:45], v[178:181], v[208:211], v[42:45]
	v_mfma_f32_16x16x32_bf16 v[10:13], v[186:189], v[208:211], v[10:13]
	v_mfma_f32_16x16x32_bf16 v[38:41], v[178:181], v[216:219], v[38:41]
	v_mfma_f32_16x16x32_bf16 v[6:9], v[186:189], v[216:219], v[6:9]
	v_mfma_f32_16x16x32_bf16 v[34:37], v[178:181], v[224:227], v[34:37]
	v_mfma_f32_16x16x32_bf16 v[2:5], v[186:189], v[224:227], v[2:5]
	v_mfma_f32_16x16x32_bf16 v[46:49], v[182:185], v[204:207], v[46:49]
	v_mfma_f32_16x16x32_bf16 v[14:17], v[190:193], v[204:207], v[14:17]
	v_mfma_f32_16x16x32_bf16 v[42:45], v[182:185], v[212:215], v[42:45]
	v_mfma_f32_16x16x32_bf16 v[10:13], v[190:193], v[212:215], v[10:13]
	v_mfma_f32_16x16x32_bf16 v[38:41], v[182:185], v[220:223], v[38:41]
	v_mfma_f32_16x16x32_bf16 v[6:9], v[190:193], v[220:223], v[6:9]
	v_mfma_f32_16x16x32_bf16 v[34:37], v[182:185], v[228:231], v[34:37]
	v_mfma_f32_16x16x32_bf16 v[2:5], v[190:193], v[228:231], v[2:5]
	s_barrier
	s_add_u32 s88, s88, 0x100
	s_addc_u32 s89, s89, 0
	s_add_u32 s24, s24, 0x100
	s_addc_u32 s25, s25, 0
	s_cmp_ge_u32 s69, s19
	s_mov_b32 s22, s69
	s_cbranch_scc0 .LBB0_1392
	s_and_b64 vcc, exec, s[10:11]
	s_cbranch_vccz .LBB0_1395
	s_barrier

.LBB0_1457:
	s_setprio 0
	v_readlane_b32 s2, v243, 51
	v_readlane_b32 s3, v243, 52
	s_cmp_lt_i32 s2, 18
	s_cselect_b64 s[2:3], -1, 0
	s_and_b64 s[0:1], s[2:3], s[0:1]
	s_andn2_b64 vcc, exec, s[0:1]
	s_cbranch_vccnz .LBB0_1510
	s_movk_i32 s0, 0x800
	v_cmp_gt_i32_e32 vcc, s0, v168
	s_and_saveexec_b64 s[0:1], vcc
	s_cbranch_execz .LBB0_1461
	v_readlane_b32 s4, v243, 33
	v_readlane_b32 s6, v243, 35
	v_readlane_b32 s5, v243, 34
	v_readlane_b32 s7, v243, 36
	s_add_u32 s4, s6, 0x2000
	v_readlane_b32 s8, v243, 37
	s_addc_u32 s5, s7, 0
	s_add_u32 s6, s90, 0x880000
	v_readlane_b32 s8, v243, 53
	v_readlane_b32 s9, v243, 38
	s_addc_u32 s7, s91, 0
	s_lshl_b32 s8, s8, 9
	v_readlane_b32 s10, v243, 39
	v_readlane_b32 s11, v243, 40
	v_readlane_b32 s12, v243, 41
	v_readlane_b32 s13, v243, 42
	v_readlane_b32 s14, v243, 43
	v_readlane_b32 s15, v243, 44
	v_readlane_b32 s16, v243, 45
	v_readlane_b32 s17, v243, 46
	v_readlane_b32 s18, v243, 47
	v_readlane_b32 s19, v243, 48
	v_ashrrev_i32_e32 v169, 31, v168
	s_ashr_i32 s9, s8, 31
	v_lshlrev_b64 v[2:3], 2, v[168:169]
	s_lshl_b64 s[10:11], s[8:9], 2
	s_mov_b64 s[12:13], 0
	s_mov_b32 s9, 0xbfb8aa3b
	s_mov_b32 s14, 0x42ce8ed0
	s_mov_b32 s15, 0xc2b17218
	s_mov_b32 s16, 0x7f800000
	v_mov_b32_e32 v6, 0x7f800000
	s_mov_b32 s17, 0x3f2aaaab
	v_mov_b32_e32 v7, 0x3ecc95a3
	s_mov_b32 s18, 0x3f317218
	s_mov_b32 s19, 0x33800000
	s_movk_i32 s20, 0x7ff
	v_mov_b32_e32 v4, 0x3f317218

.LBB0_1564:
	s_setprio 0
	v_readlane_b32 s2, v243, 51
	s_cmp_lt_i32 s2, 19
	s_cselect_b64 s[4:5], -1, 0
	s_and_b64 s[0:1], s[4:5], s[0:1]
	s_andn2_b64 vcc, exec, s[0:1]
	v_readlane_b32 s3, v243, 52
	s_cbranch_vccnz .LBB0_1574
	v_readlane_b32 s0, v243, 0
	s_lshl_b32 s0, s0, 3
	v_readlane_b32 s1, v243, 59
	s_add_i32 s6, s1, s0
	s_cmp_gt_i32 s6, 0x81ff
	s_cbranch_scc1 .LBB0_1574
	v_mbcnt_lo_u32_b32 v2, -1, 0
	v_mbcnt_hi_u32_b32 v2, -1, v2
	v_and_b32_e32 v3, 64, v2
	v_add_u32_e32 v3, 64, v3
	v_xor_b32_e32 v4, 1, v2
	v_cmp_lt_i32_e32 vcc, v4, v3
	v_readlane_b32 s16, v243, 1
	v_readlane_b32 s0, v243, 53
	v_cndmask_b32_e32 v4, v2, v4, vcc
	v_lshlrev_b32_e32 v165, 2, v4
	v_xor_b32_e32 v4, 2, v2
	v_cmp_lt_i32_e32 vcc, v4, v3
	v_readlane_b32 s17, v243, 2
	v_readlane_b32 s28, v243, 13
	v_cndmask_b32_e32 v4, v2, v4, vcc
	v_lshlrev_b32_e32 v178, 2, v4
	v_xor_b32_e32 v4, 4, v2
	v_cmp_lt_i32_e32 vcc, v4, v3
	v_readlane_b32 s29, v243, 14
	s_lshl_b32 s12, s0, 3
	v_cndmask_b32_e32 v4, v2, v4, vcc
	v_lshlrev_b32_e32 v179, 2, v4
	v_xor_b32_e32 v4, 8, v2
	v_cmp_lt_i32_e32 vcc, v4, v3
	s_mov_b64 s[16:17], s[28:29]
	s_add_u32 s0, s16, 0x6000
	v_cndmask_b32_e32 v4, v2, v4, vcc
	v_lshlrev_b32_e32 v180, 2, v4
	v_xor_b32_e32 v4, 16, v2
	v_cmp_lt_i32_e32 vcc, v4, v3
	v_mov_b32_e32 v131, 0
	s_addc_u32 s1, s17, 0
	v_cndmask_b32_e32 v4, v2, v4, vcc
	v_lshlrev_b32_e32 v181, 2, v4
	v_xor_b32_e32 v4, 32, v2
	v_cmp_lt_i32_e32 vcc, v4, v3
	v_mov_b32_e32 v7, v131
	v_mov_b32_e32 v9, v131
	v_cndmask_b32_e32 v2, v2, v4, vcc
	v_lshlrev_b32_e32 v182, 2, v2
	v_lshlrev_b32_e32 v2, 2, v166
	v_or_b32_e32 v4, 0x100, v2
	v_lshlrev_b32_e32 v6, 2, v4
	v_lshl_add_u64 v[134:135], s[0:1], 0, v[6:7]
	v_or_b32_e32 v6, 0x200, v2
	v_lshlrev_b32_e32 v8, 2, v6
	v_lshl_add_u64 v[136:137], s[0:1], 0, v[8:9]
	v_or_b32_e32 v8, 0x300, v2
	v_lshlrev_b32_e32 v10, 2, v8
	v_mov_b32_e32 v11, v131
	v_lshl_add_u64 v[138:139], s[0:1], 0, v[10:11]
	v_or_b32_e32 v10, 0x400, v2
	v_lshlrev_b32_e32 v12, 2, v10
	v_mov_b32_e32 v13, v131
	v_lshl_add_u64 v[140:141], s[0:1], 0, v[12:13]
	v_or_b32_e32 v12, 0x500, v2
	v_lshlrev_b32_e32 v14, 2, v12
	v_mov_b32_e32 v15, v131
	v_lshl_add_u64 v[142:143], s[0:1], 0, v[14:15]
	v_or_b32_e32 v14, 0x600, v2
	v_lshlrev_b32_e32 v16, 2, v14
	v_mov_b32_e32 v17, v131
	v_lshl_add_u64 v[144:145], s[0:1], 0, v[16:17]
	v_or_b32_e32 v16, 0x700, v2
	v_lshlrev_b32_e32 v130, 4, v166
	s_waitcnt vmcnt(0)
	v_lshlrev_b32_e32 v18, 2, v16
	v_mov_b32_e32 v19, v131
	v_lshl_add_u64 v[132:133], s[0:1], 0, v[130:131]
	v_lshl_add_u64 v[146:147], s[0:1], 0, v[18:19]
	v_readlane_b32 s0, v242, 19
	v_readlane_b32 s1, v242, 20
	v_readlane_b32 s18, v243, 3
	v_readlane_b32 s19, v243, 4
	v_lshl_add_u64 v[148:149], s[0:1], 0, v[130:131]
	v_readlane_b32 s0, v242, 15
	v_readlane_b32 s20, v243, 5
	v_readlane_b32 s22, v243, 7
	s_add_u32 s13, s90, 0x100000
	v_lshlrev_b32_e32 v18, 3, v166
	v_readlane_b32 s1, v242, 16
	s_addc_u32 s14, s91, 0
	s_mov_b32 s9, 0
	v_lshl_add_u64 v[150:151], s[0:1], 0, v[18:19]
	v_lshl_add_u64 v[152:153], s[90:91], 0, v[130:131]
	s_add_i32 s10, s6, 0xffff8000
	s_mov_b32 s15, 0x12000
	v_lshlrev_b32_e32 v130, 4, v166
	s_movk_i32 s16, 0x1000
	v_lshlrev_b32_e32 v183, 2, v2
	v_lshlrev_b32_e32 v184, 2, v4
	v_lshlrev_b32_e32 v185, 2, v6
	v_lshlrev_b32_e32 v186, 2, v8
	v_lshlrev_b32_e32 v187, 2, v10
	v_lshlrev_b32_e32 v188, 2, v12
	v_lshlrev_b32_e32 v189, 2, v14
	v_lshlrev_b32_e32 v190, 2, v16
	s_movk_i32 s17, 0x7fff
	s_mov_b32 s18, 0x2e100000
	s_mov_b32 s19, 0x2e101000
	v_mov_b32_e32 v191, 0x358637bd
	s_mov_b32 s20, 0xf800000
	v_mov_b32_e32 v192, 0x260
	s_mov_b32 s22, 0xffff0000
	v_readlane_b32 s21, v243, 6
	v_readlane_b32 s23, v243, 8
	v_readlane_b32 s24, v243, 9
	v_readlane_b32 s25, v243, 10
	v_readlane_b32 s26, v243, 11
	v_readlane_b32 s27, v243, 12
	v_readlane_b32 s30, v243, 15
	v_readlane_b32 s31, v243, 16
	s_branch .LBB0_1568

.LBB0_1628:
	s_setprio 0
	v_readlane_b32 s2, v243, 51
	s_cmp_lt_i32 s2, 20
	s_cselect_b64 s[4:5], -1, 0
	s_and_b64 s[0:1], s[4:5], s[0:1]
	s_andn2_b64 vcc, exec, s[0:1]
	v_readlane_b32 s3, v243, 52
	s_cbranch_vccnz .LBB0_1645
	v_readlane_b32 s0, v243, 0
	s_cmpk_gt_i32 s0, 0x1657
	v_readfirstlane_b32 s3, v0
	s_cbranch_scc1 .LBB0_1645
	v_lshrrev_b32_e32 v2, 5, v0
	v_lshrrev_b32_e32 v4, 1, v0
	v_and_b32_e32 v2, 4, v2
	v_bfe_u32 v3, v0, 2, 2
	v_and_b32_e32 v13, 24, v4
	v_or3_b32 v2, v2, v3, v13
	v_lshlrev_b32_e32 v3, 4, v0
	v_or_b32_e32 v10, 0x2000, v3
	v_lshrrev_b32_e32 v4, 7, v10
	s_movk_i32 s0, 0x60
	v_readlane_b32 s2, v243, 0
	v_and_or_b32 v5, v4, s0, v2
	v_bfe_u32 v14, v0, 2, 4
	s_movk_i32 s0, 0x70
	s_ashr_i32 s24, s2, 31
	v_and_or_b32 v4, v4, s0, v14
	s_lshr_b32 s0, s24, 29
	s_add_i32 s0, s2, s0
	s_lshr_b32 s8, s3, 6
	s_ashr_i32 s1, s0, 3
	s_and_b32 s0, s0, -8
	s_lshr_b32 s10, s3, 8
	s_lshl_b32 s20, s8, 10
	s_sub_i32 s0, s2, s0
	s_cmp_lt_i32 s0, 0
	s_movk_i32 s25, 0x2cc
	s_cselect_b32 s2, s25, 0x2cb
	s_mul_i32 s0, s2, s0
	s_add_i32 s0, s0, s1
	s_mul_hi_i32 s1, s0, 0x2e8ba2e9
	s_lshr_b32 s2, s1, 31
	s_ashr_i32 s1, s1, 6
	v_and_b32_e32 v6, 32, v0
	s_add_i32 s1, s1, s2
	v_bitop3_b32 v11, v3, v6, 48 bitop3:0x6c
	v_and_b32_e32 v12, 64, v0
	s_lshl_b32 s6, s1, 3
	v_or_b32_e32 v3, v11, v12
	s_sub_i32 s2, 0x82, s6
	s_mulk_i32 s1, 0x160
	v_lshl_or_b32 v132, v4, 12, v3
	v_lshrrev_b32_e32 v4, 3, v0
	s_min_u32 s7, s2, 8
	s_sub_i32 s9, s0, s1
	v_lshl_or_b32 v130, v5, 12, v3
	v_and_or_b32 v2, v4, 32, v2
	s_sext_i32_i16 s0, s9
	v_cvt_f32_ubyte0_e32 v5, s7
	v_lshl_or_b32 v134, v2, 12, v3
	v_and_or_b32 v2, v4, 48, v14
	v_cvt_f32_i32_e32 v4, s0
	v_rcp_iflag_f32_e32 v6, v5
	v_lshl_or_b32 v136, v2, 12, v3
	s_ashr_i32 s0, s0, 30
	s_or_b32 s2, s0, 1
	v_mul_f32_e32 v2, v4, v6
	v_trunc_f32_e32 v2, v2
	v_fma_f32 v3, -v2, v5, v4
	v_cvt_i32_f32_e32 v2, v2
	v_cmp_ge_f32_e64 s[0:1], |v3|, v5
	s_and_b64 s[0:1], s[0:1], exec
	s_cselect_b32 s0, s2, 0
	v_readfirstlane_b32 s1, v2
	s_add_i32 s2, s1, s0
	s_mul_i32 s0, s2, s7
	s_sub_i32 s0, s9, s0
	s_sext_i32_i16 s0, s0
	s_add_i32 s44, s6, s0
	s_ashr_i32 s45, s44, 31
	s_bfe_i64 s[0:1], s[2:3], 0x100000
	s_lshl_b64 s[6:7], s[44:45], 20
	s_lshl_b64 s[0:1], s[0:1], 20
	v_readlane_b32 s9, v243, 60
	s_add_u32 s0, s9, s0
	v_readlane_b32 s9, v243, 61
	s_addc_u32 s1, s9, s1
	s_add_i32 s26, s20, 0
	s_add_i32 m0, s26, 0x10000
	v_mov_b32_e32 v135, 0
	global_load_lds_dwordx4 v134, s[0:1]
	s_add_i32 m0, s26, 0x12000
	s_add_u32 s12, s0, 0x80000
	global_load_lds_dwordx4 v130, s[0:1]
	s_addc_u32 s13, s1, 0
	s_add_i32 m0, s26, 0x14000
	v_mov_b32_e32 v131, v135
	global_load_lds_dwordx4 v134, s[12:13]
	s_add_i32 m0, s26, 0x16000
	v_mov_b32_e32 v137, v135
	global_load_lds_dwordx4 v130, s[12:13]
	v_readlane_b32 s12, v242, 15
	v_readlane_b32 s13, v242, 16
	s_add_u32 s22, s12, s6
	s_addc_u32 s23, s13, s7
	s_add_i32 s27, s26, 0x2000
	s_mov_b32 m0, s26
	s_add_u32 s6, s22, 0x80000
	global_load_lds_dwordx4 v136, s[22:23]
	s_mov_b32 m0, s27
	s_addc_u32 s7, s23, 0
	s_add_i32 s30, s26, 0x4000
	global_load_lds_dwordx4 v132, s[22:23]
	s_mov_b32 m0, s30
	s_add_i32 s31, s26, 0x6000
	global_load_lds_dwordx4 v136, s[6:7]
	s_mov_b32 m0, s31
	v_mov_b32_e32 v133, v135
	global_load_lds_dwordx4 v132, s[6:7]
	s_cmp_eq_u32 s10, 1
	s_mov_b32 s33, 0
	v_lshl_add_u64 v[8:9], s[0:1], 0, v[134:135]
	v_lshl_add_u64 v[6:7], s[0:1], 0, v[130:131]
	v_lshl_add_u64 v[2:3], s[22:23], 0, v[136:137]
	s_cselect_b64 s[6:7], -1, 0
	s_cmp_lg_u32 s10, 1
	v_lshl_add_u64 v[4:5], s[22:23], 0, v[132:133]
	s_cbranch_scc1 .LBB0_1632
	s_barrier
	s_setprio 1

.LBB0_1638:
	ds_read_b128 v[146:149], v153
	ds_read_b128 v[156:159], v153 offset:1024
	ds_read_b128 v[160:163], v153 offset:2048
	ds_read_b128 v[168:171], v153 offset:3072
	ds_read_b128 v[172:175], v154
	ds_read_b128 v[176:179], v154 offset:1024
	ds_read_b128 v[180:183], v154 offset:2048
	ds_read_b128 v[184:187], v154 offset:3072
	s_add_u32 s0, s46, 0xfff80080
	s_addc_u32 s1, s47, -1
	s_cmp_eq_u32 s66, 28
	s_cselect_b32 s23, s15, s1
	s_cselect_b32 s22, s56, s0
	s_cselect_b32 s1, s13, s63
	s_cselect_b32 s0, s57, s62
	v_lshl_add_u64 v[220:221], s[46:47], 0, v[138:139]
	s_add_i32 m0, s26, 0xc000
	ds_read_b128 v[188:191], v155
	ds_read_b128 v[192:195], v155 offset:1024
	ds_read_b128 v[196:199], v155 offset:2048
	ds_read_b128 v[200:203], v155 offset:3072
	ds_read_b128 v[204:207], v155 offset:4096
	ds_read_b128 v[208:211], v155 offset:5120
	ds_read_b128 v[212:215], v155 offset:6144
	ds_read_b128 v[216:219], v155 offset:7168
	global_load_lds_dwordx4 v[220:221], off
	v_lshl_add_u64 v[220:221], s[46:47], 0, v[140:141]
	s_add_i32 m0, s26, 0xe000
	s_nop 0
	global_load_lds_dwordx4 v[220:221], off
	s_waitcnt vmcnt(8)
	s_waitcnt lgkmcnt(0)
	s_barrier
	s_waitcnt lgkmcnt(0)
	v_mfma_f32_16x16x32_bf16 v[126:129], v[146:149], v[188:191], v[126:129]
	v_mfma_f32_16x16x32_bf16 v[118:121], v[160:163], v[188:191], v[118:121]
	v_mfma_f32_16x16x32_bf16 v[110:113], v[146:149], v[196:199], v[110:113]
	v_mfma_f32_16x16x32_bf16 v[102:105], v[160:163], v[196:199], v[102:105]
	v_mfma_f32_16x16x32_bf16 v[94:97], v[146:149], v[204:207], v[94:97]
	v_mfma_f32_16x16x32_bf16 v[86:89], v[160:163], v[204:207], v[86:89]
	v_mfma_f32_16x16x32_bf16 v[78:81], v[146:149], v[212:215], v[78:81]
	v_mfma_f32_16x16x32_bf16 v[70:73], v[160:163], v[212:215], v[70:73]
	v_mfma_f32_16x16x32_bf16 v[126:129], v[156:159], v[192:195], v[126:129]
	v_mfma_f32_16x16x32_bf16 v[118:121], v[168:171], v[192:195], v[118:121]
	v_mfma_f32_16x16x32_bf16 v[110:113], v[156:159], v[200:203], v[110:113]
	v_mfma_f32_16x16x32_bf16 v[102:105], v[168:171], v[200:203], v[102:105]
	v_mfma_f32_16x16x32_bf16 v[94:97], v[156:159], v[208:211], v[94:97]
	v_mfma_f32_16x16x32_bf16 v[86:89], v[168:171], v[208:211], v[86:89]
	v_mfma_f32_16x16x32_bf16 v[78:81], v[156:159], v[216:219], v[78:81]
	v_mfma_f32_16x16x32_bf16 v[70:73], v[168:171], v[216:219], v[70:73]
	v_mfma_f32_16x16x32_bf16 v[122:125], v[172:175], v[188:191], v[122:125]
	v_mfma_f32_16x16x32_bf16 v[114:117], v[180:183], v[188:191], v[114:117]
	v_mfma_f32_16x16x32_bf16 v[106:109], v[172:175], v[196:199], v[106:109]
	v_mfma_f32_16x16x32_bf16 v[98:101], v[180:183], v[196:199], v[98:101]
	v_mfma_f32_16x16x32_bf16 v[90:93], v[172:175], v[204:207], v[90:93]
	v_mfma_f32_16x16x32_bf16 v[82:85], v[180:183], v[204:207], v[82:85]
	v_mfma_f32_16x16x32_bf16 v[74:77], v[172:175], v[212:215], v[74:77]
	v_mfma_f32_16x16x32_bf16 v[66:69], v[180:183], v[212:215], v[66:69]
	v_mfma_f32_16x16x32_bf16 v[122:125], v[176:179], v[192:195], v[122:125]
	v_mfma_f32_16x16x32_bf16 v[114:117], v[184:187], v[192:195], v[114:117]
	v_mfma_f32_16x16x32_bf16 v[106:109], v[176:179], v[200:203], v[106:109]
	v_mfma_f32_16x16x32_bf16 v[98:101], v[184:187], v[200:203], v[98:101]
	v_mfma_f32_16x16x32_bf16 v[90:93], v[176:179], v[208:211], v[90:93]
	v_mfma_f32_16x16x32_bf16 v[82:85], v[184:187], v[208:211], v[82:85]
	v_mfma_f32_16x16x32_bf16 v[74:77], v[176:179], v[216:219], v[74:77]
	v_mfma_f32_16x16x32_bf16 v[66:69], v[184:187], v[216:219], v[66:69]
	s_barrier
	s_add_i32 s21, s52, s20
	v_lshl_add_u64 v[220:221], s[0:1], 0, v[134:135]
	s_mov_b32 m0, s21
	ds_read_b128 v[188:191], v155 offset:16384
	ds_read_b128 v[192:195], v155 offset:17408
	ds_read_b128 v[196:199], v155 offset:18432
	ds_read_b128 v[200:203], v155 offset:19456
	ds_read_b128 v[204:207], v155 offset:20480
	ds_read_b128 v[208:211], v155 offset:21504
	ds_read_b128 v[212:215], v155 offset:22528
	ds_read_b128 v[216:219], v155 offset:23552
	global_load_lds_dwordx4 v[220:221], off
	s_add_i32 m0, s21, 0x2000
	s_add_u32 s28, s0, 0x80000
	v_lshl_add_u64 v[222:223], s[0:1], 0, v[130:131]
	s_addc_u32 s29, s1, 0
	s_add_i32 s21, s53, s20
	global_load_lds_dwordx4 v[222:223], off
	v_lshl_add_u64 v[224:225], s[28:29], 0, v[134:135]
	s_mov_b32 m0, s21
	v_lshl_add_u64 v[226:227], s[22:23], 0, v[132:133]
	global_load_lds_dwordx4 v[224:225], off
	v_lshl_add_u64 v[224:225], s[28:29], 0, v[130:131]
	s_add_i32 m0, s21, 0x2000
	s_nop 0
	global_load_lds_dwordx4 v[224:225], off
	v_lshl_add_u64 v[224:225], s[22:23], 0, v[136:137]
	s_mov_b32 m0, s26
	s_nop 0
	global_load_lds_dwordx4 v[224:225], off
	s_mov_b32 m0, s27
	s_nop 0
	global_load_lds_dwordx4 v[226:227], off
	s_waitcnt vmcnt(8)
	s_waitcnt lgkmcnt(0)
	s_barrier
	s_waitcnt lgkmcnt(0)
	v_mfma_f32_16x16x32_bf16 v[62:65], v[146:149], v[188:191], v[62:65]
	v_mfma_f32_16x16x32_bf16 v[54:57], v[160:163], v[188:191], v[54:57]
	v_mfma_f32_16x16x32_bf16 v[46:49], v[146:149], v[196:199], v[46:49]
	v_mfma_f32_16x16x32_bf16 v[38:41], v[160:163], v[196:199], v[38:41]
	v_mfma_f32_16x16x32_bf16 v[30:33], v[146:149], v[204:207], v[30:33]
	v_mfma_f32_16x16x32_bf16 v[22:25], v[160:163], v[204:207], v[22:25]
	v_mfma_f32_16x16x32_bf16 v[14:17], v[146:149], v[212:215], v[14:17]
	v_mfma_f32_16x16x32_bf16 v[6:9], v[160:163], v[212:215], v[6:9]
	v_mfma_f32_16x16x32_bf16 v[62:65], v[156:159], v[192:195], v[62:65]
	v_mfma_f32_16x16x32_bf16 v[54:57], v[168:171], v[192:195], v[54:57]
	v_mfma_f32_16x16x32_bf16 v[46:49], v[156:159], v[200:203], v[46:49]
	v_mfma_f32_16x16x32_bf16 v[38:41], v[168:171], v[200:203], v[38:41]
	v_mfma_f32_16x16x32_bf16 v[30:33], v[156:159], v[208:211], v[30:33]
	v_mfma_f32_16x16x32_bf16 v[22:25], v[168:171], v[208:211], v[22:25]
	v_mfma_f32_16x16x32_bf16 v[14:17], v[156:159], v[216:219], v[14:17]
	v_mfma_f32_16x16x32_bf16 v[6:9], v[168:171], v[216:219], v[6:9]
	v_mfma_f32_16x16x32_bf16 v[58:61], v[172:175], v[188:191], v[58:61]
	v_mfma_f32_16x16x32_bf16 v[50:53], v[180:183], v[188:191], v[50:53]
	v_mfma_f32_16x16x32_bf16 v[42:45], v[172:175], v[196:199], v[42:45]
	v_mfma_f32_16x16x32_bf16 v[34:37], v[180:183], v[196:199], v[34:37]
	v_mfma_f32_16x16x32_bf16 v[26:29], v[172:175], v[204:207], v[26:29]
	v_mfma_f32_16x16x32_bf16 v[18:21], v[180:183], v[204:207], v[18:21]
	v_mfma_f32_16x16x32_bf16 v[10:13], v[172:175], v[212:215], v[10:13]
	v_mfma_f32_16x16x32_bf16 v[2:5], v[180:183], v[212:215], v[2:5]
	v_mfma_f32_16x16x32_bf16 v[58:61], v[176:179], v[192:195], v[58:61]
	v_mfma_f32_16x16x32_bf16 v[50:53], v[184:187], v[192:195], v[50:53]
	v_mfma_f32_16x16x32_bf16 v[42:45], v[176:179], v[200:203], v[42:45]
	v_mfma_f32_16x16x32_bf16 v[34:37], v[184:187], v[200:203], v[34:37]
	v_mfma_f32_16x16x32_bf16 v[26:29], v[176:179], v[208:211], v[26:29]
	v_mfma_f32_16x16x32_bf16 v[18:21], v[184:187], v[208:211], v[18:21]
	v_mfma_f32_16x16x32_bf16 v[10:13], v[176:179], v[216:219], v[10:13]
	v_mfma_f32_16x16x32_bf16 v[2:5], v[184:187], v[216:219], v[2:5]
	s_barrier
	s_add_i32 s21, 0, 0x18000
	v_add_u32_e32 v165, s21, v151
	s_add_i32 s28, 0, 0x1c000
	ds_read_b128 v[146:149], v165
	ds_read_b128 v[156:159], v165 offset:1024
	ds_read_b128 v[160:163], v165 offset:2048
	ds_read_b128 v[168:171], v165 offset:3072
	v_add_u32_e32 v165, s28, v151
	ds_read_b128 v[172:175], v165
	ds_read_b128 v[176:179], v165 offset:1024
	ds_read_b128 v[180:183], v165 offset:2048
	ds_read_b128 v[184:187], v165 offset:3072
	s_add_u32 s22, s22, 0x80000
	s_addc_u32 s23, s23, 0
	s_mov_b32 m0, s30
	v_lshl_add_u64 v[228:229], s[22:23], 0, v[136:137]
	ds_read_b128 v[188:191], v155 offset:32768
	ds_read_b128 v[192:195], v155 offset:33792
	ds_read_b128 v[196:199], v155 offset:34816
	ds_read_b128 v[200:203], v155 offset:35840
	ds_read_b128 v[204:207], v155 offset:36864
	ds_read_b128 v[208:211], v155 offset:37888
	ds_read_b128 v[212:215], v155 offset:38912
	ds_read_b128 v[216:219], v155 offset:39936
	global_load_lds_dwordx4 v[228:229], off
	v_lshl_add_u64 v[228:229], s[22:23], 0, v[132:133]
	s_mov_b32 m0, s31
	s_nop 0
	global_load_lds_dwordx4 v[228:229], off
	s_waitcnt vmcnt(8)
	s_waitcnt lgkmcnt(0)
	s_barrier
	s_waitcnt lgkmcnt(0)
	v_mfma_f32_16x16x32_bf16 v[126:129], v[146:149], v[188:191], v[126:129]
	v_mfma_f32_16x16x32_bf16 v[118:121], v[160:163], v[188:191], v[118:121]
	v_mfma_f32_16x16x32_bf16 v[110:113], v[146:149], v[196:199], v[110:113]
	v_mfma_f32_16x16x32_bf16 v[102:105], v[160:163], v[196:199], v[102:105]
	v_mfma_f32_16x16x32_bf16 v[94:97], v[146:149], v[204:207], v[94:97]
	v_mfma_f32_16x16x32_bf16 v[86:89], v[160:163], v[204:207], v[86:89]
	v_mfma_f32_16x16x32_bf16 v[78:81], v[146:149], v[212:215], v[78:81]
	v_mfma_f32_16x16x32_bf16 v[70:73], v[160:163], v[212:215], v[70:73]
	v_mfma_f32_16x16x32_bf16 v[126:129], v[156:159], v[192:195], v[126:129]
	v_mfma_f32_16x16x32_bf16 v[118:121], v[168:171], v[192:195], v[118:121]
	v_mfma_f32_16x16x32_bf16 v[110:113], v[156:159], v[200:203], v[110:113]
	v_mfma_f32_16x16x32_bf16 v[102:105], v[168:171], v[200:203], v[102:105]
	v_mfma_f32_16x16x32_bf16 v[94:97], v[156:159], v[208:211], v[94:97]
	v_mfma_f32_16x16x32_bf16 v[86:89], v[168:171], v[208:211], v[86:89]
	v_mfma_f32_16x16x32_bf16 v[78:81], v[156:159], v[216:219], v[78:81]
	v_mfma_f32_16x16x32_bf16 v[70:73], v[168:171], v[216:219], v[70:73]
	v_mfma_f32_16x16x32_bf16 v[122:125], v[172:175], v[188:191], v[122:125]
	v_mfma_f32_16x16x32_bf16 v[114:117], v[180:183], v[188:191], v[114:117]
	v_mfma_f32_16x16x32_bf16 v[106:109], v[172:175], v[196:199], v[106:109]
	v_mfma_f32_16x16x32_bf16 v[98:101], v[180:183], v[196:199], v[98:101]
	v_mfma_f32_16x16x32_bf16 v[90:93], v[172:175], v[204:207], v[90:93]
	v_mfma_f32_16x16x32_bf16 v[82:85], v[180:183], v[204:207], v[82:85]
	v_mfma_f32_16x16x32_bf16 v[74:77], v[172:175], v[212:215], v[74:77]
	v_mfma_f32_16x16x32_bf16 v[66:69], v[180:183], v[212:215], v[66:69]
	v_mfma_f32_16x16x32_bf16 v[122:125], v[176:179], v[192:195], v[122:125]
	v_mfma_f32_16x16x32_bf16 v[114:117], v[184:187], v[192:195], v[114:117]
	v_mfma_f32_16x16x32_bf16 v[106:109], v[176:179], v[200:203], v[106:109]
	v_mfma_f32_16x16x32_bf16 v[98:101], v[184:187], v[200:203], v[98:101]
	v_mfma_f32_16x16x32_bf16 v[90:93], v[176:179], v[208:211], v[90:93]
	v_mfma_f32_16x16x32_bf16 v[82:85], v[184:187], v[208:211], v[82:85]
	v_mfma_f32_16x16x32_bf16 v[74:77], v[176:179], v[216:219], v[74:77]
	v_mfma_f32_16x16x32_bf16 v[66:69], v[184:187], v[216:219], v[66:69]
	s_barrier
	s_add_i32 s21, s21, s20
	v_lshl_add_u64 v[220:221], v[220:221], 0, s[8:9]
	s_mov_b32 m0, s21
	ds_read_b128 v[188:191], v155 offset:49152
	ds_read_b128 v[192:195], v155 offset:50176
	ds_read_b128 v[196:199], v155 offset:51200
	ds_read_b128 v[200:203], v155 offset:52224
	ds_read_b128 v[204:207], v155 offset:53248
	ds_read_b128 v[208:211], v155 offset:54272
	ds_read_b128 v[212:215], v155 offset:55296
	ds_read_b128 v[216:219], v155 offset:56320
	global_load_lds_dwordx4 v[220:221], off
	s_add_i32 m0, s21, 0x2000
	s_add_u32 s0, s0, 0x80080
	v_lshl_add_u64 v[220:221], v[222:223], 0, s[8:9]
	s_addc_u32 s1, s1, 0
	s_add_i32 s21, s28, s20
	global_load_lds_dwordx4 v[220:221], off
	v_lshl_add_u64 v[220:221], s[0:1], 0, v[134:135]
	s_mov_b32 m0, s21
	s_nop 0
	global_load_lds_dwordx4 v[220:221], off
	v_lshl_add_u64 v[220:221], s[0:1], 0, v[130:131]
	s_add_i32 m0, s21, 0x2000
	s_nop 0
	global_load_lds_dwordx4 v[220:221], off
	v_lshl_add_u64 v[220:221], v[224:225], 0, s[8:9]
	s_mov_b32 m0, s34
	s_nop 0
	global_load_lds_dwordx4 v[220:221], off
	v_lshl_add_u64 v[220:221], v[226:227], 0, s[8:9]
	s_mov_b32 m0, s35
	s_nop 0
	global_load_lds_dwordx4 v[220:221], off
	s_waitcnt vmcnt(8)
	s_waitcnt lgkmcnt(0)
	s_barrier
	s_waitcnt lgkmcnt(0)
	v_mfma_f32_16x16x32_bf16 v[62:65], v[146:149], v[188:191], v[62:65]
	v_mfma_f32_16x16x32_bf16 v[54:57], v[160:163], v[188:191], v[54:57]
	v_mfma_f32_16x16x32_bf16 v[46:49], v[146:149], v[196:199], v[46:49]
	v_mfma_f32_16x16x32_bf16 v[38:41], v[160:163], v[196:199], v[38:41]
	v_mfma_f32_16x16x32_bf16 v[30:33], v[146:149], v[204:207], v[30:33]
	v_mfma_f32_16x16x32_bf16 v[22:25], v[160:163], v[204:207], v[22:25]
	v_mfma_f32_16x16x32_bf16 v[14:17], v[146:149], v[212:215], v[14:17]
	v_mfma_f32_16x16x32_bf16 v[6:9], v[160:163], v[212:215], v[6:9]
	v_mfma_f32_16x16x32_bf16 v[62:65], v[156:159], v[192:195], v[62:65]
	v_mfma_f32_16x16x32_bf16 v[54:57], v[168:171], v[192:195], v[54:57]
	v_mfma_f32_16x16x32_bf16 v[46:49], v[156:159], v[200:203], v[46:49]
	v_mfma_f32_16x16x32_bf16 v[38:41], v[168:171], v[200:203], v[38:41]
	v_mfma_f32_16x16x32_bf16 v[30:33], v[156:159], v[208:211], v[30:33]
	v_mfma_f32_16x16x32_bf16 v[22:25], v[168:171], v[208:211], v[22:25]
	v_mfma_f32_16x16x32_bf16 v[14:17], v[156:159], v[216:219], v[14:17]
	v_mfma_f32_16x16x32_bf16 v[6:9], v[168:171], v[216:219], v[6:9]
	v_mfma_f32_16x16x32_bf16 v[58:61], v[172:175], v[188:191], v[58:61]
	v_mfma_f32_16x16x32_bf16 v[50:53], v[180:183], v[188:191], v[50:53]
	v_mfma_f32_16x16x32_bf16 v[42:45], v[172:175], v[196:199], v[42:45]
	v_mfma_f32_16x16x32_bf16 v[34:37], v[180:183], v[196:199], v[34:37]
	v_mfma_f32_16x16x32_bf16 v[26:29], v[172:175], v[204:207], v[26:29]
	v_mfma_f32_16x16x32_bf16 v[18:21], v[180:183], v[204:207], v[18:21]
	v_mfma_f32_16x16x32_bf16 v[10:13], v[172:175], v[212:215], v[10:13]
	v_mfma_f32_16x16x32_bf16 v[2:5], v[180:183], v[212:215], v[2:5]
	v_mfma_f32_16x16x32_bf16 v[58:61], v[176:179], v[192:195], v[58:61]
	v_mfma_f32_16x16x32_bf16 v[50:53], v[184:187], v[192:195], v[50:53]
	v_mfma_f32_16x16x32_bf16 v[42:45], v[176:179], v[200:203], v[42:45]
	v_mfma_f32_16x16x32_bf16 v[34:37], v[184:187], v[200:203], v[34:37]
	v_mfma_f32_16x16x32_bf16 v[26:29], v[176:179], v[208:211], v[26:29]
	v_mfma_f32_16x16x32_bf16 v[18:21], v[184:187], v[208:211], v[18:21]
	v_mfma_f32_16x16x32_bf16 v[10:13], v[176:179], v[216:219], v[10:13]
	v_mfma_f32_16x16x32_bf16 v[2:5], v[184:187], v[216:219], v[2:5]
	s_barrier
	s_add_i32 s66, s66, 2
	s_add_u32 s46, s46, 0x100
	s_addc_u32 s47, s47, 0
	s_add_u32 s62, s62, 0x100
	s_addc_u32 s63, s63, 0
	s_cmp_gt_u32 s66, 29
	s_cbranch_scc0 .LBB0_1638
	s_and_b64 vcc, exec, s[10:11]
	s_cbranch_vccz .LBB0_1641
	s_barrier

.LBB0_1699:
	s_setprio 0
	v_readlane_b32 s2, v243, 51
	s_cmp_lt_i32 s2, 21
	s_cselect_b64 s[4:5], -1, 0
	s_and_b64 s[0:1], s[4:5], s[0:1]
	s_andn2_b64 vcc, exec, s[0:1]
	v_readlane_b32 s3, v243, 52
	s_cbranch_vccnz .LBB0_1745
	v_readlane_b32 s6, v243, 53
	s_abs_i32 s0, s6
	v_cvt_f32_u32_e32 v2, s0
	v_readlane_b32 s8, v243, 0
	s_sub_i32 s1, s6, s8
	s_add_i32 s2, s1, 0x3ff
	v_rcp_iflag_f32_e32 v2, v2
	s_sub_i32 s1, 0xfffffc01, s1
	s_xor_b32 s6, s2, s6
	s_sub_i32 s3, 0, s0
	v_mul_f32_e32 v2, 0x4f7ffffe, v2
	v_cvt_u32_f32_e32 v2, v2
	s_max_i32 s1, s2, s1
	s_ashr_i32 s2, s6, 31
	v_readfirstlane_b32 s10, v0
	v_readfirstlane_b32 s6, v2
	s_mul_i32 s3, s3, s6
	s_mul_hi_u32 s3, s6, s3
	s_add_i32 s6, s6, s3
	s_mul_hi_u32 s3, s1, s6
	s_mul_i32 s6, s3, s0
	s_sub_i32 s1, s1, s6
	s_add_i32 s7, s3, 1
	s_sub_i32 s6, s1, s0
	s_cmp_ge_u32 s1, s0
	s_cselect_b32 s3, s7, s3
	s_cselect_b32 s1, s6, s1
	s_add_i32 s6, s3, 1
	s_cmp_ge_u32 s1, s0
	s_cselect_b32 s0, s6, s3
	s_xor_b32 s0, s0, s2
	s_sub_i32 s20, s0, s2
	s_cmp_lt_i32 s20, 1
	s_cbranch_scc1 .LBB0_1704
	s_mov_b64 s[0:1], 0
	s_cmpk_gt_i32 s8, 0x3ff
	s_mov_b64 s[2:3], 0
	s_cbranch_scc1 .LBB0_1705
	v_readlane_b32 s3, v243, 0
	s_ashr_i32 s2, s3, 31
	s_lshr_b32 s2, s2, 29
	s_add_i32 s6, s3, s2
	s_and_b32 s2, s6, -8
	s_sub_i32 s7, s3, s2
	s_cmp_gt_i32 s7, -1
	s_cbranch_scc0 .LBB0_1709
	s_lshl_b32 s8, s7, 7
	s_cbranch_execz .LBB0_1710
	s_branch .LBB0_1711

.LBB0_1712:
	s_andn2_b64 vcc, exec, s[2:3]
	s_cbranch_vccnz .LBB0_1745
	v_lshlrev_b32_e32 v2, 4, v0
	v_and_b32_e32 v3, 32, v0
	v_bfe_u32 v4, v0, 2, 4
	v_bitop3_b32 v10, v2, v3, 48 bitop3:0x6c
	v_lshrrev_b32_e32 v3, 3, v0
	s_add_u32 s27, s90, 0x6500000
	v_and_or_b32 v5, v3, 48, v4
	v_or_b32_e32 v3, 64, v3
	s_movk_i32 s0, 0x70
	s_addc_u32 s30, s91, 0
	v_and_or_b32 v3, v3, s0, v4
	s_lshr_b32 s3, s10, 6
	s_lshl_b32 s0, s18, 10
	s_lshr_b32 s2, s10, 8
	s_lshl_b32 s31, s3, 10
	s_addk_i32 s0, 0xfc00
	s_cmp_lg_u32 s18, 0
	s_cselect_b32 s8, s0, 0
	s_ashr_i32 s9, s8, 31
	s_mul_i32 s1, s17, 0x2c0000
	s_mul_hi_i32 s0, s17, 0x2c0000
	s_add_u32 s1, s27, s1
	s_addc_u32 s11, s30, s0
	v_and_b32_e32 v11, 64, v0
	s_add_u32 s0, s1, s8
	v_or_b32_e32 v2, v10, v11
	v_mul_u32_u24_e32 v12, 0x2c00, v5
	s_addc_u32 s1, s11, s9
	s_add_i32 s33, s31, 0
	v_or_b32_e32 v134, v12, v2
	s_add_i32 m0, s33, 0x10000
	s_mul_i32 s7, s16, 0x2c0000
	global_load_lds_dwordx4 v134, s[0:1]
	s_add_i32 m0, s33, 0x12000
	v_readlane_b32 s12, v242, 17
	s_mul_hi_i32 s6, s16, 0x2c0000
	v_readlane_b32 s13, v242, 18
	s_add_u32 s11, s12, s7
	v_mul_u32_u24_e32 v13, 0x2c00, v3
	s_addc_u32 s12, s13, s6
	v_or_b32_e32 v136, v13, v2
	s_add_u32 s6, s0, 0x160000
	global_load_lds_dwordx4 v136, s[0:1]
	s_addc_u32 s7, s1, 0
	s_add_i32 m0, s33, 0x14000
	v_mov_b32_e32 v135, 0
	global_load_lds_dwordx4 v134, s[6:7]
	s_add_i32 m0, s33, 0x16000
	s_add_u32 s24, s11, s8
	s_addc_u32 s25, s12, s9
	s_add_i32 s34, s33, 0x2000
	global_load_lds_dwordx4 v136, s[6:7]
	s_mov_b32 m0, s33
	s_add_u32 s6, s24, 0x160000
	global_load_lds_dwordx4 v134, s[24:25]
	s_mov_b32 m0, s34
	s_addc_u32 s7, s25, 0
	s_add_i32 s35, s33, 0x4000
	global_load_lds_dwordx4 v136, s[24:25]
	s_mov_b32 m0, s35
	s_add_i32 s52, s33, 0x6000
	global_load_lds_dwordx4 v134, s[6:7]
	s_mov_b32 m0, s52
	v_mov_b32_e32 v137, v135
	global_load_lds_dwordx4 v136, s[6:7]
	s_cmp_eq_u32 s2, 1
	s_mov_b32 s53, 0
	v_lshl_add_u64 v[8:9], s[0:1], 0, v[134:135]
	v_lshl_add_u64 v[6:7], s[0:1], 0, v[136:137]
	v_lshl_add_u64 v[2:3], s[24:25], 0, v[134:135]
	s_cselect_b64 s[6:7], -1, 0
	s_cmp_lg_u32 s2, 1
	v_lshl_add_u64 v[4:5], s[24:25], 0, v[136:137]
	s_cbranch_scc1 .LBB0_1715
	s_barrier
	s_setprio 1

.LBB0_1734:
	ds_read_b128 v[130:133], v195
	ds_read_b128 v[160:163], v195 offset:1024
	ds_read_b128 v[168:171], v195 offset:2048
	ds_read_b128 v[172:175], v195 offset:3072
	ds_read_b128 v[176:179], v196
	ds_read_b128 v[180:183], v196 offset:1024
	ds_read_b128 v[184:187], v196 offset:2048
	ds_read_b128 v[188:191], v196 offset:3072
	s_add_i32 s69, s22, 2
	s_add_u32 s0, s44, 0xffea0080
	s_addc_u32 s1, s45, -1
	s_cmp_eq_u32 s68, s22
	s_cselect_b32 s22, s12, s0
	s_cselect_b32 s23, s13, s1
	s_cselect_b32 s1, s15, s25
	s_cselect_b32 s0, s14, s24
	v_lshl_add_u64 v[192:193], s[44:45], 0, v[154:155]
	s_add_i32 m0, s33, 0xc000
	ds_read_b128 v[198:201], v197
	ds_read_b128 v[202:205], v197 offset:1024
	ds_read_b128 v[206:209], v197 offset:2048
	ds_read_b128 v[210:213], v197 offset:3072
	ds_read_b128 v[214:217], v197 offset:4096
	ds_read_b128 v[218:221], v197 offset:5120
	ds_read_b128 v[222:225], v197 offset:6144
	ds_read_b128 v[226:229], v197 offset:7168
	global_load_lds_dwordx4 v[192:193], off
	v_lshl_add_u64 v[192:193], s[44:45], 0, v[156:157]
	s_add_i32 m0, s33, 0xe000
	s_nop 0
	global_load_lds_dwordx4 v[192:193], off
	s_waitcnt vmcnt(8)
	s_waitcnt lgkmcnt(0)
	s_barrier
	s_waitcnt lgkmcnt(0)
	v_mfma_f32_16x16x32_bf16 v[126:129], v[130:133], v[198:201], v[126:129]
	v_mfma_f32_16x16x32_bf16 v[94:97], v[168:171], v[198:201], v[94:97]
	v_mfma_f32_16x16x32_bf16 v[122:125], v[130:133], v[206:209], v[122:125]
	v_mfma_f32_16x16x32_bf16 v[90:93], v[168:171], v[206:209], v[90:93]
	v_mfma_f32_16x16x32_bf16 v[118:121], v[130:133], v[214:217], v[118:121]
	v_mfma_f32_16x16x32_bf16 v[86:89], v[168:171], v[214:217], v[86:89]
	v_mfma_f32_16x16x32_bf16 v[114:117], v[130:133], v[222:225], v[114:117]
	v_mfma_f32_16x16x32_bf16 v[82:85], v[168:171], v[222:225], v[82:85]
	v_mfma_f32_16x16x32_bf16 v[126:129], v[160:163], v[202:205], v[126:129]
	v_mfma_f32_16x16x32_bf16 v[94:97], v[172:175], v[202:205], v[94:97]
	v_mfma_f32_16x16x32_bf16 v[122:125], v[160:163], v[210:213], v[122:125]
	v_mfma_f32_16x16x32_bf16 v[90:93], v[172:175], v[210:213], v[90:93]
	v_mfma_f32_16x16x32_bf16 v[118:121], v[160:163], v[218:221], v[118:121]
	v_mfma_f32_16x16x32_bf16 v[86:89], v[172:175], v[218:221], v[86:89]
	v_mfma_f32_16x16x32_bf16 v[114:117], v[160:163], v[226:229], v[114:117]
	v_mfma_f32_16x16x32_bf16 v[82:85], v[172:175], v[226:229], v[82:85]
	v_mfma_f32_16x16x32_bf16 v[62:65], v[176:179], v[198:201], v[62:65]
	v_mfma_f32_16x16x32_bf16 v[30:33], v[184:187], v[198:201], v[30:33]
	v_mfma_f32_16x16x32_bf16 v[58:61], v[176:179], v[206:209], v[58:61]
	v_mfma_f32_16x16x32_bf16 v[26:29], v[184:187], v[206:209], v[26:29]
	v_mfma_f32_16x16x32_bf16 v[54:57], v[176:179], v[214:217], v[54:57]
	v_mfma_f32_16x16x32_bf16 v[22:25], v[184:187], v[214:217], v[22:25]
	v_mfma_f32_16x16x32_bf16 v[50:53], v[176:179], v[222:225], v[50:53]
	v_mfma_f32_16x16x32_bf16 v[18:21], v[184:187], v[222:225], v[18:21]
	v_mfma_f32_16x16x32_bf16 v[62:65], v[180:183], v[202:205], v[62:65]
	v_mfma_f32_16x16x32_bf16 v[30:33], v[188:191], v[202:205], v[30:33]
	v_mfma_f32_16x16x32_bf16 v[58:61], v[180:183], v[210:213], v[58:61]
	v_mfma_f32_16x16x32_bf16 v[26:29], v[188:191], v[210:213], v[26:29]
	v_mfma_f32_16x16x32_bf16 v[54:57], v[180:183], v[218:221], v[54:57]
	v_mfma_f32_16x16x32_bf16 v[22:25], v[188:191], v[218:221], v[22:25]
	v_mfma_f32_16x16x32_bf16 v[50:53], v[180:183], v[226:229], v[50:53]
	v_mfma_f32_16x16x32_bf16 v[18:21], v[188:191], v[226:229], v[18:21]
	s_barrier
	s_add_i32 s21, s66, s31
	v_lshl_add_u64 v[192:193], s[0:1], 0, v[134:135]
	s_mov_b32 m0, s21
	ds_read_b128 v[198:201], v197 offset:16384
	ds_read_b128 v[202:205], v197 offset:17408
	ds_read_b128 v[206:209], v197 offset:18432
	ds_read_b128 v[210:213], v197 offset:19456
	ds_read_b128 v[214:217], v197 offset:20480
	ds_read_b128 v[218:221], v197 offset:21504
	ds_read_b128 v[222:225], v197 offset:22528
	ds_read_b128 v[226:229], v197 offset:23552
	global_load_lds_dwordx4 v[192:193], off
	s_add_i32 m0, s21, 0x2000
	s_add_u32 s28, s0, 0x160000
	v_lshl_add_u64 v[230:231], s[0:1], 0, v[136:137]
	s_addc_u32 s29, s1, 0
	s_add_i32 s21, s67, s31
	global_load_lds_dwordx4 v[230:231], off
	v_lshl_add_u64 v[232:233], s[28:29], 0, v[134:135]
	s_mov_b32 m0, s21
	v_lshl_add_u64 v[234:235], s[22:23], 0, v[136:137]
	global_load_lds_dwordx4 v[232:233], off
	v_lshl_add_u64 v[232:233], s[28:29], 0, v[136:137]
	s_add_i32 m0, s21, 0x2000
	s_nop 0
	global_load_lds_dwordx4 v[232:233], off
	v_lshl_add_u64 v[232:233], s[22:23], 0, v[134:135]
	s_mov_b32 m0, s33
	s_nop 0
	global_load_lds_dwordx4 v[232:233], off
	s_mov_b32 m0, s34
	s_nop 0
	global_load_lds_dwordx4 v[234:235], off
	s_waitcnt vmcnt(8)
	s_waitcnt lgkmcnt(0)
	s_barrier
	s_waitcnt lgkmcnt(0)
	v_mfma_f32_16x16x32_bf16 v[110:113], v[130:133], v[198:201], v[110:113]
	v_mfma_f32_16x16x32_bf16 v[78:81], v[168:171], v[198:201], v[78:81]
	v_mfma_f32_16x16x32_bf16 v[106:109], v[130:133], v[206:209], v[106:109]
	v_mfma_f32_16x16x32_bf16 v[74:77], v[168:171], v[206:209], v[74:77]
	v_mfma_f32_16x16x32_bf16 v[102:105], v[130:133], v[214:217], v[102:105]
	v_mfma_f32_16x16x32_bf16 v[70:73], v[168:171], v[214:217], v[70:73]
	v_mfma_f32_16x16x32_bf16 v[98:101], v[130:133], v[222:225], v[98:101]
	v_mfma_f32_16x16x32_bf16 v[66:69], v[168:171], v[222:225], v[66:69]
	v_mfma_f32_16x16x32_bf16 v[110:113], v[160:163], v[202:205], v[110:113]
	v_mfma_f32_16x16x32_bf16 v[78:81], v[172:175], v[202:205], v[78:81]
	v_mfma_f32_16x16x32_bf16 v[106:109], v[160:163], v[210:213], v[106:109]
	v_mfma_f32_16x16x32_bf16 v[74:77], v[172:175], v[210:213], v[74:77]
	v_mfma_f32_16x16x32_bf16 v[102:105], v[160:163], v[218:221], v[102:105]
	v_mfma_f32_16x16x32_bf16 v[70:73], v[172:175], v[218:221], v[70:73]
	v_mfma_f32_16x16x32_bf16 v[98:101], v[160:163], v[226:229], v[98:101]
	v_mfma_f32_16x16x32_bf16 v[66:69], v[172:175], v[226:229], v[66:69]
	v_mfma_f32_16x16x32_bf16 v[46:49], v[176:179], v[198:201], v[46:49]
	v_mfma_f32_16x16x32_bf16 v[14:17], v[184:187], v[198:201], v[14:17]
	v_mfma_f32_16x16x32_bf16 v[42:45], v[176:179], v[206:209], v[42:45]
	v_mfma_f32_16x16x32_bf16 v[10:13], v[184:187], v[206:209], v[10:13]
	v_mfma_f32_16x16x32_bf16 v[38:41], v[176:179], v[214:217], v[38:41]
	v_mfma_f32_16x16x32_bf16 v[6:9], v[184:187], v[214:217], v[6:9]
	v_mfma_f32_16x16x32_bf16 v[34:37], v[176:179], v[222:225], v[34:37]
	v_mfma_f32_16x16x32_bf16 v[2:5], v[184:187], v[222:225], v[2:5]
	v_mfma_f32_16x16x32_bf16 v[46:49], v[180:183], v[202:205], v[46:49]
	v_mfma_f32_16x16x32_bf16 v[14:17], v[188:191], v[202:205], v[14:17]
	v_mfma_f32_16x16x32_bf16 v[42:45], v[180:183], v[210:213], v[42:45]
	v_mfma_f32_16x16x32_bf16 v[10:13], v[188:191], v[210:213], v[10:13]
	v_mfma_f32_16x16x32_bf16 v[38:41], v[180:183], v[218:221], v[38:41]
	v_mfma_f32_16x16x32_bf16 v[6:9], v[188:191], v[218:221], v[6:9]
	v_mfma_f32_16x16x32_bf16 v[34:37], v[180:183], v[226:229], v[34:37]
	v_mfma_f32_16x16x32_bf16 v[2:5], v[188:191], v[226:229], v[2:5]
	s_barrier
	s_add_i32 s21, 0, 0x18000
	s_add_i32 s28, 0, 0x1c000
	v_add_u32_e32 v172, s21, v165
	v_add_u32_e32 v188, s28, v165
	ds_read_b128 v[130:133], v172
	ds_read_b128 v[160:163], v172 offset:1024
	ds_read_b128 v[168:171], v172 offset:2048
	ds_read_b128 v[172:175], v172 offset:3072
	ds_read_b128 v[176:179], v188
	ds_read_b128 v[180:183], v188 offset:1024
	ds_read_b128 v[184:187], v188 offset:2048
	ds_read_b128 v[188:191], v188 offset:3072
	s_add_u32 s22, s22, 0x160000
	s_addc_u32 s23, s23, 0
	s_mov_b32 m0, s35
	v_lshl_add_u64 v[236:237], s[22:23], 0, v[134:135]
	ds_read_b128 v[198:201], v197 offset:32768
	ds_read_b128 v[202:205], v197 offset:33792
	ds_read_b128 v[206:209], v197 offset:34816
	ds_read_b128 v[210:213], v197 offset:35840
	ds_read_b128 v[214:217], v197 offset:36864
	ds_read_b128 v[218:221], v197 offset:37888
	ds_read_b128 v[222:225], v197 offset:38912
	ds_read_b128 v[226:229], v197 offset:39936
	global_load_lds_dwordx4 v[236:237], off
	v_lshl_add_u64 v[236:237], s[22:23], 0, v[136:137]
	s_mov_b32 m0, s52
	s_nop 0
	global_load_lds_dwordx4 v[236:237], off
	s_waitcnt vmcnt(8)
	s_waitcnt lgkmcnt(0)
	s_barrier
	s_waitcnt lgkmcnt(0)
	v_mfma_f32_16x16x32_bf16 v[126:129], v[130:133], v[198:201], v[126:129]
	v_mfma_f32_16x16x32_bf16 v[94:97], v[168:171], v[198:201], v[94:97]
	v_mfma_f32_16x16x32_bf16 v[122:125], v[130:133], v[206:209], v[122:125]
	v_mfma_f32_16x16x32_bf16 v[90:93], v[168:171], v[206:209], v[90:93]
	v_mfma_f32_16x16x32_bf16 v[118:121], v[130:133], v[214:217], v[118:121]
	v_mfma_f32_16x16x32_bf16 v[86:89], v[168:171], v[214:217], v[86:89]
	v_mfma_f32_16x16x32_bf16 v[114:117], v[130:133], v[222:225], v[114:117]
	v_mfma_f32_16x16x32_bf16 v[82:85], v[168:171], v[222:225], v[82:85]
	v_mfma_f32_16x16x32_bf16 v[126:129], v[160:163], v[202:205], v[126:129]
	v_mfma_f32_16x16x32_bf16 v[94:97], v[172:175], v[202:205], v[94:97]
	v_mfma_f32_16x16x32_bf16 v[122:125], v[160:163], v[210:213], v[122:125]
	v_mfma_f32_16x16x32_bf16 v[90:93], v[172:175], v[210:213], v[90:93]
	v_mfma_f32_16x16x32_bf16 v[118:121], v[160:163], v[218:221], v[118:121]
	v_mfma_f32_16x16x32_bf16 v[86:89], v[172:175], v[218:221], v[86:89]
	v_mfma_f32_16x16x32_bf16 v[114:117], v[160:163], v[226:229], v[114:117]
	v_mfma_f32_16x16x32_bf16 v[82:85], v[172:175], v[226:229], v[82:85]
	v_mfma_f32_16x16x32_bf16 v[62:65], v[176:179], v[198:201], v[62:65]
	v_mfma_f32_16x16x32_bf16 v[30:33], v[184:187], v[198:201], v[30:33]
	v_mfma_f32_16x16x32_bf16 v[58:61], v[176:179], v[206:209], v[58:61]
	v_mfma_f32_16x16x32_bf16 v[26:29], v[184:187], v[206:209], v[26:29]
	v_mfma_f32_16x16x32_bf16 v[54:57], v[176:179], v[214:217], v[54:57]
	v_mfma_f32_16x16x32_bf16 v[22:25], v[184:187], v[214:217], v[22:25]
	v_mfma_f32_16x16x32_bf16 v[50:53], v[176:179], v[222:225], v[50:53]
	v_mfma_f32_16x16x32_bf16 v[18:21], v[184:187], v[222:225], v[18:21]
	v_mfma_f32_16x16x32_bf16 v[62:65], v[180:183], v[202:205], v[62:65]
	v_mfma_f32_16x16x32_bf16 v[30:33], v[188:191], v[202:205], v[30:33]
	v_mfma_f32_16x16x32_bf16 v[58:61], v[180:183], v[210:213], v[58:61]
	v_mfma_f32_16x16x32_bf16 v[26:29], v[188:191], v[210:213], v[26:29]
	v_mfma_f32_16x16x32_bf16 v[54:57], v[180:183], v[218:221], v[54:57]
	v_mfma_f32_16x16x32_bf16 v[22:25], v[188:191], v[218:221], v[22:25]
	v_mfma_f32_16x16x32_bf16 v[50:53], v[180:183], v[226:229], v[50:53]
	v_mfma_f32_16x16x32_bf16 v[18:21], v[188:191], v[226:229], v[18:21]
	s_barrier
	s_add_i32 s21, s21, s31
	v_lshl_add_u64 v[192:193], v[192:193], 0, s[8:9]
	s_mov_b32 m0, s21
	ds_read_b128 v[198:201], v197 offset:49152
	ds_read_b128 v[202:205], v197 offset:50176
	ds_read_b128 v[206:209], v197 offset:51200
	ds_read_b128 v[210:213], v197 offset:52224
	ds_read_b128 v[214:217], v197 offset:53248
	ds_read_b128 v[218:221], v197 offset:54272
	ds_read_b128 v[222:225], v197 offset:55296
	ds_read_b128 v[226:229], v197 offset:56320
	global_load_lds_dwordx4 v[192:193], off
	s_add_i32 m0, s21, 0x2000
	s_add_u32 s0, s0, 0x160080
	v_lshl_add_u64 v[192:193], v[230:231], 0, s[8:9]
	s_addc_u32 s1, s1, 0
	s_add_i32 s21, s28, s31
	global_load_lds_dwordx4 v[192:193], off
	v_lshl_add_u64 v[192:193], s[0:1], 0, v[134:135]
	s_mov_b32 m0, s21
	s_nop 0
	global_load_lds_dwordx4 v[192:193], off
	v_lshl_add_u64 v[192:193], s[0:1], 0, v[136:137]
	s_add_i32 m0, s21, 0x2000
	s_nop 0
	global_load_lds_dwordx4 v[192:193], off
	v_lshl_add_u64 v[192:193], v[232:233], 0, s[8:9]
	s_mov_b32 m0, s56
	s_nop 0
	global_load_lds_dwordx4 v[192:193], off
	v_lshl_add_u64 v[192:193], v[234:235], 0, s[8:9]
	s_mov_b32 m0, s57
	s_nop 0
	global_load_lds_dwordx4 v[192:193], off
	s_waitcnt vmcnt(8)
	s_waitcnt lgkmcnt(0)
	s_barrier
	s_waitcnt lgkmcnt(0)
	v_mfma_f32_16x16x32_bf16 v[110:113], v[130:133], v[198:201], v[110:113]
	v_mfma_f32_16x16x32_bf16 v[78:81], v[168:171], v[198:201], v[78:81]
	v_mfma_f32_16x16x32_bf16 v[106:109], v[130:133], v[206:209], v[106:109]
	v_mfma_f32_16x16x32_bf16 v[74:77], v[168:171], v[206:209], v[74:77]
	v_mfma_f32_16x16x32_bf16 v[102:105], v[130:133], v[214:217], v[102:105]
	v_mfma_f32_16x16x32_bf16 v[70:73], v[168:171], v[214:217], v[70:73]
	v_mfma_f32_16x16x32_bf16 v[98:101], v[130:133], v[222:225], v[98:101]
	v_mfma_f32_16x16x32_bf16 v[66:69], v[168:171], v[222:225], v[66:69]
	v_mfma_f32_16x16x32_bf16 v[110:113], v[160:163], v[202:205], v[110:113]
	v_mfma_f32_16x16x32_bf16 v[78:81], v[172:175], v[202:205], v[78:81]
	v_mfma_f32_16x16x32_bf16 v[106:109], v[160:163], v[210:213], v[106:109]
	v_mfma_f32_16x16x32_bf16 v[74:77], v[172:175], v[210:213], v[74:77]
	v_mfma_f32_16x16x32_bf16 v[102:105], v[160:163], v[218:221], v[102:105]
	v_mfma_f32_16x16x32_bf16 v[70:73], v[172:175], v[218:221], v[70:73]
	v_mfma_f32_16x16x32_bf16 v[98:101], v[160:163], v[226:229], v[98:101]
	v_mfma_f32_16x16x32_bf16 v[66:69], v[172:175], v[226:229], v[66:69]
	v_mfma_f32_16x16x32_bf16 v[46:49], v[176:179], v[198:201], v[46:49]
	v_mfma_f32_16x16x32_bf16 v[14:17], v[184:187], v[198:201], v[14:17]
	v_mfma_f32_16x16x32_bf16 v[42:45], v[176:179], v[206:209], v[42:45]
	v_mfma_f32_16x16x32_bf16 v[10:13], v[184:187], v[206:209], v[10:13]
	v_mfma_f32_16x16x32_bf16 v[38:41], v[176:179], v[214:217], v[38:41]
	v_mfma_f32_16x16x32_bf16 v[6:9], v[184:187], v[214:217], v[6:9]
	v_mfma_f32_16x16x32_bf16 v[34:37], v[176:179], v[222:225], v[34:37]
	v_mfma_f32_16x16x32_bf16 v[2:5], v[184:187], v[222:225], v[2:5]
	v_mfma_f32_16x16x32_bf16 v[46:49], v[180:183], v[202:205], v[46:49]
	v_mfma_f32_16x16x32_bf16 v[14:17], v[188:191], v[202:205], v[14:17]
	v_mfma_f32_16x16x32_bf16 v[42:45], v[180:183], v[210:213], v[42:45]
	v_mfma_f32_16x16x32_bf16 v[10:13], v[188:191], v[210:213], v[10:13]
	v_mfma_f32_16x16x32_bf16 v[38:41], v[180:183], v[218:221], v[38:41]
	v_mfma_f32_16x16x32_bf16 v[6:9], v[188:191], v[218:221], v[6:9]
	v_mfma_f32_16x16x32_bf16 v[34:37], v[180:183], v[226:229], v[34:37]
	v_mfma_f32_16x16x32_bf16 v[2:5], v[188:191], v[226:229], v[2:5]
	s_barrier
	s_add_u32 s44, s44, 0x100
	s_addc_u32 s45, s45, 0
	s_add_u32 s24, s24, 0x100
	s_addc_u32 s25, s25, 0
	s_cmp_ge_u32 s69, s19
	s_mov_b32 s22, s69
	s_cbranch_scc0 .LBB0_1734
	s_and_b64 vcc, exec, s[10:11]
	s_cbranch_vccz .LBB0_1737
	s_barrier

.LBB0_1799:
	s_setprio 0
	v_readlane_b32 s2, v243, 51
	s_cmp_lt_i32 s2, 22
	s_cselect_b64 s[4:5], -1, 0
	s_and_b64 s[0:1], s[4:5], s[0:1]
	s_andn2_b64 vcc, exec, s[0:1]
	v_readlane_b32 s3, v243, 52
	s_cbranch_vccnz .LBB0_1809
	v_readlane_b32 s0, v243, 0
	s_lshl_b32 s0, s0, 3
	v_readlane_b32 s1, v243, 59
	s_add_i32 s6, s1, s0
	s_cmp_gt_i32 s6, 0x81ff
	s_cbranch_scc1 .LBB0_1809
	v_mbcnt_lo_u32_b32 v2, -1, 0
	v_mbcnt_hi_u32_b32 v2, -1, v2
	v_and_b32_e32 v3, 64, v2
	v_add_u32_e32 v3, 64, v3
	v_xor_b32_e32 v4, 1, v2
	v_cmp_lt_i32_e32 vcc, v4, v3
	v_readlane_b32 s16, v243, 1
	v_readlane_b32 s0, v243, 53
	v_cndmask_b32_e32 v4, v2, v4, vcc
	v_lshlrev_b32_e32 v165, 2, v4
	v_xor_b32_e32 v4, 2, v2
	v_cmp_lt_i32_e32 vcc, v4, v3
	v_readlane_b32 s17, v243, 2
	v_readlane_b32 s28, v243, 13
	v_cndmask_b32_e32 v4, v2, v4, vcc
	v_lshlrev_b32_e32 v178, 2, v4
	v_xor_b32_e32 v4, 4, v2
	v_cmp_lt_i32_e32 vcc, v4, v3
	v_readlane_b32 s29, v243, 14
	s_lshl_b32 s12, s0, 3
	v_cndmask_b32_e32 v4, v2, v4, vcc
	v_lshlrev_b32_e32 v179, 2, v4
	v_xor_b32_e32 v4, 8, v2
	v_cmp_lt_i32_e32 vcc, v4, v3
	s_mov_b64 s[16:17], s[28:29]
	s_add_u32 s0, s16, 0x8000
	v_cndmask_b32_e32 v4, v2, v4, vcc
	v_lshlrev_b32_e32 v180, 2, v4
	v_xor_b32_e32 v4, 16, v2
	v_cmp_lt_i32_e32 vcc, v4, v3
	v_mov_b32_e32 v131, 0
	s_addc_u32 s1, s17, 0
	v_cndmask_b32_e32 v4, v2, v4, vcc
	v_lshlrev_b32_e32 v181, 2, v4
	v_xor_b32_e32 v4, 32, v2
	v_cmp_lt_i32_e32 vcc, v4, v3
	v_mov_b32_e32 v7, v131
	v_mov_b32_e32 v9, v131
	v_cndmask_b32_e32 v2, v2, v4, vcc
	v_lshlrev_b32_e32 v182, 2, v2
	v_lshlrev_b32_e32 v2, 2, v166
	v_or_b32_e32 v4, 0x100, v2
	v_lshlrev_b32_e32 v6, 2, v4
	v_lshl_add_u64 v[134:135], s[0:1], 0, v[6:7]
	v_or_b32_e32 v6, 0x200, v2
	v_lshlrev_b32_e32 v8, 2, v6
	v_lshl_add_u64 v[136:137], s[0:1], 0, v[8:9]
	v_or_b32_e32 v8, 0x300, v2
	v_lshlrev_b32_e32 v10, 2, v8
	v_mov_b32_e32 v11, v131
	v_lshl_add_u64 v[138:139], s[0:1], 0, v[10:11]
	v_or_b32_e32 v10, 0x400, v2
	v_lshlrev_b32_e32 v12, 2, v10
	v_mov_b32_e32 v13, v131
	v_lshl_add_u64 v[140:141], s[0:1], 0, v[12:13]
	v_or_b32_e32 v12, 0x500, v2
	v_lshlrev_b32_e32 v14, 2, v12
	v_mov_b32_e32 v15, v131
	v_lshl_add_u64 v[142:143], s[0:1], 0, v[14:15]
	v_or_b32_e32 v14, 0x600, v2
	v_lshlrev_b32_e32 v16, 2, v14
	v_mov_b32_e32 v17, v131
	v_lshl_add_u64 v[144:145], s[0:1], 0, v[16:17]
	v_or_b32_e32 v16, 0x700, v2
	v_lshlrev_b32_e32 v130, 4, v166
	s_waitcnt vmcnt(0)
	v_lshlrev_b32_e32 v18, 2, v16
	v_mov_b32_e32 v19, v131
	v_lshl_add_u64 v[132:133], s[0:1], 0, v[130:131]
	v_lshl_add_u64 v[146:147], s[0:1], 0, v[18:19]
	v_readlane_b32 s0, v242, 19
	v_readlane_b32 s1, v242, 20
	v_readlane_b32 s18, v243, 3
	v_readlane_b32 s19, v243, 4
	v_lshl_add_u64 v[148:149], s[0:1], 0, v[130:131]
	v_readlane_b32 s0, v242, 15
	v_readlane_b32 s20, v243, 5
	v_readlane_b32 s22, v243, 7
	s_add_u32 s13, s90, 0x106000
	v_lshlrev_b32_e32 v18, 3, v166
	v_readlane_b32 s1, v242, 16
	s_addc_u32 s14, s91, 0
	s_mov_b32 s9, 0
	v_lshl_add_u64 v[150:151], s[0:1], 0, v[18:19]
	v_lshl_add_u64 v[152:153], s[90:91], 0, v[130:131]
	s_add_i32 s10, s6, 0xffff8000
	s_mov_b32 s15, 0x12000
	v_lshlrev_b32_e32 v130, 4, v166
	s_movk_i32 s16, 0x1000
	v_lshlrev_b32_e32 v183, 2, v2
	v_lshlrev_b32_e32 v184, 2, v4
	v_lshlrev_b32_e32 v185, 2, v6
	v_lshlrev_b32_e32 v186, 2, v8
	v_lshlrev_b32_e32 v187, 2, v10
	v_lshlrev_b32_e32 v188, 2, v12
	v_lshlrev_b32_e32 v189, 2, v14
	v_lshlrev_b32_e32 v190, 2, v16
	s_movk_i32 s17, 0x7fff
	s_mov_b32 s18, 0x2e100000
	s_mov_b32 s19, 0x2e101000
	v_mov_b32_e32 v191, 0x358637bd
	s_mov_b32 s20, 0xf800000
	v_mov_b32_e32 v192, 0x260
	s_mov_b32 s22, 0xffff0000
	v_readlane_b32 s21, v243, 6
	v_readlane_b32 s23, v243, 8
	v_readlane_b32 s24, v243, 9
	v_readlane_b32 s25, v243, 10
	v_readlane_b32 s26, v243, 11
	v_readlane_b32 s27, v243, 12
	v_readlane_b32 s30, v243, 15
	v_readlane_b32 s31, v243, 16
	s_branch .LBB0_1803

.LBB0_1863:
	s_setprio 0
	v_readlane_b32 s2, v243, 51
	s_cmp_lt_i32 s2, 23
	s_cselect_b64 s[6:7], -1, 0
	s_and_b64 s[0:1], s[6:7], s[0:1]
	s_andn2_b64 vcc, exec, s[0:1]
	v_readlane_b32 s3, v243, 52
	s_cbranch_vccnz .LBB0_1914
	v_readlane_b32 s2, v243, 0
	s_cmpk_lt_i32 s2, 0xc30
	s_cselect_b64 s[0:1], -1, 0
	s_cmpk_gt_i32 s2, 0xc2f
	v_readfirstlane_b32 s2, v0
	s_cbranch_scc1 .LBB0_1866
	v_readlane_b32 s5, v243, 0
	s_ashr_i32 s3, s5, 31
	s_lshr_b32 s3, s3, 29
	s_add_i32 s3, s5, s3
	s_ashr_i32 s4, s3, 3
	s_and_b32 s3, s3, -8
	s_sub_i32 s3, s5, s3
	s_cmp_lt_i32 s3, 0
	s_movk_i32 s5, 0x187
	s_cselect_b32 s5, s5, 0x186
	s_mul_i32 s3, s5, s3
	s_add_i32 s3, s3, s4
	s_mul_hi_i32 s4, s3, 0x2aaaaaab
	s_lshr_b32 s5, s4, 31
	s_ashr_i32 s4, s4, 5
	s_add_i32 s4, s4, s5
	s_lshl_b32 s8, s4, 3
	s_sub_i32 s5, 0x82, s8
	s_mulk_i32 s4, 0xc0
	s_min_u32 s9, s5, 8
	s_sub_i32 s3, s3, s4
	s_sext_i32_i16 s4, s3
	v_cvt_f32_ubyte0_e32 v3, s9
	v_cvt_f32_i32_e32 v2, s4
	v_rcp_iflag_f32_e32 v4, v3
	s_ashr_i32 s4, s4, 30
	s_or_b32 s10, s4, 1
	v_mul_f32_e32 v4, v2, v4
	v_trunc_f32_e32 v4, v4
	v_fma_f32 v2, -v4, v3, v2
	v_cvt_i32_f32_e32 v4, v4
	v_cmp_ge_f32_e64 s[4:5], |v2|, v3
	s_and_b64 s[4:5], s[4:5], exec
	s_cselect_b32 s4, s10, 0
	v_readfirstlane_b32 s5, v4
	s_add_i32 s5, s5, s4
	s_sext_i32_i16 s4, s5
	s_mul_i32 s5, s5, s9
	s_sub_i32 s3, s3, s5
	s_sext_i32_i16 s3, s3
	s_add_i32 s46, s8, s3
.LBB0_1866:
	s_andn2_b64 vcc, exec, s[0:1]
	s_cbranch_vccnz .LBB0_1914
	v_lshrrev_b32_e32 v4, 1, v0
	v_and_b32_e32 v13, 24, v4
	v_lshrrev_b32_e32 v4, 5, v0
	v_lshlrev_b32_e32 v2, 4, v0
	v_and_b32_e32 v3, 32, v0
	v_and_b32_e32 v4, 4, v4
	v_bfe_u32 v5, v0, 2, 2
	v_bfe_u32 v12, v0, 2, 4
	v_bitop3_b32 v10, v2, v3, 48 bitop3:0x6c
	v_and_b32_e32 v11, 64, v0
	v_or3_b32 v4, v4, v5, v13
	v_lshrrev_b32_e32 v5, 3, v0
	v_or_b32_e32 v14, 0x2000, v2
	s_add_u32 s20, s90, 0x9100000
	v_or_b32_e32 v3, v10, v11
	v_and_or_b32 v6, v5, 48, v12
	v_and_or_b32 v5, v5, 32, v4
	v_lshrrev_b32_e32 v2, 7, v14
	s_movk_i32 s0, 0x70
	s_addc_u32 s24, s91, 0
	v_lshl_or_b32 v132, v5, 12, v3
	v_and_or_b32 v5, v2, s0, v12
	s_movk_i32 s0, 0x60
	s_lshr_b32 s10, s2, 6
	s_ashr_i32 s47, s46, 31
	s_ashr_i32 s5, s4, 31
	s_lshr_b32 s3, s2, 8
	v_and_or_b32 v2, v2, s0, v4
	s_lshl_b32 s25, s10, 10
	s_lshl_b64 s[8:9], s[46:47], 20
	s_lshl_b64 s[0:1], s[4:5], 20
	s_add_u32 s0, s20, s0
	s_addc_u32 s1, s24, s1
	s_add_i32 s26, s25, 0
	s_add_i32 m0, s26, 0x10000
	v_lshl_or_b32 v136, v2, 12, v3
	global_load_lds_dwordx4 v132, s[0:1]
	s_add_i32 m0, s26, 0x12000
	s_add_u32 s12, s0, 0x80000
	global_load_lds_dwordx4 v136, s[0:1]
	s_addc_u32 s13, s1, 0
	s_add_i32 m0, s26, 0x14000
	v_lshl_or_b32 v130, v6, 12, v3
	global_load_lds_dwordx4 v132, s[12:13]
	s_add_i32 m0, s26, 0x16000
	v_lshl_or_b32 v134, v5, 12, v3
	global_load_lds_dwordx4 v136, s[12:13]
	v_readlane_b32 s12, v242, 15
	v_readlane_b32 s13, v242, 16
	s_add_u32 s22, s12, s8
	s_addc_u32 s23, s13, s9
	s_add_i32 s27, s26, 0x2000
	s_mov_b32 m0, s26
	s_add_u32 s8, s22, 0x80000
	global_load_lds_dwordx4 v130, s[22:23]
	s_mov_b32 m0, s27
	s_addc_u32 s9, s23, 0
	s_add_i32 s30, s26, 0x4000
	global_load_lds_dwordx4 v134, s[22:23]
	s_mov_b32 m0, s30
	s_add_i32 s31, s26, 0x6000
	global_load_lds_dwordx4 v130, s[8:9]
	s_mov_b32 m0, s31
	v_mov_b32_e32 v133, 0
	global_load_lds_dwordx4 v134, s[8:9]
	v_mov_b32_e32 v137, v133
	v_mov_b32_e32 v131, v133
	v_mov_b32_e32 v135, v133
	s_cmp_eq_u32 s3, 1
	s_mov_b32 s33, 0
	v_lshl_add_u64 v[8:9], s[0:1], 0, v[132:133]
	v_lshl_add_u64 v[6:7], s[0:1], 0, v[136:137]
	v_lshl_add_u64 v[2:3], s[22:23], 0, v[130:131]
	s_cselect_b64 s[8:9], -1, 0
	s_cmp_lg_u32 s3, 1
	v_lshl_add_u64 v[4:5], s[22:23], 0, v[134:135]
	s_cbranch_scc1 .LBB0_1869
	s_barrier
	s_setprio 1

.LBB0_1875:
	ds_read_b128 v[146:149], v153
	ds_read_b128 v[156:159], v153 offset:1024
	ds_read_b128 v[160:163], v153 offset:2048
	ds_read_b128 v[168:171], v153 offset:3072
	ds_read_b128 v[172:175], v154
	ds_read_b128 v[176:179], v154 offset:1024
	ds_read_b128 v[180:183], v154 offset:2048
	ds_read_b128 v[184:187], v154 offset:3072
	s_add_u32 s0, s52, 0xfff80080
	s_addc_u32 s1, s53, -1
	s_cmp_eq_u32 s68, 28
	s_cselect_b32 s23, s5, s1
	s_cselect_b32 s22, s17, s0
	s_cselect_b32 s1, s15, s67
	s_cselect_b32 s0, s63, s66
	v_lshl_add_u64 v[220:221], s[52:53], 0, v[138:139]
	s_add_i32 m0, s26, 0xc000
	ds_read_b128 v[188:191], v155
	ds_read_b128 v[192:195], v155 offset:1024
	ds_read_b128 v[196:199], v155 offset:2048
	ds_read_b128 v[200:203], v155 offset:3072
	ds_read_b128 v[204:207], v155 offset:4096
	ds_read_b128 v[208:211], v155 offset:5120
	ds_read_b128 v[212:215], v155 offset:6144
	ds_read_b128 v[216:219], v155 offset:7168
	global_load_lds_dwordx4 v[220:221], off
	v_lshl_add_u64 v[220:221], s[52:53], 0, v[140:141]
	s_add_i32 m0, s26, 0xe000
	s_nop 0
	global_load_lds_dwordx4 v[220:221], off
	s_waitcnt vmcnt(8)
	s_waitcnt lgkmcnt(0)
	s_barrier
	s_waitcnt lgkmcnt(0)
	v_mfma_f32_16x16x32_bf16 v[126:129], v[146:149], v[188:191], v[126:129]
	v_mfma_f32_16x16x32_bf16 v[122:125], v[160:163], v[188:191], v[122:125]
	v_mfma_f32_16x16x32_bf16 v[110:113], v[146:149], v[196:199], v[110:113]
	v_mfma_f32_16x16x32_bf16 v[106:109], v[160:163], v[196:199], v[106:109]
	v_mfma_f32_16x16x32_bf16 v[94:97], v[146:149], v[204:207], v[94:97]
	v_mfma_f32_16x16x32_bf16 v[90:93], v[160:163], v[204:207], v[90:93]
	v_mfma_f32_16x16x32_bf16 v[78:81], v[146:149], v[212:215], v[78:81]
	v_mfma_f32_16x16x32_bf16 v[74:77], v[160:163], v[212:215], v[74:77]
	v_mfma_f32_16x16x32_bf16 v[126:129], v[156:159], v[192:195], v[126:129]
	v_mfma_f32_16x16x32_bf16 v[122:125], v[168:171], v[192:195], v[122:125]
	v_mfma_f32_16x16x32_bf16 v[110:113], v[156:159], v[200:203], v[110:113]
	v_mfma_f32_16x16x32_bf16 v[106:109], v[168:171], v[200:203], v[106:109]
	v_mfma_f32_16x16x32_bf16 v[94:97], v[156:159], v[208:211], v[94:97]
	v_mfma_f32_16x16x32_bf16 v[90:93], v[168:171], v[208:211], v[90:93]
	v_mfma_f32_16x16x32_bf16 v[78:81], v[156:159], v[216:219], v[78:81]
	v_mfma_f32_16x16x32_bf16 v[74:77], v[168:171], v[216:219], v[74:77]
	v_mfma_f32_16x16x32_bf16 v[118:121], v[172:175], v[188:191], v[118:121]
	v_mfma_f32_16x16x32_bf16 v[114:117], v[180:183], v[188:191], v[114:117]
	v_mfma_f32_16x16x32_bf16 v[102:105], v[172:175], v[196:199], v[102:105]
	v_mfma_f32_16x16x32_bf16 v[98:101], v[180:183], v[196:199], v[98:101]
	v_mfma_f32_16x16x32_bf16 v[86:89], v[172:175], v[204:207], v[86:89]
	v_mfma_f32_16x16x32_bf16 v[82:85], v[180:183], v[204:207], v[82:85]
	v_mfma_f32_16x16x32_bf16 v[70:73], v[172:175], v[212:215], v[70:73]
	v_mfma_f32_16x16x32_bf16 v[66:69], v[180:183], v[212:215], v[66:69]
	v_mfma_f32_16x16x32_bf16 v[118:121], v[176:179], v[192:195], v[118:121]
	v_mfma_f32_16x16x32_bf16 v[114:117], v[184:187], v[192:195], v[114:117]
	v_mfma_f32_16x16x32_bf16 v[102:105], v[176:179], v[200:203], v[102:105]
	v_mfma_f32_16x16x32_bf16 v[98:101], v[184:187], v[200:203], v[98:101]
	v_mfma_f32_16x16x32_bf16 v[86:89], v[176:179], v[208:211], v[86:89]
	v_mfma_f32_16x16x32_bf16 v[82:85], v[184:187], v[208:211], v[82:85]
	v_mfma_f32_16x16x32_bf16 v[70:73], v[176:179], v[216:219], v[70:73]
	v_mfma_f32_16x16x32_bf16 v[66:69], v[184:187], v[216:219], v[66:69]
	s_barrier
	s_add_i32 s21, s56, s25
	v_lshl_add_u64 v[220:221], s[0:1], 0, v[132:133]
	s_mov_b32 m0, s21
	ds_read_b128 v[188:191], v155 offset:16384
	ds_read_b128 v[192:195], v155 offset:17408
	ds_read_b128 v[196:199], v155 offset:18432
	ds_read_b128 v[200:203], v155 offset:19456
	ds_read_b128 v[204:207], v155 offset:20480
	ds_read_b128 v[208:211], v155 offset:21504
	ds_read_b128 v[212:215], v155 offset:22528
	ds_read_b128 v[216:219], v155 offset:23552
	global_load_lds_dwordx4 v[220:221], off
	s_add_i32 m0, s21, 0x2000
	s_add_u32 s28, s0, 0x80000
	v_lshl_add_u64 v[222:223], s[0:1], 0, v[136:137]
	s_addc_u32 s29, s1, 0
	s_add_i32 s21, s57, s25
	global_load_lds_dwordx4 v[222:223], off
	v_lshl_add_u64 v[224:225], s[28:29], 0, v[132:133]
	s_mov_b32 m0, s21
	v_lshl_add_u64 v[226:227], s[22:23], 0, v[134:135]
	global_load_lds_dwordx4 v[224:225], off
	v_lshl_add_u64 v[224:225], s[28:29], 0, v[136:137]
	s_add_i32 m0, s21, 0x2000
	s_nop 0
	global_load_lds_dwordx4 v[224:225], off
	v_lshl_add_u64 v[224:225], s[22:23], 0, v[130:131]
	s_mov_b32 m0, s26
	s_nop 0
	global_load_lds_dwordx4 v[224:225], off
	s_mov_b32 m0, s27
	s_nop 0
	global_load_lds_dwordx4 v[226:227], off
	s_waitcnt vmcnt(8)
	s_waitcnt lgkmcnt(0)
	s_barrier
	s_waitcnt lgkmcnt(0)
	v_mfma_f32_16x16x32_bf16 v[62:65], v[146:149], v[188:191], v[62:65]
	v_mfma_f32_16x16x32_bf16 v[58:61], v[160:163], v[188:191], v[58:61]
	v_mfma_f32_16x16x32_bf16 v[46:49], v[146:149], v[196:199], v[46:49]
	v_mfma_f32_16x16x32_bf16 v[42:45], v[160:163], v[196:199], v[42:45]
	v_mfma_f32_16x16x32_bf16 v[30:33], v[146:149], v[204:207], v[30:33]
	v_mfma_f32_16x16x32_bf16 v[26:29], v[160:163], v[204:207], v[26:29]
	v_mfma_f32_16x16x32_bf16 v[14:17], v[146:149], v[212:215], v[14:17]
	v_mfma_f32_16x16x32_bf16 v[10:13], v[160:163], v[212:215], v[10:13]
	v_mfma_f32_16x16x32_bf16 v[62:65], v[156:159], v[192:195], v[62:65]
	v_mfma_f32_16x16x32_bf16 v[58:61], v[168:171], v[192:195], v[58:61]
	v_mfma_f32_16x16x32_bf16 v[46:49], v[156:159], v[200:203], v[46:49]
	v_mfma_f32_16x16x32_bf16 v[42:45], v[168:171], v[200:203], v[42:45]
	v_mfma_f32_16x16x32_bf16 v[30:33], v[156:159], v[208:211], v[30:33]
	v_mfma_f32_16x16x32_bf16 v[26:29], v[168:171], v[208:211], v[26:29]
	v_mfma_f32_16x16x32_bf16 v[14:17], v[156:159], v[216:219], v[14:17]
	v_mfma_f32_16x16x32_bf16 v[10:13], v[168:171], v[216:219], v[10:13]
	v_mfma_f32_16x16x32_bf16 v[54:57], v[172:175], v[188:191], v[54:57]
	v_mfma_f32_16x16x32_bf16 v[50:53], v[180:183], v[188:191], v[50:53]
	v_mfma_f32_16x16x32_bf16 v[38:41], v[172:175], v[196:199], v[38:41]
	v_mfma_f32_16x16x32_bf16 v[34:37], v[180:183], v[196:199], v[34:37]
	v_mfma_f32_16x16x32_bf16 v[22:25], v[172:175], v[204:207], v[22:25]
	v_mfma_f32_16x16x32_bf16 v[18:21], v[180:183], v[204:207], v[18:21]
	v_mfma_f32_16x16x32_bf16 v[6:9], v[172:175], v[212:215], v[6:9]
	v_mfma_f32_16x16x32_bf16 v[2:5], v[180:183], v[212:215], v[2:5]
	v_mfma_f32_16x16x32_bf16 v[54:57], v[176:179], v[192:195], v[54:57]
	v_mfma_f32_16x16x32_bf16 v[50:53], v[184:187], v[192:195], v[50:53]
	v_mfma_f32_16x16x32_bf16 v[38:41], v[176:179], v[200:203], v[38:41]
	v_mfma_f32_16x16x32_bf16 v[34:37], v[184:187], v[200:203], v[34:37]
	v_mfma_f32_16x16x32_bf16 v[22:25], v[176:179], v[208:211], v[22:25]
	v_mfma_f32_16x16x32_bf16 v[18:21], v[184:187], v[208:211], v[18:21]
	v_mfma_f32_16x16x32_bf16 v[6:9], v[176:179], v[216:219], v[6:9]
	v_mfma_f32_16x16x32_bf16 v[2:5], v[184:187], v[216:219], v[2:5]
	s_barrier
	s_add_i32 s21, 0, 0x18000
	v_add_u32_e32 v165, s21, v151
	s_add_i32 s28, 0, 0x1c000
	ds_read_b128 v[146:149], v165
	ds_read_b128 v[156:159], v165 offset:1024
	ds_read_b128 v[160:163], v165 offset:2048
	ds_read_b128 v[168:171], v165 offset:3072
	v_add_u32_e32 v165, s28, v151
	ds_read_b128 v[172:175], v165
	ds_read_b128 v[176:179], v165 offset:1024
	ds_read_b128 v[180:183], v165 offset:2048
	ds_read_b128 v[184:187], v165 offset:3072
	s_add_u32 s22, s22, 0x80000
	s_addc_u32 s23, s23, 0
	s_mov_b32 m0, s30
	v_lshl_add_u64 v[228:229], s[22:23], 0, v[130:131]
	ds_read_b128 v[188:191], v155 offset:32768
	ds_read_b128 v[192:195], v155 offset:33792
	ds_read_b128 v[196:199], v155 offset:34816
	ds_read_b128 v[200:203], v155 offset:35840
	ds_read_b128 v[204:207], v155 offset:36864
	ds_read_b128 v[208:211], v155 offset:37888
	ds_read_b128 v[212:215], v155 offset:38912
	ds_read_b128 v[216:219], v155 offset:39936
	global_load_lds_dwordx4 v[228:229], off
	v_lshl_add_u64 v[228:229], s[22:23], 0, v[134:135]
	s_mov_b32 m0, s31
	s_nop 0
	global_load_lds_dwordx4 v[228:229], off
	s_waitcnt vmcnt(8)
	s_waitcnt lgkmcnt(0)
	s_barrier
	s_waitcnt lgkmcnt(0)
	v_mfma_f32_16x16x32_bf16 v[126:129], v[146:149], v[188:191], v[126:129]
	v_mfma_f32_16x16x32_bf16 v[122:125], v[160:163], v[188:191], v[122:125]
	v_mfma_f32_16x16x32_bf16 v[110:113], v[146:149], v[196:199], v[110:113]
	v_mfma_f32_16x16x32_bf16 v[106:109], v[160:163], v[196:199], v[106:109]
	v_mfma_f32_16x16x32_bf16 v[94:97], v[146:149], v[204:207], v[94:97]
	v_mfma_f32_16x16x32_bf16 v[90:93], v[160:163], v[204:207], v[90:93]
	v_mfma_f32_16x16x32_bf16 v[78:81], v[146:149], v[212:215], v[78:81]
	v_mfma_f32_16x16x32_bf16 v[74:77], v[160:163], v[212:215], v[74:77]
	v_mfma_f32_16x16x32_bf16 v[126:129], v[156:159], v[192:195], v[126:129]
	v_mfma_f32_16x16x32_bf16 v[122:125], v[168:171], v[192:195], v[122:125]
	v_mfma_f32_16x16x32_bf16 v[110:113], v[156:159], v[200:203], v[110:113]
	v_mfma_f32_16x16x32_bf16 v[106:109], v[168:171], v[200:203], v[106:109]
	v_mfma_f32_16x16x32_bf16 v[94:97], v[156:159], v[208:211], v[94:97]
	v_mfma_f32_16x16x32_bf16 v[90:93], v[168:171], v[208:211], v[90:93]
	v_mfma_f32_16x16x32_bf16 v[78:81], v[156:159], v[216:219], v[78:81]
	v_mfma_f32_16x16x32_bf16 v[74:77], v[168:171], v[216:219], v[74:77]
	v_mfma_f32_16x16x32_bf16 v[118:121], v[172:175], v[188:191], v[118:121]
	v_mfma_f32_16x16x32_bf16 v[114:117], v[180:183], v[188:191], v[114:117]
	v_mfma_f32_16x16x32_bf16 v[102:105], v[172:175], v[196:199], v[102:105]
	v_mfma_f32_16x16x32_bf16 v[98:101], v[180:183], v[196:199], v[98:101]
	v_mfma_f32_16x16x32_bf16 v[86:89], v[172:175], v[204:207], v[86:89]
	v_mfma_f32_16x16x32_bf16 v[82:85], v[180:183], v[204:207], v[82:85]
	v_mfma_f32_16x16x32_bf16 v[70:73], v[172:175], v[212:215], v[70:73]
	v_mfma_f32_16x16x32_bf16 v[66:69], v[180:183], v[212:215], v[66:69]
	v_mfma_f32_16x16x32_bf16 v[118:121], v[176:179], v[192:195], v[118:121]
	v_mfma_f32_16x16x32_bf16 v[114:117], v[184:187], v[192:195], v[114:117]
	v_mfma_f32_16x16x32_bf16 v[102:105], v[176:179], v[200:203], v[102:105]
	v_mfma_f32_16x16x32_bf16 v[98:101], v[184:187], v[200:203], v[98:101]
	v_mfma_f32_16x16x32_bf16 v[86:89], v[176:179], v[208:211], v[86:89]
	v_mfma_f32_16x16x32_bf16 v[82:85], v[184:187], v[208:211], v[82:85]
	v_mfma_f32_16x16x32_bf16 v[70:73], v[176:179], v[216:219], v[70:73]
	v_mfma_f32_16x16x32_bf16 v[66:69], v[184:187], v[216:219], v[66:69]
	s_barrier
	s_add_i32 s21, s21, s25
	v_lshl_add_u64 v[220:221], v[220:221], 0, s[10:11]
	s_mov_b32 m0, s21
	ds_read_b128 v[188:191], v155 offset:49152
	ds_read_b128 v[192:195], v155 offset:50176
	ds_read_b128 v[196:199], v155 offset:51200
	ds_read_b128 v[200:203], v155 offset:52224
	ds_read_b128 v[204:207], v155 offset:53248
	ds_read_b128 v[208:211], v155 offset:54272
	ds_read_b128 v[212:215], v155 offset:55296
	ds_read_b128 v[216:219], v155 offset:56320
	global_load_lds_dwordx4 v[220:221], off
	s_add_i32 m0, s21, 0x2000
	s_add_u32 s0, s0, 0x80080
	v_lshl_add_u64 v[220:221], v[222:223], 0, s[10:11]
	s_addc_u32 s1, s1, 0
	s_add_i32 s21, s28, s25
	global_load_lds_dwordx4 v[220:221], off
	v_lshl_add_u64 v[220:221], s[0:1], 0, v[132:133]
	s_mov_b32 m0, s21
	s_nop 0
	global_load_lds_dwordx4 v[220:221], off
	v_lshl_add_u64 v[220:221], s[0:1], 0, v[136:137]
	s_add_i32 m0, s21, 0x2000
	s_nop 0
	global_load_lds_dwordx4 v[220:221], off
	v_lshl_add_u64 v[220:221], v[224:225], 0, s[10:11]
	s_mov_b32 m0, s34
	s_nop 0
	global_load_lds_dwordx4 v[220:221], off
	v_lshl_add_u64 v[220:221], v[226:227], 0, s[10:11]
	s_mov_b32 m0, s35
	s_nop 0
	global_load_lds_dwordx4 v[220:221], off
	s_waitcnt vmcnt(8)
	s_waitcnt lgkmcnt(0)
	s_barrier
	s_waitcnt lgkmcnt(0)
	v_mfma_f32_16x16x32_bf16 v[62:65], v[146:149], v[188:191], v[62:65]
	v_mfma_f32_16x16x32_bf16 v[58:61], v[160:163], v[188:191], v[58:61]
	v_mfma_f32_16x16x32_bf16 v[46:49], v[146:149], v[196:199], v[46:49]
	v_mfma_f32_16x16x32_bf16 v[42:45], v[160:163], v[196:199], v[42:45]
	v_mfma_f32_16x16x32_bf16 v[30:33], v[146:149], v[204:207], v[30:33]
	v_mfma_f32_16x16x32_bf16 v[26:29], v[160:163], v[204:207], v[26:29]
	v_mfma_f32_16x16x32_bf16 v[14:17], v[146:149], v[212:215], v[14:17]
	v_mfma_f32_16x16x32_bf16 v[10:13], v[160:163], v[212:215], v[10:13]
	v_mfma_f32_16x16x32_bf16 v[62:65], v[156:159], v[192:195], v[62:65]
	v_mfma_f32_16x16x32_bf16 v[58:61], v[168:171], v[192:195], v[58:61]
	v_mfma_f32_16x16x32_bf16 v[46:49], v[156:159], v[200:203], v[46:49]
	v_mfma_f32_16x16x32_bf16 v[42:45], v[168:171], v[200:203], v[42:45]
	v_mfma_f32_16x16x32_bf16 v[30:33], v[156:159], v[208:211], v[30:33]
	v_mfma_f32_16x16x32_bf16 v[26:29], v[168:171], v[208:211], v[26:29]
	v_mfma_f32_16x16x32_bf16 v[14:17], v[156:159], v[216:219], v[14:17]
	v_mfma_f32_16x16x32_bf16 v[10:13], v[168:171], v[216:219], v[10:13]
	v_mfma_f32_16x16x32_bf16 v[54:57], v[172:175], v[188:191], v[54:57]
	v_mfma_f32_16x16x32_bf16 v[50:53], v[180:183], v[188:191], v[50:53]
	v_mfma_f32_16x16x32_bf16 v[38:41], v[172:175], v[196:199], v[38:41]
	v_mfma_f32_16x16x32_bf16 v[34:37], v[180:183], v[196:199], v[34:37]
	v_mfma_f32_16x16x32_bf16 v[22:25], v[172:175], v[204:207], v[22:25]
	v_mfma_f32_16x16x32_bf16 v[18:21], v[180:183], v[204:207], v[18:21]
	v_mfma_f32_16x16x32_bf16 v[6:9], v[172:175], v[212:215], v[6:9]
	v_mfma_f32_16x16x32_bf16 v[2:5], v[180:183], v[212:215], v[2:5]
	v_mfma_f32_16x16x32_bf16 v[54:57], v[176:179], v[192:195], v[54:57]
	v_mfma_f32_16x16x32_bf16 v[50:53], v[184:187], v[192:195], v[50:53]
	v_mfma_f32_16x16x32_bf16 v[38:41], v[176:179], v[200:203], v[38:41]
	v_mfma_f32_16x16x32_bf16 v[34:37], v[184:187], v[200:203], v[34:37]
	v_mfma_f32_16x16x32_bf16 v[22:25], v[176:179], v[208:211], v[22:25]
	v_mfma_f32_16x16x32_bf16 v[18:21], v[184:187], v[208:211], v[18:21]
	v_mfma_f32_16x16x32_bf16 v[6:9], v[176:179], v[216:219], v[6:9]
	v_mfma_f32_16x16x32_bf16 v[2:5], v[184:187], v[216:219], v[2:5]
	s_barrier
	s_add_i32 s68, s68, 2
	s_add_u32 s52, s52, 0x100
	s_addc_u32 s53, s53, 0
	s_add_u32 s66, s66, 0x100
	s_addc_u32 s67, s67, 0
	s_cmp_gt_u32 s68, 29
	s_cbranch_scc0 .LBB0_1875
	s_and_b64 vcc, exec, s[12:13]
	s_cbranch_vccz .LBB0_1878
	s_barrier

.LBB0_1968:
	s_setprio 0
	v_readlane_b32 s2, v243, 51
	s_cmp_lt_i32 s2, 24
	s_cselect_b64 s[28:29], -1, 0
	s_and_b64 s[0:1], s[28:29], s[0:1]
	s_andn2_b64 vcc, exec, s[0:1]
	v_readlane_b32 s3, v243, 52
	s_cbranch_vccnz .LBB0_2010
	v_readlane_b32 s0, v243, 0
	s_lshl_b32 s0, s0, 3
	v_readlane_b32 s1, v243, 59
	s_add_i32 s4, s1, s0
	s_cmp_gt_i32 s4, 0x81ff
	s_cbranch_scc1 .LBB0_1978
	s_add_u32 s6, s90, 0x900000
	s_addc_u32 s7, s91, 0
	s_add_u32 s8, s90, 0xb00000
	v_readlane_b32 s11, v243, 53
	s_addc_u32 s9, s91, 0
	s_lshl_b32 s16, s11, 3
	v_mov_b32_e32 v2, s79
	v_mov_b32_e32 v3, s77
	v_cmp_gt_u32_e32 vcc, 32, v166
	s_mul_i32 s12, s4, 0x3000
	v_readlane_b32 s0, v242, 17
	v_mov_b32_e32 v47, 0
	v_cndmask_b32_e32 v11, v2, v3, vcc
	v_mov_b32_e32 v2, s78
	v_mov_b32_e32 v3, s76
	v_lshlrev_b32_e32 v12, 7, v166
	s_mul_hi_i32 s5, s4, 0x3000
	v_readlane_b32 s1, v242, 18
	s_add_u32 s0, s0, s12
	v_cndmask_b32_e32 v10, v2, v3, vcc
	v_readlane_b32 s36, v243, 33
	v_and_b32_e32 v12, 0x80, v12
	v_mov_b32_e32 v13, v47
	v_lshlrev_b32_e32 v48, 4, v166
	s_addc_u32 s1, s1, s5
	v_mov_b32_e32 v49, v47
	v_lshlrev_b32_e32 v6, 5, v166
	v_readlane_b32 s40, v243, 37
	v_readlane_b32 s41, v243, 38
	s_waitcnt lgkmcnt(0)
	v_lshl_add_u64 v[38:39], v[10:11], 0, v[12:13]
	v_lshl_add_u64 v[42:43], s[0:1], 0, v[48:49]
	s_movk_i32 s10, 0x2000
	v_lshlrev_b32_e32 v46, 3, v166
	global_load_dwordx4 v[2:5], v6, s[40:41] offset:2064
	s_nop 0
	global_load_dwordx4 v[6:9], v6, s[40:41] offset:2048
	s_nop 0
	global_load_dwordx4 v[10:13], v[38:39], off offset:368
	global_load_dwordx4 v[14:17], v[38:39], off offset:352
	global_load_dwordx4 v[18:21], v[38:39], off offset:336
	global_load_dwordx4 v[22:25], v[38:39], off offset:320
	global_load_dwordx4 v[26:29], v[38:39], off offset:304
	global_load_dwordx4 v[30:33], v[38:39], off offset:288
	global_load_dwordx4 v[34:37], v[38:39], off offset:272
	s_nop 0
	global_load_dwordx4 v[38:41], v[38:39], off offset:256
	v_add_co_u32_e64 v42, s[2:3], s10, v42
	v_lshl_add_u64 v[44:45], s[0:1], 0, v[46:47]
	s_nop 0
	v_addc_co_u32_e64 v43, s[2:3], 0, v43, s[2:3]
	v_lshlrev_b32_e32 v50, 6, v166
	v_mov_b32_e32 v51, v47
	v_add_co_u32_e64 v44, s[2:3], s10, v44
	v_lshl_add_u64 v[52:53], s[0:1], 0, v[50:51]
	s_mov_b64 s[0:1], 0x1000
	v_addc_co_u32_e64 v45, s[2:3], 0, v45, s[2:3]
	v_lshl_add_u64 v[54:55], v[52:53], 0, s[0:1]
	s_movk_i32 s0, 0x1000
	v_add_co_u32_e64 v52, s[2:3], s0, v52
	v_readlane_b32 s42, v243, 39
	s_nop 0
	v_addc_co_u32_e64 v53, s[2:3], 0, v53, s[2:3]
	v_readlane_b32 s43, v243, 40
	global_load_dwordx4 v[142:145], v[52:53], off
	global_load_dwordx4 v[134:137], v[54:55], off offset:32
	global_load_dwordx4 v[138:141], v[54:55], off offset:16
	global_load_dwordx4 v[130:133], v[54:55], off offset:48
	global_load_dwordx4 v[146:149], v[42:43], off offset:2048
	global_load_dwordx2 v[170:171], v[44:45], off offset:3072
	s_nop 0
	global_load_dwordx4 v[42:45], v48, s[42:43] offset:1024
	v_mbcnt_lo_u32_b32 v47, -1, 0
	v_mbcnt_hi_u32_b32 v47, -1, v47
	v_and_b32_e32 v49, 64, v47
	v_add_u32_e32 v49, 64, v49
	v_xor_b32_e32 v51, 1, v47
	v_cmp_lt_i32_e64 s[2:3], v51, v49
	v_readlane_b32 s0, v243, 0
	v_readlane_b32 s1, v243, 59
	v_cndmask_b32_e64 v51, v47, v51, s[2:3]
	v_lshlrev_b32_e32 v165, 2, v51
	v_xor_b32_e32 v51, 2, v47
	v_cmp_lt_i32_e64 s[2:3], v51, v49
	s_lshl_b32 s0, s0, 8
	s_lshl_b32 s1, s1, 5
	v_cndmask_b32_e64 v51, v47, v51, s[2:3]
	v_lshlrev_b32_e32 v184, 2, v51
	v_xor_b32_e32 v51, 4, v47
	v_cmp_lt_i32_e64 s[2:3], v51, v49
	s_add_i32 s17, s0, s1
	s_add_i32 s0, s4, s16
	v_cndmask_b32_e64 v51, v47, v51, s[2:3]
	v_lshlrev_b32_e32 v185, 2, v51
	v_xor_b32_e32 v51, 8, v47
	v_cmp_lt_i32_e64 s[2:3], v51, v49
	s_mul_hi_i32 s1, s0, 0x3000
	s_mul_i32 s13, s0, 0x3000
	v_cndmask_b32_e64 v51, v47, v51, s[2:3]
	v_lshlrev_b32_e32 v186, 2, v51
	v_xor_b32_e32 v51, 16, v47
	v_cmp_lt_i32_e64 s[2:3], v51, v49
	v_or_b32_e32 v158, s12, v48
	v_mov_b32_e32 v159, s5
	v_cndmask_b32_e64 v51, v47, v51, s[2:3]
	v_lshlrev_b32_e32 v187, 2, v51
	v_xor_b32_e32 v51, 32, v47
	v_cmp_lt_i32_e64 s[2:3], v51, v49
	s_lshl_b32 s18, s11, 8
	s_mul_i32 s19, s11, 0x18000
	v_cndmask_b32_e64 v47, v47, v51, s[2:3]
	v_lshlrev_b32_e32 v188, 2, v47
	v_mov_b32_e32 v47, 0x3e38aa3b
	v_cndmask_b32_e32 v150, 1.0, v47, vcc
	v_and_b32_e32 v47, 1, v0
	s_mov_b64 s[10:11], 0x15b02c00
	v_cmp_eq_u32_e64 s[2:3], 0, v47
	v_mov_b32_e32 v151, v150
	s_mul_hi_i32 s20, s16, 0x3000
	s_mov_b32 s22, 0x15b01000
	s_movk_i32 s23, 0x7fff
	s_mov_b32 s24, 0xffff0000
	v_mov_b32_e32 v189, 0x358637bd
	s_mov_b32 s25, 0xf800000
	v_mov_b32_e32 v190, 0x260
	v_mov_b32_e32 v191, 1
	v_readlane_b32 s37, v243, 34
	v_readlane_b32 s38, v243, 35
	s_waitcnt vmcnt(0)
	v_mov_b32_e32 v152, v7
	v_mov_b32_e32 v153, v9
	v_mov_b32_e32 v7, v8
	v_mov_b32_e32 v8, v3
	v_mov_b32_e32 v9, v5
	v_mov_b32_e32 v3, v4
	v_or_b32_e32 v4, s13, v48
	v_mov_b32_e32 v5, s1
	s_mov_b64 s[0:1], 0x15b02800
	v_lshl_add_u64 v[154:155], v[4:5], 0, s[0:1]
	v_or_b32_e32 v4, s13, v46
	v_lshl_add_u64 v[160:161], v[158:159], 0, s[0:1]
	v_or_b32_e32 v158, s12, v46
	v_lshl_add_u64 v[156:157], v[4:5], 0, s[10:11]
	v_or_b32_e32 v4, s13, v50
	v_lshl_add_u64 v[162:163], v[158:159], 0, s[10:11]
	v_or_b32_e32 v158, s12, v50
	v_mov_b64_e32 v[66:67], v[142:143]
	v_mov_b64_e32 v[74:75], v[134:135]
	v_mov_b64_e32 v[70:71], v[138:139]
	v_mov_b64_e32 v[78:79], v[130:131]
	v_mov_b64_e32 v[62:63], v[146:147]
	s_mov_b64 s[10:11], 0x15b01000
	s_mov_b64 s[12:13], s[90:91]
	v_mov_b64_e32 v[68:69], v[144:145]
	v_mov_b64_e32 v[72:73], v[140:141]
	v_mov_b64_e32 v[76:77], v[136:137]
	v_mov_b64_e32 v[80:81], v[132:133]
	v_mov_b64_e32 v[168:169], v[170:171]
	v_mov_b64_e32 v[64:65], v[148:149]
	v_readlane_b32 s39, v243, 36
	v_readlane_b32 s44, v243, 41
	v_readlane_b32 s45, v243, 42
	v_readlane_b32 s46, v243, 43
	v_readlane_b32 s47, v243, 44
	v_readlane_b32 s48, v243, 45
	v_readlane_b32 s49, v243, 46
	v_readlane_b32 s50, v243, 47
	v_readlane_b32 s51, v243, 48
	s_branch .LBB0_1972

.LBB0_2064:
	s_setprio 0
	v_readlane_b32 s2, v243, 51
	s_cmp_lt_i32 s2, 25
	s_cselect_b64 s[44:45], -1, 0
	s_and_b64 s[0:1], s[44:45], s[0:1]
	s_andn2_b64 vcc, exec, s[0:1]
	v_readlane_b32 s3, v243, 52
	s_cbranch_vccnz .LBB0_2144
	v_lshrrev_b32_e32 v4, 5, v0
	v_lshrrev_b32_e32 v6, 1, v0
	v_lshlrev_b32_e32 v2, 4, v0
	v_and_b32_e32 v172, 32, v0
	v_and_b32_e32 v4, 4, v4
	v_bfe_u32 v5, v0, 2, 2
	v_and_b32_e32 v147, 24, v6
	v_bfe_u32 v3, v0, 2, 4
	v_bitop3_b32 v10, v2, v172, 48 bitop3:0x6c
	v_and_b32_e32 v11, 64, v0
	v_or3_b32 v4, v4, v5, v147
	v_lshrrev_b32_e32 v5, 3, v0
	v_or_b32_e32 v150, v10, v11
	v_and_or_b32 v6, v5, 48, v3
	v_lshrrev_b32_e32 v2, 1, v150
	v_mul_u32_u24_e32 v12, 0x1800, v6
	v_and_or_b32 v151, v5, 32, v4
	v_or_b32_e32 v5, v2, v12
	v_lshlrev_b32_e32 v130, 1, v5
	v_bfe_u32 v5, v0, 3, 25
	v_or_b32_e32 v5, 64, v5
	s_movk_i32 s0, 0x70
	v_and_or_b32 v3, v5, s0, v3
	v_mul_u32_u24_e32 v13, 0x1800, v3
	v_or_b32_e32 v2, v13, v2
	v_lshlrev_b32_e32 v132, 1, v2
	v_lshlrev_b32_e32 v2, 6, v0
	s_movk_i32 s0, 0x60
	v_lshlrev_b32_e32 v148, 1, v147
	v_and_b32_e32 v2, 0x3c0, v2
	v_and_b32_e32 v3, 32, v164
	v_readlane_b32 s5, v243, 0
	v_readfirstlane_b32 s3, v0
	v_and_b32_e32 v146, 15, v0
	v_and_or_b32 v152, v5, s0, v4
	s_cmpk_gt_i32 s5, 0x30b
	v_bitop3_b32 v149, v148, v3, v2 bitop3:0x36
	s_cbranch_scc1 .LBB0_2091
	s_ashr_i32 s20, s5, 31
	s_lshr_b32 s0, s20, 29
	s_add_i32 s4, s5, s0
	s_and_b32 s0, s4, -8
	s_sub_i32 s5, s5, s0
	s_cmp_gt_i32 s5, 3
	s_cbranch_scc0 .LBB0_2068
	s_mul_i32 s0, s5, 0x61
	s_add_i32 s2, s0, 4
	s_cbranch_execz .LBB0_2069
	s_branch .LBB0_2070

.LBB0_2070:
	s_ashr_i32 s0, s4, 3
	s_add_u32 s22, s90, 0x15b02800
	s_addc_u32 s23, s91, 0
	s_add_u32 s24, s90, 0xd500000
	s_addc_u32 s25, s91, 0
	s_add_i32 s0, s2, s0
	s_mul_hi_i32 s1, s0, 0x2aaaaaab
	s_lshr_b32 s2, s1, 31
	s_ashr_i32 s1, s1, 3
	s_add_i32 s1, s1, s2
	s_lshl_b32 s6, s1, 3
	s_sub_i32 s2, 0x82, s6
	s_mul_i32 s1, s1, 48
	s_min_u32 s7, s2, 8
	s_sub_i32 s8, s0, s1
	s_sext_i32_i8 s0, s8
	v_cvt_f32_ubyte0_e32 v3, s7
	v_cvt_f32_i32_e32 v2, s0
	v_rcp_iflag_f32_e32 v4, v3
	s_lshr_b32 s5, s3, 6
	s_ashr_i32 s0, s0, 30
	s_lshr_b32 s4, s3, 8
	v_mul_f32_e32 v4, v2, v4
	v_trunc_f32_e32 v4, v4
	v_fma_f32 v2, -v4, v3, v2
	v_cvt_i32_f32_e32 v4, v4
	s_lshl_b32 s26, s5, 10
	s_or_b32 s2, s0, 1
	v_cmp_ge_f32_e64 s[0:1], |v2|, v3
	s_and_b64 s[0:1], s[0:1], exec
	s_cselect_b32 s0, s2, 0
	v_readfirstlane_b32 s1, v4
	s_add_i32 s2, s1, s0
	s_mul_i32 s0, s2, s7
	s_sub_i32 s0, s8, s0
	s_sext_i32_i8 s0, s0
	s_add_i32 s55, s6, s0
	s_bfe_i64 s[0:1], s[2:3], 0x80000
	s_lshl_b64 s[0:1], s[0:1], 18
	s_add_u32 s0, s24, s0
	s_addc_u32 s1, s25, s1
	s_add_i32 s27, s26, 0
	v_lshl_or_b32 v134, v151, 10, v150
	s_add_i32 m0, s27, 0x10000
	v_lshl_or_b32 v136, v152, 10, v150
	global_load_lds_dwordx4 v134, s[0:1]
	s_add_i32 m0, s27, 0x12000
	s_add_u32 s6, s0, 0x20000
	global_load_lds_dwordx4 v136, s[0:1]
	s_addc_u32 s7, s1, 0
	s_add_i32 m0, s27, 0x14000
	s_mul_i32 s9, s55, 0x300000
	global_load_lds_dwordx4 v134, s[6:7]
	s_add_i32 m0, s27, 0x16000
	s_mul_hi_i32 s8, s55, 0x300000
	s_add_u32 s18, s22, s9
	s_addc_u32 s19, s23, s8
	s_add_i32 s30, s27, 0x2000
	global_load_lds_dwordx4 v136, s[6:7]
	s_mov_b32 m0, s27
	s_add_u32 s6, s18, 0x180000
	global_load_lds_dwordx4 v130, s[18:19]
	s_mov_b32 m0, s30
	s_addc_u32 s7, s19, 0
	s_add_i32 s31, s27, 0x4000
	global_load_lds_dwordx4 v132, s[18:19]
	s_mov_b32 m0, s31
	s_add_i32 s33, s27, 0x6000
	global_load_lds_dwordx4 v130, s[6:7]
	s_mov_b32 m0, s33
	v_mov_b32_e32 v135, 0
	global_load_lds_dwordx4 v132, s[6:7]
	v_mov_b32_e32 v137, v135
	v_mov_b32_e32 v131, v135
	v_mov_b32_e32 v133, v135
	s_cmp_eq_u32 s4, 1
	s_mov_b32 s34, 0
	v_lshl_add_u64 v[8:9], s[0:1], 0, v[134:135]
	v_lshl_add_u64 v[6:7], s[0:1], 0, v[136:137]
	v_lshl_add_u64 v[2:3], s[18:19], 0, v[130:131]
	s_cselect_b64 s[6:7], -1, 0
	s_cmp_lg_u32 s4, 1
	v_lshl_add_u64 v[4:5], s[18:19], 0, v[132:133]
	s_cbranch_scc1 .LBB0_2072
	s_barrier
	s_setprio 1

.LBB0_2084:
	ds_read_b128 v[160:163], v156
	ds_read_b128 v[168:171], v156 offset:1024
	ds_read_b128 v[174:177], v156 offset:2048
	ds_read_b128 v[178:181], v156 offset:3072
	ds_read_b128 v[182:185], v157
	ds_read_b128 v[186:189], v157 offset:1024
	ds_read_b128 v[190:193], v157 offset:2048
	ds_read_b128 v[194:197], v157 offset:3072
	s_add_u32 s0, s4, 0xffe80080
	s_addc_u32 s1, s5, -1
	s_cmp_eq_u32 s67, 4
	s_cselect_b32 s19, s15, s1
	s_cselect_b32 s18, s14, s0
	s_cselect_b32 s1, s13, s66
	s_cselect_b32 s0, s62, s63
	v_lshl_add_u64 v[230:231], s[4:5], 0, v[138:139]
	s_add_i32 m0, s27, 0xc000
	ds_read_b128 v[198:201], v158
	ds_read_b128 v[202:205], v158 offset:1024
	ds_read_b128 v[206:209], v158 offset:2048
	ds_read_b128 v[210:213], v158 offset:3072
	ds_read_b128 v[214:217], v158 offset:4096
	ds_read_b128 v[218:221], v158 offset:5120
	ds_read_b128 v[222:225], v158 offset:6144
	ds_read_b128 v[226:229], v158 offset:7168
	global_load_lds_dwordx4 v[230:231], off
	v_lshl_add_u64 v[230:231], s[4:5], 0, v[140:141]
	s_add_i32 m0, s27, 0xe000
	s_nop 0
	global_load_lds_dwordx4 v[230:231], off
	s_waitcnt vmcnt(8)
	s_waitcnt lgkmcnt(0)
	s_barrier
	s_waitcnt lgkmcnt(0)
	v_mfma_f32_16x16x32_bf16 v[126:129], v[160:163], v[198:201], v[126:129]
	v_mfma_f32_16x16x32_bf16 v[122:125], v[174:177], v[198:201], v[122:125]
	v_mfma_f32_16x16x32_bf16 v[118:121], v[160:163], v[206:209], v[118:121]
	v_mfma_f32_16x16x32_bf16 v[114:117], v[174:177], v[206:209], v[114:117]
	v_mfma_f32_16x16x32_bf16 v[102:105], v[160:163], v[214:217], v[102:105]
	v_mfma_f32_16x16x32_bf16 v[98:101], v[174:177], v[214:217], v[98:101]
	v_mfma_f32_16x16x32_bf16 v[86:89], v[160:163], v[222:225], v[86:89]
	v_mfma_f32_16x16x32_bf16 v[82:85], v[174:177], v[222:225], v[82:85]
	v_mfma_f32_16x16x32_bf16 v[126:129], v[168:171], v[202:205], v[126:129]
	v_mfma_f32_16x16x32_bf16 v[122:125], v[178:181], v[202:205], v[122:125]
	v_mfma_f32_16x16x32_bf16 v[118:121], v[168:171], v[210:213], v[118:121]
	v_mfma_f32_16x16x32_bf16 v[114:117], v[178:181], v[210:213], v[114:117]
	v_mfma_f32_16x16x32_bf16 v[102:105], v[168:171], v[218:221], v[102:105]
	v_mfma_f32_16x16x32_bf16 v[98:101], v[178:181], v[218:221], v[98:101]
	v_mfma_f32_16x16x32_bf16 v[86:89], v[168:171], v[226:229], v[86:89]
	v_mfma_f32_16x16x32_bf16 v[82:85], v[178:181], v[226:229], v[82:85]
	v_mfma_f32_16x16x32_bf16 v[110:113], v[182:185], v[198:201], v[110:113]
	v_mfma_f32_16x16x32_bf16 v[106:109], v[190:193], v[198:201], v[106:109]
	v_mfma_f32_16x16x32_bf16 v[94:97], v[182:185], v[206:209], v[94:97]
	v_mfma_f32_16x16x32_bf16 v[90:93], v[190:193], v[206:209], v[90:93]
	v_mfma_f32_16x16x32_bf16 v[78:81], v[182:185], v[214:217], v[78:81]
	v_mfma_f32_16x16x32_bf16 v[74:77], v[190:193], v[214:217], v[74:77]
	v_mfma_f32_16x16x32_bf16 v[70:73], v[182:185], v[222:225], v[70:73]
	v_mfma_f32_16x16x32_bf16 v[66:69], v[190:193], v[222:225], v[66:69]
	v_mfma_f32_16x16x32_bf16 v[110:113], v[186:189], v[202:205], v[110:113]
	v_mfma_f32_16x16x32_bf16 v[106:109], v[194:197], v[202:205], v[106:109]
	v_mfma_f32_16x16x32_bf16 v[94:97], v[186:189], v[210:213], v[94:97]
	v_mfma_f32_16x16x32_bf16 v[90:93], v[194:197], v[210:213], v[90:93]
	v_mfma_f32_16x16x32_bf16 v[78:81], v[186:189], v[218:221], v[78:81]
	v_mfma_f32_16x16x32_bf16 v[74:77], v[194:197], v[218:221], v[74:77]
	v_mfma_f32_16x16x32_bf16 v[70:73], v[186:189], v[226:229], v[70:73]
	v_mfma_f32_16x16x32_bf16 v[66:69], v[194:197], v[226:229], v[66:69]
	s_barrier
	s_add_i32 s21, s52, s26
	v_lshl_add_u64 v[230:231], s[0:1], 0, v[134:135]
	s_mov_b32 m0, s21
	ds_read_b128 v[198:201], v158 offset:16384
	ds_read_b128 v[202:205], v158 offset:17408
	ds_read_b128 v[206:209], v158 offset:18432
	ds_read_b128 v[210:213], v158 offset:19456
	ds_read_b128 v[214:217], v158 offset:20480
	ds_read_b128 v[218:221], v158 offset:21504
	ds_read_b128 v[222:225], v158 offset:22528
	ds_read_b128 v[226:229], v158 offset:23552
	global_load_lds_dwordx4 v[230:231], off
	s_add_i32 m0, s21, 0x2000
	s_add_u32 s28, s0, 0x20000
	v_lshl_add_u64 v[232:233], s[0:1], 0, v[136:137]
	s_addc_u32 s29, s1, 0
	s_add_i32 s21, s53, s26
	global_load_lds_dwordx4 v[232:233], off
	v_lshl_add_u64 v[234:235], s[28:29], 0, v[134:135]
	s_mov_b32 m0, s21
	v_lshl_add_u64 v[236:237], s[18:19], 0, v[132:133]
	global_load_lds_dwordx4 v[234:235], off
	v_lshl_add_u64 v[234:235], s[28:29], 0, v[136:137]
	s_add_i32 m0, s21, 0x2000
	s_nop 0
	global_load_lds_dwordx4 v[234:235], off
	v_lshl_add_u64 v[234:235], s[18:19], 0, v[130:131]
	s_mov_b32 m0, s27
	s_nop 0
	global_load_lds_dwordx4 v[234:235], off
	s_mov_b32 m0, s30
	s_nop 0
	global_load_lds_dwordx4 v[236:237], off
	s_waitcnt vmcnt(8)
	s_waitcnt lgkmcnt(0)
	s_barrier
	s_waitcnt lgkmcnt(0)
	v_mfma_f32_16x16x32_bf16 v[62:65], v[160:163], v[198:201], v[62:65]
	v_mfma_f32_16x16x32_bf16 v[58:61], v[174:177], v[198:201], v[58:61]
	v_mfma_f32_16x16x32_bf16 v[54:57], v[160:163], v[206:209], v[54:57]
	v_mfma_f32_16x16x32_bf16 v[50:53], v[174:177], v[206:209], v[50:53]
	v_mfma_f32_16x16x32_bf16 v[38:41], v[160:163], v[214:217], v[38:41]
	v_mfma_f32_16x16x32_bf16 v[34:37], v[174:177], v[214:217], v[34:37]
	v_mfma_f32_16x16x32_bf16 v[22:25], v[160:163], v[222:225], v[22:25]
	v_mfma_f32_16x16x32_bf16 v[18:21], v[174:177], v[222:225], v[18:21]
	v_mfma_f32_16x16x32_bf16 v[62:65], v[168:171], v[202:205], v[62:65]
	v_mfma_f32_16x16x32_bf16 v[58:61], v[178:181], v[202:205], v[58:61]
	v_mfma_f32_16x16x32_bf16 v[54:57], v[168:171], v[210:213], v[54:57]
	v_mfma_f32_16x16x32_bf16 v[50:53], v[178:181], v[210:213], v[50:53]
	v_mfma_f32_16x16x32_bf16 v[38:41], v[168:171], v[218:221], v[38:41]
	v_mfma_f32_16x16x32_bf16 v[34:37], v[178:181], v[218:221], v[34:37]
	v_mfma_f32_16x16x32_bf16 v[22:25], v[168:171], v[226:229], v[22:25]
	v_mfma_f32_16x16x32_bf16 v[18:21], v[178:181], v[226:229], v[18:21]
	v_mfma_f32_16x16x32_bf16 v[46:49], v[182:185], v[198:201], v[46:49]
	v_mfma_f32_16x16x32_bf16 v[42:45], v[190:193], v[198:201], v[42:45]
	v_mfma_f32_16x16x32_bf16 v[30:33], v[182:185], v[206:209], v[30:33]
	v_mfma_f32_16x16x32_bf16 v[26:29], v[190:193], v[206:209], v[26:29]
	v_mfma_f32_16x16x32_bf16 v[14:17], v[182:185], v[214:217], v[14:17]
	v_mfma_f32_16x16x32_bf16 v[10:13], v[190:193], v[214:217], v[10:13]
	v_mfma_f32_16x16x32_bf16 v[6:9], v[182:185], v[222:225], v[6:9]
	v_mfma_f32_16x16x32_bf16 v[2:5], v[190:193], v[222:225], v[2:5]
	v_mfma_f32_16x16x32_bf16 v[46:49], v[186:189], v[202:205], v[46:49]
	v_mfma_f32_16x16x32_bf16 v[42:45], v[194:197], v[202:205], v[42:45]
	v_mfma_f32_16x16x32_bf16 v[30:33], v[186:189], v[210:213], v[30:33]
	v_mfma_f32_16x16x32_bf16 v[26:29], v[194:197], v[210:213], v[26:29]
	v_mfma_f32_16x16x32_bf16 v[14:17], v[186:189], v[218:221], v[14:17]
	v_mfma_f32_16x16x32_bf16 v[10:13], v[194:197], v[218:221], v[10:13]
	v_mfma_f32_16x16x32_bf16 v[6:9], v[186:189], v[226:229], v[6:9]
	v_mfma_f32_16x16x32_bf16 v[2:5], v[194:197], v[226:229], v[2:5]
	s_barrier
	s_add_i32 s21, 0, 0x18000
	v_add_u32_e32 v159, s21, v154
	s_add_i32 s28, 0, 0x1c000
	ds_read_b128 v[160:163], v159
	ds_read_b128 v[168:171], v159 offset:1024
	ds_read_b128 v[174:177], v159 offset:2048
	ds_read_b128 v[178:181], v159 offset:3072
	v_add_u32_e32 v159, s28, v154
	ds_read_b128 v[182:185], v159
	ds_read_b128 v[186:189], v159 offset:1024
	ds_read_b128 v[190:193], v159 offset:2048
	ds_read_b128 v[194:197], v159 offset:3072
	s_add_u32 s18, s18, 0x180000
	s_addc_u32 s19, s19, 0
	s_mov_b32 m0, s31
	v_lshl_add_u64 v[238:239], s[18:19], 0, v[130:131]
	ds_read_b128 v[198:201], v158 offset:32768
	ds_read_b128 v[202:205], v158 offset:33792
	ds_read_b128 v[206:209], v158 offset:34816
	ds_read_b128 v[210:213], v158 offset:35840
	ds_read_b128 v[214:217], v158 offset:36864
	ds_read_b128 v[218:221], v158 offset:37888
	ds_read_b128 v[222:225], v158 offset:38912
	ds_read_b128 v[226:229], v158 offset:39936
	global_load_lds_dwordx4 v[238:239], off
	v_lshl_add_u64 v[238:239], s[18:19], 0, v[132:133]
	s_mov_b32 m0, s33
	s_nop 0
	global_load_lds_dwordx4 v[238:239], off
	s_waitcnt vmcnt(8)
	s_waitcnt lgkmcnt(0)
	s_barrier
	s_waitcnt lgkmcnt(0)
	v_mfma_f32_16x16x32_bf16 v[126:129], v[160:163], v[198:201], v[126:129]
	v_mfma_f32_16x16x32_bf16 v[122:125], v[174:177], v[198:201], v[122:125]
	v_mfma_f32_16x16x32_bf16 v[118:121], v[160:163], v[206:209], v[118:121]
	v_mfma_f32_16x16x32_bf16 v[114:117], v[174:177], v[206:209], v[114:117]
	v_mfma_f32_16x16x32_bf16 v[102:105], v[160:163], v[214:217], v[102:105]
	v_mfma_f32_16x16x32_bf16 v[98:101], v[174:177], v[214:217], v[98:101]
	v_mfma_f32_16x16x32_bf16 v[86:89], v[160:163], v[222:225], v[86:89]
	v_mfma_f32_16x16x32_bf16 v[82:85], v[174:177], v[222:225], v[82:85]
	v_mfma_f32_16x16x32_bf16 v[126:129], v[168:171], v[202:205], v[126:129]
	v_mfma_f32_16x16x32_bf16 v[122:125], v[178:181], v[202:205], v[122:125]
	v_mfma_f32_16x16x32_bf16 v[118:121], v[168:171], v[210:213], v[118:121]
	v_mfma_f32_16x16x32_bf16 v[114:117], v[178:181], v[210:213], v[114:117]
	v_mfma_f32_16x16x32_bf16 v[102:105], v[168:171], v[218:221], v[102:105]
	v_mfma_f32_16x16x32_bf16 v[98:101], v[178:181], v[218:221], v[98:101]
	v_mfma_f32_16x16x32_bf16 v[86:89], v[168:171], v[226:229], v[86:89]
	v_mfma_f32_16x16x32_bf16 v[82:85], v[178:181], v[226:229], v[82:85]
	v_mfma_f32_16x16x32_bf16 v[110:113], v[182:185], v[198:201], v[110:113]
	v_mfma_f32_16x16x32_bf16 v[106:109], v[190:193], v[198:201], v[106:109]
	v_mfma_f32_16x16x32_bf16 v[94:97], v[182:185], v[206:209], v[94:97]
	v_mfma_f32_16x16x32_bf16 v[90:93], v[190:193], v[206:209], v[90:93]
	v_mfma_f32_16x16x32_bf16 v[78:81], v[182:185], v[214:217], v[78:81]
	v_mfma_f32_16x16x32_bf16 v[74:77], v[190:193], v[214:217], v[74:77]
	v_mfma_f32_16x16x32_bf16 v[70:73], v[182:185], v[222:225], v[70:73]
	v_mfma_f32_16x16x32_bf16 v[66:69], v[190:193], v[222:225], v[66:69]
	v_mfma_f32_16x16x32_bf16 v[110:113], v[186:189], v[202:205], v[110:113]
	v_mfma_f32_16x16x32_bf16 v[106:109], v[194:197], v[202:205], v[106:109]
	v_mfma_f32_16x16x32_bf16 v[94:97], v[186:189], v[210:213], v[94:97]
	v_mfma_f32_16x16x32_bf16 v[90:93], v[194:197], v[210:213], v[90:93]
	v_mfma_f32_16x16x32_bf16 v[78:81], v[186:189], v[218:221], v[78:81]
	v_mfma_f32_16x16x32_bf16 v[74:77], v[194:197], v[218:221], v[74:77]
	v_mfma_f32_16x16x32_bf16 v[70:73], v[186:189], v[226:229], v[70:73]
	v_mfma_f32_16x16x32_bf16 v[66:69], v[194:197], v[226:229], v[66:69]
	s_barrier
	s_add_i32 s18, s21, s26
	v_lshl_add_u64 v[230:231], v[230:231], 0, s[8:9]
	s_mov_b32 m0, s18
	ds_read_b128 v[198:201], v158 offset:49152
	ds_read_b128 v[202:205], v158 offset:50176
	ds_read_b128 v[206:209], v158 offset:51200
	ds_read_b128 v[210:213], v158 offset:52224
	ds_read_b128 v[214:217], v158 offset:53248
	ds_read_b128 v[218:221], v158 offset:54272
	ds_read_b128 v[222:225], v158 offset:55296
	ds_read_b128 v[226:229], v158 offset:56320
	global_load_lds_dwordx4 v[230:231], off
	s_add_i32 m0, s18, 0x2000
	s_add_u32 s0, s0, 0x20080
	v_lshl_add_u64 v[230:231], v[232:233], 0, s[8:9]
	s_addc_u32 s1, s1, 0
	s_add_i32 s18, s28, s26
	global_load_lds_dwordx4 v[230:231], off
	v_lshl_add_u64 v[230:231], s[0:1], 0, v[134:135]
	s_mov_b32 m0, s18
	s_nop 0
	global_load_lds_dwordx4 v[230:231], off
	v_lshl_add_u64 v[230:231], s[0:1], 0, v[136:137]
	s_add_i32 m0, s18, 0x2000
	s_nop 0
	global_load_lds_dwordx4 v[230:231], off
	v_lshl_add_u64 v[230:231], v[234:235], 0, s[8:9]
	s_mov_b32 m0, s35
	s_nop 0
	global_load_lds_dwordx4 v[230:231], off
	v_lshl_add_u64 v[230:231], v[236:237], 0, s[8:9]
	s_mov_b32 m0, s46
	s_nop 0
	global_load_lds_dwordx4 v[230:231], off
	s_waitcnt vmcnt(8)
	s_waitcnt lgkmcnt(0)
	s_barrier
	s_waitcnt lgkmcnt(0)
	v_mfma_f32_16x16x32_bf16 v[62:65], v[160:163], v[198:201], v[62:65]
	v_mfma_f32_16x16x32_bf16 v[58:61], v[174:177], v[198:201], v[58:61]
	v_mfma_f32_16x16x32_bf16 v[54:57], v[160:163], v[206:209], v[54:57]
	v_mfma_f32_16x16x32_bf16 v[50:53], v[174:177], v[206:209], v[50:53]
	v_mfma_f32_16x16x32_bf16 v[38:41], v[160:163], v[214:217], v[38:41]
	v_mfma_f32_16x16x32_bf16 v[34:37], v[174:177], v[214:217], v[34:37]
	v_mfma_f32_16x16x32_bf16 v[22:25], v[160:163], v[222:225], v[22:25]
	v_mfma_f32_16x16x32_bf16 v[18:21], v[174:177], v[222:225], v[18:21]
	v_mfma_f32_16x16x32_bf16 v[62:65], v[168:171], v[202:205], v[62:65]
	v_mfma_f32_16x16x32_bf16 v[58:61], v[178:181], v[202:205], v[58:61]
	v_mfma_f32_16x16x32_bf16 v[54:57], v[168:171], v[210:213], v[54:57]
	v_mfma_f32_16x16x32_bf16 v[50:53], v[178:181], v[210:213], v[50:53]
	v_mfma_f32_16x16x32_bf16 v[38:41], v[168:171], v[218:221], v[38:41]
	v_mfma_f32_16x16x32_bf16 v[34:37], v[178:181], v[218:221], v[34:37]
	v_mfma_f32_16x16x32_bf16 v[22:25], v[168:171], v[226:229], v[22:25]
	v_mfma_f32_16x16x32_bf16 v[18:21], v[178:181], v[226:229], v[18:21]
	v_mfma_f32_16x16x32_bf16 v[46:49], v[182:185], v[198:201], v[46:49]
	v_mfma_f32_16x16x32_bf16 v[42:45], v[190:193], v[198:201], v[42:45]
	v_mfma_f32_16x16x32_bf16 v[30:33], v[182:185], v[206:209], v[30:33]
	v_mfma_f32_16x16x32_bf16 v[26:29], v[190:193], v[206:209], v[26:29]
	v_mfma_f32_16x16x32_bf16 v[14:17], v[182:185], v[214:217], v[14:17]
	v_mfma_f32_16x16x32_bf16 v[10:13], v[190:193], v[214:217], v[10:13]
	v_mfma_f32_16x16x32_bf16 v[6:9], v[182:185], v[222:225], v[6:9]
	v_mfma_f32_16x16x32_bf16 v[2:5], v[190:193], v[222:225], v[2:5]
	v_mfma_f32_16x16x32_bf16 v[46:49], v[186:189], v[202:205], v[46:49]
	v_mfma_f32_16x16x32_bf16 v[42:45], v[194:197], v[202:205], v[42:45]
	v_mfma_f32_16x16x32_bf16 v[30:33], v[186:189], v[210:213], v[30:33]
	v_mfma_f32_16x16x32_bf16 v[26:29], v[194:197], v[210:213], v[26:29]
	v_mfma_f32_16x16x32_bf16 v[14:17], v[186:189], v[218:221], v[14:17]
	v_mfma_f32_16x16x32_bf16 v[10:13], v[194:197], v[218:221], v[10:13]
	v_mfma_f32_16x16x32_bf16 v[6:9], v[186:189], v[226:229], v[6:9]
	v_mfma_f32_16x16x32_bf16 v[2:5], v[194:197], v[226:229], v[2:5]
	s_barrier
	s_add_i32 s67, s67, 2
	s_add_u32 s4, s4, 0x100
	s_addc_u32 s5, s5, 0
	s_add_u32 s63, s63, 0x100
	s_addc_u32 s66, s66, 0
	s_cmp_gt_u32 s67, 5
	s_cbranch_scc0 .LBB0_2084
	s_and_b64 vcc, exec, s[10:11]
	s_cbranch_vccz .LBB0_2087
	s_barrier

.LBB0_2091:
	s_cmpk_gt_i32 s5, 0x40f
	v_readfirstlane_b32 s1, v0
	s_cbranch_scc1 .LBB0_2109
	s_add_u32 s20, s90, 0x15b02c00
	s_addc_u32 s26, s91, 0
	s_add_u32 s27, s90, 0xd680000
	s_addc_u32 s30, s91, 0
	s_ashr_i32 s33, s5, 31
	s_lshr_b32 s0, s33, 29
	s_add_i32 s0, s5, s0
	s_lshr_b32 s3, s1, 6
	s_ashr_i32 s4, s0, 3
	s_and_b32 s0, s0, -8
	s_lshr_b32 s2, s1, 8
	s_lshl_b32 s31, s3, 10
	s_sub_i32 s0, s5, s0
	s_cmp_lt_i32 s0, 0
	s_movk_i32 s34, 0x83
	s_cselect_b32 s5, s34, 0x82
	s_mul_i32 s0, s5, s0
	s_add_i32 s0, s0, s4
	s_ashr_i32 s4, s0, 31
	s_lshr_b32 s4, s4, 26
	s_add_i32 s4, s0, s4
	s_ashr_i32 s4, s4, 6
	s_lshl_b32 s6, s4, 3
	s_sub_i32 s5, 0x82, s6
	s_lshl_b32 s4, s4, 6
	s_min_u32 s7, s5, 8
	s_sub_i32 s8, s0, s4
	s_sext_i32_i8 s0, s8
	v_cvt_f32_ubyte0_e32 v3, s7
	v_cvt_f32_i32_e32 v2, s0
	v_rcp_iflag_f32_e32 v4, v3
	s_ashr_i32 s0, s0, 30
	s_or_b32 s0, s0, 1
	v_lshl_or_b32 v136, v151, 9, v150
	v_mul_f32_e32 v4, v2, v4
	v_trunc_f32_e32 v4, v4
	v_fma_f32 v2, -v4, v3, v2
	v_cvt_i32_f32_e32 v4, v4
	v_cmp_ge_f32_e64 s[4:5], |v2|, v3
	s_and_b64 s[4:5], s[4:5], exec
	s_cselect_b32 s0, s0, 0
	v_readfirstlane_b32 s4, v4
	s_add_i32 s0, s4, s0
	s_mul_i32 s4, s0, s7
	s_sub_i32 s4, s8, s4
	s_sext_i32_i8 s4, s4
	s_add_i32 s76, s6, s4
	s_bfe_i64 s[4:5], s[0:1], 0x80000
	s_lshl_b64 s[4:5], s[4:5], 17
	s_add_u32 s16, s27, s4
	s_addc_u32 s17, s30, s5
	s_add_i32 s35, s31, 0
	s_add_i32 m0, s35, 0x10000
	v_lshl_or_b32 v134, v152, 9, v150
	global_load_lds_dwordx4 v136, s[16:17]
	s_add_i32 m0, s35, 0x12000
	s_add_u32 s4, s16, 0x10000
	global_load_lds_dwordx4 v134, s[16:17]
	s_addc_u32 s5, s17, 0
	s_add_i32 m0, s35, 0x14000
	s_mul_i32 s7, s76, 0x300000
	global_load_lds_dwordx4 v136, s[4:5]
	s_add_i32 m0, s35, 0x16000
	s_mul_hi_i32 s6, s76, 0x300000
	s_add_u32 s52, s20, s7
	s_addc_u32 s53, s26, s6
	s_add_i32 s66, s35, 0x2000
	global_load_lds_dwordx4 v134, s[4:5]
	s_mov_b32 m0, s35
	s_add_u32 s4, s52, 0x180000
	global_load_lds_dwordx4 v130, s[52:53]
	s_mov_b32 m0, s66
	s_addc_u32 s5, s53, 0
	s_add_i32 s67, s35, 0x4000
	global_load_lds_dwordx4 v132, s[52:53]
	s_mov_b32 m0, s67
	s_add_i32 s70, s35, 0x6000
	global_load_lds_dwordx4 v130, s[4:5]
	s_mov_b32 m0, s70
	v_mov_b32_e32 v137, 0
	global_load_lds_dwordx4 v132, s[4:5]
	v_mov_b32_e32 v135, v137
	v_mov_b32_e32 v131, v137
	v_mov_b32_e32 v133, v137
	s_cmp_eq_u32 s2, 1
	s_mov_b32 s71, 0
	v_lshl_add_u64 v[8:9], s[16:17], 0, v[136:137]
	v_lshl_add_u64 v[6:7], s[16:17], 0, v[134:135]
	v_lshl_add_u64 v[2:3], s[52:53], 0, v[130:131]
	s_cselect_b64 s[6:7], -1, 0
	s_cmp_lg_u32 s2, 1
	v_lshl_add_u64 v[4:5], s[52:53], 0, v[132:133]
	s_cbranch_scc1 .LBB0_2094
	s_barrier
	s_setprio 1

.LBB0_2102:
	s_add_u32 s21, s52, s24
	s_addc_u32 s25, s53, 0
	s_add_u32 s28, s21, 0x100
	s_addc_u32 s29, s25, 0
	s_and_b64 s[22:23], s[0:1], exec
	s_cselect_b32 s23, s19, s29
	s_cselect_b32 s22, s18, s28
	s_add_u32 s24, s16, s24
	s_addc_u32 s28, s17, 0
	s_add_u32 s24, s24, 0x100
	s_addc_u32 s28, s28, 0
	s_and_b64 s[0:1], s[0:1], exec
	s_cselect_b32 s55, s15, s28
	s_cselect_b32 s54, s78, s24
	s_add_u32 s62, s21, 0x180080
	ds_read_b128 v[150:153], v145
	ds_read_b128 v[154:157], v145 offset:1024
	ds_read_b128 v[158:161], v145 offset:2048
	ds_read_b128 v[168:171], v145 offset:3072
	ds_read_b128 v[174:177], v147
	ds_read_b128 v[178:181], v147 offset:1024
	ds_read_b128 v[182:185], v147 offset:2048
	ds_read_b128 v[186:189], v147 offset:3072
	s_addc_u32 s63, s25, 0
	s_add_i32 s88, s68, s31
	s_add_i32 m0, s35, 0xc000
	s_add_i32 s28, s35, 0xe000
	s_add_i32 s85, s88, 0x2000
	s_add_u32 s56, s54, 0x10000
	s_addc_u32 s57, s55, 0
	s_add_i32 s87, s69, s31
	s_add_i32 s86, s87, 0x2000
	s_add_i32 s84, 0, 0x18000
	s_add_i32 s83, 0, 0x1c000
	s_add_u32 s24, s22, 0x180000
	s_addc_u32 s25, s23, 0
	s_add_i32 s82, s84, s31
	s_add_i32 s80, s82, 0x2000
	s_add_u32 s0, s54, 0x10080
	s_addc_u32 s1, s55, 0
	s_add_i32 s81, s83, s31
	s_add_i32 s79, s81, 0x2000
	v_lshl_add_u64 v[162:163], s[62:63], 0, v[130:131]
	ds_read_b128 v[190:193], v148
	ds_read_b128 v[194:197], v148 offset:1024
	ds_read_b128 v[198:201], v148 offset:2048
	ds_read_b128 v[202:205], v148 offset:3072
	ds_read_b128 v[206:209], v148 offset:4096
	ds_read_b128 v[210:213], v148 offset:5120
	ds_read_b128 v[214:217], v148 offset:6144
	ds_read_b128 v[218:221], v148 offset:7168
	global_load_lds_dwordx4 v[162:163], off
	v_lshl_add_u64 v[162:163], s[62:63], 0, v[132:133]
	s_mov_b32 m0, s28
	s_nop 0
	global_load_lds_dwordx4 v[162:163], off
	s_waitcnt vmcnt(8)
	s_waitcnt lgkmcnt(0)
	s_barrier
	s_waitcnt lgkmcnt(0)
	v_mfma_f32_16x16x32_bf16 v[126:129], v[150:153], v[190:193], v[126:129]
	v_mfma_f32_16x16x32_bf16 v[122:125], v[158:161], v[190:193], v[122:125]
	v_mfma_f32_16x16x32_bf16 v[118:121], v[150:153], v[198:201], v[118:121]
	v_mfma_f32_16x16x32_bf16 v[114:117], v[158:161], v[198:201], v[114:117]
	v_mfma_f32_16x16x32_bf16 v[102:105], v[150:153], v[206:209], v[102:105]
	v_mfma_f32_16x16x32_bf16 v[98:101], v[158:161], v[206:209], v[98:101]
	v_mfma_f32_16x16x32_bf16 v[86:89], v[150:153], v[214:217], v[86:89]
	v_mfma_f32_16x16x32_bf16 v[82:85], v[158:161], v[214:217], v[82:85]
	v_mfma_f32_16x16x32_bf16 v[126:129], v[154:157], v[194:197], v[126:129]
	v_mfma_f32_16x16x32_bf16 v[122:125], v[168:171], v[194:197], v[122:125]
	v_mfma_f32_16x16x32_bf16 v[118:121], v[154:157], v[202:205], v[118:121]
	v_mfma_f32_16x16x32_bf16 v[114:117], v[168:171], v[202:205], v[114:117]
	v_mfma_f32_16x16x32_bf16 v[102:105], v[154:157], v[210:213], v[102:105]
	v_mfma_f32_16x16x32_bf16 v[98:101], v[168:171], v[210:213], v[98:101]
	v_mfma_f32_16x16x32_bf16 v[86:89], v[154:157], v[218:221], v[86:89]
	v_mfma_f32_16x16x32_bf16 v[82:85], v[168:171], v[218:221], v[82:85]
	v_mfma_f32_16x16x32_bf16 v[110:113], v[174:177], v[190:193], v[110:113]
	v_mfma_f32_16x16x32_bf16 v[106:109], v[182:185], v[190:193], v[106:109]
	v_mfma_f32_16x16x32_bf16 v[94:97], v[174:177], v[198:201], v[94:97]
	v_mfma_f32_16x16x32_bf16 v[90:93], v[182:185], v[198:201], v[90:93]
	v_mfma_f32_16x16x32_bf16 v[78:81], v[174:177], v[206:209], v[78:81]
	v_mfma_f32_16x16x32_bf16 v[74:77], v[182:185], v[206:209], v[74:77]
	v_mfma_f32_16x16x32_bf16 v[70:73], v[174:177], v[214:217], v[70:73]
	v_mfma_f32_16x16x32_bf16 v[66:69], v[182:185], v[214:217], v[66:69]
	v_mfma_f32_16x16x32_bf16 v[110:113], v[178:181], v[194:197], v[110:113]
	v_mfma_f32_16x16x32_bf16 v[106:109], v[186:189], v[194:197], v[106:109]
	v_mfma_f32_16x16x32_bf16 v[94:97], v[178:181], v[202:205], v[94:97]
	v_mfma_f32_16x16x32_bf16 v[90:93], v[186:189], v[202:205], v[90:93]
	v_mfma_f32_16x16x32_bf16 v[78:81], v[178:181], v[210:213], v[78:81]
	v_mfma_f32_16x16x32_bf16 v[74:77], v[186:189], v[210:213], v[74:77]
	v_mfma_f32_16x16x32_bf16 v[70:73], v[178:181], v[218:221], v[70:73]
	v_mfma_f32_16x16x32_bf16 v[66:69], v[186:189], v[218:221], v[66:69]
	s_barrier
	s_mov_b32 m0, s88
	v_lshl_add_u64 v[162:163], s[54:55], 0, v[136:137]
	ds_read_b128 v[190:193], v148 offset:16384
	ds_read_b128 v[194:197], v148 offset:17408
	ds_read_b128 v[198:201], v148 offset:18432
	ds_read_b128 v[202:205], v148 offset:19456
	ds_read_b128 v[206:209], v148 offset:20480
	ds_read_b128 v[210:213], v148 offset:21504
	ds_read_b128 v[214:217], v148 offset:22528
	ds_read_b128 v[218:221], v148 offset:23552
	global_load_lds_dwordx4 v[162:163], off
	v_lshl_add_u64 v[222:223], s[54:55], 0, v[134:135]
	s_mov_b32 m0, s85
	v_lshl_add_u64 v[224:225], s[56:57], 0, v[136:137]
	global_load_lds_dwordx4 v[222:223], off
	s_mov_b32 m0, s87
	v_lshl_add_u64 v[226:227], s[22:23], 0, v[132:133]
	global_load_lds_dwordx4 v[224:225], off
	v_lshl_add_u64 v[224:225], s[56:57], 0, v[134:135]
	s_mov_b32 m0, s86
	s_nop 0
	global_load_lds_dwordx4 v[224:225], off
	v_lshl_add_u64 v[224:225], s[22:23], 0, v[130:131]
	s_mov_b32 m0, s35
	s_nop 0
	global_load_lds_dwordx4 v[224:225], off
	s_mov_b32 m0, s66
	s_nop 0
	global_load_lds_dwordx4 v[226:227], off
	s_waitcnt vmcnt(8)
	s_waitcnt lgkmcnt(0)
	s_barrier
	s_waitcnt lgkmcnt(0)
	v_mfma_f32_16x16x32_bf16 v[62:65], v[150:153], v[190:193], v[62:65]
	v_mfma_f32_16x16x32_bf16 v[58:61], v[158:161], v[190:193], v[58:61]
	v_mfma_f32_16x16x32_bf16 v[54:57], v[150:153], v[198:201], v[54:57]
	v_mfma_f32_16x16x32_bf16 v[50:53], v[158:161], v[198:201], v[50:53]
	v_mfma_f32_16x16x32_bf16 v[38:41], v[150:153], v[206:209], v[38:41]
	v_mfma_f32_16x16x32_bf16 v[34:37], v[158:161], v[206:209], v[34:37]
	v_mfma_f32_16x16x32_bf16 v[22:25], v[150:153], v[214:217], v[22:25]
	v_mfma_f32_16x16x32_bf16 v[18:21], v[158:161], v[214:217], v[18:21]
	v_mfma_f32_16x16x32_bf16 v[62:65], v[154:157], v[194:197], v[62:65]
	v_mfma_f32_16x16x32_bf16 v[58:61], v[168:171], v[194:197], v[58:61]
	v_mfma_f32_16x16x32_bf16 v[54:57], v[154:157], v[202:205], v[54:57]
	v_mfma_f32_16x16x32_bf16 v[50:53], v[168:171], v[202:205], v[50:53]
	v_mfma_f32_16x16x32_bf16 v[38:41], v[154:157], v[210:213], v[38:41]
	v_mfma_f32_16x16x32_bf16 v[34:37], v[168:171], v[210:213], v[34:37]
	v_mfma_f32_16x16x32_bf16 v[22:25], v[154:157], v[218:221], v[22:25]
	v_mfma_f32_16x16x32_bf16 v[18:21], v[168:171], v[218:221], v[18:21]
	v_mfma_f32_16x16x32_bf16 v[46:49], v[174:177], v[190:193], v[46:49]
	v_mfma_f32_16x16x32_bf16 v[42:45], v[182:185], v[190:193], v[42:45]
	v_mfma_f32_16x16x32_bf16 v[30:33], v[174:177], v[198:201], v[30:33]
	v_mfma_f32_16x16x32_bf16 v[26:29], v[182:185], v[198:201], v[26:29]
	v_mfma_f32_16x16x32_bf16 v[14:17], v[174:177], v[206:209], v[14:17]
	v_mfma_f32_16x16x32_bf16 v[10:13], v[182:185], v[206:209], v[10:13]
	v_mfma_f32_16x16x32_bf16 v[6:9], v[174:177], v[214:217], v[6:9]
	v_mfma_f32_16x16x32_bf16 v[2:5], v[182:185], v[214:217], v[2:5]
	v_mfma_f32_16x16x32_bf16 v[46:49], v[178:181], v[194:197], v[46:49]
	v_mfma_f32_16x16x32_bf16 v[42:45], v[186:189], v[194:197], v[42:45]
	v_mfma_f32_16x16x32_bf16 v[30:33], v[178:181], v[202:205], v[30:33]
	v_mfma_f32_16x16x32_bf16 v[26:29], v[186:189], v[202:205], v[26:29]
	v_mfma_f32_16x16x32_bf16 v[14:17], v[178:181], v[210:213], v[14:17]
	v_mfma_f32_16x16x32_bf16 v[10:13], v[186:189], v[210:213], v[10:13]
	v_mfma_f32_16x16x32_bf16 v[6:9], v[178:181], v[218:221], v[6:9]
	v_mfma_f32_16x16x32_bf16 v[2:5], v[186:189], v[218:221], v[2:5]
	s_barrier
	v_add_u32_e32 v149, s84, v143
	ds_read_b128 v[150:153], v149
	ds_read_b128 v[154:157], v149 offset:1024
	ds_read_b128 v[158:161], v149 offset:2048
	ds_read_b128 v[168:171], v149 offset:3072
	v_add_u32_e32 v149, s83, v143
	ds_read_b128 v[174:177], v149
	ds_read_b128 v[178:181], v149 offset:1024
	ds_read_b128 v[182:185], v149 offset:2048
	ds_read_b128 v[186:189], v149 offset:3072
	s_mov_b32 m0, s67
	v_lshl_add_u64 v[228:229], s[24:25], 0, v[130:131]
	ds_read_b128 v[190:193], v148 offset:32768
	ds_read_b128 v[194:197], v148 offset:33792
	ds_read_b128 v[198:201], v148 offset:34816
	ds_read_b128 v[202:205], v148 offset:35840
	ds_read_b128 v[206:209], v148 offset:36864
	ds_read_b128 v[210:213], v148 offset:37888
	ds_read_b128 v[214:217], v148 offset:38912
	ds_read_b128 v[218:221], v148 offset:39936
	global_load_lds_dwordx4 v[228:229], off
	v_lshl_add_u64 v[228:229], s[24:25], 0, v[132:133]
	s_mov_b32 m0, s70
	s_nop 0
	global_load_lds_dwordx4 v[228:229], off
	s_waitcnt vmcnt(8)
	s_waitcnt lgkmcnt(0)
	s_barrier
	s_waitcnt lgkmcnt(0)
	v_mfma_f32_16x16x32_bf16 v[126:129], v[150:153], v[190:193], v[126:129]
	v_mfma_f32_16x16x32_bf16 v[122:125], v[158:161], v[190:193], v[122:125]
	v_mfma_f32_16x16x32_bf16 v[118:121], v[150:153], v[198:201], v[118:121]
	v_mfma_f32_16x16x32_bf16 v[114:117], v[158:161], v[198:201], v[114:117]
	v_mfma_f32_16x16x32_bf16 v[102:105], v[150:153], v[206:209], v[102:105]
	v_mfma_f32_16x16x32_bf16 v[98:101], v[158:161], v[206:209], v[98:101]
	v_mfma_f32_16x16x32_bf16 v[86:89], v[150:153], v[214:217], v[86:89]
	v_mfma_f32_16x16x32_bf16 v[82:85], v[158:161], v[214:217], v[82:85]
	v_mfma_f32_16x16x32_bf16 v[126:129], v[154:157], v[194:197], v[126:129]
	v_mfma_f32_16x16x32_bf16 v[122:125], v[168:171], v[194:197], v[122:125]
	v_mfma_f32_16x16x32_bf16 v[118:121], v[154:157], v[202:205], v[118:121]
	v_mfma_f32_16x16x32_bf16 v[114:117], v[168:171], v[202:205], v[114:117]
	v_mfma_f32_16x16x32_bf16 v[102:105], v[154:157], v[210:213], v[102:105]
	v_mfma_f32_16x16x32_bf16 v[98:101], v[168:171], v[210:213], v[98:101]
	v_mfma_f32_16x16x32_bf16 v[86:89], v[154:157], v[218:221], v[86:89]
	v_mfma_f32_16x16x32_bf16 v[82:85], v[168:171], v[218:221], v[82:85]
	v_mfma_f32_16x16x32_bf16 v[110:113], v[174:177], v[190:193], v[110:113]
	v_mfma_f32_16x16x32_bf16 v[106:109], v[182:185], v[190:193], v[106:109]
	v_mfma_f32_16x16x32_bf16 v[94:97], v[174:177], v[198:201], v[94:97]
	v_mfma_f32_16x16x32_bf16 v[90:93], v[182:185], v[198:201], v[90:93]
	v_mfma_f32_16x16x32_bf16 v[78:81], v[174:177], v[206:209], v[78:81]
	v_mfma_f32_16x16x32_bf16 v[74:77], v[182:185], v[206:209], v[74:77]
	v_mfma_f32_16x16x32_bf16 v[70:73], v[174:177], v[214:217], v[70:73]
	v_mfma_f32_16x16x32_bf16 v[66:69], v[182:185], v[214:217], v[66:69]
	v_mfma_f32_16x16x32_bf16 v[110:113], v[178:181], v[194:197], v[110:113]
	v_mfma_f32_16x16x32_bf16 v[106:109], v[186:189], v[194:197], v[106:109]
	v_mfma_f32_16x16x32_bf16 v[94:97], v[178:181], v[202:205], v[94:97]
	v_mfma_f32_16x16x32_bf16 v[90:93], v[186:189], v[202:205], v[90:93]
	v_mfma_f32_16x16x32_bf16 v[78:81], v[178:181], v[210:213], v[78:81]
	v_mfma_f32_16x16x32_bf16 v[74:77], v[186:189], v[210:213], v[74:77]
	v_mfma_f32_16x16x32_bf16 v[70:73], v[178:181], v[218:221], v[70:73]
	v_mfma_f32_16x16x32_bf16 v[66:69], v[186:189], v[218:221], v[66:69]
	s_barrier
	s_mov_b32 m0, s82
	v_lshl_add_u64 v[162:163], v[162:163], 0, s[10:11]
	ds_read_b128 v[190:193], v148 offset:49152
	ds_read_b128 v[194:197], v148 offset:50176
	ds_read_b128 v[198:201], v148 offset:51200
	ds_read_b128 v[202:205], v148 offset:52224
	ds_read_b128 v[206:209], v148 offset:53248
	ds_read_b128 v[210:213], v148 offset:54272
	ds_read_b128 v[214:217], v148 offset:55296
	ds_read_b128 v[218:221], v148 offset:56320
	global_load_lds_dwordx4 v[162:163], off
	v_lshl_add_u64 v[162:163], v[222:223], 0, s[10:11]
	s_mov_b32 m0, s80
	s_nop 0
	global_load_lds_dwordx4 v[162:163], off
	v_lshl_add_u64 v[162:163], s[0:1], 0, v[136:137]
	s_mov_b32 m0, s81
	s_nop 0
	global_load_lds_dwordx4 v[162:163], off
	v_lshl_add_u64 v[162:163], s[0:1], 0, v[134:135]
	s_mov_b32 m0, s79
	s_nop 0
	global_load_lds_dwordx4 v[162:163], off
	v_lshl_add_u64 v[162:163], v[224:225], 0, s[10:11]
	s_mov_b32 m0, s72
	s_nop 0
	global_load_lds_dwordx4 v[162:163], off
	v_lshl_add_u64 v[162:163], v[226:227], 0, s[10:11]
	s_mov_b32 m0, s73
	s_nop 0
	global_load_lds_dwordx4 v[162:163], off
	s_waitcnt vmcnt(8)
	s_waitcnt lgkmcnt(0)
	s_barrier
	s_waitcnt lgkmcnt(0)
	v_mfma_f32_16x16x32_bf16 v[62:65], v[150:153], v[190:193], v[62:65]
	v_mfma_f32_16x16x32_bf16 v[58:61], v[158:161], v[190:193], v[58:61]
	v_mfma_f32_16x16x32_bf16 v[54:57], v[150:153], v[198:201], v[54:57]
	v_mfma_f32_16x16x32_bf16 v[50:53], v[158:161], v[198:201], v[50:53]
	v_mfma_f32_16x16x32_bf16 v[38:41], v[150:153], v[206:209], v[38:41]
	v_mfma_f32_16x16x32_bf16 v[34:37], v[158:161], v[206:209], v[34:37]
	v_mfma_f32_16x16x32_bf16 v[22:25], v[150:153], v[214:217], v[22:25]
	v_mfma_f32_16x16x32_bf16 v[18:21], v[158:161], v[214:217], v[18:21]
	v_mfma_f32_16x16x32_bf16 v[62:65], v[154:157], v[194:197], v[62:65]
	v_mfma_f32_16x16x32_bf16 v[58:61], v[168:171], v[194:197], v[58:61]
	v_mfma_f32_16x16x32_bf16 v[54:57], v[154:157], v[202:205], v[54:57]
	v_mfma_f32_16x16x32_bf16 v[50:53], v[168:171], v[202:205], v[50:53]
	v_mfma_f32_16x16x32_bf16 v[38:41], v[154:157], v[210:213], v[38:41]
	v_mfma_f32_16x16x32_bf16 v[34:37], v[168:171], v[210:213], v[34:37]
	v_mfma_f32_16x16x32_bf16 v[22:25], v[154:157], v[218:221], v[22:25]
	v_mfma_f32_16x16x32_bf16 v[18:21], v[168:171], v[218:221], v[18:21]
	v_mfma_f32_16x16x32_bf16 v[46:49], v[174:177], v[190:193], v[46:49]
	v_mfma_f32_16x16x32_bf16 v[42:45], v[182:185], v[190:193], v[42:45]
	v_mfma_f32_16x16x32_bf16 v[30:33], v[174:177], v[198:201], v[30:33]
	v_mfma_f32_16x16x32_bf16 v[26:29], v[182:185], v[198:201], v[26:29]
	v_mfma_f32_16x16x32_bf16 v[14:17], v[174:177], v[206:209], v[14:17]
	v_mfma_f32_16x16x32_bf16 v[10:13], v[182:185], v[206:209], v[10:13]
	v_mfma_f32_16x16x32_bf16 v[6:9], v[174:177], v[214:217], v[6:9]
	v_mfma_f32_16x16x32_bf16 v[2:5], v[182:185], v[214:217], v[2:5]
	v_mfma_f32_16x16x32_bf16 v[46:49], v[178:181], v[194:197], v[46:49]
	v_mfma_f32_16x16x32_bf16 v[42:45], v[186:189], v[194:197], v[42:45]
	v_mfma_f32_16x16x32_bf16 v[30:33], v[178:181], v[202:205], v[30:33]
	v_mfma_f32_16x16x32_bf16 v[26:29], v[186:189], v[202:205], v[26:29]
	v_mfma_f32_16x16x32_bf16 v[14:17], v[178:181], v[210:213], v[14:17]
	v_mfma_f32_16x16x32_bf16 v[10:13], v[186:189], v[210:213], v[10:13]
	v_mfma_f32_16x16x32_bf16 v[6:9], v[178:181], v[218:221], v[6:9]
	v_mfma_f32_16x16x32_bf16 v[2:5], v[186:189], v[218:221], v[2:5]
	s_barrier
	s_movk_i32 s24, 0x100
	s_andn2_b64 vcc, exec, s[4:5]
	s_mov_b64 s[0:1], -1
	s_mov_b64 s[4:5], 0
	s_cbranch_vccz .LBB0_2102
	s_and_b64 vcc, exec, s[12:13]
	s_cbranch_vccz .LBB0_2105
	s_barrier

.LBB0_2198:
	s_setprio 0
	v_readlane_b32 s2, v243, 51
	s_cmp_lt_i32 s2, 26
	s_cselect_b64 s[8:9], -1, 0
	s_and_b64 s[0:1], s[8:9], s[0:1]
	s_andn2_b64 vcc, exec, s[0:1]
	v_readlane_b32 s3, v243, 52
	s_cbranch_vccnz .LBB0_2210
	v_readlane_b32 s0, v243, 0
	s_lshl_b32 s0, s0, 3
	v_readlane_b32 s1, v243, 59
	s_add_i32 s4, s1, s0
	s_cmp_gt_i32 s4, 0x81ff
	s_cbranch_scc1 .LBB0_2210
	v_readlane_b32 s16, v243, 33
	v_readlane_b32 s17, v243, 34
	v_readlane_b32 s18, v243, 35
	v_readlane_b32 s19, v243, 36
	v_readlane_b32 s28, v243, 45
	v_readlane_b32 s29, v243, 46
	v_readlane_b32 s14, v243, 53
	v_readlane_b32 s30, v243, 47
	v_readlane_b32 s31, v243, 48
	s_mov_b64 s[16:17], s[28:29]
	s_lshl_b32 s10, s14, 3
	v_lshrrev_b32_e32 v5, 3, v166
	v_lshlrev_b32_e32 v4, 5, v1
	s_mov_b64 s[18:19], s[30:31]
	v_lshlrev_b32_e32 v54, 6, v1
	s_ashr_i32 s5, s4, 31
	s_mul_i32 s7, s4, 0xc00
	v_readlane_b32 s0, v242, 21
	v_mov_b32_e32 v3, 0
	global_load_dwordx4 v[6:9], v4, s[18:19] offset:1296
	global_load_dwordx4 v[10:13], v4, s[16:17] offset:1296
	global_load_dwordx4 v[14:17], v4, s[18:19] offset:1280
	global_load_dwordx4 v[18:21], v4, s[16:17] offset:1280
	global_load_dwordx4 v[22:25], v54, s[18:19] offset:768
	global_load_dwordx4 v[26:29], v54, s[18:19] offset:784
	global_load_dwordx4 v[30:33], v54, s[18:19] offset:816
	global_load_dwordx4 v[34:37], v54, s[16:17] offset:816
	s_waitcnt lgkmcnt(0)
	global_load_dwordx4 v[38:41], v54, s[18:19] offset:800
	global_load_dwordx4 v[42:45], v54, s[16:17] offset:800
	global_load_dwordx4 v[46:49], v54, s[16:17] offset:784
	global_load_dwordx4 v[50:53], v54, s[16:17] offset:768
	s_mul_hi_i32 s6, s4, 0xc00
	v_readlane_b32 s1, v242, 22
	s_add_u32 s0, s0, s7
	v_mul_u32_u24_e32 v54, 0xc0, v5
	s_addc_u32 s1, s1, s6
	v_lshlrev_b32_e32 v54, 1, v54
	v_mov_b32_e32 v55, v3
	v_lshl_add_u64 v[56:57], s[0:1], 0, v[54:55]
	s_lshl_b64 s[0:1], s[4:5], 12
	s_add_u32 s0, s90, s0
	s_addc_u32 s1, s91, s1
	v_lshlrev_b32_e32 v58, 9, v5
	v_mov_b32_e32 v59, v3
	v_lshlrev_b32_e32 v2, 4, v1
	v_lshl_add_u64 v[58:59], s[0:1], 0, v[58:59]
	v_mov_b32_e32 v5, v3
	v_lshl_add_u64 v[58:59], v[58:59], 0, v[4:5]
	v_lshl_add_u64 v[62:63], v[56:57], 0, v[4:5]
	v_lshl_add_u64 v[56:57], v[56:57], 0, v[2:3]
	s_mov_b32 s0, 0x34300000
	global_load_dwordx4 v[104:107], v[62:63], off offset:16
	global_load_dwordx4 v[100:103], v[56:57], off offset:256
	v_add_co_u32_e32 v56, vcc, s0, v58
	s_mul_i32 s0, s4, 0x3000
	v_readlane_b32 s2, v242, 17
	s_mul_hi_i32 s1, s4, 0x3000
	v_readlane_b32 s3, v242, 18
	s_add_u32 s0, s2, s0
	s_mov_b64 s[12:13], 0x34300000
	s_addc_u32 s1, s3, s1
	v_lshl_add_u64 v[60:61], v[58:59], 0, s[12:13]
	v_addc_co_u32_e32 v57, vcc, 0, v59, vcc
	v_lshl_add_u64 v[58:59], s[0:1], 0, v[2:3]
	s_movk_i32 s0, 0x2000
	v_add_co_u32_e32 v58, vcc, s0, v58
	global_load_dwordx4 v[108:111], v[62:63], off
	global_load_dwordx4 v[88:91], v[60:61], off offset:16
	v_addc_co_u32_e32 v59, vcc, 0, v59, vcc
	global_load_dwordx4 v[96:99], v[56:57], off
	global_load_dwordx4 v[92:95], v[58:59], off offset:3584
	v_lshlrev_b32_e32 v5, 5, v0
	v_and_b32_e32 v56, 0x60, v5
	v_mov_b32_e32 v57, v3
	v_lshl_add_u64 v[56:57], s[90:91], 0, v[56:57]
	s_mov_b64 s[0:1], 0x900000
	v_mbcnt_lo_u32_b32 v5, -1, 0
	v_lshl_add_u64 v[112:113], v[56:57], 0, s[0:1]
	s_mov_b64 s[0:1], 0xb00000
	v_mbcnt_hi_u32_b32 v5, -1, v5
	v_lshl_add_u64 v[114:115], v[56:57], 0, s[0:1]
	v_and_b32_e32 v57, 64, v5
	v_xor_b32_e32 v56, 1, v5
	v_add_u32_e32 v57, 64, v57
	v_cmp_lt_i32_e32 vcc, v56, v57
	v_readlane_b32 s0, v243, 0
	v_readlane_b32 s1, v243, 59
	v_cndmask_b32_e32 v56, v5, v56, vcc
	v_lshlrev_b32_e32 v148, 2, v56
	v_xor_b32_e32 v56, 2, v5
	v_cmp_lt_i32_e32 vcc, v56, v57
	v_readlane_b32 s20, v243, 37
	s_lshl_b32 s0, s0, 8
	v_cndmask_b32_e32 v56, v5, v56, vcc
	s_lshl_b32 s1, s1, 5
	v_lshlrev_b32_e32 v149, 2, v56
	v_xor_b32_e32 v56, 4, v5
	s_add_i32 s20, s0, s1
	s_add_i32 s0, s4, s10
	v_cmp_lt_i32_e32 vcc, v56, v57
	s_mul_hi_i32 s5, s0, 0x3000
	s_ashr_i32 s1, s0, 31
	s_waitcnt vmcnt(0)
	v_mov_b32_e32 v116, v23
	v_mov_b32_e32 v117, v25
	v_mov_b32_e32 v23, v24
	v_mov_b32_e32 v24, v27
	v_mov_b32_e32 v25, v29
	v_mov_b32_e32 v27, v28
	v_mov_b32_e32 v28, v39
	v_mov_b32_e32 v29, v41
	v_mov_b32_e32 v39, v40
	v_mov_b32_e32 v40, v31
	v_mov_b32_e32 v41, v33
	v_mov_b32_e32 v31, v32
	v_mov_b32_e32 v32, v51
	v_mov_b32_e32 v33, v53
	v_mov_b32_e32 v51, v52
	v_or_b32_e32 v52, s7, v2
	v_mov_b32_e32 v53, s6
	v_mov_b32_e32 v118, v47
	v_mov_b32_e32 v119, v49
	v_mov_b32_e32 v47, v48
	v_mov_b32_e32 v48, v43
	v_mov_b32_e32 v49, v45
	v_mov_b32_e32 v43, v44
	v_mov_b32_e32 v44, v35
	v_mov_b32_e32 v45, v37
	v_mov_b32_e32 v35, v36
	v_lshl_add_u64 v[36:37], v[52:53], 0, v[54:55]
	v_or_b32_e32 v52, s7, v4
	s_mul_i32 s6, s0, 0x3000
	v_cndmask_b32_e32 v5, v5, v56, vcc
	v_lshl_add_u64 v[120:121], v[52:53], 0, v[54:55]
	v_or_b32_e32 v52, s6, v2
	v_mov_b32_e32 v53, s5
	s_mov_b64 s[6:7], 0x15b02e00
	v_lshlrev_b32_e32 v150, 2, v5
	v_and_b32_e32 v5, 4, v0
	v_lshl_add_u64 v[122:123], v[52:53], 0, s[6:7]
	s_lshl_b64 s[6:7], s[0:1], 12
	s_mul_hi_i32 s1, s0, 0xc00
	s_mul_i32 s5, s0, 0xc00
	v_cmp_eq_u32_e64 s[2:3], 0, v5
	v_and_b32_e32 v5, 56, v0
	v_or_b32_e32 v52, s5, v2
	v_mov_b32_e32 v53, s1
	v_readlane_b32 s22, v243, 39
	v_readlane_b32 s23, v243, 40
	v_readlane_b32 s24, v243, 41
	v_readlane_b32 s25, v243, 42
	v_readlane_b32 s26, v243, 43
	s_ashr_i32 s11, s10, 31
	v_lshlrev_b32_e32 v5, 6, v5
	v_lshl_add_u64 v[56:57], v[52:53], 0, v[54:55]
	s_mov_b64 s[0:1], 0x2e100100
	v_or_b32_e32 v52, s5, v4
	v_mov_b64_e32 v[64:65], v[108:109]
	v_mov_b64_e32 v[72:73], v[104:105]
	v_mov_b64_e32 v[68:69], v[100:101]
	v_mov_b64_e32 v[80:81], v[96:97]
	v_mov_b64_e32 v[76:77], v[88:89]
	v_mov_b64_e32 v[84:85], v[92:93]
	s_mov_b32 s15, 0
	s_lshl_b32 s22, s14, 8
	s_mul_i32 s16, s14, 0x6000
	s_mul_hi_i32 s17, s10, 0xc00
	s_mul_i32 s18, s14, 0x18000
	s_mul_hi_i32 s19, s10, 0x3000
	v_or3_b32 v124, s6, v5, v4
	v_mov_b32_e32 v125, s7
	s_lshl_b64 s[44:45], s[10:11], 12
	v_lshl_add_u64 v[126:127], v[56:57], 0, s[0:1]
	v_lshl_add_u64 v[128:129], v[52:53], 0, v[54:55]
	s_mov_b64 s[46:47], 0x2e100000
	s_mov_b32 s11, 0x2e100000
	s_movk_i32 s23, 0x7fff
	s_mov_b32 s24, 0xffff0000
	v_mov_b32_e32 v151, 0x358637bd
	s_mov_b32 s25, 0xf800000
	v_mov_b32_e32 v152, 0x260
	s_mov_b32 s52, 0x3dd53b94
	s_mov_b32 s26, 0x3c500000
	v_mov_b32_e32 v2, v3
	v_mov_b32_e32 v4, v3
	v_mov_b32_e32 v5, v3
	v_mov_b32_e32 v52, v3
	v_mov_b32_e32 v53, v3
	v_mov_b32_e32 v54, v3
	v_mov_b64_e32 v[66:67], v[110:111]
	v_mov_b64_e32 v[74:75], v[106:107]
	v_mov_b64_e32 v[70:71], v[102:103]
	v_mov_b64_e32 v[82:83], v[98:99]
	v_mov_b64_e32 v[78:79], v[90:91]
	v_mov_b64_e32 v[86:87], v[94:95]
	v_readlane_b32 s21, v243, 38
	v_readlane_b32 s27, v243, 44
	s_branch .LBB0_2202

.LBB0_2264:
	s_setprio 0
	v_readlane_b32 s2, v243, 51
	s_cmp_lt_i32 s2, 27
	s_cselect_b64 s[10:11], -1, 0
	s_and_b64 s[0:1], s[10:11], s[0:1]
	s_andn2_b64 vcc, exec, s[0:1]
	v_readlane_b32 s3, v243, 52
	s_cbranch_vccnz .LBB0_2324
	v_readlane_b32 s12, v243, 33
	v_readlane_b32 s13, v243, 34
	v_readlane_b32 s14, v243, 35
	v_readlane_b32 s15, v243, 36
	v_readlane_b32 s24, v243, 45
	v_readlane_b32 s25, v243, 46
	v_mov_b32_e32 v2, 0x300
	v_readlane_b32 s26, v243, 47
	v_readlane_b32 s27, v243, 48
	s_mov_b64 s[12:13], s[24:25]
	v_lshl_or_b32 v2, v166, 2, v2
	v_mov_b32_e32 v3, 0
	s_mov_b64 s[14:15], s[26:27]
	v_lshl_add_u64 v[4:5], s[14:15], 0, v[2:3]
	v_lshl_add_u64 v[6:7], s[12:13], 0, v[2:3]
	v_or_b32_e32 v8, 0xffffffc0, v166
	s_mov_b64 s[0:1], 0
	s_mov_b64 s[2:3], 0x100
	s_movk_i32 s4, 0x7f
	v_mov_b32_e32 v2, v3
	v_readlane_b32 s16, v243, 37
	v_readlane_b32 s17, v243, 38
	v_readlane_b32 s18, v243, 39
	v_readlane_b32 s19, v243, 40
	v_readlane_b32 s20, v243, 41
	v_readlane_b32 s21, v243, 42
	v_readlane_b32 s22, v243, 43
	v_readlane_b32 s23, v243, 44

.LBB0_2378:
	s_setprio 0
	v_readlane_b32 s2, v243, 51
	s_cmp_gt_i32 s2, 27
	s_cselect_b64 s[4:5], -1, 0
	s_xor_b64 s[0:1], s[0:1], -1
	v_readlane_b32 s3, v243, 52
	s_or_b64 s[0:1], s[4:5], s[0:1]
	s_mov_b64 s[2:3], -1
	s_and_b64 vcc, exec, s[0:1]
	s_cbranch_vccnz .LBB0_2388
	v_lshlrev_b32_e32 v2, 2, v166
	global_load_dword v3, v2, s[80:81] offset:1024
	global_load_dword v4, v2, s[80:81] offset:1280
	global_load_dword v5, v2, s[80:81] offset:1536
	global_load_dword v6, v2, s[80:81] offset:1792
	v_mbcnt_lo_u32_b32 v2, -1, 0
	v_mbcnt_hi_u32_b32 v2, -1, v2
	v_and_b32_e32 v7, 64, v2
	v_xor_b32_e32 v8, 1, v2
	v_add_u32_e32 v7, 64, v7
	v_cmp_lt_i32_e32 vcc, v8, v7
	v_xor_b32_e32 v9, 2, v2
	v_xor_b32_e32 v10, 4, v2
	v_cndmask_b32_e32 v8, v2, v8, vcc
	v_lshlrev_b32_e32 v60, 2, v8
	v_cmp_lt_i32_e32 vcc, v9, v7
	v_xor_b32_e32 v11, 8, v2
	v_xor_b32_e32 v12, 16, v2
	v_cndmask_b32_e32 v9, v2, v9, vcc
	v_lshlrev_b32_e32 v61, 2, v9
	v_cmp_lt_i32_e32 vcc, v10, v7
	v_xor_b32_e32 v13, 32, v2
	v_readlane_b32 s0, v243, 0
	s_lshl_b32 s0, s0, 3
	v_readlane_b32 s1, v243, 59
	s_add_i32 s0, s1, s0
	s_cmp_lt_i32 s0, 0x8200
	s_cselect_b64 s[4:5], -1, 0
	v_lshlrev_b32_e32 v34, 4, v1
	s_waitcnt vmcnt(0)
	v_mul_f32_e32 v8, v3, v4
	ds_bpermute_b32 v8, v60, v8
	v_mul_f32_e32 v14, v5, v6
	ds_bpermute_b32 v14, v60, v14
	s_waitcnt lgkmcnt(1)
	v_fmac_f32_e32 v8, v3, v4
	ds_bpermute_b32 v3, v61, v8
	s_waitcnt lgkmcnt(1)
	v_fmac_f32_e32 v14, v5, v6
	ds_bpermute_b32 v4, v61, v14
	v_cndmask_b32_e32 v5, v2, v10, vcc
	v_lshlrev_b32_e32 v62, 2, v5
	s_waitcnt lgkmcnt(1)
	v_add_f32_e32 v3, v8, v3
	ds_bpermute_b32 v5, v62, v3
	s_waitcnt lgkmcnt(1)
	v_add_f32_e32 v4, v14, v4
	ds_bpermute_b32 v6, v62, v4
	v_cmp_lt_i32_e32 vcc, v11, v7
	s_waitcnt lgkmcnt(1)
	v_add_f32_e32 v3, v3, v5
	v_cndmask_b32_e32 v8, v2, v11, vcc
	v_lshlrev_b32_e32 v8, 2, v8
	s_waitcnt lgkmcnt(0)
	v_add_f32_e32 v4, v4, v6
	ds_bpermute_b32 v5, v8, v3
	ds_bpermute_b32 v6, v8, v4
	v_cmp_lt_i32_e32 vcc, v12, v7
	s_waitcnt lgkmcnt(1)
	v_add_f32_e32 v3, v3, v5
	v_cndmask_b32_e32 v8, v2, v12, vcc
	v_lshlrev_b32_e32 v8, 2, v8
	s_waitcnt lgkmcnt(0)
	v_add_f32_e32 v4, v4, v6
	ds_bpermute_b32 v5, v8, v3
	ds_bpermute_b32 v6, v8, v4
	v_cmp_lt_i32_e32 vcc, v13, v7
	s_waitcnt lgkmcnt(1)
	v_add_f32_e32 v36, v3, v5
	v_cndmask_b32_e32 v2, v2, v13, vcc
	v_lshlrev_b32_e32 v2, 2, v2
	s_waitcnt lgkmcnt(0)
	v_add_f32_e32 v37, v4, v6
	ds_bpermute_b32 v38, v2, v36
	ds_bpermute_b32 v39, v2, v37
	s_and_b64 vcc, exec, s[4:5]
	s_cbranch_vccnz .LBB0_2381
	v_mov_b32_e32 v35, 0
	s_mov_b64 s[2:3], 0

.LBB0_2388:
	v_readlane_b32 s2, v243, 51
	s_cmp_lt_i32 s2, 29
	v_readlane_b32 s3, v243, 52
	s_cselect_b64 s[4:5], -1, 0
	s_cmp_gt_i32 s2, 28
	s_cselect_b64 s[0:1], -1, 0
	s_cmp_lt_i32 s3, 29
	s_cselect_b64 s[2:3], -1, 0
	s_or_b64 s[0:1], s[0:1], s[2:3]
	s_and_b64 vcc, exec, s[0:1]
	s_cbranch_vccnz .LBB0_2405
	v_readlane_b32 s0, v243, 0
	s_cmpk_gt_i32 s0, 0xbff
	v_readfirstlane_b32 s3, v0
	s_cbranch_scc1 .LBB0_2405
	v_lshrrev_b32_e32 v1, 5, v0
	v_lshrrev_b32_e32 v3, 1, v0
	v_and_b32_e32 v1, 4, v1
	v_bfe_u32 v2, v0, 2, 2
	v_and_b32_e32 v13, 24, v3
	v_or3_b32 v1, v1, v2, v13
	v_lshlrev_b32_e32 v2, 4, v0
	v_or_b32_e32 v10, 0x2000, v2
	s_add_u32 s20, s90, 0xa900000
	v_lshrrev_b32_e32 v3, 7, v10
	s_movk_i32 s0, 0x60
	v_readlane_b32 s2, v243, 0
	s_addc_u32 s24, s91, 0
	v_and_or_b32 v4, v3, s0, v1
	v_bfe_u32 v14, v0, 2, 4
	s_movk_i32 s0, 0x70
	s_ashr_i32 s26, s2, 31
	v_and_or_b32 v3, v3, s0, v14
	s_lshr_b32 s0, s26, 29
	s_add_i32 s0, s2, s0
	s_lshr_b32 s8, s3, 6
	s_ashr_i32 s1, s0, 3
	s_and_b32 s0, s0, -8
	s_lshr_b32 s10, s3, 8
	s_lshl_b32 s25, s8, 10
	s_sub_i32 s0, s2, s0
	s_cmp_lt_i32 s0, 0
	s_movk_i32 s27, 0x181
	s_cselect_b32 s2, s27, 0x180
	s_mul_i32 s0, s2, s0
	s_add_i32 s0, s0, s1
	s_mul_hi_i32 s1, s0, 0x2aaaaaab
	s_lshr_b32 s2, s1, 31
	s_ashr_i32 s1, s1, 5
	s_add_i32 s1, s1, s2
	s_lshl_b32 s6, s1, 3
	s_mulk_i32 s1, 0xc0
	s_sub_i32 s0, s0, s1
	s_sext_i32_i16 s1, s0
	s_bfe_u32 s1, s1, 0x3001c
	s_add_i32 s1, s0, s1
	s_sext_i32_i16 s2, s1
	s_and_b32 s1, s1, 0xfff8
	s_sub_i32 s0, s0, s1
	s_sext_i32_i16 s0, s0
	v_and_b32_e32 v5, 32, v0
	s_lshr_b32 s2, s2, 3
	s_add_i32 s36, s6, s0
	v_bitop3_b32 v11, v2, v5, 48 bitop3:0x6c
	v_and_b32_e32 v12, 64, v0
	s_ashr_i32 s37, s36, 31
	s_bfe_i64 s[0:1], s[2:3], 0x100000
	v_or_b32_e32 v2, v11, v12
	s_lshl_b64 s[6:7], s[36:37], 20
	s_lshl_b64 s[0:1], s[0:1], 20
	v_lshl_or_b32 v132, v3, 12, v2
	v_lshrrev_b32_e32 v3, 3, v0
	s_add_u32 s0, s20, s0
	v_and_or_b32 v1, v3, 32, v1
	s_addc_u32 s1, s24, s1
	s_add_i32 s30, s25, 0
	v_lshl_or_b32 v134, v1, 12, v2
	s_add_i32 m0, s30, 0x10000
	v_lshl_or_b32 v130, v4, 12, v2
	global_load_lds_dwordx4 v134, s[0:1]
	s_add_i32 m0, s30, 0x12000
	s_add_u32 s12, s0, 0x80000
	global_load_lds_dwordx4 v130, s[0:1]
	s_addc_u32 s13, s1, 0
	s_add_i32 m0, s30, 0x14000
	v_and_or_b32 v1, v3, 48, v14
	global_load_lds_dwordx4 v134, s[12:13]
	s_add_i32 m0, s30, 0x16000
	v_lshl_or_b32 v136, v1, 12, v2
	global_load_lds_dwordx4 v130, s[12:13]
	v_readlane_b32 s12, v242, 15
	v_readlane_b32 s13, v242, 16
	s_add_u32 s22, s12, s6
	s_addc_u32 s23, s13, s7
	s_add_i32 s31, s30, 0x2000
	s_mov_b32 m0, s30
	s_add_u32 s6, s22, 0x80000
	global_load_lds_dwordx4 v136, s[22:23]
	s_mov_b32 m0, s31
	s_addc_u32 s7, s23, 0
	s_add_i32 s33, s30, 0x4000
	global_load_lds_dwordx4 v132, s[22:23]
	s_mov_b32 m0, s33
	s_add_i32 s34, s30, 0x6000
	global_load_lds_dwordx4 v136, s[6:7]
	s_mov_b32 m0, s34
	v_mov_b32_e32 v135, 0
	global_load_lds_dwordx4 v132, s[6:7]
	v_mov_b32_e32 v131, v135
	v_mov_b32_e32 v137, v135
	v_mov_b32_e32 v133, v135
	s_cmp_eq_u32 s10, 1
	s_mov_b32 s35, 0
	v_lshl_add_u64 v[8:9], s[0:1], 0, v[134:135]
	v_lshl_add_u64 v[6:7], s[0:1], 0, v[130:131]
	v_lshl_add_u64 v[2:3], s[22:23], 0, v[136:137]
	s_cselect_b64 s[6:7], -1, 0
	s_cmp_lg_u32 s10, 1
	v_lshl_add_u64 v[4:5], s[22:23], 0, v[132:133]
	s_cbranch_scc1 .LBB0_2392
	s_barrier
	s_setprio 1

.LBB0_2398:
	ds_read_b128 v[146:149], v152
	ds_read_b128 v[156:159], v152 offset:1024
	ds_read_b128 v[160:163], v152 offset:2048
	ds_read_b128 v[168:171], v152 offset:3072
	ds_read_b128 v[172:175], v153
	ds_read_b128 v[176:179], v153 offset:1024
	ds_read_b128 v[180:183], v153 offset:2048
	ds_read_b128 v[184:187], v153 offset:3072
	s_add_u32 s0, s38, 0xfff80080
	s_addc_u32 s1, s39, -1
	s_cmp_eq_u32 s54, 28
	s_cselect_b32 s23, s15, s1
	s_cselect_b32 s22, s46, s0
	s_cselect_b32 s1, s13, s53
	s_cselect_b32 s0, s47, s52
	v_lshl_add_u64 v[220:221], s[38:39], 0, v[138:139]
	s_add_i32 m0, s30, 0xc000
	ds_read_b128 v[188:191], v154
	ds_read_b128 v[192:195], v154 offset:1024
	ds_read_b128 v[196:199], v154 offset:2048
	ds_read_b128 v[200:203], v154 offset:3072
	ds_read_b128 v[204:207], v154 offset:4096
	ds_read_b128 v[208:211], v154 offset:5120
	ds_read_b128 v[212:215], v154 offset:6144
	ds_read_b128 v[216:219], v154 offset:7168
	global_load_lds_dwordx4 v[220:221], off
	v_lshl_add_u64 v[220:221], s[38:39], 0, v[140:141]
	s_add_i32 m0, s30, 0xe000
	s_nop 0
	global_load_lds_dwordx4 v[220:221], off
	s_waitcnt vmcnt(8)
	s_waitcnt lgkmcnt(0)
	s_barrier
	s_waitcnt lgkmcnt(0)
	v_mfma_f32_16x16x32_bf16 v[126:129], v[146:149], v[188:191], v[126:129]
	v_mfma_f32_16x16x32_bf16 v[122:125], v[160:163], v[188:191], v[122:125]
	v_mfma_f32_16x16x32_bf16 v[110:113], v[146:149], v[196:199], v[110:113]
	v_mfma_f32_16x16x32_bf16 v[106:109], v[160:163], v[196:199], v[106:109]
	v_mfma_f32_16x16x32_bf16 v[94:97], v[146:149], v[204:207], v[94:97]
	v_mfma_f32_16x16x32_bf16 v[90:93], v[160:163], v[204:207], v[90:93]
	v_mfma_f32_16x16x32_bf16 v[78:81], v[146:149], v[212:215], v[78:81]
	v_mfma_f32_16x16x32_bf16 v[74:77], v[160:163], v[212:215], v[74:77]
	v_mfma_f32_16x16x32_bf16 v[126:129], v[156:159], v[192:195], v[126:129]
	v_mfma_f32_16x16x32_bf16 v[122:125], v[168:171], v[192:195], v[122:125]
	v_mfma_f32_16x16x32_bf16 v[110:113], v[156:159], v[200:203], v[110:113]
	v_mfma_f32_16x16x32_bf16 v[106:109], v[168:171], v[200:203], v[106:109]
	v_mfma_f32_16x16x32_bf16 v[94:97], v[156:159], v[208:211], v[94:97]
	v_mfma_f32_16x16x32_bf16 v[90:93], v[168:171], v[208:211], v[90:93]
	v_mfma_f32_16x16x32_bf16 v[78:81], v[156:159], v[216:219], v[78:81]
	v_mfma_f32_16x16x32_bf16 v[74:77], v[168:171], v[216:219], v[74:77]
	v_mfma_f32_16x16x32_bf16 v[118:121], v[172:175], v[188:191], v[118:121]
	v_mfma_f32_16x16x32_bf16 v[114:117], v[180:183], v[188:191], v[114:117]
	v_mfma_f32_16x16x32_bf16 v[102:105], v[172:175], v[196:199], v[102:105]
	v_mfma_f32_16x16x32_bf16 v[98:101], v[180:183], v[196:199], v[98:101]
	v_mfma_f32_16x16x32_bf16 v[86:89], v[172:175], v[204:207], v[86:89]
	v_mfma_f32_16x16x32_bf16 v[82:85], v[180:183], v[204:207], v[82:85]
	v_mfma_f32_16x16x32_bf16 v[70:73], v[172:175], v[212:215], v[70:73]
	v_mfma_f32_16x16x32_bf16 v[66:69], v[180:183], v[212:215], v[66:69]
	v_mfma_f32_16x16x32_bf16 v[118:121], v[176:179], v[192:195], v[118:121]
	v_mfma_f32_16x16x32_bf16 v[114:117], v[184:187], v[192:195], v[114:117]
	v_mfma_f32_16x16x32_bf16 v[102:105], v[176:179], v[200:203], v[102:105]
	v_mfma_f32_16x16x32_bf16 v[98:101], v[184:187], v[200:203], v[98:101]
	v_mfma_f32_16x16x32_bf16 v[86:89], v[176:179], v[208:211], v[86:89]
	v_mfma_f32_16x16x32_bf16 v[82:85], v[184:187], v[208:211], v[82:85]
	v_mfma_f32_16x16x32_bf16 v[70:73], v[176:179], v[216:219], v[70:73]
	v_mfma_f32_16x16x32_bf16 v[66:69], v[184:187], v[216:219], v[66:69]
	s_barrier
	s_add_i32 s21, s42, s25
	v_lshl_add_u64 v[220:221], s[0:1], 0, v[134:135]
	s_mov_b32 m0, s21
	ds_read_b128 v[188:191], v154 offset:16384
	ds_read_b128 v[192:195], v154 offset:17408
	ds_read_b128 v[196:199], v154 offset:18432
	ds_read_b128 v[200:203], v154 offset:19456
	ds_read_b128 v[204:207], v154 offset:20480
	ds_read_b128 v[208:211], v154 offset:21504
	ds_read_b128 v[212:215], v154 offset:22528
	ds_read_b128 v[216:219], v154 offset:23552
	global_load_lds_dwordx4 v[220:221], off
	s_add_i32 m0, s21, 0x2000
	s_add_u32 s28, s0, 0x80000
	v_lshl_add_u64 v[222:223], s[0:1], 0, v[130:131]
	s_addc_u32 s29, s1, 0
	s_add_i32 s21, s43, s25
	global_load_lds_dwordx4 v[222:223], off
	v_lshl_add_u64 v[224:225], s[28:29], 0, v[134:135]
	s_mov_b32 m0, s21
	v_lshl_add_u64 v[226:227], s[22:23], 0, v[132:133]
	global_load_lds_dwordx4 v[224:225], off
	v_lshl_add_u64 v[224:225], s[28:29], 0, v[130:131]
	s_add_i32 m0, s21, 0x2000
	s_nop 0
	global_load_lds_dwordx4 v[224:225], off
	v_lshl_add_u64 v[224:225], s[22:23], 0, v[136:137]
	s_mov_b32 m0, s30
	s_nop 0
	global_load_lds_dwordx4 v[224:225], off
	s_mov_b32 m0, s31
	s_nop 0
	global_load_lds_dwordx4 v[226:227], off
	s_waitcnt vmcnt(8)
	s_waitcnt lgkmcnt(0)
	s_barrier
	s_waitcnt lgkmcnt(0)
	v_mfma_f32_16x16x32_bf16 v[62:65], v[146:149], v[188:191], v[62:65]
	v_mfma_f32_16x16x32_bf16 v[58:61], v[160:163], v[188:191], v[58:61]
	v_mfma_f32_16x16x32_bf16 v[46:49], v[146:149], v[196:199], v[46:49]
	v_mfma_f32_16x16x32_bf16 v[42:45], v[160:163], v[196:199], v[42:45]
	v_mfma_f32_16x16x32_bf16 v[30:33], v[146:149], v[204:207], v[30:33]
	v_mfma_f32_16x16x32_bf16 v[26:29], v[160:163], v[204:207], v[26:29]
	v_mfma_f32_16x16x32_bf16 v[14:17], v[146:149], v[212:215], v[14:17]
	v_mfma_f32_16x16x32_bf16 v[10:13], v[160:163], v[212:215], v[10:13]
	v_mfma_f32_16x16x32_bf16 v[62:65], v[156:159], v[192:195], v[62:65]
	v_mfma_f32_16x16x32_bf16 v[58:61], v[168:171], v[192:195], v[58:61]
	v_mfma_f32_16x16x32_bf16 v[46:49], v[156:159], v[200:203], v[46:49]
	v_mfma_f32_16x16x32_bf16 v[42:45], v[168:171], v[200:203], v[42:45]
	v_mfma_f32_16x16x32_bf16 v[30:33], v[156:159], v[208:211], v[30:33]
	v_mfma_f32_16x16x32_bf16 v[26:29], v[168:171], v[208:211], v[26:29]
	v_mfma_f32_16x16x32_bf16 v[14:17], v[156:159], v[216:219], v[14:17]
	v_mfma_f32_16x16x32_bf16 v[10:13], v[168:171], v[216:219], v[10:13]
	v_mfma_f32_16x16x32_bf16 v[54:57], v[172:175], v[188:191], v[54:57]
	v_mfma_f32_16x16x32_bf16 v[50:53], v[180:183], v[188:191], v[50:53]
	v_mfma_f32_16x16x32_bf16 v[38:41], v[172:175], v[196:199], v[38:41]
	v_mfma_f32_16x16x32_bf16 v[34:37], v[180:183], v[196:199], v[34:37]
	v_mfma_f32_16x16x32_bf16 v[22:25], v[172:175], v[204:207], v[22:25]
	v_mfma_f32_16x16x32_bf16 v[18:21], v[180:183], v[204:207], v[18:21]
	v_mfma_f32_16x16x32_bf16 v[6:9], v[172:175], v[212:215], v[6:9]
	v_mfma_f32_16x16x32_bf16 v[2:5], v[180:183], v[212:215], v[2:5]
	v_mfma_f32_16x16x32_bf16 v[54:57], v[176:179], v[192:195], v[54:57]
	v_mfma_f32_16x16x32_bf16 v[50:53], v[184:187], v[192:195], v[50:53]
	v_mfma_f32_16x16x32_bf16 v[38:41], v[176:179], v[200:203], v[38:41]
	v_mfma_f32_16x16x32_bf16 v[34:37], v[184:187], v[200:203], v[34:37]
	v_mfma_f32_16x16x32_bf16 v[22:25], v[176:179], v[208:211], v[22:25]
	v_mfma_f32_16x16x32_bf16 v[18:21], v[184:187], v[208:211], v[18:21]
	v_mfma_f32_16x16x32_bf16 v[6:9], v[176:179], v[216:219], v[6:9]
	v_mfma_f32_16x16x32_bf16 v[2:5], v[184:187], v[216:219], v[2:5]
	s_barrier
	s_add_i32 s21, 0, 0x18000
	v_add_u32_e32 v155, s21, v150
	s_add_i32 s28, 0, 0x1c000
	ds_read_b128 v[146:149], v155
	ds_read_b128 v[156:159], v155 offset:1024
	ds_read_b128 v[160:163], v155 offset:2048
	ds_read_b128 v[168:171], v155 offset:3072
	v_add_u32_e32 v155, s28, v150
	ds_read_b128 v[172:175], v155
	ds_read_b128 v[176:179], v155 offset:1024
	ds_read_b128 v[180:183], v155 offset:2048
	ds_read_b128 v[184:187], v155 offset:3072
	s_add_u32 s22, s22, 0x80000
	s_addc_u32 s23, s23, 0
	s_mov_b32 m0, s33
	v_lshl_add_u64 v[228:229], s[22:23], 0, v[136:137]
	ds_read_b128 v[188:191], v154 offset:32768
	ds_read_b128 v[192:195], v154 offset:33792
	ds_read_b128 v[196:199], v154 offset:34816
	ds_read_b128 v[200:203], v154 offset:35840
	ds_read_b128 v[204:207], v154 offset:36864
	ds_read_b128 v[208:211], v154 offset:37888
	ds_read_b128 v[212:215], v154 offset:38912
	ds_read_b128 v[216:219], v154 offset:39936
	global_load_lds_dwordx4 v[228:229], off
	v_lshl_add_u64 v[228:229], s[22:23], 0, v[132:133]
	s_mov_b32 m0, s34
	s_nop 0
	global_load_lds_dwordx4 v[228:229], off
	s_waitcnt vmcnt(8)
	s_waitcnt lgkmcnt(0)
	s_barrier
	s_waitcnt lgkmcnt(0)
	v_mfma_f32_16x16x32_bf16 v[126:129], v[146:149], v[188:191], v[126:129]
	v_mfma_f32_16x16x32_bf16 v[122:125], v[160:163], v[188:191], v[122:125]
	v_mfma_f32_16x16x32_bf16 v[110:113], v[146:149], v[196:199], v[110:113]
	v_mfma_f32_16x16x32_bf16 v[106:109], v[160:163], v[196:199], v[106:109]
	v_mfma_f32_16x16x32_bf16 v[94:97], v[146:149], v[204:207], v[94:97]
	v_mfma_f32_16x16x32_bf16 v[90:93], v[160:163], v[204:207], v[90:93]
	v_mfma_f32_16x16x32_bf16 v[78:81], v[146:149], v[212:215], v[78:81]
	v_mfma_f32_16x16x32_bf16 v[74:77], v[160:163], v[212:215], v[74:77]
	v_mfma_f32_16x16x32_bf16 v[126:129], v[156:159], v[192:195], v[126:129]
	v_mfma_f32_16x16x32_bf16 v[122:125], v[168:171], v[192:195], v[122:125]
	v_mfma_f32_16x16x32_bf16 v[110:113], v[156:159], v[200:203], v[110:113]
	v_mfma_f32_16x16x32_bf16 v[106:109], v[168:171], v[200:203], v[106:109]
	v_mfma_f32_16x16x32_bf16 v[94:97], v[156:159], v[208:211], v[94:97]
	v_mfma_f32_16x16x32_bf16 v[90:93], v[168:171], v[208:211], v[90:93]
	v_mfma_f32_16x16x32_bf16 v[78:81], v[156:159], v[216:219], v[78:81]
	v_mfma_f32_16x16x32_bf16 v[74:77], v[168:171], v[216:219], v[74:77]
	v_mfma_f32_16x16x32_bf16 v[118:121], v[172:175], v[188:191], v[118:121]
	v_mfma_f32_16x16x32_bf16 v[114:117], v[180:183], v[188:191], v[114:117]
	v_mfma_f32_16x16x32_bf16 v[102:105], v[172:175], v[196:199], v[102:105]
	v_mfma_f32_16x16x32_bf16 v[98:101], v[180:183], v[196:199], v[98:101]
	v_mfma_f32_16x16x32_bf16 v[86:89], v[172:175], v[204:207], v[86:89]
	v_mfma_f32_16x16x32_bf16 v[82:85], v[180:183], v[204:207], v[82:85]
	v_mfma_f32_16x16x32_bf16 v[70:73], v[172:175], v[212:215], v[70:73]
	v_mfma_f32_16x16x32_bf16 v[66:69], v[180:183], v[212:215], v[66:69]
	v_mfma_f32_16x16x32_bf16 v[118:121], v[176:179], v[192:195], v[118:121]
	v_mfma_f32_16x16x32_bf16 v[114:117], v[184:187], v[192:195], v[114:117]
	v_mfma_f32_16x16x32_bf16 v[102:105], v[176:179], v[200:203], v[102:105]
	v_mfma_f32_16x16x32_bf16 v[98:101], v[184:187], v[200:203], v[98:101]
	v_mfma_f32_16x16x32_bf16 v[86:89], v[176:179], v[208:211], v[86:89]
	v_mfma_f32_16x16x32_bf16 v[82:85], v[184:187], v[208:211], v[82:85]
	v_mfma_f32_16x16x32_bf16 v[70:73], v[176:179], v[216:219], v[70:73]
	v_mfma_f32_16x16x32_bf16 v[66:69], v[184:187], v[216:219], v[66:69]
	s_barrier
	s_add_i32 s21, s21, s25
	v_lshl_add_u64 v[220:221], v[220:221], 0, s[8:9]
	s_mov_b32 m0, s21
	ds_read_b128 v[188:191], v154 offset:49152
	ds_read_b128 v[192:195], v154 offset:50176
	ds_read_b128 v[196:199], v154 offset:51200
	ds_read_b128 v[200:203], v154 offset:52224
	ds_read_b128 v[204:207], v154 offset:53248
	ds_read_b128 v[208:211], v154 offset:54272
	ds_read_b128 v[212:215], v154 offset:55296
	ds_read_b128 v[216:219], v154 offset:56320
	global_load_lds_dwordx4 v[220:221], off
	s_add_i32 m0, s21, 0x2000
	s_add_u32 s0, s0, 0x80080
	v_lshl_add_u64 v[220:221], v[222:223], 0, s[8:9]
	s_addc_u32 s1, s1, 0
	s_add_i32 s21, s28, s25
	global_load_lds_dwordx4 v[220:221], off
	v_lshl_add_u64 v[220:221], s[0:1], 0, v[134:135]
	s_mov_b32 m0, s21
	s_nop 0
	global_load_lds_dwordx4 v[220:221], off
	v_lshl_add_u64 v[220:221], s[0:1], 0, v[130:131]
	s_add_i32 m0, s21, 0x2000
	s_nop 0
	global_load_lds_dwordx4 v[220:221], off
	v_lshl_add_u64 v[220:221], v[224:225], 0, s[8:9]
	s_mov_b32 m0, s37
	s_nop 0
	global_load_lds_dwordx4 v[220:221], off
	v_lshl_add_u64 v[220:221], v[226:227], 0, s[8:9]
	s_mov_b32 m0, s40
	s_nop 0
	global_load_lds_dwordx4 v[220:221], off
	s_waitcnt vmcnt(8)
	s_waitcnt lgkmcnt(0)
	s_barrier
	s_waitcnt lgkmcnt(0)
	v_mfma_f32_16x16x32_bf16 v[62:65], v[146:149], v[188:191], v[62:65]
	v_mfma_f32_16x16x32_bf16 v[58:61], v[160:163], v[188:191], v[58:61]
	v_mfma_f32_16x16x32_bf16 v[46:49], v[146:149], v[196:199], v[46:49]
	v_mfma_f32_16x16x32_bf16 v[42:45], v[160:163], v[196:199], v[42:45]
	v_mfma_f32_16x16x32_bf16 v[30:33], v[146:149], v[204:207], v[30:33]
	v_mfma_f32_16x16x32_bf16 v[26:29], v[160:163], v[204:207], v[26:29]
	v_mfma_f32_16x16x32_bf16 v[14:17], v[146:149], v[212:215], v[14:17]
	v_mfma_f32_16x16x32_bf16 v[10:13], v[160:163], v[212:215], v[10:13]
	v_mfma_f32_16x16x32_bf16 v[62:65], v[156:159], v[192:195], v[62:65]
	v_mfma_f32_16x16x32_bf16 v[58:61], v[168:171], v[192:195], v[58:61]
	v_mfma_f32_16x16x32_bf16 v[46:49], v[156:159], v[200:203], v[46:49]
	v_mfma_f32_16x16x32_bf16 v[42:45], v[168:171], v[200:203], v[42:45]
	v_mfma_f32_16x16x32_bf16 v[30:33], v[156:159], v[208:211], v[30:33]
	v_mfma_f32_16x16x32_bf16 v[26:29], v[168:171], v[208:211], v[26:29]
	v_mfma_f32_16x16x32_bf16 v[14:17], v[156:159], v[216:219], v[14:17]
	v_mfma_f32_16x16x32_bf16 v[10:13], v[168:171], v[216:219], v[10:13]
	v_mfma_f32_16x16x32_bf16 v[54:57], v[172:175], v[188:191], v[54:57]
	v_mfma_f32_16x16x32_bf16 v[50:53], v[180:183], v[188:191], v[50:53]
	v_mfma_f32_16x16x32_bf16 v[38:41], v[172:175], v[196:199], v[38:41]
	v_mfma_f32_16x16x32_bf16 v[34:37], v[180:183], v[196:199], v[34:37]
	v_mfma_f32_16x16x32_bf16 v[22:25], v[172:175], v[204:207], v[22:25]
	v_mfma_f32_16x16x32_bf16 v[18:21], v[180:183], v[204:207], v[18:21]
	v_mfma_f32_16x16x32_bf16 v[6:9], v[172:175], v[212:215], v[6:9]
	v_mfma_f32_16x16x32_bf16 v[2:5], v[180:183], v[212:215], v[2:5]
	v_mfma_f32_16x16x32_bf16 v[54:57], v[176:179], v[192:195], v[54:57]
	v_mfma_f32_16x16x32_bf16 v[50:53], v[184:187], v[192:195], v[50:53]
	v_mfma_f32_16x16x32_bf16 v[38:41], v[176:179], v[200:203], v[38:41]
	v_mfma_f32_16x16x32_bf16 v[34:37], v[184:187], v[200:203], v[34:37]
	v_mfma_f32_16x16x32_bf16 v[22:25], v[176:179], v[208:211], v[22:25]
	v_mfma_f32_16x16x32_bf16 v[18:21], v[184:187], v[208:211], v[18:21]
	v_mfma_f32_16x16x32_bf16 v[6:9], v[176:179], v[216:219], v[6:9]
	v_mfma_f32_16x16x32_bf16 v[2:5], v[184:187], v[216:219], v[2:5]
	s_barrier
	s_add_i32 s54, s54, 2
	s_add_u32 s38, s38, 0x100
	s_addc_u32 s39, s39, 0
	s_add_u32 s52, s52, 0x100
	s_addc_u32 s53, s53, 0
	s_cmp_gt_u32 s54, 29
	s_cbranch_scc0 .LBB0_2398
	s_and_b64 vcc, exec, s[10:11]
	s_cbranch_vccz .LBB0_2401
	s_barrier

.LBB0_2459:
	s_setprio 0
	v_readlane_b32 s2, v243, 51
	s_cmp_lt_i32 s2, 30
	s_cselect_b64 s[6:7], -1, 0
	s_and_b64 s[0:1], s[6:7], s[0:1]
	s_andn2_b64 vcc, exec, s[0:1]
	v_readlane_b32 s3, v243, 52
	s_cbranch_vccnz .LBB0_2522
	v_readlane_b32 s2, v243, 0
	s_cmpk_lt_i32 s2, 0x400
	s_cselect_b64 s[0:1], -1, 0
	s_cmpk_gt_i32 s2, 0x3ff
	v_readfirstlane_b32 s4, v0
	s_cbranch_scc1 .LBB0_2466
	v_readlane_b32 s3, v243, 0
	s_ashr_i32 s2, s3, 31
	s_lshr_b32 s2, s2, 29
	s_add_i32 s5, s3, s2
	s_and_b32 s2, s5, -8
	s_sub_i32 s8, s3, s2
	s_cmp_gt_i32 s8, -1
	s_cbranch_scc0 .LBB0_2463
	s_lshl_b32 s9, s8, 7
	s_cbranch_execz .LBB0_2464
	s_branch .LBB0_2465

.LBB0_2466:
	s_andn2_b64 vcc, exec, s[0:1]
	s_cbranch_vccnz .LBB0_2522
	v_lshlrev_b32_e32 v1, 4, v0
	v_and_b32_e32 v2, 32, v0
	v_bitop3_b32 v10, v1, v2, 48 bitop3:0x6c
	v_lshrrev_b32_e32 v2, 1, v0
	v_and_b32_e32 v12, 24, v2
	v_lshrrev_b32_e32 v2, 5, v0
	v_and_b32_e32 v2, 4, v2
	v_bfe_u32 v4, v0, 2, 2
	v_bfe_u32 v3, v0, 2, 4
	v_and_b32_e32 v11, 64, v0
	v_or3_b32 v2, v2, v4, v12
	v_lshrrev_b32_e32 v4, 3, v0
	v_or_b32_e32 v1, v10, v11
	v_and_or_b32 v5, v4, 48, v3
	v_and_or_b32 v4, v4, 32, v2
	s_add_u32 s20, s90, 0xc100000
	v_lshl_or_b32 v170, v4, 11, v1
	v_bfe_u32 v4, v0, 3, 25
	s_addc_u32 s24, s91, 0
	v_or_b32_e32 v4, 64, v4
	s_movk_i32 s0, 0x70
	s_lshr_b32 s10, s4, 6
	s_lshr_b32 s5, s4, 8
	v_and_or_b32 v3, v4, s0, v3
	s_movk_i32 s0, 0x60
	s_lshl_b32 s25, s10, 10
	s_mul_i32 s1, s44, 0x300000
	v_readlane_b32 s2, v242, 17
	v_and_or_b32 v2, v4, s0, v2
	s_mul_hi_i32 s0, s44, 0x300000
	v_readlane_b32 s3, v242, 18
	s_add_u32 s2, s2, s1
	s_addc_u32 s3, s3, s0
	s_ashr_i32 s39, s38, 31
	s_lshl_b64 s[0:1], s[38:39], 19
	s_add_u32 s0, s20, s0
	s_addc_u32 s1, s24, s1
	s_add_i32 s26, s25, 0
	s_add_i32 m0, s26, 0x10000
	v_lshl_or_b32 v174, v2, 11, v1
	global_load_lds_dwordx4 v170, s[0:1]
	s_add_i32 m0, s26, 0x12000
	s_add_u32 s8, s0, 0x40000
	v_mul_u32_u24_e32 v13, 0x3000, v5
	v_mov_b32_e32 v171, 0
	global_load_lds_dwordx4 v174, s[0:1]
	s_addc_u32 s9, s1, 0
	s_add_i32 m0, s26, 0x14000
	v_or_b32_e32 v168, v1, v13
	global_load_lds_dwordx4 v170, s[8:9]
	s_add_i32 m0, s26, 0x16000
	v_mov_b32_e32 v169, v171
	v_mul_u32_u24_e32 v14, 0x3000, v3
	global_load_lds_dwordx4 v174, s[8:9]
	v_lshl_add_u64 v[2:3], s[2:3], 0, v[168:169]
	s_mov_b64 s[8:9], 0x800
	v_or_b32_e32 v172, v14, v1
	v_lshl_add_u64 v[4:5], v[2:3], 0, s[8:9]
	s_mov_b32 m0, s26
	v_mov_b32_e32 v173, v171
	global_load_lds_dwordx4 v[4:5], off
	v_lshl_add_u64 v[4:5], s[2:3], 0, v[172:173]
	s_add_i32 s27, s26, 0x2000
	v_lshl_add_u64 v[6:7], v[4:5], 0, s[8:9]
	s_add_u32 s8, s2, 0x180800
	s_mov_b32 m0, s27
	s_addc_u32 s9, s3, 0
	s_add_i32 s30, s26, 0x4000
	global_load_lds_dwordx4 v[6:7], off
	s_mov_b32 m0, s30
	s_add_i32 s31, s26, 0x6000
	global_load_lds_dwordx4 v168, s[8:9]
	s_mov_b32 m0, s31
	v_mov_b32_e32 v175, v171
	global_load_lds_dwordx4 v172, s[8:9]
	s_cmp_eq_u32 s5, 1
	s_movk_i32 s33, 0x3000
	s_mov_b32 s45, 0
	v_lshl_add_u64 v[6:7], s[0:1], 0, v[170:171]
	s_cselect_b64 s[8:9], -1, 0
	s_cmp_lg_u32 s5, 1
	v_lshl_add_u64 v[8:9], s[0:1], 0, v[174:175]
	s_cbranch_scc1 .LBB0_2469
	s_barrier
	s_setprio 1

.LBB0_2481:
	ds_read_b128 v[130:133], v198
	ds_read_b128 v[134:137], v198 offset:1024
	ds_read_b128 v[138:141], v198 offset:2048
	ds_read_b128 v[142:145], v198 offset:3072
	ds_read_b128 v[146:149], v199
	ds_read_b128 v[150:153], v199 offset:1024
	ds_read_b128 v[154:157], v199 offset:2048
	ds_read_b128 v[158:161], v199 offset:3072
	s_add_u32 s0, s4, 0xffe80080
	s_addc_u32 s1, s5, -1
	s_cmp_eq_u32 s52, 12
	s_cselect_b32 s23, s19, s1
	s_cselect_b32 s22, s18, s0
	s_cselect_b32 s1, s15, s47
	s_cselect_b32 s0, s17, s46
	v_lshl_add_u64 v[162:163], s[4:5], 0, v[176:177]
	s_add_i32 m0, s26, 0xc000
	ds_read_b128 v[184:187], v200
	ds_read_b128 v[188:191], v200 offset:1024
	ds_read_b128 v[192:195], v200 offset:2048
	ds_read_b128 v[202:205], v200 offset:3072
	ds_read_b128 v[206:209], v200 offset:4096
	ds_read_b128 v[210:213], v200 offset:5120
	ds_read_b128 v[214:217], v200 offset:6144
	ds_read_b128 v[218:221], v200 offset:7168
	global_load_lds_dwordx4 v[162:163], off
	v_lshl_add_u64 v[162:163], s[4:5], 0, v[178:179]
	s_add_i32 m0, s26, 0xe000
	s_nop 0
	global_load_lds_dwordx4 v[162:163], off
	s_waitcnt vmcnt(8)
	s_waitcnt lgkmcnt(0)
	s_barrier
	s_waitcnt lgkmcnt(0)
	v_mfma_f32_16x16x32_bf16 v[126:129], v[130:133], v[184:187], v[126:129]
	v_mfma_f32_16x16x32_bf16 v[122:125], v[138:141], v[184:187], v[122:125]
	v_mfma_f32_16x16x32_bf16 v[118:121], v[130:133], v[192:195], v[118:121]
	v_mfma_f32_16x16x32_bf16 v[114:117], v[138:141], v[192:195], v[114:117]
	v_mfma_f32_16x16x32_bf16 v[94:97], v[130:133], v[206:209], v[94:97]
	v_mfma_f32_16x16x32_bf16 v[90:93], v[138:141], v[206:209], v[90:93]
	v_mfma_f32_16x16x32_bf16 v[86:89], v[130:133], v[214:217], v[86:89]
	v_mfma_f32_16x16x32_bf16 v[82:85], v[138:141], v[214:217], v[82:85]
	v_mfma_f32_16x16x32_bf16 v[126:129], v[134:137], v[188:191], v[126:129]
	v_mfma_f32_16x16x32_bf16 v[122:125], v[142:145], v[188:191], v[122:125]
	v_mfma_f32_16x16x32_bf16 v[118:121], v[134:137], v[202:205], v[118:121]
	v_mfma_f32_16x16x32_bf16 v[114:117], v[142:145], v[202:205], v[114:117]
	v_mfma_f32_16x16x32_bf16 v[94:97], v[134:137], v[210:213], v[94:97]
	v_mfma_f32_16x16x32_bf16 v[90:93], v[142:145], v[210:213], v[90:93]
	v_mfma_f32_16x16x32_bf16 v[86:89], v[134:137], v[218:221], v[86:89]
	v_mfma_f32_16x16x32_bf16 v[82:85], v[142:145], v[218:221], v[82:85]
	v_mfma_f32_16x16x32_bf16 v[110:113], v[146:149], v[184:187], v[110:113]
	v_mfma_f32_16x16x32_bf16 v[106:109], v[154:157], v[184:187], v[106:109]
	v_mfma_f32_16x16x32_bf16 v[102:105], v[146:149], v[192:195], v[102:105]
	v_mfma_f32_16x16x32_bf16 v[98:101], v[154:157], v[192:195], v[98:101]
	v_mfma_f32_16x16x32_bf16 v[78:81], v[146:149], v[206:209], v[78:81]
	v_mfma_f32_16x16x32_bf16 v[74:77], v[154:157], v[206:209], v[74:77]
	v_mfma_f32_16x16x32_bf16 v[70:73], v[146:149], v[214:217], v[70:73]
	v_mfma_f32_16x16x32_bf16 v[66:69], v[154:157], v[214:217], v[66:69]
	v_mfma_f32_16x16x32_bf16 v[110:113], v[150:153], v[188:191], v[110:113]
	v_mfma_f32_16x16x32_bf16 v[106:109], v[158:161], v[188:191], v[106:109]
	v_mfma_f32_16x16x32_bf16 v[102:105], v[150:153], v[202:205], v[102:105]
	v_mfma_f32_16x16x32_bf16 v[98:101], v[158:161], v[202:205], v[98:101]
	v_mfma_f32_16x16x32_bf16 v[78:81], v[150:153], v[210:213], v[78:81]
	v_mfma_f32_16x16x32_bf16 v[74:77], v[158:161], v[210:213], v[74:77]
	v_mfma_f32_16x16x32_bf16 v[70:73], v[150:153], v[218:221], v[70:73]
	v_mfma_f32_16x16x32_bf16 v[66:69], v[158:161], v[218:221], v[66:69]
	s_barrier
	s_add_i32 s21, s40, s25
	v_lshl_add_u64 v[162:163], s[0:1], 0, v[170:171]
	s_mov_b32 m0, s21
	ds_read_b128 v[184:187], v200 offset:16384
	ds_read_b128 v[188:191], v200 offset:17408
	ds_read_b128 v[192:195], v200 offset:18432
	ds_read_b128 v[202:205], v200 offset:19456
	ds_read_b128 v[206:209], v200 offset:20480
	ds_read_b128 v[210:213], v200 offset:21504
	ds_read_b128 v[214:217], v200 offset:22528
	ds_read_b128 v[218:221], v200 offset:23552
	global_load_lds_dwordx4 v[162:163], off
	s_add_i32 m0, s21, 0x2000
	s_add_u32 s28, s0, 0x40000
	v_lshl_add_u64 v[196:197], s[0:1], 0, v[174:175]
	s_addc_u32 s29, s1, 0
	s_add_i32 s21, s41, s25
	global_load_lds_dwordx4 v[196:197], off
	v_lshl_add_u64 v[222:223], s[28:29], 0, v[170:171]
	s_mov_b32 m0, s21
	v_lshl_add_u64 v[224:225], s[22:23], 0, v[172:173]
	global_load_lds_dwordx4 v[222:223], off
	v_lshl_add_u64 v[222:223], s[28:29], 0, v[174:175]
	s_add_i32 m0, s21, 0x2000
	s_nop 0
	global_load_lds_dwordx4 v[222:223], off
	v_lshl_add_u64 v[222:223], s[22:23], 0, v[168:169]
	s_mov_b32 m0, s26
	s_nop 0
	global_load_lds_dwordx4 v[222:223], off
	s_mov_b32 m0, s27
	s_nop 0
	global_load_lds_dwordx4 v[224:225], off
	s_waitcnt vmcnt(8)
	s_waitcnt lgkmcnt(0)
	s_barrier
	s_waitcnt lgkmcnt(0)
	v_mfma_f32_16x16x32_bf16 v[62:65], v[130:133], v[184:187], v[62:65]
	v_mfma_f32_16x16x32_bf16 v[58:61], v[138:141], v[184:187], v[58:61]
	v_mfma_f32_16x16x32_bf16 v[54:57], v[130:133], v[192:195], v[54:57]
	v_mfma_f32_16x16x32_bf16 v[50:53], v[138:141], v[192:195], v[50:53]
	v_mfma_f32_16x16x32_bf16 v[30:33], v[130:133], v[206:209], v[30:33]
	v_mfma_f32_16x16x32_bf16 v[26:29], v[138:141], v[206:209], v[26:29]
	v_mfma_f32_16x16x32_bf16 v[18:21], v[130:133], v[214:217], v[18:21]
	v_mfma_f32_16x16x32_bf16 v[10:13], v[138:141], v[214:217], v[10:13]
	v_mfma_f32_16x16x32_bf16 v[62:65], v[134:137], v[188:191], v[62:65]
	v_mfma_f32_16x16x32_bf16 v[58:61], v[142:145], v[188:191], v[58:61]
	v_mfma_f32_16x16x32_bf16 v[54:57], v[134:137], v[202:205], v[54:57]
	v_mfma_f32_16x16x32_bf16 v[50:53], v[142:145], v[202:205], v[50:53]
	v_mfma_f32_16x16x32_bf16 v[30:33], v[134:137], v[210:213], v[30:33]
	v_mfma_f32_16x16x32_bf16 v[26:29], v[142:145], v[210:213], v[26:29]
	v_mfma_f32_16x16x32_bf16 v[18:21], v[134:137], v[218:221], v[18:21]
	v_mfma_f32_16x16x32_bf16 v[10:13], v[142:145], v[218:221], v[10:13]
	v_mfma_f32_16x16x32_bf16 v[46:49], v[146:149], v[184:187], v[46:49]
	v_mfma_f32_16x16x32_bf16 v[42:45], v[154:157], v[184:187], v[42:45]
	v_mfma_f32_16x16x32_bf16 v[38:41], v[146:149], v[192:195], v[38:41]
	v_mfma_f32_16x16x32_bf16 v[34:37], v[154:157], v[192:195], v[34:37]
	v_mfma_f32_16x16x32_bf16 v[22:25], v[146:149], v[206:209], v[22:25]
	v_mfma_f32_16x16x32_bf16 v[14:17], v[154:157], v[206:209], v[14:17]
	v_mfma_f32_16x16x32_bf16 v[6:9], v[146:149], v[214:217], v[6:9]
	v_mfma_f32_16x16x32_bf16 v[2:5], v[154:157], v[214:217], v[2:5]
	v_mfma_f32_16x16x32_bf16 v[46:49], v[150:153], v[188:191], v[46:49]
	v_mfma_f32_16x16x32_bf16 v[42:45], v[158:161], v[188:191], v[42:45]
	v_mfma_f32_16x16x32_bf16 v[38:41], v[150:153], v[202:205], v[38:41]
	v_mfma_f32_16x16x32_bf16 v[34:37], v[158:161], v[202:205], v[34:37]
	v_mfma_f32_16x16x32_bf16 v[22:25], v[150:153], v[210:213], v[22:25]
	v_mfma_f32_16x16x32_bf16 v[14:17], v[158:161], v[210:213], v[14:17]
	v_mfma_f32_16x16x32_bf16 v[6:9], v[150:153], v[218:221], v[6:9]
	v_mfma_f32_16x16x32_bf16 v[2:5], v[158:161], v[218:221], v[2:5]
	s_barrier
	s_add_i32 s21, 0, 0x18000
	s_add_i32 s28, 0, 0x1c000
	v_add_u32_e32 v142, s21, v165
	v_add_u32_e32 v158, s28, v165
	ds_read_b128 v[130:133], v142
	ds_read_b128 v[134:137], v142 offset:1024
	ds_read_b128 v[138:141], v142 offset:2048
	ds_read_b128 v[142:145], v142 offset:3072
	ds_read_b128 v[146:149], v158
	ds_read_b128 v[150:153], v158 offset:1024
	ds_read_b128 v[154:157], v158 offset:2048
	ds_read_b128 v[158:161], v158 offset:3072
	s_add_u32 s22, s22, 0x180000
	s_addc_u32 s23, s23, 0
	s_mov_b32 m0, s30
	v_lshl_add_u64 v[226:227], s[22:23], 0, v[168:169]
	ds_read_b128 v[184:187], v200 offset:32768
	ds_read_b128 v[188:191], v200 offset:33792
	ds_read_b128 v[192:195], v200 offset:34816
	ds_read_b128 v[202:205], v200 offset:35840
	ds_read_b128 v[206:209], v200 offset:36864
	ds_read_b128 v[210:213], v200 offset:37888
	ds_read_b128 v[214:217], v200 offset:38912
	ds_read_b128 v[218:221], v200 offset:39936
	global_load_lds_dwordx4 v[226:227], off
	v_lshl_add_u64 v[226:227], s[22:23], 0, v[172:173]
	s_mov_b32 m0, s31
	s_nop 0
	global_load_lds_dwordx4 v[226:227], off
	s_waitcnt vmcnt(8)
	s_waitcnt lgkmcnt(0)
	s_barrier
	s_waitcnt lgkmcnt(0)
	v_mfma_f32_16x16x32_bf16 v[126:129], v[130:133], v[184:187], v[126:129]
	v_mfma_f32_16x16x32_bf16 v[122:125], v[138:141], v[184:187], v[122:125]
	v_mfma_f32_16x16x32_bf16 v[118:121], v[130:133], v[192:195], v[118:121]
	v_mfma_f32_16x16x32_bf16 v[114:117], v[138:141], v[192:195], v[114:117]
	v_mfma_f32_16x16x32_bf16 v[94:97], v[130:133], v[206:209], v[94:97]
	v_mfma_f32_16x16x32_bf16 v[90:93], v[138:141], v[206:209], v[90:93]
	v_mfma_f32_16x16x32_bf16 v[86:89], v[130:133], v[214:217], v[86:89]
	v_mfma_f32_16x16x32_bf16 v[82:85], v[138:141], v[214:217], v[82:85]
	v_mfma_f32_16x16x32_bf16 v[126:129], v[134:137], v[188:191], v[126:129]
	v_mfma_f32_16x16x32_bf16 v[122:125], v[142:145], v[188:191], v[122:125]
	v_mfma_f32_16x16x32_bf16 v[118:121], v[134:137], v[202:205], v[118:121]
	v_mfma_f32_16x16x32_bf16 v[114:117], v[142:145], v[202:205], v[114:117]
	v_mfma_f32_16x16x32_bf16 v[94:97], v[134:137], v[210:213], v[94:97]
	v_mfma_f32_16x16x32_bf16 v[90:93], v[142:145], v[210:213], v[90:93]
	v_mfma_f32_16x16x32_bf16 v[86:89], v[134:137], v[218:221], v[86:89]
	v_mfma_f32_16x16x32_bf16 v[82:85], v[142:145], v[218:221], v[82:85]
	v_mfma_f32_16x16x32_bf16 v[110:113], v[146:149], v[184:187], v[110:113]
	v_mfma_f32_16x16x32_bf16 v[106:109], v[154:157], v[184:187], v[106:109]
	v_mfma_f32_16x16x32_bf16 v[102:105], v[146:149], v[192:195], v[102:105]
	v_mfma_f32_16x16x32_bf16 v[98:101], v[154:157], v[192:195], v[98:101]
	v_mfma_f32_16x16x32_bf16 v[78:81], v[146:149], v[206:209], v[78:81]
	v_mfma_f32_16x16x32_bf16 v[74:77], v[154:157], v[206:209], v[74:77]
	v_mfma_f32_16x16x32_bf16 v[70:73], v[146:149], v[214:217], v[70:73]
	v_mfma_f32_16x16x32_bf16 v[66:69], v[154:157], v[214:217], v[66:69]
	v_mfma_f32_16x16x32_bf16 v[110:113], v[150:153], v[188:191], v[110:113]
	v_mfma_f32_16x16x32_bf16 v[106:109], v[158:161], v[188:191], v[106:109]
	v_mfma_f32_16x16x32_bf16 v[102:105], v[150:153], v[202:205], v[102:105]
	v_mfma_f32_16x16x32_bf16 v[98:101], v[158:161], v[202:205], v[98:101]
	v_mfma_f32_16x16x32_bf16 v[78:81], v[150:153], v[210:213], v[78:81]
	v_mfma_f32_16x16x32_bf16 v[74:77], v[158:161], v[210:213], v[74:77]
	v_mfma_f32_16x16x32_bf16 v[70:73], v[150:153], v[218:221], v[70:73]
	v_mfma_f32_16x16x32_bf16 v[66:69], v[158:161], v[218:221], v[66:69]
	s_barrier
	s_add_i32 s21, s21, s25
	v_lshl_add_u64 v[162:163], v[162:163], 0, s[10:11]
	s_mov_b32 m0, s21
	ds_read_b128 v[184:187], v200 offset:49152
	ds_read_b128 v[188:191], v200 offset:50176
	ds_read_b128 v[192:195], v200 offset:51200
	ds_read_b128 v[202:205], v200 offset:52224
	ds_read_b128 v[206:209], v200 offset:53248
	ds_read_b128 v[210:213], v200 offset:54272
	ds_read_b128 v[214:217], v200 offset:55296
	ds_read_b128 v[218:221], v200 offset:56320
	global_load_lds_dwordx4 v[162:163], off
	s_add_i32 m0, s21, 0x2000
	s_add_u32 s0, s0, 0x40080
	v_lshl_add_u64 v[162:163], v[196:197], 0, s[10:11]
	s_addc_u32 s1, s1, 0
	s_add_i32 s21, s28, s25
	global_load_lds_dwordx4 v[162:163], off
	v_lshl_add_u64 v[162:163], s[0:1], 0, v[170:171]
	s_mov_b32 m0, s21
	s_nop 0
	global_load_lds_dwordx4 v[162:163], off
	v_lshl_add_u64 v[162:163], s[0:1], 0, v[174:175]
	s_add_i32 m0, s21, 0x2000
	s_nop 0
	global_load_lds_dwordx4 v[162:163], off
	v_lshl_add_u64 v[162:163], v[222:223], 0, s[10:11]
	s_mov_b32 m0, s34
	s_nop 0
	global_load_lds_dwordx4 v[162:163], off
	v_lshl_add_u64 v[162:163], v[224:225], 0, s[10:11]
	s_mov_b32 m0, s35
	s_nop 0
	global_load_lds_dwordx4 v[162:163], off
	s_waitcnt vmcnt(8)
	s_waitcnt lgkmcnt(0)
	s_barrier
	s_waitcnt lgkmcnt(0)
	v_mfma_f32_16x16x32_bf16 v[62:65], v[130:133], v[184:187], v[62:65]
	v_mfma_f32_16x16x32_bf16 v[58:61], v[138:141], v[184:187], v[58:61]
	v_mfma_f32_16x16x32_bf16 v[54:57], v[130:133], v[192:195], v[54:57]
	v_mfma_f32_16x16x32_bf16 v[50:53], v[138:141], v[192:195], v[50:53]
	v_mfma_f32_16x16x32_bf16 v[30:33], v[130:133], v[206:209], v[30:33]
	v_mfma_f32_16x16x32_bf16 v[26:29], v[138:141], v[206:209], v[26:29]
	v_mfma_f32_16x16x32_bf16 v[18:21], v[130:133], v[214:217], v[18:21]
	v_mfma_f32_16x16x32_bf16 v[10:13], v[138:141], v[214:217], v[10:13]
	v_mfma_f32_16x16x32_bf16 v[62:65], v[134:137], v[188:191], v[62:65]
	v_mfma_f32_16x16x32_bf16 v[58:61], v[142:145], v[188:191], v[58:61]
	v_mfma_f32_16x16x32_bf16 v[54:57], v[134:137], v[202:205], v[54:57]
	v_mfma_f32_16x16x32_bf16 v[50:53], v[142:145], v[202:205], v[50:53]
	v_mfma_f32_16x16x32_bf16 v[30:33], v[134:137], v[210:213], v[30:33]
	v_mfma_f32_16x16x32_bf16 v[26:29], v[142:145], v[210:213], v[26:29]
	v_mfma_f32_16x16x32_bf16 v[18:21], v[134:137], v[218:221], v[18:21]
	v_mfma_f32_16x16x32_bf16 v[10:13], v[142:145], v[218:221], v[10:13]
	v_mfma_f32_16x16x32_bf16 v[46:49], v[146:149], v[184:187], v[46:49]
	v_mfma_f32_16x16x32_bf16 v[42:45], v[154:157], v[184:187], v[42:45]
	v_mfma_f32_16x16x32_bf16 v[38:41], v[146:149], v[192:195], v[38:41]
	v_mfma_f32_16x16x32_bf16 v[34:37], v[154:157], v[192:195], v[34:37]
	v_mfma_f32_16x16x32_bf16 v[22:25], v[146:149], v[206:209], v[22:25]
	v_mfma_f32_16x16x32_bf16 v[14:17], v[154:157], v[206:209], v[14:17]
	v_mfma_f32_16x16x32_bf16 v[6:9], v[146:149], v[214:217], v[6:9]
	v_mfma_f32_16x16x32_bf16 v[2:5], v[154:157], v[214:217], v[2:5]
	v_mfma_f32_16x16x32_bf16 v[46:49], v[150:153], v[188:191], v[46:49]
	v_mfma_f32_16x16x32_bf16 v[42:45], v[158:161], v[188:191], v[42:45]
	v_mfma_f32_16x16x32_bf16 v[38:41], v[150:153], v[202:205], v[38:41]
	v_mfma_f32_16x16x32_bf16 v[34:37], v[158:161], v[202:205], v[34:37]
	v_mfma_f32_16x16x32_bf16 v[22:25], v[150:153], v[210:213], v[22:25]
	v_mfma_f32_16x16x32_bf16 v[14:17], v[158:161], v[210:213], v[14:17]
	v_mfma_f32_16x16x32_bf16 v[6:9], v[150:153], v[218:221], v[6:9]
	v_mfma_f32_16x16x32_bf16 v[2:5], v[158:161], v[218:221], v[2:5]
	s_barrier
	s_add_i32 s52, s52, 2
	s_add_u32 s4, s4, 0x100
	s_addc_u32 s5, s5, 0
	s_add_u32 s46, s46, 0x100
	s_addc_u32 s47, s47, 0
	s_cmp_gt_u32 s52, 13
	s_cbranch_scc0 .LBB0_2481
	s_and_b64 vcc, exec, s[12:13]
	s_cbranch_vccz .LBB0_2484
	s_barrier

.LBB0_2576:
	s_setprio 0
	v_readlane_b32 s2, v243, 51
	s_cmp_lt_i32 s2, 31
	s_cselect_b64 s[4:5], -1, 0
	s_and_b64 s[0:1], s[4:5], s[0:1]
	s_andn2_b64 vcc, exec, s[0:1]
	v_readlane_b32 s3, v243, 52
	s_cbranch_vccnz .LBB0_2601
	v_readlane_b32 s0, v243, 0
	s_cmpk_gt_i32 s0, 0x3ff
	v_readfirstlane_b32 s3, v0
	s_cbranch_scc1 .LBB0_2601
	v_readlane_b32 s1, v243, 0
	s_ashr_i32 s20, s1, 31
	s_lshr_b32 s0, s20, 29
	s_add_i32 s6, s1, s0
	s_and_b32 s0, s6, -8
	s_sub_i32 s7, s1, s0
	s_cmp_gt_i32 s7, -1
	s_cbranch_scc0 .LBB0_2580
	s_lshl_b32 s2, s7, 7
	s_cbranch_execz .LBB0_2581
	s_branch .LBB0_2582

.LBB0_2582:
	s_ashr_i32 s0, s6, 3
	v_lshlrev_b32_e32 v1, 4, v0
	s_add_u32 s24, s90, 0xcd00000
	v_and_b32_e32 v2, 32, v0
	v_or_b32_e32 v13, 0x2000, v1
	s_addc_u32 s25, s91, 0
	v_bfe_u32 v12, v0, 2, 4
	v_bitop3_b32 v10, v1, v2, 48 bitop3:0x6c
	v_lshrrev_b32_e32 v1, 7, v13
	s_movk_i32 s1, 0x70
	s_add_i32 s0, s2, s0
	v_and_or_b32 v1, v1, s1, v12
	s_ashr_i32 s1, s0, 31
	s_lshr_b32 s1, s1, 26
	s_add_i32 s1, s0, s1
	s_ashr_i32 s2, s1, 6
	s_andn2_b32 s1, s1, 63
	s_sub_i32 s0, s0, s1
	s_bfe_i32 s1, s0, 0x80000
	s_bfe_u32 s1, s1, 0x3000c
	s_add_i32 s1, s0, s1
	s_lshl_b32 s6, s2, 3
	s_bfe_i32 s2, s1, 0x80000
	s_and_b32 s1, s1, 0xf8
	s_sub_i32 s0, s0, s1
	s_sext_i32_i16 s2, s2
	s_sext_i32_i8 s0, s0
	s_lshr_b32 s2, s2, 3
	s_add_i32 s36, s6, s0
	s_lshr_b32 s8, s3, 6
	s_ashr_i32 s37, s36, 31
	s_bfe_i64 s[0:1], s[2:3], 0x100000
	s_lshr_b32 s10, s3, 8
	s_lshl_b32 s26, s8, 10
	s_lshl_b64 s[6:7], s[36:37], 20
	s_lshl_b64 s[0:1], s[0:1], 20
	v_and_b32_e32 v11, 64, v0
	v_lshrrev_b32_e32 v3, 3, v0
	s_add_u32 s0, s24, s0
	v_or_b32_e32 v2, v10, v11
	v_and_or_b32 v3, v3, 48, v12
	s_addc_u32 s1, s25, s1
	s_add_i32 s27, s26, 0
	v_lshl_or_b32 v138, v3, 12, v2
	s_add_i32 m0, s27, 0x10000
	v_lshl_or_b32 v140, v1, 12, v2
	global_load_lds_dwordx4 v138, s[0:1]
	s_add_i32 m0, s27, 0x12000
	s_add_u32 s12, s0, 0x80000
	global_load_lds_dwordx4 v140, s[0:1]
	s_addc_u32 s13, s1, 0
	s_add_i32 m0, s27, 0x14000
	v_mov_b32_e32 v139, 0
	global_load_lds_dwordx4 v138, s[12:13]
	s_add_i32 m0, s27, 0x16000
	v_mov_b32_e32 v141, v139
	global_load_lds_dwordx4 v140, s[12:13]
	v_readlane_b32 s12, v242, 15
	v_readlane_b32 s13, v242, 16
	s_add_u32 s22, s12, s6
	s_addc_u32 s23, s13, s7
	s_add_i32 s30, s27, 0x2000
	s_mov_b32 m0, s27
	s_add_u32 s6, s22, 0x80000
	global_load_lds_dwordx4 v138, s[22:23]
	s_mov_b32 m0, s30
	s_addc_u32 s7, s23, 0
	s_add_i32 s31, s27, 0x4000
	global_load_lds_dwordx4 v140, s[22:23]
	s_mov_b32 m0, s31
	s_add_i32 s33, s27, 0x6000
	global_load_lds_dwordx4 v138, s[6:7]
	s_mov_b32 m0, s33
	s_cmp_eq_u32 s10, 1
	global_load_lds_dwordx4 v140, s[6:7]
	s_mov_b32 s34, 0
	v_lshl_add_u64 v[8:9], s[0:1], 0, v[138:139]
	v_lshl_add_u64 v[6:7], s[0:1], 0, v[140:141]
	v_lshl_add_u64 v[2:3], s[22:23], 0, v[138:139]
	s_cselect_b64 s[6:7], -1, 0
	s_cmp_lg_u32 s10, 1
	v_lshl_add_u64 v[4:5], s[22:23], 0, v[140:141]
	s_cbranch_scc1 .LBB0_2584
	s_barrier
	s_setprio 1

.LBB0_2594:
	ds_read_b128 v[106:109], v167
	ds_read_b128 v[134:137], v167 offset:1024
	ds_read_b128 v[170:173], v167 offset:2048
	ds_read_b128 v[174:177], v167 offset:3072
	ds_read_b128 v[178:181], v186
	ds_read_b128 v[182:185], v186 offset:1024
	ds_read_b128 v[188:191], v186 offset:2048
	ds_read_b128 v[192:195], v186 offset:3072
	s_add_u32 s0, s38, 0xfff80080
	s_addc_u32 s1, s39, -1
	s_cmp_eq_u32 s55, 28
	s_cselect_b32 s23, s15, s1
	s_cselect_b32 s22, s47, s0
	s_cselect_b32 s1, s13, s54
	s_cselect_b32 s0, s52, s53
	v_lshl_add_u64 v[228:229], s[38:39], 0, v[158:159]
	s_add_i32 m0, s27, 0xc000
	ds_read_b128 v[196:199], v187
	ds_read_b128 v[200:203], v187 offset:1024
	ds_read_b128 v[204:207], v187 offset:2048
	ds_read_b128 v[208:211], v187 offset:3072
	ds_read_b128 v[212:215], v187 offset:4096
	ds_read_b128 v[216:219], v187 offset:5120
	ds_read_b128 v[220:223], v187 offset:6144
	ds_read_b128 v[224:227], v187 offset:7168
	global_load_lds_dwordx4 v[228:229], off
	v_lshl_add_u64 v[228:229], s[38:39], 0, v[160:161]
	s_add_i32 m0, s27, 0xe000
	s_nop 0
	global_load_lds_dwordx4 v[228:229], off
	s_waitcnt vmcnt(8)
	s_waitcnt lgkmcnt(0)
	s_barrier
	s_waitcnt lgkmcnt(0)
	v_mfma_f32_16x16x32_bf16 v[130:133], v[106:109], v[196:199], v[130:133]
	v_mfma_f32_16x16x32_bf16 v[94:97], v[170:173], v[196:199], v[94:97]
	v_mfma_f32_16x16x32_bf16 v[126:129], v[106:109], v[204:207], v[126:129]
	v_mfma_f32_16x16x32_bf16 v[90:93], v[170:173], v[204:207], v[90:93]
	v_mfma_f32_16x16x32_bf16 v[122:125], v[106:109], v[212:215], v[122:125]
	v_mfma_f32_16x16x32_bf16 v[86:89], v[170:173], v[212:215], v[86:89]
	v_mfma_f32_16x16x32_bf16 v[118:121], v[106:109], v[220:223], v[118:121]
	v_mfma_f32_16x16x32_bf16 v[82:85], v[170:173], v[220:223], v[82:85]
	v_mfma_f32_16x16x32_bf16 v[130:133], v[134:137], v[200:203], v[130:133]
	v_mfma_f32_16x16x32_bf16 v[94:97], v[174:177], v[200:203], v[94:97]
	v_mfma_f32_16x16x32_bf16 v[126:129], v[134:137], v[208:211], v[126:129]
	v_mfma_f32_16x16x32_bf16 v[90:93], v[174:177], v[208:211], v[90:93]
	v_mfma_f32_16x16x32_bf16 v[122:125], v[134:137], v[216:219], v[122:125]
	v_mfma_f32_16x16x32_bf16 v[86:89], v[174:177], v[216:219], v[86:89]
	v_mfma_f32_16x16x32_bf16 v[118:121], v[134:137], v[224:227], v[118:121]
	v_mfma_f32_16x16x32_bf16 v[82:85], v[174:177], v[224:227], v[82:85]
	v_mfma_f32_16x16x32_bf16 v[62:65], v[178:181], v[196:199], v[62:65]
	v_mfma_f32_16x16x32_bf16 v[30:33], v[188:191], v[196:199], v[30:33]
	v_mfma_f32_16x16x32_bf16 v[58:61], v[178:181], v[204:207], v[58:61]
	v_mfma_f32_16x16x32_bf16 v[26:29], v[188:191], v[204:207], v[26:29]
	v_mfma_f32_16x16x32_bf16 v[54:57], v[178:181], v[212:215], v[54:57]
	v_mfma_f32_16x16x32_bf16 v[22:25], v[188:191], v[212:215], v[22:25]
	v_mfma_f32_16x16x32_bf16 v[50:53], v[178:181], v[220:223], v[50:53]
	v_mfma_f32_16x16x32_bf16 v[18:21], v[188:191], v[220:223], v[18:21]
	v_mfma_f32_16x16x32_bf16 v[62:65], v[182:185], v[200:203], v[62:65]
	v_mfma_f32_16x16x32_bf16 v[30:33], v[192:195], v[200:203], v[30:33]
	v_mfma_f32_16x16x32_bf16 v[58:61], v[182:185], v[208:211], v[58:61]
	v_mfma_f32_16x16x32_bf16 v[26:29], v[192:195], v[208:211], v[26:29]
	v_mfma_f32_16x16x32_bf16 v[54:57], v[182:185], v[216:219], v[54:57]
	v_mfma_f32_16x16x32_bf16 v[22:25], v[192:195], v[216:219], v[22:25]
	v_mfma_f32_16x16x32_bf16 v[50:53], v[182:185], v[224:227], v[50:53]
	v_mfma_f32_16x16x32_bf16 v[18:21], v[192:195], v[224:227], v[18:21]
	s_barrier
	s_add_i32 s21, s43, s26
	v_lshl_add_u64 v[228:229], s[0:1], 0, v[138:139]
	s_mov_b32 m0, s21
	ds_read_b128 v[196:199], v187 offset:16384
	ds_read_b128 v[200:203], v187 offset:17408
	ds_read_b128 v[204:207], v187 offset:18432
	ds_read_b128 v[208:211], v187 offset:19456
	ds_read_b128 v[212:215], v187 offset:20480
	ds_read_b128 v[216:219], v187 offset:21504
	ds_read_b128 v[220:223], v187 offset:22528
	ds_read_b128 v[224:227], v187 offset:23552
	global_load_lds_dwordx4 v[228:229], off
	s_add_i32 m0, s21, 0x2000
	s_add_u32 s28, s0, 0x80000
	v_lshl_add_u64 v[230:231], s[0:1], 0, v[140:141]
	s_addc_u32 s29, s1, 0
	s_add_i32 s21, s44, s26
	global_load_lds_dwordx4 v[230:231], off
	v_lshl_add_u64 v[232:233], s[28:29], 0, v[138:139]
	s_mov_b32 m0, s21
	v_lshl_add_u64 v[234:235], s[22:23], 0, v[140:141]
	global_load_lds_dwordx4 v[232:233], off
	v_lshl_add_u64 v[232:233], s[28:29], 0, v[140:141]
	s_add_i32 m0, s21, 0x2000
	s_nop 0
	global_load_lds_dwordx4 v[232:233], off
	v_lshl_add_u64 v[232:233], s[22:23], 0, v[138:139]
	s_mov_b32 m0, s27
	s_nop 0
	global_load_lds_dwordx4 v[232:233], off
	s_mov_b32 m0, s30
	s_nop 0
	global_load_lds_dwordx4 v[234:235], off
	s_waitcnt vmcnt(8)
	s_waitcnt lgkmcnt(0)
	s_barrier
	s_waitcnt lgkmcnt(0)
	v_mfma_f32_16x16x32_bf16 v[114:117], v[106:109], v[196:199], v[114:117]
	v_mfma_f32_16x16x32_bf16 v[78:81], v[170:173], v[196:199], v[78:81]
	v_mfma_f32_16x16x32_bf16 v[110:113], v[106:109], v[204:207], v[110:113]
	v_mfma_f32_16x16x32_bf16 v[74:77], v[170:173], v[204:207], v[74:77]
	v_mfma_f32_16x16x32_bf16 v[102:105], v[106:109], v[212:215], v[102:105]
	v_mfma_f32_16x16x32_bf16 v[70:73], v[170:173], v[212:215], v[70:73]
	v_mfma_f32_16x16x32_bf16 v[98:101], v[106:109], v[220:223], v[98:101]
	v_mfma_f32_16x16x32_bf16 v[66:69], v[170:173], v[220:223], v[66:69]
	v_mfma_f32_16x16x32_bf16 v[114:117], v[134:137], v[200:203], v[114:117]
	v_mfma_f32_16x16x32_bf16 v[78:81], v[174:177], v[200:203], v[78:81]
	v_mfma_f32_16x16x32_bf16 v[110:113], v[134:137], v[208:211], v[110:113]
	v_mfma_f32_16x16x32_bf16 v[74:77], v[174:177], v[208:211], v[74:77]
	v_mfma_f32_16x16x32_bf16 v[102:105], v[134:137], v[216:219], v[102:105]
	v_mfma_f32_16x16x32_bf16 v[70:73], v[174:177], v[216:219], v[70:73]
	v_mfma_f32_16x16x32_bf16 v[98:101], v[134:137], v[224:227], v[98:101]
	v_mfma_f32_16x16x32_bf16 v[66:69], v[174:177], v[224:227], v[66:69]
	v_mfma_f32_16x16x32_bf16 v[46:49], v[178:181], v[196:199], v[46:49]
	v_mfma_f32_16x16x32_bf16 v[14:17], v[188:191], v[196:199], v[14:17]
	v_mfma_f32_16x16x32_bf16 v[42:45], v[178:181], v[204:207], v[42:45]
	v_mfma_f32_16x16x32_bf16 v[10:13], v[188:191], v[204:207], v[10:13]
	v_mfma_f32_16x16x32_bf16 v[38:41], v[178:181], v[212:215], v[38:41]
	v_mfma_f32_16x16x32_bf16 v[6:9], v[188:191], v[212:215], v[6:9]
	v_mfma_f32_16x16x32_bf16 v[34:37], v[178:181], v[220:223], v[34:37]
	v_mfma_f32_16x16x32_bf16 v[2:5], v[188:191], v[220:223], v[2:5]
	v_mfma_f32_16x16x32_bf16 v[46:49], v[182:185], v[200:203], v[46:49]
	v_mfma_f32_16x16x32_bf16 v[14:17], v[192:195], v[200:203], v[14:17]
	v_mfma_f32_16x16x32_bf16 v[42:45], v[182:185], v[208:211], v[42:45]
	v_mfma_f32_16x16x32_bf16 v[10:13], v[192:195], v[208:211], v[10:13]
	v_mfma_f32_16x16x32_bf16 v[38:41], v[182:185], v[216:219], v[38:41]
	v_mfma_f32_16x16x32_bf16 v[6:9], v[192:195], v[216:219], v[6:9]
	v_mfma_f32_16x16x32_bf16 v[34:37], v[182:185], v[224:227], v[34:37]
	v_mfma_f32_16x16x32_bf16 v[2:5], v[192:195], v[224:227], v[2:5]
	s_barrier
	s_add_i32 s21, 0, 0x18000
	s_add_i32 s28, 0, 0x1c000
	v_add_u32_e32 v174, s21, v1
	v_add_u32_e32 v192, s28, v1
	ds_read_b128 v[106:109], v174
	ds_read_b128 v[134:137], v174 offset:1024
	ds_read_b128 v[170:173], v174 offset:2048
	ds_read_b128 v[174:177], v174 offset:3072
	ds_read_b128 v[178:181], v192
	ds_read_b128 v[182:185], v192 offset:1024
	ds_read_b128 v[188:191], v192 offset:2048
	ds_read_b128 v[192:195], v192 offset:3072
	s_add_u32 s22, s22, 0x80000
	s_addc_u32 s23, s23, 0
	s_mov_b32 m0, s31
	v_lshl_add_u64 v[236:237], s[22:23], 0, v[138:139]
	ds_read_b128 v[196:199], v187 offset:32768
	ds_read_b128 v[200:203], v187 offset:33792
	ds_read_b128 v[204:207], v187 offset:34816
	ds_read_b128 v[208:211], v187 offset:35840
	ds_read_b128 v[212:215], v187 offset:36864
	ds_read_b128 v[216:219], v187 offset:37888
	ds_read_b128 v[220:223], v187 offset:38912
	ds_read_b128 v[224:227], v187 offset:39936
	global_load_lds_dwordx4 v[236:237], off
	v_lshl_add_u64 v[236:237], s[22:23], 0, v[140:141]
	s_mov_b32 m0, s33
	s_nop 0
	global_load_lds_dwordx4 v[236:237], off
	s_waitcnt vmcnt(8)
	s_waitcnt lgkmcnt(0)
	s_barrier
	s_waitcnt lgkmcnt(0)
	v_mfma_f32_16x16x32_bf16 v[130:133], v[106:109], v[196:199], v[130:133]
	v_mfma_f32_16x16x32_bf16 v[94:97], v[170:173], v[196:199], v[94:97]
	v_mfma_f32_16x16x32_bf16 v[126:129], v[106:109], v[204:207], v[126:129]
	v_mfma_f32_16x16x32_bf16 v[90:93], v[170:173], v[204:207], v[90:93]
	v_mfma_f32_16x16x32_bf16 v[122:125], v[106:109], v[212:215], v[122:125]
	v_mfma_f32_16x16x32_bf16 v[86:89], v[170:173], v[212:215], v[86:89]
	v_mfma_f32_16x16x32_bf16 v[118:121], v[106:109], v[220:223], v[118:121]
	v_mfma_f32_16x16x32_bf16 v[82:85], v[170:173], v[220:223], v[82:85]
	v_mfma_f32_16x16x32_bf16 v[130:133], v[134:137], v[200:203], v[130:133]
	v_mfma_f32_16x16x32_bf16 v[94:97], v[174:177], v[200:203], v[94:97]
	v_mfma_f32_16x16x32_bf16 v[126:129], v[134:137], v[208:211], v[126:129]
	v_mfma_f32_16x16x32_bf16 v[90:93], v[174:177], v[208:211], v[90:93]
	v_mfma_f32_16x16x32_bf16 v[122:125], v[134:137], v[216:219], v[122:125]
	v_mfma_f32_16x16x32_bf16 v[86:89], v[174:177], v[216:219], v[86:89]
	v_mfma_f32_16x16x32_bf16 v[118:121], v[134:137], v[224:227], v[118:121]
	v_mfma_f32_16x16x32_bf16 v[82:85], v[174:177], v[224:227], v[82:85]
	v_mfma_f32_16x16x32_bf16 v[62:65], v[178:181], v[196:199], v[62:65]
	v_mfma_f32_16x16x32_bf16 v[30:33], v[188:191], v[196:199], v[30:33]
	v_mfma_f32_16x16x32_bf16 v[58:61], v[178:181], v[204:207], v[58:61]
	v_mfma_f32_16x16x32_bf16 v[26:29], v[188:191], v[204:207], v[26:29]
	v_mfma_f32_16x16x32_bf16 v[54:57], v[178:181], v[212:215], v[54:57]
	v_mfma_f32_16x16x32_bf16 v[22:25], v[188:191], v[212:215], v[22:25]
	v_mfma_f32_16x16x32_bf16 v[50:53], v[178:181], v[220:223], v[50:53]
	v_mfma_f32_16x16x32_bf16 v[18:21], v[188:191], v[220:223], v[18:21]
	v_mfma_f32_16x16x32_bf16 v[62:65], v[182:185], v[200:203], v[62:65]
	v_mfma_f32_16x16x32_bf16 v[30:33], v[192:195], v[200:203], v[30:33]
	v_mfma_f32_16x16x32_bf16 v[58:61], v[182:185], v[208:211], v[58:61]
	v_mfma_f32_16x16x32_bf16 v[26:29], v[192:195], v[208:211], v[26:29]
	v_mfma_f32_16x16x32_bf16 v[54:57], v[182:185], v[216:219], v[54:57]
	v_mfma_f32_16x16x32_bf16 v[22:25], v[192:195], v[216:219], v[22:25]
	v_mfma_f32_16x16x32_bf16 v[50:53], v[182:185], v[224:227], v[50:53]
	v_mfma_f32_16x16x32_bf16 v[18:21], v[192:195], v[224:227], v[18:21]
	s_barrier
	s_add_i32 s21, s21, s26
	v_lshl_add_u64 v[228:229], v[228:229], 0, s[8:9]
	s_mov_b32 m0, s21
	ds_read_b128 v[196:199], v187 offset:49152
	ds_read_b128 v[200:203], v187 offset:50176
	ds_read_b128 v[204:207], v187 offset:51200
	ds_read_b128 v[208:211], v187 offset:52224
	ds_read_b128 v[212:215], v187 offset:53248
	ds_read_b128 v[216:219], v187 offset:54272
	ds_read_b128 v[220:223], v187 offset:55296
	ds_read_b128 v[224:227], v187 offset:56320
	global_load_lds_dwordx4 v[228:229], off
	s_add_i32 m0, s21, 0x2000
	s_add_u32 s0, s0, 0x80080
	v_lshl_add_u64 v[228:229], v[230:231], 0, s[8:9]
	s_addc_u32 s1, s1, 0
	s_add_i32 s21, s28, s26
	global_load_lds_dwordx4 v[228:229], off
	v_lshl_add_u64 v[228:229], s[0:1], 0, v[138:139]
	s_mov_b32 m0, s21
	s_nop 0
	global_load_lds_dwordx4 v[228:229], off
	v_lshl_add_u64 v[228:229], s[0:1], 0, v[140:141]
	s_add_i32 m0, s21, 0x2000
	s_nop 0
	global_load_lds_dwordx4 v[228:229], off
	v_lshl_add_u64 v[228:229], v[232:233], 0, s[8:9]
	s_mov_b32 m0, s40
	s_nop 0
	global_load_lds_dwordx4 v[228:229], off
	v_lshl_add_u64 v[228:229], v[234:235], 0, s[8:9]
	s_mov_b32 m0, s41
	s_nop 0
	global_load_lds_dwordx4 v[228:229], off
	s_waitcnt vmcnt(8)
	s_waitcnt lgkmcnt(0)
	s_barrier
	s_waitcnt lgkmcnt(0)
	v_mfma_f32_16x16x32_bf16 v[114:117], v[106:109], v[196:199], v[114:117]
	v_mfma_f32_16x16x32_bf16 v[78:81], v[170:173], v[196:199], v[78:81]
	v_mfma_f32_16x16x32_bf16 v[110:113], v[106:109], v[204:207], v[110:113]
	v_mfma_f32_16x16x32_bf16 v[74:77], v[170:173], v[204:207], v[74:77]
	v_mfma_f32_16x16x32_bf16 v[102:105], v[106:109], v[212:215], v[102:105]
	v_mfma_f32_16x16x32_bf16 v[70:73], v[170:173], v[212:215], v[70:73]
	v_mfma_f32_16x16x32_bf16 v[98:101], v[106:109], v[220:223], v[98:101]
	v_mfma_f32_16x16x32_bf16 v[66:69], v[170:173], v[220:223], v[66:69]
	v_mfma_f32_16x16x32_bf16 v[114:117], v[134:137], v[200:203], v[114:117]
	v_mfma_f32_16x16x32_bf16 v[78:81], v[174:177], v[200:203], v[78:81]
	v_mfma_f32_16x16x32_bf16 v[110:113], v[134:137], v[208:211], v[110:113]
	v_mfma_f32_16x16x32_bf16 v[74:77], v[174:177], v[208:211], v[74:77]
	v_mfma_f32_16x16x32_bf16 v[102:105], v[134:137], v[216:219], v[102:105]
	v_mfma_f32_16x16x32_bf16 v[70:73], v[174:177], v[216:219], v[70:73]
	v_mfma_f32_16x16x32_bf16 v[98:101], v[134:137], v[224:227], v[98:101]
	v_mfma_f32_16x16x32_bf16 v[66:69], v[174:177], v[224:227], v[66:69]
	v_mfma_f32_16x16x32_bf16 v[46:49], v[178:181], v[196:199], v[46:49]
	v_mfma_f32_16x16x32_bf16 v[14:17], v[188:191], v[196:199], v[14:17]
	v_mfma_f32_16x16x32_bf16 v[42:45], v[178:181], v[204:207], v[42:45]
	v_mfma_f32_16x16x32_bf16 v[10:13], v[188:191], v[204:207], v[10:13]
	v_mfma_f32_16x16x32_bf16 v[38:41], v[178:181], v[212:215], v[38:41]
	v_mfma_f32_16x16x32_bf16 v[6:9], v[188:191], v[212:215], v[6:9]
	v_mfma_f32_16x16x32_bf16 v[34:37], v[178:181], v[220:223], v[34:37]
	v_mfma_f32_16x16x32_bf16 v[2:5], v[188:191], v[220:223], v[2:5]
	v_mfma_f32_16x16x32_bf16 v[46:49], v[182:185], v[200:203], v[46:49]
	v_mfma_f32_16x16x32_bf16 v[14:17], v[192:195], v[200:203], v[14:17]
	v_mfma_f32_16x16x32_bf16 v[42:45], v[182:185], v[208:211], v[42:45]
	v_mfma_f32_16x16x32_bf16 v[10:13], v[192:195], v[208:211], v[10:13]
	v_mfma_f32_16x16x32_bf16 v[38:41], v[182:185], v[216:219], v[38:41]
	v_mfma_f32_16x16x32_bf16 v[6:9], v[192:195], v[216:219], v[6:9]
	v_mfma_f32_16x16x32_bf16 v[34:37], v[182:185], v[224:227], v[34:37]
	v_mfma_f32_16x16x32_bf16 v[2:5], v[192:195], v[224:227], v[2:5]
	s_barrier
	s_add_i32 s55, s55, 2
	s_add_u32 s38, s38, 0x100
	s_addc_u32 s39, s39, 0
	s_add_u32 s53, s53, 0x100
	s_addc_u32 s54, s54, 0
	s_cmp_gt_u32 s55, 29
	s_cbranch_scc0 .LBB0_2594
	s_and_b64 vcc, exec, s[10:11]
	s_cbranch_vccz .LBB0_2597
	s_barrier

.LBB0_2655:
	s_setprio 0
	v_readlane_b32 s0, v243, 51
	v_readlane_b32 s1, v243, 52
	s_cmp_lt_i32 s0, 32
	s_cselect_b64 s[0:1], -1, 0
	s_and_b64 s[2:3], s[0:1], s[2:3]
	s_andn2_b64 vcc, exec, s[2:3]
	s_cbranch_vccnz .LBB0_2659
	v_readlane_b32 s2, v243, 0
	s_lshl_b32 s2, s2, 3
	v_readlane_b32 s3, v243, 59
	s_add_i32 s4, s3, s2
	s_cmp_gt_i32 s4, 0x81ff
	s_cbranch_scc1 .LBB0_2659
	v_mbcnt_lo_u32_b32 v1, -1, 0
	v_mbcnt_hi_u32_b32 v2, -1, v1
	v_and_b32_e32 v1, 64, v2
	v_add_u32_e32 v3, 64, v1
	v_xor_b32_e32 v1, 1, v2
	v_cmp_lt_i32_e32 vcc, v1, v3
	v_xor_b32_e32 v4, 2, v2
	v_readlane_b32 s8, v243, 1
	v_cndmask_b32_e32 v1, v2, v1, vcc
	v_cmp_lt_i32_e32 vcc, v4, v3
	v_readlane_b32 s2, v243, 53
	v_readlane_b32 s12, v243, 5
	v_cndmask_b32_e32 v4, v2, v4, vcc
	v_lshlrev_b32_e32 v150, 2, v4
	v_xor_b32_e32 v4, 4, v2
	v_cmp_lt_i32_e32 vcc, v4, v3
	v_readlane_b32 s13, v243, 6
	v_readlane_b32 s20, v243, 13
	v_cndmask_b32_e32 v4, v2, v4, vcc
	v_lshlrev_b32_e32 v151, 2, v4
	v_xor_b32_e32 v4, 8, v2
	v_cmp_lt_i32_e32 vcc, v4, v3
	v_readlane_b32 s21, v243, 14
	s_lshl_b32 s6, s2, 3
	v_cndmask_b32_e32 v4, v2, v4, vcc
	v_lshlrev_b32_e32 v152, 2, v4
	v_xor_b32_e32 v4, 16, v2
	v_cmp_lt_i32_e32 vcc, v4, v3
	s_mov_b64 s[12:13], s[20:21]
	s_add_u32 s2, s12, 0xa000
	v_cndmask_b32_e32 v4, v2, v4, vcc
	v_lshlrev_b32_e32 v153, 2, v4
	v_xor_b32_e32 v4, 32, v2
	v_cmp_lt_i32_e32 vcc, v4, v3
	s_addc_u32 s3, s13, 0
	v_mov_b32_e32 v131, 0
	v_cndmask_b32_e32 v2, v2, v4, vcc
	v_lshlrev_b32_e32 v154, 2, v2
	v_lshlrev_b32_e32 v2, 2, v166
	v_lshlrev_b32_e32 v130, 4, v166
	v_or_b32_e32 v4, 0x100, v2
	v_lshl_add_u64 v[132:133], s[2:3], 0, v[130:131]
	v_lshlrev_b32_e32 v130, 2, v4
	v_or_b32_e32 v6, 0x200, v2
	v_lshl_add_u64 v[134:135], s[2:3], 0, v[130:131]
	v_lshlrev_b32_e32 v130, 2, v6
	v_or_b32_e32 v8, 0x300, v2
	v_lshl_add_u64 v[136:137], s[2:3], 0, v[130:131]
	v_lshlrev_b32_e32 v130, 2, v8
	v_or_b32_e32 v10, 0x400, v2
	v_lshl_add_u64 v[138:139], s[2:3], 0, v[130:131]
	v_lshlrev_b32_e32 v130, 2, v10
	v_or_b32_e32 v12, 0x500, v2
	v_readlane_b32 s10, v243, 3
	v_lshl_add_u64 v[140:141], s[2:3], 0, v[130:131]
	v_lshlrev_b32_e32 v130, 2, v12
	v_or_b32_e32 v14, 0x600, v2
	v_readlane_b32 s11, v243, 4
	s_add_u32 s10, s90, 0x10c000
	v_lshl_add_u64 v[142:143], s[2:3], 0, v[130:131]
	v_lshlrev_b32_e32 v130, 2, v14
	v_or_b32_e32 v16, 0x700, v2
	s_addc_u32 s11, s91, 0
	v_lshl_add_u64 v[144:145], s[2:3], 0, v[130:131]
	v_lshlrev_b32_e32 v130, 2, v16
	s_ashr_i32 s5, s4, 31
	v_lshl_add_u64 v[146:147], s[2:3], 0, v[130:131]
	s_lshl_b64 s[2:3], s[4:5], 12
	s_add_u32 s2, s90, s2
	v_lshlrev_b32_e32 v130, 3, v166
	s_addc_u32 s3, s91, s3
	v_readlane_b32 s9, v243, 2
	v_readlane_b32 s14, v243, 7
	v_readlane_b32 s15, v243, 8
	v_readlane_b32 s16, v243, 9
	s_waitcnt vmcnt(0)
	v_lshl_add_u64 v[18:19], s[2:3], 0, v[130:131]
	s_mov_b64 s[2:3], 0xd900000
	s_ashr_i32 s7, s6, 31
	v_readlane_b32 s20, v242, 19
	v_lshlrev_b32_e32 v1, 2, v1
	v_lshl_add_u64 v[148:149], v[18:19], 0, s[2:3]
	s_lshl_b64 s[8:9], s[6:7], 12
	s_mov_b32 s12, 0x12000
	v_lshlrev_b32_e32 v130, 4, v166
	s_movk_i32 s13, 0x1000
	v_lshlrev_b32_e32 v155, 2, v2
	v_lshlrev_b32_e32 v156, 2, v4
	v_lshlrev_b32_e32 v157, 2, v6
	v_lshlrev_b32_e32 v158, 2, v8
	v_lshlrev_b32_e32 v159, 2, v10
	v_lshlrev_b32_e32 v160, 2, v12
	v_lshlrev_b32_e32 v161, 2, v14
	v_lshlrev_b32_e32 v162, 2, v16
	v_mov_b32_e32 v163, 0x358637bd
	s_mov_b32 s14, 0xf800000
	v_mov_b32_e32 v165, 0x260
	s_movk_i32 s15, 0x7fff
	s_mov_b32 s16, 0xffff0000
	v_readlane_b32 s21, v242, 20
	v_readlane_b32 s17, v243, 10
	v_readlane_b32 s18, v243, 11
	v_readlane_b32 s19, v243, 12
	v_readlane_b32 s22, v243, 15
	v_readlane_b32 s23, v243, 16

.LBB0_2713:
	s_setprio 0
	v_readlane_b32 s0, v243, 51
	s_cmp_lt_i32 s0, 33
	v_readlane_b32 s1, v243, 52
	s_cselect_b64 s[4:5], -1, 0
	s_and_b64 s[0:1], s[4:5], s[2:3]
	s_andn2_b64 vcc, exec, s[0:1]
	s_cbranch_vccnz .LBB0_2730
	v_readlane_b32 s0, v243, 0
	s_cmpk_gt_i32 s0, 0x15ff
	v_readfirstlane_b32 s3, v0
	s_cbranch_scc1 .LBB0_2730
	v_lshrrev_b32_e32 v1, 5, v0
	v_lshrrev_b32_e32 v3, 1, v0
	v_and_b32_e32 v1, 4, v1
	v_bfe_u32 v2, v0, 2, 2
	v_and_b32_e32 v13, 24, v3
	v_or3_b32 v1, v1, v2, v13
	v_lshlrev_b32_e32 v2, 4, v0
	v_or_b32_e32 v10, 0x2000, v2
	s_add_u32 s20, s90, 0x3900000
	v_lshrrev_b32_e32 v3, 7, v10
	s_movk_i32 s0, 0x60
	v_readlane_b32 s2, v243, 0
	s_addc_u32 s24, s91, 0
	v_and_or_b32 v4, v3, s0, v1
	v_bfe_u32 v14, v0, 2, 4
	s_movk_i32 s0, 0x70
	s_ashr_i32 s26, s2, 31
	v_and_or_b32 v3, v3, s0, v14
	s_lshr_b32 s0, s26, 29
	s_add_i32 s0, s2, s0
	s_lshr_b32 s8, s3, 6
	s_ashr_i32 s1, s0, 3
	s_and_b32 s0, s0, -8
	s_lshr_b32 s10, s3, 8
	s_lshl_b32 s25, s8, 10
	s_sub_i32 s0, s2, s0
	s_cmp_lt_i32 s0, 0
	s_movk_i32 s27, 0x2c1
	s_cselect_b32 s2, s27, 0x2c0
	s_mul_i32 s0, s2, s0
	s_add_i32 s0, s0, s1
	s_mul_hi_i32 s1, s0, 0x2e8ba2e9
	s_lshr_b32 s2, s1, 31
	s_ashr_i32 s1, s1, 6
	s_add_i32 s1, s1, s2
	s_lshl_b32 s6, s1, 3
	s_mulk_i32 s1, 0x160
	s_sub_i32 s0, s0, s1
	s_sext_i32_i16 s1, s0
	s_bfe_u32 s1, s1, 0x3001c
	s_add_i32 s1, s0, s1
	s_sext_i32_i16 s2, s1
	s_and_b32 s1, s1, 0xfff8
	s_sub_i32 s0, s0, s1
	s_sext_i32_i16 s0, s0
	v_and_b32_e32 v5, 32, v0
	s_lshr_b32 s2, s2, 3
	s_add_i32 s36, s6, s0
	v_bitop3_b32 v11, v2, v5, 48 bitop3:0x6c
	v_and_b32_e32 v12, 64, v0
	s_ashr_i32 s37, s36, 31
	s_bfe_i64 s[0:1], s[2:3], 0x100000
	v_or_b32_e32 v2, v11, v12
	s_lshl_b64 s[6:7], s[36:37], 20
	s_lshl_b64 s[0:1], s[0:1], 20
	v_lshl_or_b32 v132, v3, 12, v2
	v_lshrrev_b32_e32 v3, 3, v0
	s_add_u32 s0, s20, s0
	v_and_or_b32 v1, v3, 32, v1
	s_addc_u32 s1, s24, s1
	s_add_i32 s30, s25, 0
	v_lshl_or_b32 v134, v1, 12, v2
	s_add_i32 m0, s30, 0x10000
	v_lshl_or_b32 v130, v4, 12, v2
	global_load_lds_dwordx4 v134, s[0:1]
	s_add_i32 m0, s30, 0x12000
	s_add_u32 s12, s0, 0x80000
	global_load_lds_dwordx4 v130, s[0:1]
	s_addc_u32 s13, s1, 0
	s_add_i32 m0, s30, 0x14000
	v_and_or_b32 v1, v3, 48, v14
	global_load_lds_dwordx4 v134, s[12:13]
	s_add_i32 m0, s30, 0x16000
	v_lshl_or_b32 v136, v1, 12, v2
	global_load_lds_dwordx4 v130, s[12:13]
	v_readlane_b32 s12, v242, 15
	v_readlane_b32 s13, v242, 16
	s_add_u32 s22, s12, s6
	s_addc_u32 s23, s13, s7
	s_add_i32 s31, s30, 0x2000
	s_mov_b32 m0, s30
	s_add_u32 s6, s22, 0x80000
	global_load_lds_dwordx4 v136, s[22:23]
	s_mov_b32 m0, s31
	s_addc_u32 s7, s23, 0
	s_add_i32 s33, s30, 0x4000
	global_load_lds_dwordx4 v132, s[22:23]
	s_mov_b32 m0, s33
	s_add_i32 s34, s30, 0x6000
	global_load_lds_dwordx4 v136, s[6:7]
	s_mov_b32 m0, s34
	v_mov_b32_e32 v135, 0
	global_load_lds_dwordx4 v132, s[6:7]
	v_mov_b32_e32 v131, v135
	v_mov_b32_e32 v137, v135
	v_mov_b32_e32 v133, v135
	s_cmp_eq_u32 s10, 1
	s_mov_b32 s35, 0
	v_lshl_add_u64 v[8:9], s[0:1], 0, v[134:135]
	v_lshl_add_u64 v[6:7], s[0:1], 0, v[130:131]
	v_lshl_add_u64 v[2:3], s[22:23], 0, v[136:137]
	s_cselect_b64 s[6:7], -1, 0
	s_cmp_lg_u32 s10, 1
	v_lshl_add_u64 v[4:5], s[22:23], 0, v[132:133]
	s_cbranch_scc1 .LBB0_2717
	s_barrier
	s_setprio 1

.LBB0_2723:
	ds_read_b128 v[146:149], v152
	ds_read_b128 v[156:159], v152 offset:1024
	ds_read_b128 v[160:163], v152 offset:2048
	ds_read_b128 v[166:169], v152 offset:3072
	ds_read_b128 v[170:173], v153
	ds_read_b128 v[174:177], v153 offset:1024
	ds_read_b128 v[178:181], v153 offset:2048
	ds_read_b128 v[182:185], v153 offset:3072
	s_add_u32 s0, s38, 0xfff80080
	s_addc_u32 s1, s39, -1
	s_cmp_eq_u32 s54, 28
	s_cselect_b32 s23, s15, s1
	s_cselect_b32 s22, s46, s0
	s_cselect_b32 s1, s13, s53
	s_cselect_b32 s0, s47, s52
	v_lshl_add_u64 v[218:219], s[38:39], 0, v[138:139]
	s_add_i32 m0, s30, 0xc000
	ds_read_b128 v[186:189], v154
	ds_read_b128 v[190:193], v154 offset:1024
	ds_read_b128 v[194:197], v154 offset:2048
	ds_read_b128 v[198:201], v154 offset:3072
	ds_read_b128 v[202:205], v154 offset:4096
	ds_read_b128 v[206:209], v154 offset:5120
	ds_read_b128 v[210:213], v154 offset:6144
	ds_read_b128 v[214:217], v154 offset:7168
	global_load_lds_dwordx4 v[218:219], off
	v_lshl_add_u64 v[218:219], s[38:39], 0, v[140:141]
	s_add_i32 m0, s30, 0xe000
	s_nop 0
	global_load_lds_dwordx4 v[218:219], off
	s_waitcnt vmcnt(8)
	s_waitcnt lgkmcnt(0)
	s_barrier
	s_waitcnt lgkmcnt(0)
	v_mfma_f32_16x16x32_bf16 v[126:129], v[146:149], v[186:189], v[126:129]
	v_mfma_f32_16x16x32_bf16 v[118:121], v[160:163], v[186:189], v[118:121]
	v_mfma_f32_16x16x32_bf16 v[110:113], v[146:149], v[194:197], v[110:113]
	v_mfma_f32_16x16x32_bf16 v[102:105], v[160:163], v[194:197], v[102:105]
	v_mfma_f32_16x16x32_bf16 v[94:97], v[146:149], v[202:205], v[94:97]
	v_mfma_f32_16x16x32_bf16 v[86:89], v[160:163], v[202:205], v[86:89]
	v_mfma_f32_16x16x32_bf16 v[78:81], v[146:149], v[210:213], v[78:81]
	v_mfma_f32_16x16x32_bf16 v[70:73], v[160:163], v[210:213], v[70:73]
	v_mfma_f32_16x16x32_bf16 v[126:129], v[156:159], v[190:193], v[126:129]
	v_mfma_f32_16x16x32_bf16 v[118:121], v[166:169], v[190:193], v[118:121]
	v_mfma_f32_16x16x32_bf16 v[110:113], v[156:159], v[198:201], v[110:113]
	v_mfma_f32_16x16x32_bf16 v[102:105], v[166:169], v[198:201], v[102:105]
	v_mfma_f32_16x16x32_bf16 v[94:97], v[156:159], v[206:209], v[94:97]
	v_mfma_f32_16x16x32_bf16 v[86:89], v[166:169], v[206:209], v[86:89]
	v_mfma_f32_16x16x32_bf16 v[78:81], v[156:159], v[214:217], v[78:81]
	v_mfma_f32_16x16x32_bf16 v[70:73], v[166:169], v[214:217], v[70:73]
	v_mfma_f32_16x16x32_bf16 v[122:125], v[170:173], v[186:189], v[122:125]
	v_mfma_f32_16x16x32_bf16 v[114:117], v[178:181], v[186:189], v[114:117]
	v_mfma_f32_16x16x32_bf16 v[106:109], v[170:173], v[194:197], v[106:109]
	v_mfma_f32_16x16x32_bf16 v[98:101], v[178:181], v[194:197], v[98:101]
	v_mfma_f32_16x16x32_bf16 v[90:93], v[170:173], v[202:205], v[90:93]
	v_mfma_f32_16x16x32_bf16 v[82:85], v[178:181], v[202:205], v[82:85]
	v_mfma_f32_16x16x32_bf16 v[74:77], v[170:173], v[210:213], v[74:77]
	v_mfma_f32_16x16x32_bf16 v[66:69], v[178:181], v[210:213], v[66:69]
	v_mfma_f32_16x16x32_bf16 v[122:125], v[174:177], v[190:193], v[122:125]
	v_mfma_f32_16x16x32_bf16 v[114:117], v[182:185], v[190:193], v[114:117]
	v_mfma_f32_16x16x32_bf16 v[106:109], v[174:177], v[198:201], v[106:109]
	v_mfma_f32_16x16x32_bf16 v[98:101], v[182:185], v[198:201], v[98:101]
	v_mfma_f32_16x16x32_bf16 v[90:93], v[174:177], v[206:209], v[90:93]
	v_mfma_f32_16x16x32_bf16 v[82:85], v[182:185], v[206:209], v[82:85]
	v_mfma_f32_16x16x32_bf16 v[74:77], v[174:177], v[214:217], v[74:77]
	v_mfma_f32_16x16x32_bf16 v[66:69], v[182:185], v[214:217], v[66:69]
	s_barrier
	s_add_i32 s21, s42, s25
	v_lshl_add_u64 v[218:219], s[0:1], 0, v[134:135]
	s_mov_b32 m0, s21
	ds_read_b128 v[186:189], v154 offset:16384
	ds_read_b128 v[190:193], v154 offset:17408
	ds_read_b128 v[194:197], v154 offset:18432
	ds_read_b128 v[198:201], v154 offset:19456
	ds_read_b128 v[202:205], v154 offset:20480
	ds_read_b128 v[206:209], v154 offset:21504
	ds_read_b128 v[210:213], v154 offset:22528
	ds_read_b128 v[214:217], v154 offset:23552
	global_load_lds_dwordx4 v[218:219], off
	s_add_i32 m0, s21, 0x2000
	s_add_u32 s28, s0, 0x80000
	v_lshl_add_u64 v[220:221], s[0:1], 0, v[130:131]
	s_addc_u32 s29, s1, 0
	s_add_i32 s21, s43, s25
	global_load_lds_dwordx4 v[220:221], off
	v_lshl_add_u64 v[222:223], s[28:29], 0, v[134:135]
	s_mov_b32 m0, s21
	v_lshl_add_u64 v[224:225], s[22:23], 0, v[132:133]
	global_load_lds_dwordx4 v[222:223], off
	v_lshl_add_u64 v[222:223], s[28:29], 0, v[130:131]
	s_add_i32 m0, s21, 0x2000
	s_nop 0
	global_load_lds_dwordx4 v[222:223], off
	v_lshl_add_u64 v[222:223], s[22:23], 0, v[136:137]
	s_mov_b32 m0, s30
	s_nop 0
	global_load_lds_dwordx4 v[222:223], off
	s_mov_b32 m0, s31
	s_nop 0
	global_load_lds_dwordx4 v[224:225], off
	s_waitcnt vmcnt(8)
	s_waitcnt lgkmcnt(0)
	s_barrier
	s_waitcnt lgkmcnt(0)
	v_mfma_f32_16x16x32_bf16 v[62:65], v[146:149], v[186:189], v[62:65]
	v_mfma_f32_16x16x32_bf16 v[54:57], v[160:163], v[186:189], v[54:57]
	v_mfma_f32_16x16x32_bf16 v[46:49], v[146:149], v[194:197], v[46:49]
	v_mfma_f32_16x16x32_bf16 v[38:41], v[160:163], v[194:197], v[38:41]
	v_mfma_f32_16x16x32_bf16 v[30:33], v[146:149], v[202:205], v[30:33]
	v_mfma_f32_16x16x32_bf16 v[22:25], v[160:163], v[202:205], v[22:25]
	v_mfma_f32_16x16x32_bf16 v[14:17], v[146:149], v[210:213], v[14:17]
	v_mfma_f32_16x16x32_bf16 v[6:9], v[160:163], v[210:213], v[6:9]
	v_mfma_f32_16x16x32_bf16 v[62:65], v[156:159], v[190:193], v[62:65]
	v_mfma_f32_16x16x32_bf16 v[54:57], v[166:169], v[190:193], v[54:57]
	v_mfma_f32_16x16x32_bf16 v[46:49], v[156:159], v[198:201], v[46:49]
	v_mfma_f32_16x16x32_bf16 v[38:41], v[166:169], v[198:201], v[38:41]
	v_mfma_f32_16x16x32_bf16 v[30:33], v[156:159], v[206:209], v[30:33]
	v_mfma_f32_16x16x32_bf16 v[22:25], v[166:169], v[206:209], v[22:25]
	v_mfma_f32_16x16x32_bf16 v[14:17], v[156:159], v[214:217], v[14:17]
	v_mfma_f32_16x16x32_bf16 v[6:9], v[166:169], v[214:217], v[6:9]
	v_mfma_f32_16x16x32_bf16 v[58:61], v[170:173], v[186:189], v[58:61]
	v_mfma_f32_16x16x32_bf16 v[50:53], v[178:181], v[186:189], v[50:53]
	v_mfma_f32_16x16x32_bf16 v[42:45], v[170:173], v[194:197], v[42:45]
	v_mfma_f32_16x16x32_bf16 v[34:37], v[178:181], v[194:197], v[34:37]
	v_mfma_f32_16x16x32_bf16 v[26:29], v[170:173], v[202:205], v[26:29]
	v_mfma_f32_16x16x32_bf16 v[18:21], v[178:181], v[202:205], v[18:21]
	v_mfma_f32_16x16x32_bf16 v[10:13], v[170:173], v[210:213], v[10:13]
	v_mfma_f32_16x16x32_bf16 v[2:5], v[178:181], v[210:213], v[2:5]
	v_mfma_f32_16x16x32_bf16 v[58:61], v[174:177], v[190:193], v[58:61]
	v_mfma_f32_16x16x32_bf16 v[50:53], v[182:185], v[190:193], v[50:53]
	v_mfma_f32_16x16x32_bf16 v[42:45], v[174:177], v[198:201], v[42:45]
	v_mfma_f32_16x16x32_bf16 v[34:37], v[182:185], v[198:201], v[34:37]
	v_mfma_f32_16x16x32_bf16 v[26:29], v[174:177], v[206:209], v[26:29]
	v_mfma_f32_16x16x32_bf16 v[18:21], v[182:185], v[206:209], v[18:21]
	v_mfma_f32_16x16x32_bf16 v[10:13], v[174:177], v[214:217], v[10:13]
	v_mfma_f32_16x16x32_bf16 v[2:5], v[182:185], v[214:217], v[2:5]
	s_barrier
	s_add_i32 s21, 0, 0x18000
	v_add_u32_e32 v155, s21, v150
	s_add_i32 s28, 0, 0x1c000
	ds_read_b128 v[146:149], v155
	ds_read_b128 v[156:159], v155 offset:1024
	ds_read_b128 v[160:163], v155 offset:2048
	ds_read_b128 v[166:169], v155 offset:3072
	v_add_u32_e32 v155, s28, v150
	ds_read_b128 v[170:173], v155
	ds_read_b128 v[174:177], v155 offset:1024
	ds_read_b128 v[178:181], v155 offset:2048
	ds_read_b128 v[182:185], v155 offset:3072
	s_add_u32 s22, s22, 0x80000
	s_addc_u32 s23, s23, 0
	s_mov_b32 m0, s33
	v_lshl_add_u64 v[226:227], s[22:23], 0, v[136:137]
	ds_read_b128 v[186:189], v154 offset:32768
	ds_read_b128 v[190:193], v154 offset:33792
	ds_read_b128 v[194:197], v154 offset:34816
	ds_read_b128 v[198:201], v154 offset:35840
	ds_read_b128 v[202:205], v154 offset:36864
	ds_read_b128 v[206:209], v154 offset:37888
	ds_read_b128 v[210:213], v154 offset:38912
	ds_read_b128 v[214:217], v154 offset:39936
	global_load_lds_dwordx4 v[226:227], off
	v_lshl_add_u64 v[226:227], s[22:23], 0, v[132:133]
	s_mov_b32 m0, s34
	s_nop 0
	global_load_lds_dwordx4 v[226:227], off
	s_waitcnt vmcnt(8)
	s_waitcnt lgkmcnt(0)
	s_barrier
	s_waitcnt lgkmcnt(0)
	v_mfma_f32_16x16x32_bf16 v[126:129], v[146:149], v[186:189], v[126:129]
	v_mfma_f32_16x16x32_bf16 v[118:121], v[160:163], v[186:189], v[118:121]
	v_mfma_f32_16x16x32_bf16 v[110:113], v[146:149], v[194:197], v[110:113]
	v_mfma_f32_16x16x32_bf16 v[102:105], v[160:163], v[194:197], v[102:105]
	v_mfma_f32_16x16x32_bf16 v[94:97], v[146:149], v[202:205], v[94:97]
	v_mfma_f32_16x16x32_bf16 v[86:89], v[160:163], v[202:205], v[86:89]
	v_mfma_f32_16x16x32_bf16 v[78:81], v[146:149], v[210:213], v[78:81]
	v_mfma_f32_16x16x32_bf16 v[70:73], v[160:163], v[210:213], v[70:73]
	v_mfma_f32_16x16x32_bf16 v[126:129], v[156:159], v[190:193], v[126:129]
	v_mfma_f32_16x16x32_bf16 v[118:121], v[166:169], v[190:193], v[118:121]
	v_mfma_f32_16x16x32_bf16 v[110:113], v[156:159], v[198:201], v[110:113]
	v_mfma_f32_16x16x32_bf16 v[102:105], v[166:169], v[198:201], v[102:105]
	v_mfma_f32_16x16x32_bf16 v[94:97], v[156:159], v[206:209], v[94:97]
	v_mfma_f32_16x16x32_bf16 v[86:89], v[166:169], v[206:209], v[86:89]
	v_mfma_f32_16x16x32_bf16 v[78:81], v[156:159], v[214:217], v[78:81]
	v_mfma_f32_16x16x32_bf16 v[70:73], v[166:169], v[214:217], v[70:73]
	v_mfma_f32_16x16x32_bf16 v[122:125], v[170:173], v[186:189], v[122:125]
	v_mfma_f32_16x16x32_bf16 v[114:117], v[178:181], v[186:189], v[114:117]
	v_mfma_f32_16x16x32_bf16 v[106:109], v[170:173], v[194:197], v[106:109]
	v_mfma_f32_16x16x32_bf16 v[98:101], v[178:181], v[194:197], v[98:101]
	v_mfma_f32_16x16x32_bf16 v[90:93], v[170:173], v[202:205], v[90:93]
	v_mfma_f32_16x16x32_bf16 v[82:85], v[178:181], v[202:205], v[82:85]
	v_mfma_f32_16x16x32_bf16 v[74:77], v[170:173], v[210:213], v[74:77]
	v_mfma_f32_16x16x32_bf16 v[66:69], v[178:181], v[210:213], v[66:69]
	v_mfma_f32_16x16x32_bf16 v[122:125], v[174:177], v[190:193], v[122:125]
	v_mfma_f32_16x16x32_bf16 v[114:117], v[182:185], v[190:193], v[114:117]
	v_mfma_f32_16x16x32_bf16 v[106:109], v[174:177], v[198:201], v[106:109]
	v_mfma_f32_16x16x32_bf16 v[98:101], v[182:185], v[198:201], v[98:101]
	v_mfma_f32_16x16x32_bf16 v[90:93], v[174:177], v[206:209], v[90:93]
	v_mfma_f32_16x16x32_bf16 v[82:85], v[182:185], v[206:209], v[82:85]
	v_mfma_f32_16x16x32_bf16 v[74:77], v[174:177], v[214:217], v[74:77]
	v_mfma_f32_16x16x32_bf16 v[66:69], v[182:185], v[214:217], v[66:69]
	s_barrier
	s_add_i32 s21, s21, s25
	v_lshl_add_u64 v[218:219], v[218:219], 0, s[8:9]
	s_mov_b32 m0, s21
	ds_read_b128 v[186:189], v154 offset:49152
	ds_read_b128 v[190:193], v154 offset:50176
	ds_read_b128 v[194:197], v154 offset:51200
	ds_read_b128 v[198:201], v154 offset:52224
	ds_read_b128 v[202:205], v154 offset:53248
	ds_read_b128 v[206:209], v154 offset:54272
	ds_read_b128 v[210:213], v154 offset:55296
	ds_read_b128 v[214:217], v154 offset:56320
	global_load_lds_dwordx4 v[218:219], off
	s_add_i32 m0, s21, 0x2000
	s_add_u32 s0, s0, 0x80080
	v_lshl_add_u64 v[218:219], v[220:221], 0, s[8:9]
	s_addc_u32 s1, s1, 0
	s_add_i32 s21, s28, s25
	global_load_lds_dwordx4 v[218:219], off
	v_lshl_add_u64 v[218:219], s[0:1], 0, v[134:135]
	s_mov_b32 m0, s21
	s_nop 0
	global_load_lds_dwordx4 v[218:219], off
	v_lshl_add_u64 v[218:219], s[0:1], 0, v[130:131]
	s_add_i32 m0, s21, 0x2000
	s_nop 0
	global_load_lds_dwordx4 v[218:219], off
	v_lshl_add_u64 v[218:219], v[222:223], 0, s[8:9]
	s_mov_b32 m0, s37
	s_nop 0
	global_load_lds_dwordx4 v[218:219], off
	v_lshl_add_u64 v[218:219], v[224:225], 0, s[8:9]
	s_mov_b32 m0, s40
	s_nop 0
	global_load_lds_dwordx4 v[218:219], off
	s_waitcnt vmcnt(8)
	s_waitcnt lgkmcnt(0)
	s_barrier
	s_waitcnt lgkmcnt(0)
	v_mfma_f32_16x16x32_bf16 v[62:65], v[146:149], v[186:189], v[62:65]
	v_mfma_f32_16x16x32_bf16 v[54:57], v[160:163], v[186:189], v[54:57]
	v_mfma_f32_16x16x32_bf16 v[46:49], v[146:149], v[194:197], v[46:49]
	v_mfma_f32_16x16x32_bf16 v[38:41], v[160:163], v[194:197], v[38:41]
	v_mfma_f32_16x16x32_bf16 v[30:33], v[146:149], v[202:205], v[30:33]
	v_mfma_f32_16x16x32_bf16 v[22:25], v[160:163], v[202:205], v[22:25]
	v_mfma_f32_16x16x32_bf16 v[14:17], v[146:149], v[210:213], v[14:17]
	v_mfma_f32_16x16x32_bf16 v[6:9], v[160:163], v[210:213], v[6:9]
	v_mfma_f32_16x16x32_bf16 v[62:65], v[156:159], v[190:193], v[62:65]
	v_mfma_f32_16x16x32_bf16 v[54:57], v[166:169], v[190:193], v[54:57]
	v_mfma_f32_16x16x32_bf16 v[46:49], v[156:159], v[198:201], v[46:49]
	v_mfma_f32_16x16x32_bf16 v[38:41], v[166:169], v[198:201], v[38:41]
	v_mfma_f32_16x16x32_bf16 v[30:33], v[156:159], v[206:209], v[30:33]
	v_mfma_f32_16x16x32_bf16 v[22:25], v[166:169], v[206:209], v[22:25]
	v_mfma_f32_16x16x32_bf16 v[14:17], v[156:159], v[214:217], v[14:17]
	v_mfma_f32_16x16x32_bf16 v[6:9], v[166:169], v[214:217], v[6:9]
	v_mfma_f32_16x16x32_bf16 v[58:61], v[170:173], v[186:189], v[58:61]
	v_mfma_f32_16x16x32_bf16 v[50:53], v[178:181], v[186:189], v[50:53]
	v_mfma_f32_16x16x32_bf16 v[42:45], v[170:173], v[194:197], v[42:45]
	v_mfma_f32_16x16x32_bf16 v[34:37], v[178:181], v[194:197], v[34:37]
	v_mfma_f32_16x16x32_bf16 v[26:29], v[170:173], v[202:205], v[26:29]
	v_mfma_f32_16x16x32_bf16 v[18:21], v[178:181], v[202:205], v[18:21]
	v_mfma_f32_16x16x32_bf16 v[10:13], v[170:173], v[210:213], v[10:13]
	v_mfma_f32_16x16x32_bf16 v[2:5], v[178:181], v[210:213], v[2:5]
	v_mfma_f32_16x16x32_bf16 v[58:61], v[174:177], v[190:193], v[58:61]
	v_mfma_f32_16x16x32_bf16 v[50:53], v[182:185], v[190:193], v[50:53]
	v_mfma_f32_16x16x32_bf16 v[42:45], v[174:177], v[198:201], v[42:45]
	v_mfma_f32_16x16x32_bf16 v[34:37], v[182:185], v[198:201], v[34:37]
	v_mfma_f32_16x16x32_bf16 v[26:29], v[174:177], v[206:209], v[26:29]
	v_mfma_f32_16x16x32_bf16 v[18:21], v[182:185], v[206:209], v[18:21]
	v_mfma_f32_16x16x32_bf16 v[10:13], v[174:177], v[214:217], v[10:13]
	v_mfma_f32_16x16x32_bf16 v[2:5], v[182:185], v[214:217], v[2:5]
	s_barrier
	s_add_i32 s54, s54, 2
	s_add_u32 s38, s38, 0x100
	s_addc_u32 s39, s39, 0
	s_add_u32 s52, s52, 0x100
	s_addc_u32 s53, s53, 0
	s_cmp_gt_u32 s54, 29
	s_cbranch_scc0 .LBB0_2723
	s_and_b64 vcc, exec, s[10:11]
	s_cbranch_vccz .LBB0_2726
	s_barrier

.LBB0_2784:
	s_setprio 0
	v_readlane_b32 s2, v243, 51
	s_cmp_lt_i32 s2, 34
	s_cselect_b64 s[4:5], -1, 0
	s_and_b64 s[0:1], s[4:5], s[0:1]
	s_andn2_b64 vcc, exec, s[0:1]
	v_readlane_b32 s3, v243, 52
	s_cbranch_vccnz .LBB0_2830
	v_readlane_b32 s6, v243, 53
	s_abs_i32 s0, s6
	v_cvt_f32_u32_e32 v1, s0
	v_readlane_b32 s8, v243, 0
	s_sub_i32 s1, s6, s8
	s_add_i32 s2, s1, 0x3ff
	v_rcp_iflag_f32_e32 v1, v1
	s_sub_i32 s1, 0xfffffc01, s1
	s_xor_b32 s6, s2, s6
	s_sub_i32 s3, 0, s0
	v_mul_f32_e32 v1, 0x4f7ffffe, v1
	v_cvt_u32_f32_e32 v1, v1
	s_max_i32 s1, s2, s1
	s_ashr_i32 s2, s6, 31
	v_readfirstlane_b32 s10, v0
	v_readfirstlane_b32 s6, v1
	s_mul_i32 s3, s3, s6
	s_mul_hi_u32 s3, s6, s3
	s_add_i32 s6, s6, s3
	s_mul_hi_u32 s3, s1, s6
	s_mul_i32 s6, s3, s0
	s_sub_i32 s1, s1, s6
	s_add_i32 s7, s3, 1
	s_sub_i32 s6, s1, s0
	s_cmp_ge_u32 s1, s0
	s_cselect_b32 s3, s7, s3
	s_cselect_b32 s1, s6, s1
	s_add_i32 s6, s3, 1
	s_cmp_ge_u32 s1, s0
	s_cselect_b32 s0, s6, s3
	s_xor_b32 s0, s0, s2
	s_sub_i32 s20, s0, s2
	s_cmp_lt_i32 s20, 1
	s_cbranch_scc1 .LBB0_2789
	s_mov_b64 s[0:1], 0
	s_cmpk_gt_i32 s8, 0x3ff
	s_mov_b64 s[2:3], 0
	s_cbranch_scc1 .LBB0_2790
	v_readlane_b32 s3, v243, 0
	s_ashr_i32 s2, s3, 31
	s_lshr_b32 s2, s2, 29
	s_add_i32 s8, s3, s2
	s_and_b32 s2, s8, -8
	s_sub_i32 s6, s3, s2
	s_cmp_gt_i32 s6, -1
	s_cbranch_scc0 .LBB0_2794
	s_lshl_b32 s7, s6, 7
	s_ashr_i32 s2, s8, 3
	s_cbranch_execz .LBB0_2795
	s_branch .LBB0_2796

.LBB0_2797:
	s_andn2_b64 vcc, exec, s[2:3]
	s_cbranch_vccnz .LBB0_2830
	v_bfe_u32 v3, v0, 2, 4
	v_lshrrev_b32_e32 v4, 3, v0
	s_add_u32 s27, s90, 0x7b00000
	v_and_or_b32 v5, v4, 48, v3
	v_or_b32_e32 v4, 64, v4
	s_movk_i32 s0, 0x70
	s_addc_u32 s30, s91, 0
	v_and_or_b32 v3, v4, s0, v3
	s_lshr_b32 s3, s10, 6
	s_lshl_b32 s0, s18, 10
	s_lshr_b32 s2, s10, 8
	s_lshl_b32 s31, s3, 10
	s_addk_i32 s0, 0xfc00
	s_cmp_lg_u32 s18, 0
	s_cselect_b32 s8, s0, 0
	s_ashr_i32 s9, s8, 31
	s_mul_i32 s1, s17, 0x2c0000
	s_mul_hi_i32 s0, s17, 0x2c0000
	s_add_u32 s1, s27, s1
	v_lshlrev_b32_e32 v1, 4, v0
	v_and_b32_e32 v2, 32, v0
	s_addc_u32 s11, s30, s0
	v_bitop3_b32 v1, v1, v2, 48 bitop3:0x6c
	v_and_b32_e32 v10, 64, v0
	s_add_u32 s0, s1, s8
	v_or_b32_e32 v2, v1, v10
	v_mul_u32_u24_e32 v11, 0x2c00, v5
	s_addc_u32 s1, s11, s9
	s_add_i32 s33, s31, 0
	v_or_b32_e32 v132, v11, v2
	s_add_i32 m0, s33, 0x10000
	s_mul_i32 s7, s16, 0x2c0000
	global_load_lds_dwordx4 v132, s[0:1]
	s_add_i32 m0, s33, 0x12000
	v_readlane_b32 s12, v242, 17
	s_mul_hi_i32 s6, s16, 0x2c0000
	v_readlane_b32 s13, v242, 18
	s_add_u32 s11, s12, s7
	v_mul_u32_u24_e32 v12, 0x2c00, v3
	s_addc_u32 s12, s13, s6
	v_or_b32_e32 v134, v12, v2
	s_add_u32 s6, s0, 0x160000
	global_load_lds_dwordx4 v134, s[0:1]
	s_addc_u32 s7, s1, 0
	s_add_i32 m0, s33, 0x14000
	v_mov_b32_e32 v133, 0
	global_load_lds_dwordx4 v132, s[6:7]
	s_add_i32 m0, s33, 0x16000
	s_add_u32 s24, s11, s8
	s_addc_u32 s25, s12, s9
	s_add_i32 s34, s33, 0x2000
	global_load_lds_dwordx4 v134, s[6:7]
	s_mov_b32 m0, s33
	s_add_u32 s6, s24, 0x160000
	global_load_lds_dwordx4 v132, s[24:25]
	s_mov_b32 m0, s34
	s_addc_u32 s7, s25, 0
	s_add_i32 s35, s33, 0x4000
	global_load_lds_dwordx4 v134, s[24:25]
	s_mov_b32 m0, s35
	s_add_i32 s40, s33, 0x6000
	global_load_lds_dwordx4 v132, s[6:7]
	s_mov_b32 m0, s40
	v_mov_b32_e32 v135, v133
	global_load_lds_dwordx4 v134, s[6:7]
	s_cmp_eq_u32 s2, 1
	s_mov_b32 s41, 0
	v_lshl_add_u64 v[8:9], s[0:1], 0, v[132:133]
	v_lshl_add_u64 v[6:7], s[0:1], 0, v[134:135]
	v_lshl_add_u64 v[2:3], s[24:25], 0, v[132:133]
	s_cselect_b64 s[6:7], -1, 0
	s_cmp_lg_u32 s2, 1
	v_lshl_add_u64 v[4:5], s[24:25], 0, v[134:135]
	s_cbranch_scc1 .LBB0_2800
	s_barrier
	s_setprio 1

.LBB0_2818:
	ds_read_b128 v[128:131], v190
	ds_read_b128 v[158:161], v190 offset:1024
	ds_read_b128 v[162:165], v190 offset:2048
	ds_read_b128 v[166:169], v190 offset:3072
	ds_read_b128 v[170:173], v191
	ds_read_b128 v[174:177], v191 offset:1024
	ds_read_b128 v[178:181], v191 offset:2048
	ds_read_b128 v[182:185], v191 offset:3072
	s_add_i32 s59, s22, 2
	s_add_u32 s0, s36, 0xffea0080
	s_addc_u32 s1, s37, -1
	s_cmp_eq_u32 s58, s22
	s_cselect_b32 s22, s12, s0
	s_cselect_b32 s23, s13, s1
	s_cselect_b32 s1, s15, s25
	s_cselect_b32 s0, s14, s24
	v_lshl_add_u64 v[186:187], s[36:37], 0, v[152:153]
	s_add_i32 m0, s33, 0xc000
	ds_read_b128 v[194:197], v192
	ds_read_b128 v[198:201], v192 offset:1024
	ds_read_b128 v[202:205], v192 offset:2048
	ds_read_b128 v[206:209], v192 offset:3072
	ds_read_b128 v[210:213], v192 offset:4096
	ds_read_b128 v[214:217], v192 offset:5120
	ds_read_b128 v[218:221], v192 offset:6144
	ds_read_b128 v[222:225], v192 offset:7168
	global_load_lds_dwordx4 v[186:187], off
	v_lshl_add_u64 v[186:187], s[36:37], 0, v[154:155]
	s_add_i32 m0, s33, 0xe000
	s_nop 0
	global_load_lds_dwordx4 v[186:187], off
	s_waitcnt vmcnt(8)
	s_waitcnt lgkmcnt(0)
	s_barrier
	s_waitcnt lgkmcnt(0)
	v_mfma_f32_16x16x32_bf16 v[124:127], v[128:131], v[194:197], v[124:127]
	v_mfma_f32_16x16x32_bf16 v[92:95], v[162:165], v[194:197], v[92:95]
	v_mfma_f32_16x16x32_bf16 v[120:123], v[128:131], v[202:205], v[120:123]
	v_mfma_f32_16x16x32_bf16 v[88:91], v[162:165], v[202:205], v[88:91]
	v_mfma_f32_16x16x32_bf16 v[116:119], v[128:131], v[210:213], v[116:119]
	v_mfma_f32_16x16x32_bf16 v[84:87], v[162:165], v[210:213], v[84:87]
	v_mfma_f32_16x16x32_bf16 v[112:115], v[128:131], v[218:221], v[112:115]
	v_mfma_f32_16x16x32_bf16 v[80:83], v[162:165], v[218:221], v[80:83]
	v_mfma_f32_16x16x32_bf16 v[124:127], v[158:161], v[198:201], v[124:127]
	v_mfma_f32_16x16x32_bf16 v[92:95], v[166:169], v[198:201], v[92:95]
	v_mfma_f32_16x16x32_bf16 v[120:123], v[158:161], v[206:209], v[120:123]
	v_mfma_f32_16x16x32_bf16 v[88:91], v[166:169], v[206:209], v[88:91]
	v_mfma_f32_16x16x32_bf16 v[116:119], v[158:161], v[214:217], v[116:119]
	v_mfma_f32_16x16x32_bf16 v[84:87], v[166:169], v[214:217], v[84:87]
	v_mfma_f32_16x16x32_bf16 v[112:115], v[158:161], v[222:225], v[112:115]
	v_mfma_f32_16x16x32_bf16 v[80:83], v[166:169], v[222:225], v[80:83]
	v_mfma_f32_16x16x32_bf16 v[60:63], v[170:173], v[194:197], v[60:63]
	v_mfma_f32_16x16x32_bf16 v[28:31], v[178:181], v[194:197], v[28:31]
	v_mfma_f32_16x16x32_bf16 v[56:59], v[170:173], v[202:205], v[56:59]
	v_mfma_f32_16x16x32_bf16 v[24:27], v[178:181], v[202:205], v[24:27]
	v_mfma_f32_16x16x32_bf16 v[52:55], v[170:173], v[210:213], v[52:55]
	v_mfma_f32_16x16x32_bf16 v[20:23], v[178:181], v[210:213], v[20:23]
	v_mfma_f32_16x16x32_bf16 v[48:51], v[170:173], v[218:221], v[48:51]
	v_mfma_f32_16x16x32_bf16 v[16:19], v[178:181], v[218:221], v[16:19]
	v_mfma_f32_16x16x32_bf16 v[60:63], v[174:177], v[198:201], v[60:63]
	v_mfma_f32_16x16x32_bf16 v[28:31], v[182:185], v[198:201], v[28:31]
	v_mfma_f32_16x16x32_bf16 v[56:59], v[174:177], v[206:209], v[56:59]
	v_mfma_f32_16x16x32_bf16 v[24:27], v[182:185], v[206:209], v[24:27]
	v_mfma_f32_16x16x32_bf16 v[52:55], v[174:177], v[214:217], v[52:55]
	v_mfma_f32_16x16x32_bf16 v[20:23], v[182:185], v[214:217], v[20:23]
	v_mfma_f32_16x16x32_bf16 v[48:51], v[174:177], v[222:225], v[48:51]
	v_mfma_f32_16x16x32_bf16 v[16:19], v[182:185], v[222:225], v[16:19]
	s_barrier
	s_add_i32 s21, s52, s31
	v_lshl_add_u64 v[186:187], s[0:1], 0, v[132:133]
	s_mov_b32 m0, s21
	ds_read_b128 v[194:197], v192 offset:16384
	ds_read_b128 v[198:201], v192 offset:17408
	ds_read_b128 v[202:205], v192 offset:18432
	ds_read_b128 v[206:209], v192 offset:19456
	ds_read_b128 v[210:213], v192 offset:20480
	ds_read_b128 v[214:217], v192 offset:21504
	ds_read_b128 v[218:221], v192 offset:22528
	ds_read_b128 v[222:225], v192 offset:23552
	global_load_lds_dwordx4 v[186:187], off
	s_add_i32 m0, s21, 0x2000
	s_add_u32 s28, s0, 0x160000
	v_lshl_add_u64 v[226:227], s[0:1], 0, v[134:135]
	s_addc_u32 s29, s1, 0
	s_add_i32 s21, s53, s31
	global_load_lds_dwordx4 v[226:227], off
	v_lshl_add_u64 v[228:229], s[28:29], 0, v[132:133]
	s_mov_b32 m0, s21
	v_lshl_add_u64 v[230:231], s[22:23], 0, v[134:135]
	global_load_lds_dwordx4 v[228:229], off
	v_lshl_add_u64 v[228:229], s[28:29], 0, v[134:135]
	s_add_i32 m0, s21, 0x2000
	s_nop 0
	global_load_lds_dwordx4 v[228:229], off
	v_lshl_add_u64 v[228:229], s[22:23], 0, v[132:133]
	s_mov_b32 m0, s33
	s_nop 0
	global_load_lds_dwordx4 v[228:229], off
	s_mov_b32 m0, s34
	s_nop 0
	global_load_lds_dwordx4 v[230:231], off
	s_waitcnt vmcnt(8)
	s_waitcnt lgkmcnt(0)
	s_barrier
	s_waitcnt lgkmcnt(0)
	v_mfma_f32_16x16x32_bf16 v[108:111], v[128:131], v[194:197], v[108:111]
	v_mfma_f32_16x16x32_bf16 v[76:79], v[162:165], v[194:197], v[76:79]
	v_mfma_f32_16x16x32_bf16 v[104:107], v[128:131], v[202:205], v[104:107]
	v_mfma_f32_16x16x32_bf16 v[72:75], v[162:165], v[202:205], v[72:75]
	v_mfma_f32_16x16x32_bf16 v[100:103], v[128:131], v[210:213], v[100:103]
	v_mfma_f32_16x16x32_bf16 v[68:71], v[162:165], v[210:213], v[68:71]
	v_mfma_f32_16x16x32_bf16 v[96:99], v[128:131], v[218:221], v[96:99]
	v_mfma_f32_16x16x32_bf16 v[64:67], v[162:165], v[218:221], v[64:67]
	v_mfma_f32_16x16x32_bf16 v[108:111], v[158:161], v[198:201], v[108:111]
	v_mfma_f32_16x16x32_bf16 v[76:79], v[166:169], v[198:201], v[76:79]
	v_mfma_f32_16x16x32_bf16 v[104:107], v[158:161], v[206:209], v[104:107]
	v_mfma_f32_16x16x32_bf16 v[72:75], v[166:169], v[206:209], v[72:75]
	v_mfma_f32_16x16x32_bf16 v[100:103], v[158:161], v[214:217], v[100:103]
	v_mfma_f32_16x16x32_bf16 v[68:71], v[166:169], v[214:217], v[68:71]
	v_mfma_f32_16x16x32_bf16 v[96:99], v[158:161], v[222:225], v[96:99]
	v_mfma_f32_16x16x32_bf16 v[64:67], v[166:169], v[222:225], v[64:67]
	v_mfma_f32_16x16x32_bf16 v[44:47], v[170:173], v[194:197], v[44:47]
	v_mfma_f32_16x16x32_bf16 v[12:15], v[178:181], v[194:197], v[12:15]
	v_mfma_f32_16x16x32_bf16 v[40:43], v[170:173], v[202:205], v[40:43]
	v_mfma_f32_16x16x32_bf16 v[8:11], v[178:181], v[202:205], v[8:11]
	v_mfma_f32_16x16x32_bf16 v[36:39], v[170:173], v[210:213], v[36:39]
	v_mfma_f32_16x16x32_bf16 v[4:7], v[178:181], v[210:213], v[4:7]
	v_mfma_f32_16x16x32_bf16 v[32:35], v[170:173], v[218:221], v[32:35]
	v_mfma_f32_16x16x32_bf16 v[0:3], v[178:181], v[218:221], v[0:3]
	v_mfma_f32_16x16x32_bf16 v[44:47], v[174:177], v[198:201], v[44:47]
	v_mfma_f32_16x16x32_bf16 v[12:15], v[182:185], v[198:201], v[12:15]
	v_mfma_f32_16x16x32_bf16 v[40:43], v[174:177], v[206:209], v[40:43]
	v_mfma_f32_16x16x32_bf16 v[8:11], v[182:185], v[206:209], v[8:11]
	v_mfma_f32_16x16x32_bf16 v[36:39], v[174:177], v[214:217], v[36:39]
	v_mfma_f32_16x16x32_bf16 v[4:7], v[182:185], v[214:217], v[4:7]
	v_mfma_f32_16x16x32_bf16 v[32:35], v[174:177], v[222:225], v[32:35]
	v_mfma_f32_16x16x32_bf16 v[0:3], v[182:185], v[222:225], v[0:3]
	s_barrier
	s_add_i32 s21, 0, 0x18000
	s_add_i32 s28, 0, 0x1c000
	v_add_u32_e32 v166, s21, v188
	v_add_u32_e32 v182, s28, v188
	ds_read_b128 v[128:131], v166
	ds_read_b128 v[158:161], v166 offset:1024
	ds_read_b128 v[162:165], v166 offset:2048
	ds_read_b128 v[166:169], v166 offset:3072
	ds_read_b128 v[170:173], v182
	ds_read_b128 v[174:177], v182 offset:1024
	ds_read_b128 v[178:181], v182 offset:2048
	ds_read_b128 v[182:185], v182 offset:3072
	s_add_u32 s22, s22, 0x160000
	s_addc_u32 s23, s23, 0
	s_mov_b32 m0, s35
	v_lshl_add_u64 v[232:233], s[22:23], 0, v[132:133]
	ds_read_b128 v[194:197], v192 offset:32768
	ds_read_b128 v[198:201], v192 offset:33792
	ds_read_b128 v[202:205], v192 offset:34816
	ds_read_b128 v[206:209], v192 offset:35840
	ds_read_b128 v[210:213], v192 offset:36864
	ds_read_b128 v[214:217], v192 offset:37888
	ds_read_b128 v[218:221], v192 offset:38912
	ds_read_b128 v[222:225], v192 offset:39936
	global_load_lds_dwordx4 v[232:233], off
	v_lshl_add_u64 v[232:233], s[22:23], 0, v[134:135]
	s_mov_b32 m0, s40
	s_nop 0
	global_load_lds_dwordx4 v[232:233], off
	s_waitcnt vmcnt(8)
	s_waitcnt lgkmcnt(0)
	s_barrier
	s_waitcnt lgkmcnt(0)
	v_mfma_f32_16x16x32_bf16 v[124:127], v[128:131], v[194:197], v[124:127]
	v_mfma_f32_16x16x32_bf16 v[92:95], v[162:165], v[194:197], v[92:95]
	v_mfma_f32_16x16x32_bf16 v[120:123], v[128:131], v[202:205], v[120:123]
	v_mfma_f32_16x16x32_bf16 v[88:91], v[162:165], v[202:205], v[88:91]
	v_mfma_f32_16x16x32_bf16 v[116:119], v[128:131], v[210:213], v[116:119]
	v_mfma_f32_16x16x32_bf16 v[84:87], v[162:165], v[210:213], v[84:87]
	v_mfma_f32_16x16x32_bf16 v[112:115], v[128:131], v[218:221], v[112:115]
	v_mfma_f32_16x16x32_bf16 v[80:83], v[162:165], v[218:221], v[80:83]
	v_mfma_f32_16x16x32_bf16 v[124:127], v[158:161], v[198:201], v[124:127]
	v_mfma_f32_16x16x32_bf16 v[92:95], v[166:169], v[198:201], v[92:95]
	v_mfma_f32_16x16x32_bf16 v[120:123], v[158:161], v[206:209], v[120:123]
	v_mfma_f32_16x16x32_bf16 v[88:91], v[166:169], v[206:209], v[88:91]
	v_mfma_f32_16x16x32_bf16 v[116:119], v[158:161], v[214:217], v[116:119]
	v_mfma_f32_16x16x32_bf16 v[84:87], v[166:169], v[214:217], v[84:87]
	v_mfma_f32_16x16x32_bf16 v[112:115], v[158:161], v[222:225], v[112:115]
	v_mfma_f32_16x16x32_bf16 v[80:83], v[166:169], v[222:225], v[80:83]
	v_mfma_f32_16x16x32_bf16 v[60:63], v[170:173], v[194:197], v[60:63]
	v_mfma_f32_16x16x32_bf16 v[28:31], v[178:181], v[194:197], v[28:31]
	v_mfma_f32_16x16x32_bf16 v[56:59], v[170:173], v[202:205], v[56:59]
	v_mfma_f32_16x16x32_bf16 v[24:27], v[178:181], v[202:205], v[24:27]
	v_mfma_f32_16x16x32_bf16 v[52:55], v[170:173], v[210:213], v[52:55]
	v_mfma_f32_16x16x32_bf16 v[20:23], v[178:181], v[210:213], v[20:23]
	v_mfma_f32_16x16x32_bf16 v[48:51], v[170:173], v[218:221], v[48:51]
	v_mfma_f32_16x16x32_bf16 v[16:19], v[178:181], v[218:221], v[16:19]
	v_mfma_f32_16x16x32_bf16 v[60:63], v[174:177], v[198:201], v[60:63]
	v_mfma_f32_16x16x32_bf16 v[28:31], v[182:185], v[198:201], v[28:31]
	v_mfma_f32_16x16x32_bf16 v[56:59], v[174:177], v[206:209], v[56:59]
	v_mfma_f32_16x16x32_bf16 v[24:27], v[182:185], v[206:209], v[24:27]
	v_mfma_f32_16x16x32_bf16 v[52:55], v[174:177], v[214:217], v[52:55]
	v_mfma_f32_16x16x32_bf16 v[20:23], v[182:185], v[214:217], v[20:23]
	v_mfma_f32_16x16x32_bf16 v[48:51], v[174:177], v[222:225], v[48:51]
	v_mfma_f32_16x16x32_bf16 v[16:19], v[182:185], v[222:225], v[16:19]
	s_barrier
	s_add_i32 s21, s21, s31
	v_lshl_add_u64 v[186:187], v[186:187], 0, s[8:9]
	s_mov_b32 m0, s21
	ds_read_b128 v[194:197], v192 offset:49152
	ds_read_b128 v[198:201], v192 offset:50176
	ds_read_b128 v[202:205], v192 offset:51200
	ds_read_b128 v[206:209], v192 offset:52224
	ds_read_b128 v[210:213], v192 offset:53248
	ds_read_b128 v[214:217], v192 offset:54272
	ds_read_b128 v[218:221], v192 offset:55296
	ds_read_b128 v[222:225], v192 offset:56320
	global_load_lds_dwordx4 v[186:187], off
	s_add_i32 m0, s21, 0x2000
	s_add_u32 s0, s0, 0x160080
	v_lshl_add_u64 v[186:187], v[226:227], 0, s[8:9]
	s_addc_u32 s1, s1, 0
	s_add_i32 s21, s28, s31
	global_load_lds_dwordx4 v[186:187], off
	v_lshl_add_u64 v[186:187], s[0:1], 0, v[132:133]
	s_mov_b32 m0, s21
	s_nop 0
	global_load_lds_dwordx4 v[186:187], off
	v_lshl_add_u64 v[186:187], s[0:1], 0, v[134:135]
	s_add_i32 m0, s21, 0x2000
	s_nop 0
	global_load_lds_dwordx4 v[186:187], off
	v_lshl_add_u64 v[186:187], v[228:229], 0, s[8:9]
	s_mov_b32 m0, s44
	s_nop 0
	global_load_lds_dwordx4 v[186:187], off
	v_lshl_add_u64 v[186:187], v[230:231], 0, s[8:9]
	s_mov_b32 m0, s45
	s_nop 0
	global_load_lds_dwordx4 v[186:187], off
	s_waitcnt vmcnt(8)
	s_waitcnt lgkmcnt(0)
	s_barrier
	s_waitcnt lgkmcnt(0)
	v_mfma_f32_16x16x32_bf16 v[108:111], v[128:131], v[194:197], v[108:111]
	v_mfma_f32_16x16x32_bf16 v[76:79], v[162:165], v[194:197], v[76:79]
	v_mfma_f32_16x16x32_bf16 v[104:107], v[128:131], v[202:205], v[104:107]
	v_mfma_f32_16x16x32_bf16 v[72:75], v[162:165], v[202:205], v[72:75]
	v_mfma_f32_16x16x32_bf16 v[100:103], v[128:131], v[210:213], v[100:103]
	v_mfma_f32_16x16x32_bf16 v[68:71], v[162:165], v[210:213], v[68:71]
	v_mfma_f32_16x16x32_bf16 v[96:99], v[128:131], v[218:221], v[96:99]
	v_mfma_f32_16x16x32_bf16 v[64:67], v[162:165], v[218:221], v[64:67]
	v_mfma_f32_16x16x32_bf16 v[108:111], v[158:161], v[198:201], v[108:111]
	v_mfma_f32_16x16x32_bf16 v[76:79], v[166:169], v[198:201], v[76:79]
	v_mfma_f32_16x16x32_bf16 v[104:107], v[158:161], v[206:209], v[104:107]
	v_mfma_f32_16x16x32_bf16 v[72:75], v[166:169], v[206:209], v[72:75]
	v_mfma_f32_16x16x32_bf16 v[100:103], v[158:161], v[214:217], v[100:103]
	v_mfma_f32_16x16x32_bf16 v[68:71], v[166:169], v[214:217], v[68:71]
	v_mfma_f32_16x16x32_bf16 v[96:99], v[158:161], v[222:225], v[96:99]
	v_mfma_f32_16x16x32_bf16 v[64:67], v[166:169], v[222:225], v[64:67]
	v_mfma_f32_16x16x32_bf16 v[44:47], v[170:173], v[194:197], v[44:47]
	v_mfma_f32_16x16x32_bf16 v[12:15], v[178:181], v[194:197], v[12:15]
	v_mfma_f32_16x16x32_bf16 v[40:43], v[170:173], v[202:205], v[40:43]
	v_mfma_f32_16x16x32_bf16 v[8:11], v[178:181], v[202:205], v[8:11]
	v_mfma_f32_16x16x32_bf16 v[36:39], v[170:173], v[210:213], v[36:39]
	v_mfma_f32_16x16x32_bf16 v[4:7], v[178:181], v[210:213], v[4:7]
	v_mfma_f32_16x16x32_bf16 v[32:35], v[170:173], v[218:221], v[32:35]
	v_mfma_f32_16x16x32_bf16 v[0:3], v[178:181], v[218:221], v[0:3]
	v_mfma_f32_16x16x32_bf16 v[44:47], v[174:177], v[198:201], v[44:47]
	v_mfma_f32_16x16x32_bf16 v[12:15], v[182:185], v[198:201], v[12:15]
	v_mfma_f32_16x16x32_bf16 v[40:43], v[174:177], v[206:209], v[40:43]
	v_mfma_f32_16x16x32_bf16 v[8:11], v[182:185], v[206:209], v[8:11]
	v_mfma_f32_16x16x32_bf16 v[36:39], v[174:177], v[214:217], v[36:39]
	v_mfma_f32_16x16x32_bf16 v[4:7], v[182:185], v[214:217], v[4:7]
	v_mfma_f32_16x16x32_bf16 v[32:35], v[174:177], v[222:225], v[32:35]
	v_mfma_f32_16x16x32_bf16 v[0:3], v[182:185], v[222:225], v[0:3]
	s_barrier
	s_add_u32 s36, s36, 0x100
	s_addc_u32 s37, s37, 0
	s_add_u32 s24, s24, 0x100
	s_addc_u32 s25, s25, 0
	s_cmp_ge_u32 s59, s19
	s_mov_b32 s22, s59
	s_cbranch_scc0 .LBB0_2818
	s_and_b64 vcc, exec, s[10:11]
	s_cbranch_vccz .LBB0_2821
	s_barrier

.LBB0_2884:
	s_setprio 0
	s_endpgm
